# stack + fold-norm table loads issued together + wave sums of the norm phases as DPP/permlane butterflies (same pairs and order, no LDS round trips)
# baseline (speedup 1.0000x reference)
; __device__ __forceinline__ float ssq8(const f32x4& a, const f32x4& b) { return ((a[0] * a[0] + a[1] * a[1]) + (a[2] * a[2] + a[3] * a[3])) + ((b[0] * b[0] + b[1] * b[1]) + (b[2] * b[2] + b[3] * b[3])); }
; template <int XF32> __device__ __forceinline__ void norm_mod_phase(const void* x, const float* modl, int ch_shift, int ch_scale, bf16* H, int gw, int NGW, int lane) {
;     ...
;     for (int blk = gw; blk < M / 8; blk += NGW) {
;         const int r0 = blk * 8, b = r0 >> 12;
;         const f32x4* shp = (const f32x4*)(modl + (size_t)b * MODW + ch_shift * DM); const f32x4* scp = (const f32x4*)(modl + (size_t)b * MODW + ch_scale * DM);
;         f32x4 sh[4][2], sc[4][2];
; #pragma unroll
;         for (int j = 0; j < 4; ++j)
; #pragma unroll
;             for (int q = 0; q < 2; ++q) { sh[j][q] = shp[2 * (lane + 64 * j) + q]; sc[j][q] = scp[2 * (lane + 64 * j) + q] + 1.f; }
;         for (int rr = 0; rr < 8; ++rr) {
;             const unsigned char* xr = (const unsigned char*)x + (size_t)(r0 + rr) * rowb; f32x4 v[4][2]; float s = 0.f;
; #pragma unroll
;             for (int j = 0; j < 4; ++j) ld_row8<XF32>(xr, lane, j, v[j][0], v[j][1]);
; #pragma unroll
;             for (int j = 0; j < 4; ++j) s += ssq8(v[j][0], v[j][1]);
.LBB0_161:
	s_ashr_i32 s0, s3, 9
	s_mul_hi_i32 s1, s0, 0x12000
	s_mul_i32 s0, s0, 0x12000
	s_add_u32 s64, s24, s0
	s_addc_u32 s65, s26, s1
	s_add_u32 s4, s64, 0x2000
	s_addc_u32 s5, s65, 0
	v_lshl_add_u64 v[16:17], s[64:65], 0, v[38:39]
	v_lshl_add_u64 v[4:5], s[4:5], 0, v[38:39]
	global_load_dwordx4 v[8:11], v[16:17], off offset:16
	global_load_dwordx4 v[12:15], v[16:17], off
	global_load_dwordx4 v[178:181], v[4:5], off offset:16
	s_nop 0
	global_load_dwordx4 v[182:185], v[4:5], off
	v_lshl_add_u64 v[20:21], v[32:33], 4, s[4:5]
	v_lshl_add_u64 v[28:29], s[4:5], 0, v[40:41]
	v_lshl_add_u64 v[68:69], s[4:5], 0, v[42:43]
	s_add_i32 s0, s8, -7
	s_ashr_i32 s1, s0, 31
	s_ashr_i32 s9, s8, 31
	s_add_i32 s3, s3, s58
	global_load_dwordx4 v[0:3], v[16:17], off offset:2064
	global_load_dwordx4 v[4:7], v[16:17], off offset:2048
	s_nop 0
	global_load_dwordx4 v[186:189], v[20:21], off offset:16
	s_nop 0
	global_load_dwordx4 v[190:193], v[20:21], off
	v_lshl_add_u64 v[20:21], s[64:65], 0, v[40:41]
	global_load_dwordx4 v[16:19], v[20:21], off offset:16
	s_nop 0
	global_load_dwordx4 v[20:23], v[20:21], off
	s_nop 0
	global_load_dwordx4 v[194:197], v[28:29], off offset:16
	s_nop 0
	global_load_dwordx4 v[198:201], v[28:29], off
	v_lshl_add_u64 v[28:29], s[64:65], 0, v[42:43]
	global_load_dwordx4 v[24:27], v[28:29], off offset:16
	s_nop 0
	global_load_dwordx4 v[28:31], v[28:29], off
	s_nop 0
	global_load_dwordx4 v[202:205], v[68:69], off offset:16
	s_nop 0
	global_load_dwordx4 v[206:209], v[68:69], off
	s_lshl_b64 s[64:65], s[0:1], 12
	v_lshl_add_u64 v[88:89], v[34:35], 0, s[64:65]
	global_load_dwordx4 v[76:79], v[88:89], off
	global_load_dwordx4 v[80:83], v[88:89], off offset:1024
	global_load_dwordx4 v[84:87], v[88:89], off offset:2048
	s_nop 0
	global_load_dwordx4 v[88:91], v[88:89], off offset:3072
	s_waitcnt vmcnt(4)
	v_pk_add_f32 v[52:53], v[180:181], 1.0 op_sel_hi:[1,0]
	v_pk_add_f32 v[56:57], v[184:185], 1.0 op_sel_hi:[1,0]
	v_pk_add_f32 v[58:59], v[182:183], 1.0 op_sel_hi:[1,0]
	v_pk_add_f32 v[54:55], v[178:179], 1.0 op_sel_hi:[1,0]
	v_pk_add_f32 v[44:45], v[188:189], 1.0 op_sel_hi:[1,0]
	v_pk_add_f32 v[50:51], v[190:191], 1.0 op_sel_hi:[1,0]
	v_pk_add_f32 v[48:49], v[192:193], 1.0 op_sel_hi:[1,0]
	v_pk_add_f32 v[46:47], v[186:187], 1.0 op_sel_hi:[1,0]
	v_pk_add_f32 v[60:61], v[196:197], 1.0 op_sel_hi:[1,0]
	v_pk_add_f32 v[66:67], v[198:199], 1.0 op_sel_hi:[1,0]
	v_pk_add_f32 v[64:65], v[200:201], 1.0 op_sel_hi:[1,0]
	v_pk_add_f32 v[62:63], v[194:195], 1.0 op_sel_hi:[1,0]
	v_pk_add_f32 v[72:73], v[208:209], 1.0 op_sel_hi:[1,0]
	v_pk_add_f32 v[74:75], v[206:207], 1.0 op_sel_hi:[1,0]
	v_pk_add_f32 v[68:69], v[204:205], 1.0 op_sel_hi:[1,0]
	v_pk_add_f32 v[70:71], v[202:203], 1.0 op_sel_hi:[1,0]
	s_add_i32 s100, s8, -6
	s_ashr_i32 s101, s100, 31
	s_lshl_b64 s[100:101], s[100:101], 12
	v_lshl_add_u64 v[210:211], v[34:35], 0, s[100:101]
	s_nop 0
	global_load_dwordx4 v[194:197], v[210:211], off
	global_load_dwordx4 v[198:201], v[210:211], off offset:1024
	global_load_dwordx4 v[202:205], v[210:211], off offset:2048
	global_load_dwordx4 v[206:209], v[210:211], off offset:3072
	s_waitcnt vmcnt(7)
	v_lshlrev_b32_e32 v97, 16, v77
	v_lshlrev_b32_e32 v96, 16, v76
	v_and_b32_e32 v77, 0xffff0000, v77
	v_and_b32_e32 v76, 0xffff0000, v76
	v_lshlrev_b32_e32 v101, 16, v79
	v_lshlrev_b32_e32 v100, 16, v78
	v_and_b32_e32 v79, 0xffff0000, v79
	v_and_b32_e32 v78, 0xffff0000, v78
	v_pk_mul_f32 v[98:99], v[76:77], v[76:77]
	v_pk_mul_f32 v[102:103], v[78:79], v[78:79]
	s_waitcnt vmcnt(4)
	v_lshlrev_b32_e32 v92, 16, v88
	v_and_b32_e32 v93, 0xffff0000, v88
	v_pk_fma_f32 v[98:99], v[96:97], v[96:97], v[98:99]
	v_pk_fma_f32 v[102:103], v[100:101], v[100:101], v[102:103]
	v_lshlrev_b32_e32 v105, 16, v81
	v_lshlrev_b32_e32 v104, 16, v80
	v_and_b32_e32 v81, 0xffff0000, v81
	v_and_b32_e32 v80, 0xffff0000, v80
	v_lshlrev_b32_e32 v109, 16, v83
	v_lshlrev_b32_e32 v108, 16, v82
	v_and_b32_e32 v83, 0xffff0000, v83
	v_and_b32_e32 v82, 0xffff0000, v82
	v_pk_mul_f32 v[106:107], v[80:81], v[80:81]
	v_pk_mul_f32 v[110:111], v[82:83], v[82:83]
	v_mul_f32_e32 v116, v92, v92
	v_mul_f32_e32 v117, v93, v93
	v_pk_add_f32 v[98:99], v[98:99], v[98:99] op_sel:[0,1] op_sel_hi:[1,0]
	v_pk_add_f32 v[102:103], v[102:103], v[102:103] op_sel:[0,1] op_sel_hi:[1,0]
	v_lshlrev_b32_e32 v88, 16, v89
	v_and_b32_e32 v89, 0xffff0000, v89
	v_pk_fma_f32 v[106:107], v[104:105], v[104:105], v[106:107]
	v_pk_fma_f32 v[110:111], v[108:109], v[108:109], v[110:111]
	v_mov_b32_e32 v99, v116
	v_mov_b32_e32 v103, v117
	v_mul_f32_e32 v118, v88, v88
	v_mul_f32_e32 v119, v89, v89
	v_pk_add_f32 v[98:99], v[98:99], v[102:103]
	v_pk_add_f32 v[102:103], v[106:107], v[106:107] op_sel:[0,1] op_sel_hi:[1,0]
	v_pk_add_f32 v[106:107], v[110:111], v[110:111] op_sel:[0,1] op_sel_hi:[1,0]
	v_mov_b32_e32 v103, v118
	v_mov_b32_e32 v107, v119
	v_lshlrev_b32_e32 v112, 16, v84
	v_and_b32_e32 v113, 0xffff0000, v84
	v_lshlrev_b32_e32 v84, 16, v85
	v_and_b32_e32 v85, 0xffff0000, v85
	v_pk_add_f32 v[102:103], v[102:103], v[106:107]
	v_lshlrev_b32_e32 v94, 16, v90
	v_and_b32_e32 v95, 0xffff0000, v90
	v_pk_add_f32 v[98:99], v[98:99], v[102:103]
	v_mul_f32_e32 v102, v113, v113
	v_mul_f32_e32 v106, v85, v85
	v_mul_f32_e32 v120, v94, v94
	v_mul_f32_e32 v121, v95, v95
	v_pk_fma_f32 v[102:103], v[112:113], v[112:113], v[102:103] op_sel_hi:[1,1,0]
	v_pk_fma_f32 v[106:107], v[84:85], v[84:85], v[106:107] op_sel_hi:[1,1,0]
	v_lshlrev_b32_e32 v114, 16, v86
	v_and_b32_e32 v115, 0xffff0000, v86
	v_lshlrev_b32_e32 v86, 16, v87
	v_and_b32_e32 v87, 0xffff0000, v87
	v_mov_b32_e32 v103, v120
	v_mov_b32_e32 v107, v121
	v_lshlrev_b32_e32 v90, 16, v91
; __device__ __forceinline__ v4u pk8(f32x4 a, f32x4 b) { v4u w; w.x = pk2(a[0], a[1]); w.y = pk2(a[2], a[3]); w.z = pk2(b[0], b[1]); w.w = pk2(b[2], b[3]); return w; }
; __device__ __forceinline__ float ssq8(const f32x4& a, const f32x4& b) { return ((a[0] * a[0] + a[1] * a[1]) + (a[2] * a[2] + a[3] * a[3])) + ((b[0] * b[0] + b[1] * b[1]) + (b[2] * b[2] + b[3] * b[3])); }
; __device__ __forceinline__ float wave_sum(float v) {
; #pragma unroll
;     for (int o = 1; o < 64; o <<= 1) v += shfl_xor_f(v, o);
;     return v;
; template <int XF32> __device__ __forceinline__ void norm_mod_phase(const void* x, const float* modl, int ch_shift, int ch_scale, bf16* H, int gw, int NGW, int lane) {
;     ...
;             for (int j = 0; j < 4; ++j) s += ssq8(v[j][0], v[j][1]);
;             const float rstd = 1.f / sqrtf(wave_sum(s) * (1.f / DM) + EPS);
;             v4u* o = (v4u*)(H + (size_t)(r0 + rr) * DM);
; #pragma unroll
;             for (int j = 0; j < 4; ++j) o[lane + 64 * j] = pk8(v[j][0] * rstd * sc[j][0] + sh[j][0], v[j][1] * rstd * sc[j][1] + sh[j][1]);
	v_and_b32_e32 v91, 0xffff0000, v91
	s_add_i32 s100, s8, -5
	s_ashr_i32 s101, s100, 31
	s_lshl_b64 s[100:101], s[100:101], 12
	v_lshl_add_u64 v[210:211], v[34:35], 0, s[100:101]
	s_nop 0
	global_load_dwordx4 v[178:181], v[210:211], off
	global_load_dwordx4 v[182:185], v[210:211], off offset:1024
	global_load_dwordx4 v[186:189], v[210:211], off offset:2048
	global_load_dwordx4 v[190:193], v[210:211], off offset:3072
	v_pk_add_f32 v[102:103], v[102:103], v[106:107]
	v_mul_f32_e32 v106, v115, v115
	v_mul_f32_e32 v110, v87, v87
	v_mul_f32_e32 v122, v90, v90
	v_mul_f32_e32 v123, v91, v91
	v_pk_fma_f32 v[106:107], v[114:115], v[114:115], v[106:107] op_sel_hi:[1,1,0]
	v_pk_fma_f32 v[110:111], v[86:87], v[86:87], v[110:111] op_sel_hi:[1,1,0]
	v_mov_b32_e32 v107, v122
	v_mov_b32_e32 v111, v123
	v_pk_add_f32 v[106:107], v[106:107], v[110:111]
	s_nop 0
	v_pk_add_f32 v[102:103], v[102:103], v[106:107]
	s_nop 0
	v_pk_add_f32 v[98:99], v[98:99], v[102:103]
	s_nop 0
	v_add_f32_e32 v98, v98, v99
	s_nop 1
	v_add_f32_dpp v98, v98, v98 quad_perm:[1,0,3,2] row_mask:0xf bank_mask:0xf
	s_nop 1
	v_add_f32_dpp v98, v98, v98 quad_perm:[2,3,0,1] row_mask:0xf bank_mask:0xf
	s_nop 1
	v_add_f32_dpp v98, v98, v98 row_half_mirror row_mask:0xf bank_mask:0xf
	s_nop 1
	v_add_f32_dpp v98, v98, v98 row_mirror row_mask:0xf bank_mask:0xf
	v_mov_b32_e32 v99, v98
	s_nop 1
	v_permlane16_swap_b32_e32 v99, v98
	s_nop 1
	v_add_f32_e32 v98, v98, v99
	v_mov_b32_e32 v99, v98
	s_nop 1
	v_permlane32_swap_b32_e32 v99, v98
	s_nop 1
	v_add_f32_e32 v98, v98, v99
	v_fmamk_f32 v98, v98, 0x3a000000, v224
	v_cmp_gt_f32_e32 vcc, s41, v98
	v_mul_f32_e32 v99, 0x4f800000, v98
	s_nop 0
	v_cndmask_b32_e32 v98, v98, v99, vcc
	v_sqrt_f32_e32 v99, v98
	s_nop 0
	v_add_u32_e32 v102, -1, v99
	v_fma_f32 v103, -v102, v99, v98
	v_cmp_ge_f32_e64 s[4:5], 0, v103
	v_add_u32_e32 v103, 1, v99
	s_nop 0
	v_cndmask_b32_e64 v102, v99, v102, s[4:5]
	v_fma_f32 v99, -v103, v99, v98
	v_cmp_lt_f32_e64 s[4:5], 0, v99
	s_nop 1
	v_cndmask_b32_e64 v99, v102, v103, s[4:5]
	v_mul_f32_e32 v102, 0x37800000, v99
	v_cndmask_b32_e32 v99, v99, v102, vcc
	v_cmp_class_f32_e32 vcc, v98, v225
	s_nop 1
	v_cndmask_b32_e32 v98, v99, v98, vcc
	v_div_scale_f32 v99, s[0:1], v98, v98, 1.0
	v_rcp_f32_e32 v102, v99
	s_add_i32 s0, s8, -6
	s_ashr_i32 s1, s0, 31
	v_fma_f32 v103, -v99, v102, 1.0
	v_fmac_f32_e32 v102, v103, v102
	v_div_scale_f32 v103, vcc, 1.0, v98, 1.0
	v_mul_f32_e32 v106, v103, v102
	v_fma_f32 v107, -v99, v106, v103
	v_fmac_f32_e32 v106, v107, v102
	v_fma_f32 v99, -v99, v106, v103
	v_div_fmas_f32 v99, v99, v102, v106
	v_div_fixup_f32 v98, v99, v98, 1.0
	v_mov_b32_e32 v102, v96
	v_mov_b32_e32 v103, v76
	v_mov_b32_e32 v76, v97
	v_pk_mul_f32 v[102:103], v[98:99], v[102:103] op_sel_hi:[0,1]
	v_pk_mul_f32 v[76:77], v[98:99], v[76:77] op_sel_hi:[0,1]
	v_pk_fma_f32 v[96:97], v[56:57], v[76:77], v[14:15]
	v_pk_fma_f32 v[76:77], v[58:59], v[102:103], v[12:13]
	v_mov_b32_e32 v102, v100
	v_mov_b32_e32 v103, v78
	v_mov_b32_e32 v78, v101
	v_pk_mul_f32 v[102:103], v[98:99], v[102:103] op_sel_hi:[0,1]
	v_pk_mul_f32 v[78:79], v[98:99], v[78:79] op_sel_hi:[0,1]
	v_pk_fma_f32 v[100:101], v[52:53], v[78:79], v[10:11]
	v_pk_fma_f32 v[78:79], v[54:55], v[102:103], v[8:9]
	v_cvt_pk_bf16_f32 v76, v76, v77
	v_cvt_pk_bf16_f32 v77, v96, v97
	v_cvt_pk_bf16_f32 v78, v78, v79
	v_cvt_pk_bf16_f32 v79, v100, v101
	v_lshl_add_u64 v[96:97], v[36:37], 0, s[64:65]
	global_store_dwordx4 v[96:97], v[76:79], off
	s_lshl_b64 s[64:65], s[0:1], 12
	s_nop 0
	v_mov_b32_e32 v77, v80
	v_mov_b32_e32 v80, v105
	v_mov_b32_e32 v76, v104
	v_pk_mul_f32 v[78:79], v[98:99], v[80:81] op_sel_hi:[0,1]
	v_mov_b32_e32 v80, v108
	v_mov_b32_e32 v81, v82
	v_mov_b32_e32 v82, v109
	v_pk_mul_f32 v[76:77], v[98:99], v[76:77] op_sel_hi:[0,1]
	v_pk_mul_f32 v[80:81], v[98:99], v[80:81] op_sel_hi:[0,1]
	v_pk_mul_f32 v[82:83], v[98:99], v[82:83] op_sel_hi:[0,1]
	v_pk_fma_f32 v[78:79], v[48:49], v[78:79], v[6:7]
	v_pk_fma_f32 v[76:77], v[50:51], v[76:77], v[4:5]
	v_pk_fma_f32 v[82:83], v[44:45], v[82:83], v[2:3]
	v_pk_fma_f32 v[80:81], v[46:47], v[80:81], v[0:1]
	v_cvt_pk_bf16_f32 v76, v76, v77
	v_cvt_pk_bf16_f32 v77, v78, v79
	v_cvt_pk_bf16_f32 v78, v80, v81
	v_cvt_pk_bf16_f32 v79, v82, v83
	global_store_dwordx4 v[96:97], v[76:79], off offset:1024
	v_pk_mul_f32 v[80:81], v[98:99], v[114:115] op_sel_hi:[0,1]
	v_pk_mul_f32 v[82:83], v[98:99], v[86:87] op_sel_hi:[0,1]
	v_pk_mul_f32 v[76:77], v[98:99], v[112:113] op_sel_hi:[0,1]
	v_pk_mul_f32 v[78:79], v[98:99], v[84:85] op_sel_hi:[0,1]
	v_pk_fma_f32 v[78:79], v[64:65], v[78:79], v[22:23]
	v_pk_fma_f32 v[76:77], v[66:67], v[76:77], v[20:21]
	v_pk_fma_f32 v[82:83], v[60:61], v[82:83], v[18:19]
	v_pk_fma_f32 v[80:81], v[62:63], v[80:81], v[16:17]
	v_cvt_pk_bf16_f32 v76, v76, v77
	v_cvt_pk_bf16_f32 v77, v78, v79
	v_cvt_pk_bf16_f32 v78, v80, v81
	v_cvt_pk_bf16_f32 v79, v82, v83
	global_store_dwordx4 v[96:97], v[76:79], off offset:2048
	v_pk_mul_f32 v[80:81], v[94:95], v[98:99] op_sel_hi:[1,0]
	v_pk_mul_f32 v[82:83], v[90:91], v[98:99] op_sel_hi:[1,0]
	v_pk_mul_f32 v[76:77], v[92:93], v[98:99] op_sel_hi:[1,0]
	v_pk_mul_f32 v[78:79], v[88:89], v[98:99] op_sel_hi:[1,0]
	v_pk_fma_f32 v[76:77], v[74:75], v[76:77], v[28:29]
	v_pk_fma_f32 v[78:79], v[72:73], v[78:79], v[30:31]
	v_pk_fma_f32 v[82:83], v[68:69], v[82:83], v[26:27]
	v_pk_fma_f32 v[80:81], v[70:71], v[80:81], v[24:25]
	v_cvt_pk_bf16_f32 v76, v76, v77
	v_cvt_pk_bf16_f32 v77, v78, v79
	v_cvt_pk_bf16_f32 v78, v80, v81
	v_cvt_pk_bf16_f32 v79, v82, v83
	global_store_dwordx4 v[96:97], v[76:79], off offset:3072
	s_waitcnt vmcnt(11)
; __device__ __forceinline__ v4u pk8(f32x4 a, f32x4 b) { v4u w; w.x = pk2(a[0], a[1]); w.y = pk2(a[2], a[3]); w.z = pk2(b[0], b[1]); w.w = pk2(b[2], b[3]); return w; }
; __device__ __forceinline__ float ssq8(const f32x4& a, const f32x4& b) { return ((a[0] * a[0] + a[1] * a[1]) + (a[2] * a[2] + a[3] * a[3])) + ((b[0] * b[0] + b[1] * b[1]) + (b[2] * b[2] + b[3] * b[3])); }
; __device__ __forceinline__ float wave_sum(float v) {
; #pragma unroll
;     for (int o = 1; o < 64; o <<= 1) v += shfl_xor_f(v, o);
;     return v;
; template <int XF32> __device__ __forceinline__ void norm_mod_phase(const void* x, const float* modl, int ch_shift, int ch_scale, bf16* H, int gw, int NGW, int lane) {
;     ...
;             for (int j = 0; j < 4; ++j) s += ssq8(v[j][0], v[j][1]);
;             const float rstd = 1.f / sqrtf(wave_sum(s) * (1.f / DM) + EPS);
;             v4u* o = (v4u*)(H + (size_t)(r0 + rr) * DM);
; #pragma unroll
;             for (int j = 0; j < 4; ++j) o[lane + 64 * j] = pk8(v[j][0] * rstd * sc[j][0] + sh[j][0], v[j][1] * rstd * sc[j][1] + sh[j][1]);
	v_lshlrev_b32_e32 v97, 16, v195
	v_lshlrev_b32_e32 v96, 16, v194
	v_and_b32_e32 v77, 0xffff0000, v195
	v_and_b32_e32 v76, 0xffff0000, v194
	v_lshlrev_b32_e32 v101, 16, v197
	v_lshlrev_b32_e32 v100, 16, v196
	v_and_b32_e32 v79, 0xffff0000, v197
	v_and_b32_e32 v78, 0xffff0000, v196
	v_pk_mul_f32 v[98:99], v[76:77], v[76:77]
	v_pk_mul_f32 v[102:103], v[78:79], v[78:79]
	s_waitcnt vmcnt(8)
	v_lshlrev_b32_e32 v92, 16, v206
	v_and_b32_e32 v93, 0xffff0000, v206
	v_pk_fma_f32 v[98:99], v[96:97], v[96:97], v[98:99]
	v_pk_fma_f32 v[102:103], v[100:101], v[100:101], v[102:103]
	v_lshlrev_b32_e32 v105, 16, v199
	v_lshlrev_b32_e32 v104, 16, v198
	v_and_b32_e32 v81, 0xffff0000, v199
	v_and_b32_e32 v80, 0xffff0000, v198
	v_lshlrev_b32_e32 v109, 16, v201
	v_lshlrev_b32_e32 v108, 16, v200
	v_and_b32_e32 v83, 0xffff0000, v201
	v_and_b32_e32 v82, 0xffff0000, v200
	v_pk_mul_f32 v[106:107], v[80:81], v[80:81]
	v_pk_mul_f32 v[110:111], v[82:83], v[82:83]
	v_mul_f32_e32 v116, v92, v92
	v_mul_f32_e32 v117, v93, v93
	v_pk_add_f32 v[98:99], v[98:99], v[98:99] op_sel:[0,1] op_sel_hi:[1,0]
	v_pk_add_f32 v[102:103], v[102:103], v[102:103] op_sel:[0,1] op_sel_hi:[1,0]
	v_lshlrev_b32_e32 v88, 16, v207
	v_and_b32_e32 v89, 0xffff0000, v207
	v_pk_fma_f32 v[106:107], v[104:105], v[104:105], v[106:107]
	v_pk_fma_f32 v[110:111], v[108:109], v[108:109], v[110:111]
	v_mov_b32_e32 v99, v116
	v_mov_b32_e32 v103, v117
	v_mul_f32_e32 v118, v88, v88
	v_mul_f32_e32 v119, v89, v89
	v_pk_add_f32 v[98:99], v[98:99], v[102:103]
	v_pk_add_f32 v[102:103], v[106:107], v[106:107] op_sel:[0,1] op_sel_hi:[1,0]
	v_pk_add_f32 v[106:107], v[110:111], v[110:111] op_sel:[0,1] op_sel_hi:[1,0]
	v_mov_b32_e32 v103, v118
	v_mov_b32_e32 v107, v119
	v_lshlrev_b32_e32 v112, 16, v202
	v_and_b32_e32 v113, 0xffff0000, v202
	v_lshlrev_b32_e32 v84, 16, v203
	v_and_b32_e32 v85, 0xffff0000, v203
	v_pk_add_f32 v[102:103], v[102:103], v[106:107]
	v_lshlrev_b32_e32 v94, 16, v208
	v_and_b32_e32 v95, 0xffff0000, v208
	v_pk_add_f32 v[98:99], v[98:99], v[102:103]
	v_mul_f32_e32 v102, v113, v113
	v_mul_f32_e32 v106, v85, v85
	v_mul_f32_e32 v120, v94, v94
	v_mul_f32_e32 v121, v95, v95
	v_pk_fma_f32 v[102:103], v[112:113], v[112:113], v[102:103] op_sel_hi:[1,1,0]
	v_pk_fma_f32 v[106:107], v[84:85], v[84:85], v[106:107] op_sel_hi:[1,1,0]
	v_lshlrev_b32_e32 v114, 16, v204
	v_and_b32_e32 v115, 0xffff0000, v204
	v_lshlrev_b32_e32 v86, 16, v205
	v_and_b32_e32 v87, 0xffff0000, v205
	v_mov_b32_e32 v103, v120
	v_mov_b32_e32 v107, v121
	v_lshlrev_b32_e32 v90, 16, v209
	v_and_b32_e32 v91, 0xffff0000, v209
	s_add_i32 s100, s8, -4
	s_ashr_i32 s101, s100, 31
	s_lshl_b64 s[100:101], s[100:101], 12
	v_lshl_add_u64 v[210:211], v[34:35], 0, s[100:101]
	s_nop 0
	global_load_dwordx4 v[194:197], v[210:211], off
	global_load_dwordx4 v[198:201], v[210:211], off offset:1024
	global_load_dwordx4 v[202:205], v[210:211], off offset:2048
	global_load_dwordx4 v[206:209], v[210:211], off offset:3072
	v_pk_add_f32 v[102:103], v[102:103], v[106:107]
	v_mul_f32_e32 v106, v115, v115
	v_mul_f32_e32 v110, v87, v87
	v_mul_f32_e32 v122, v90, v90
	v_mul_f32_e32 v123, v91, v91
	v_pk_fma_f32 v[106:107], v[114:115], v[114:115], v[106:107] op_sel_hi:[1,1,0]
	v_pk_fma_f32 v[110:111], v[86:87], v[86:87], v[110:111] op_sel_hi:[1,1,0]
	v_mov_b32_e32 v107, v122
	v_mov_b32_e32 v111, v123
	v_pk_add_f32 v[106:107], v[106:107], v[110:111]
	s_nop 0
	v_pk_add_f32 v[102:103], v[102:103], v[106:107]
	s_nop 0
	v_pk_add_f32 v[98:99], v[98:99], v[102:103]
	s_nop 0
	v_add_f32_e32 v98, v98, v99
	s_nop 1
	v_add_f32_dpp v98, v98, v98 quad_perm:[1,0,3,2] row_mask:0xf bank_mask:0xf
	s_nop 1
	v_add_f32_dpp v98, v98, v98 quad_perm:[2,3,0,1] row_mask:0xf bank_mask:0xf
	s_nop 1
	v_add_f32_dpp v98, v98, v98 row_half_mirror row_mask:0xf bank_mask:0xf
	s_nop 1
	v_add_f32_dpp v98, v98, v98 row_mirror row_mask:0xf bank_mask:0xf
	v_mov_b32_e32 v99, v98
	s_nop 1
	v_permlane16_swap_b32_e32 v99, v98
	s_nop 1
	v_add_f32_e32 v98, v98, v99
	v_mov_b32_e32 v99, v98
	s_nop 1
	v_permlane32_swap_b32_e32 v99, v98
	s_nop 1
	v_add_f32_e32 v98, v98, v99
	v_fmamk_f32 v98, v98, 0x3a000000, v224
	v_cmp_gt_f32_e32 vcc, s41, v98
	v_mul_f32_e32 v99, 0x4f800000, v98
	s_nop 0
	v_cndmask_b32_e32 v98, v98, v99, vcc
	v_sqrt_f32_e32 v99, v98
	s_nop 0
	v_add_u32_e32 v102, -1, v99
	v_fma_f32 v103, -v102, v99, v98
	v_cmp_ge_f32_e64 s[4:5], 0, v103
	v_add_u32_e32 v103, 1, v99
	s_nop 0
	v_cndmask_b32_e64 v102, v99, v102, s[4:5]
	v_fma_f32 v99, -v103, v99, v98
	v_cmp_lt_f32_e64 s[4:5], 0, v99
	s_nop 1
	v_cndmask_b32_e64 v99, v102, v103, s[4:5]
	v_mul_f32_e32 v102, 0x37800000, v99
	v_cndmask_b32_e32 v99, v99, v102, vcc
	v_cmp_class_f32_e32 vcc, v98, v225
	s_nop 1
	v_cndmask_b32_e32 v98, v99, v98, vcc
	v_div_scale_f32 v99, s[0:1], v98, v98, 1.0
	v_rcp_f32_e32 v102, v99
	s_add_i32 s0, s8, -5
	s_ashr_i32 s1, s0, 31
	v_fma_f32 v103, -v99, v102, 1.0
	v_fmac_f32_e32 v102, v103, v102
	v_div_scale_f32 v103, vcc, 1.0, v98, 1.0
	v_mul_f32_e32 v106, v103, v102
	v_fma_f32 v107, -v99, v106, v103
	v_fmac_f32_e32 v106, v107, v102
	v_fma_f32 v99, -v99, v106, v103
	v_div_fmas_f32 v99, v99, v102, v106
	v_div_fixup_f32 v98, v99, v98, 1.0
	v_mov_b32_e32 v102, v96
	v_mov_b32_e32 v103, v76
	v_mov_b32_e32 v76, v97
	v_pk_mul_f32 v[102:103], v[98:99], v[102:103] op_sel_hi:[0,1]
	v_pk_mul_f32 v[76:77], v[98:99], v[76:77] op_sel_hi:[0,1]
	v_pk_fma_f32 v[96:97], v[56:57], v[76:77], v[14:15]
	v_pk_fma_f32 v[76:77], v[58:59], v[102:103], v[12:13]
	v_mov_b32_e32 v102, v100
	v_mov_b32_e32 v103, v78
	v_mov_b32_e32 v78, v101
	v_pk_mul_f32 v[102:103], v[98:99], v[102:103] op_sel_hi:[0,1]
	v_pk_mul_f32 v[78:79], v[98:99], v[78:79] op_sel_hi:[0,1]
; __device__ __forceinline__ v4u pk8(f32x4 a, f32x4 b) { v4u w; w.x = pk2(a[0], a[1]); w.y = pk2(a[2], a[3]); w.z = pk2(b[0], b[1]); w.w = pk2(b[2], b[3]); return w; }
; __device__ __forceinline__ float ssq8(const f32x4& a, const f32x4& b) { return ((a[0] * a[0] + a[1] * a[1]) + (a[2] * a[2] + a[3] * a[3])) + ((b[0] * b[0] + b[1] * b[1]) + (b[2] * b[2] + b[3] * b[3])); }
; template <int XF32> __device__ __forceinline__ void norm_mod_phase(const void* x, const float* modl, int ch_shift, int ch_scale, bf16* H, int gw, int NGW, int lane) {
;     ...
;             const unsigned char* xr = (const unsigned char*)x + (size_t)(r0 + rr) * rowb; f32x4 v[4][2]; float s = 0.f;
; #pragma unroll
;             for (int j = 0; j < 4; ++j) ld_row8<XF32>(xr, lane, j, v[j][0], v[j][1]);
; #pragma unroll
;             for (int j = 0; j < 4; ++j) s += ssq8(v[j][0], v[j][1]);
;             const float rstd = 1.f / sqrtf(wave_sum(s) * (1.f / DM) + EPS);
;             v4u* o = (v4u*)(H + (size_t)(r0 + rr) * DM);
; #pragma unroll
;             for (int j = 0; j < 4; ++j) o[lane + 64 * j] = pk8(v[j][0] * rstd * sc[j][0] + sh[j][0], v[j][1] * rstd * sc[j][1] + sh[j][1]);
	v_pk_fma_f32 v[100:101], v[52:53], v[78:79], v[10:11]
	v_pk_fma_f32 v[78:79], v[54:55], v[102:103], v[8:9]
	v_cvt_pk_bf16_f32 v76, v76, v77
	v_cvt_pk_bf16_f32 v77, v96, v97
	v_cvt_pk_bf16_f32 v78, v78, v79
	v_cvt_pk_bf16_f32 v79, v100, v101
	v_lshl_add_u64 v[96:97], v[36:37], 0, s[64:65]
	global_store_dwordx4 v[96:97], v[76:79], off
	s_lshl_b64 s[64:65], s[0:1], 12
	s_nop 0
	v_mov_b32_e32 v77, v80
	v_mov_b32_e32 v80, v105
	v_mov_b32_e32 v76, v104
	v_pk_mul_f32 v[78:79], v[98:99], v[80:81] op_sel_hi:[0,1]
	v_mov_b32_e32 v80, v108
	v_mov_b32_e32 v81, v82
	v_mov_b32_e32 v82, v109
	v_pk_mul_f32 v[76:77], v[98:99], v[76:77] op_sel_hi:[0,1]
	v_pk_mul_f32 v[80:81], v[98:99], v[80:81] op_sel_hi:[0,1]
	v_pk_mul_f32 v[82:83], v[98:99], v[82:83] op_sel_hi:[0,1]
	v_pk_fma_f32 v[78:79], v[48:49], v[78:79], v[6:7]
	v_pk_fma_f32 v[76:77], v[50:51], v[76:77], v[4:5]
	v_pk_fma_f32 v[82:83], v[44:45], v[82:83], v[2:3]
	v_pk_fma_f32 v[80:81], v[46:47], v[80:81], v[0:1]
	v_cvt_pk_bf16_f32 v76, v76, v77
	v_cvt_pk_bf16_f32 v77, v78, v79
	v_cvt_pk_bf16_f32 v78, v80, v81
	v_cvt_pk_bf16_f32 v79, v82, v83
	global_store_dwordx4 v[96:97], v[76:79], off offset:1024
	v_pk_mul_f32 v[80:81], v[98:99], v[114:115] op_sel_hi:[0,1]
	v_pk_mul_f32 v[82:83], v[98:99], v[86:87] op_sel_hi:[0,1]
	v_pk_mul_f32 v[76:77], v[98:99], v[112:113] op_sel_hi:[0,1]
	v_pk_mul_f32 v[78:79], v[98:99], v[84:85] op_sel_hi:[0,1]
	v_pk_fma_f32 v[78:79], v[64:65], v[78:79], v[22:23]
	v_pk_fma_f32 v[76:77], v[66:67], v[76:77], v[20:21]
	v_pk_fma_f32 v[82:83], v[60:61], v[82:83], v[18:19]
	v_pk_fma_f32 v[80:81], v[62:63], v[80:81], v[16:17]
	v_cvt_pk_bf16_f32 v76, v76, v77
	v_cvt_pk_bf16_f32 v77, v78, v79
	v_cvt_pk_bf16_f32 v78, v80, v81
	v_cvt_pk_bf16_f32 v79, v82, v83
	global_store_dwordx4 v[96:97], v[76:79], off offset:2048
	v_pk_mul_f32 v[80:81], v[94:95], v[98:99] op_sel_hi:[1,0]
	v_pk_mul_f32 v[82:83], v[90:91], v[98:99] op_sel_hi:[1,0]
	v_pk_mul_f32 v[76:77], v[92:93], v[98:99] op_sel_hi:[1,0]
	v_pk_mul_f32 v[78:79], v[88:89], v[98:99] op_sel_hi:[1,0]
	v_pk_fma_f32 v[76:77], v[74:75], v[76:77], v[28:29]
	v_pk_fma_f32 v[78:79], v[72:73], v[78:79], v[30:31]
	v_pk_fma_f32 v[82:83], v[68:69], v[82:83], v[26:27]
	v_pk_fma_f32 v[80:81], v[70:71], v[80:81], v[24:25]
	v_cvt_pk_bf16_f32 v76, v76, v77
	v_cvt_pk_bf16_f32 v77, v78, v79
	v_cvt_pk_bf16_f32 v78, v80, v81
	v_cvt_pk_bf16_f32 v79, v82, v83
	global_store_dwordx4 v[96:97], v[76:79], off offset:3072
	s_waitcnt vmcnt(11)
	v_lshlrev_b32_e32 v97, 16, v179
	v_lshlrev_b32_e32 v96, 16, v178
	v_and_b32_e32 v77, 0xffff0000, v179
	v_and_b32_e32 v76, 0xffff0000, v178
	v_lshlrev_b32_e32 v101, 16, v181
	v_lshlrev_b32_e32 v100, 16, v180
	v_and_b32_e32 v79, 0xffff0000, v181
	v_and_b32_e32 v78, 0xffff0000, v180
	v_pk_mul_f32 v[98:99], v[76:77], v[76:77]
	v_pk_mul_f32 v[102:103], v[78:79], v[78:79]
	s_waitcnt vmcnt(8)
	v_lshlrev_b32_e32 v92, 16, v190
	v_and_b32_e32 v93, 0xffff0000, v190
	v_pk_fma_f32 v[98:99], v[96:97], v[96:97], v[98:99]
	v_pk_fma_f32 v[102:103], v[100:101], v[100:101], v[102:103]
	v_lshlrev_b32_e32 v105, 16, v183
	v_lshlrev_b32_e32 v104, 16, v182
	v_and_b32_e32 v81, 0xffff0000, v183
	v_and_b32_e32 v80, 0xffff0000, v182
	v_lshlrev_b32_e32 v109, 16, v185
	v_lshlrev_b32_e32 v108, 16, v184
	v_and_b32_e32 v83, 0xffff0000, v185
	v_and_b32_e32 v82, 0xffff0000, v184
	v_pk_mul_f32 v[106:107], v[80:81], v[80:81]
	v_pk_mul_f32 v[110:111], v[82:83], v[82:83]
	v_mul_f32_e32 v116, v92, v92
	v_mul_f32_e32 v117, v93, v93
	v_pk_add_f32 v[98:99], v[98:99], v[98:99] op_sel:[0,1] op_sel_hi:[1,0]
	v_pk_add_f32 v[102:103], v[102:103], v[102:103] op_sel:[0,1] op_sel_hi:[1,0]
	v_lshlrev_b32_e32 v88, 16, v191
	v_and_b32_e32 v89, 0xffff0000, v191
	v_pk_fma_f32 v[106:107], v[104:105], v[104:105], v[106:107]
	v_pk_fma_f32 v[110:111], v[108:109], v[108:109], v[110:111]
	v_mov_b32_e32 v99, v116
	v_mov_b32_e32 v103, v117
	v_mul_f32_e32 v118, v88, v88
	v_mul_f32_e32 v119, v89, v89
	v_pk_add_f32 v[98:99], v[98:99], v[102:103]
	v_pk_add_f32 v[102:103], v[106:107], v[106:107] op_sel:[0,1] op_sel_hi:[1,0]
	v_pk_add_f32 v[106:107], v[110:111], v[110:111] op_sel:[0,1] op_sel_hi:[1,0]
	v_mov_b32_e32 v103, v118
	v_mov_b32_e32 v107, v119
	v_lshlrev_b32_e32 v112, 16, v186
	v_and_b32_e32 v113, 0xffff0000, v186
	v_lshlrev_b32_e32 v84, 16, v187
	v_and_b32_e32 v85, 0xffff0000, v187
	v_pk_add_f32 v[102:103], v[102:103], v[106:107]
	v_lshlrev_b32_e32 v94, 16, v192
	v_and_b32_e32 v95, 0xffff0000, v192
	v_pk_add_f32 v[98:99], v[98:99], v[102:103]
	v_mul_f32_e32 v102, v113, v113
	v_mul_f32_e32 v106, v85, v85
	v_mul_f32_e32 v120, v94, v94
	v_mul_f32_e32 v121, v95, v95
	v_pk_fma_f32 v[102:103], v[112:113], v[112:113], v[102:103] op_sel_hi:[1,1,0]
	v_pk_fma_f32 v[106:107], v[84:85], v[84:85], v[106:107] op_sel_hi:[1,1,0]
	v_lshlrev_b32_e32 v114, 16, v188
	v_and_b32_e32 v115, 0xffff0000, v188
	v_lshlrev_b32_e32 v86, 16, v189
	v_and_b32_e32 v87, 0xffff0000, v189
	v_mov_b32_e32 v103, v120
	v_mov_b32_e32 v107, v121
	v_lshlrev_b32_e32 v90, 16, v193
	v_and_b32_e32 v91, 0xffff0000, v193
	s_add_i32 s100, s8, -3
	s_ashr_i32 s101, s100, 31
	s_lshl_b64 s[100:101], s[100:101], 12
	v_lshl_add_u64 v[210:211], v[34:35], 0, s[100:101]
	s_nop 0
	global_load_dwordx4 v[178:181], v[210:211], off
	global_load_dwordx4 v[182:185], v[210:211], off offset:1024
	global_load_dwordx4 v[186:189], v[210:211], off offset:2048
	global_load_dwordx4 v[190:193], v[210:211], off offset:3072
	v_pk_add_f32 v[102:103], v[102:103], v[106:107]
	v_mul_f32_e32 v106, v115, v115
	v_mul_f32_e32 v110, v87, v87
	v_mul_f32_e32 v122, v90, v90
	v_mul_f32_e32 v123, v91, v91
	v_pk_fma_f32 v[106:107], v[114:115], v[114:115], v[106:107] op_sel_hi:[1,1,0]
; __device__ __forceinline__ v4u pk8(f32x4 a, f32x4 b) { v4u w; w.x = pk2(a[0], a[1]); w.y = pk2(a[2], a[3]); w.z = pk2(b[0], b[1]); w.w = pk2(b[2], b[3]); return w; }
; __device__ __forceinline__ float ssq8(const f32x4& a, const f32x4& b) { return ((a[0] * a[0] + a[1] * a[1]) + (a[2] * a[2] + a[3] * a[3])) + ((b[0] * b[0] + b[1] * b[1]) + (b[2] * b[2] + b[3] * b[3])); }
; __device__ __forceinline__ float wave_sum(float v) {
; #pragma unroll
;     for (int o = 1; o < 64; o <<= 1) v += shfl_xor_f(v, o);
;     return v;
; template <int XF32> __device__ __forceinline__ void norm_mod_phase(const void* x, const float* modl, int ch_shift, int ch_scale, bf16* H, int gw, int NGW, int lane) {
;     ...
;             for (int j = 0; j < 4; ++j) s += ssq8(v[j][0], v[j][1]);
;             const float rstd = 1.f / sqrtf(wave_sum(s) * (1.f / DM) + EPS);
;             v4u* o = (v4u*)(H + (size_t)(r0 + rr) * DM);
; #pragma unroll
;             for (int j = 0; j < 4; ++j) o[lane + 64 * j] = pk8(v[j][0] * rstd * sc[j][0] + sh[j][0], v[j][1] * rstd * sc[j][1] + sh[j][1]);
	v_pk_fma_f32 v[110:111], v[86:87], v[86:87], v[110:111] op_sel_hi:[1,1,0]
	v_mov_b32_e32 v107, v122
	v_mov_b32_e32 v111, v123
	v_pk_add_f32 v[106:107], v[106:107], v[110:111]
	s_nop 0
	v_pk_add_f32 v[102:103], v[102:103], v[106:107]
	s_nop 0
	v_pk_add_f32 v[98:99], v[98:99], v[102:103]
	s_nop 0
	v_add_f32_e32 v98, v98, v99
	s_nop 1
	v_add_f32_dpp v98, v98, v98 quad_perm:[1,0,3,2] row_mask:0xf bank_mask:0xf
	s_nop 1
	v_add_f32_dpp v98, v98, v98 quad_perm:[2,3,0,1] row_mask:0xf bank_mask:0xf
	s_nop 1
	v_add_f32_dpp v98, v98, v98 row_half_mirror row_mask:0xf bank_mask:0xf
	s_nop 1
	v_add_f32_dpp v98, v98, v98 row_mirror row_mask:0xf bank_mask:0xf
	v_mov_b32_e32 v99, v98
	s_nop 1
	v_permlane16_swap_b32_e32 v99, v98
	s_nop 1
	v_add_f32_e32 v98, v98, v99
	v_mov_b32_e32 v99, v98
	s_nop 1
	v_permlane32_swap_b32_e32 v99, v98
	s_nop 1
	v_add_f32_e32 v98, v98, v99
	v_fmamk_f32 v98, v98, 0x3a000000, v224
	v_cmp_gt_f32_e32 vcc, s41, v98
	v_mul_f32_e32 v99, 0x4f800000, v98
	s_nop 0
	v_cndmask_b32_e32 v98, v98, v99, vcc
	v_sqrt_f32_e32 v99, v98
	s_nop 0
	v_add_u32_e32 v102, -1, v99
	v_fma_f32 v103, -v102, v99, v98
	v_cmp_ge_f32_e64 s[4:5], 0, v103
	v_add_u32_e32 v103, 1, v99
	s_nop 0
	v_cndmask_b32_e64 v102, v99, v102, s[4:5]
	v_fma_f32 v99, -v103, v99, v98
	v_cmp_lt_f32_e64 s[4:5], 0, v99
	s_nop 1
	v_cndmask_b32_e64 v99, v102, v103, s[4:5]
	v_mul_f32_e32 v102, 0x37800000, v99
	v_cndmask_b32_e32 v99, v99, v102, vcc
	v_cmp_class_f32_e32 vcc, v98, v225
	s_nop 1
	v_cndmask_b32_e32 v98, v99, v98, vcc
	v_div_scale_f32 v99, s[0:1], v98, v98, 1.0
	v_rcp_f32_e32 v102, v99
	s_add_i32 s0, s8, -4
	s_ashr_i32 s1, s0, 31
	v_fma_f32 v103, -v99, v102, 1.0
	v_fmac_f32_e32 v102, v103, v102
	v_div_scale_f32 v103, vcc, 1.0, v98, 1.0
	v_mul_f32_e32 v106, v103, v102
	v_fma_f32 v107, -v99, v106, v103
	v_fmac_f32_e32 v106, v107, v102
	v_fma_f32 v99, -v99, v106, v103
	v_div_fmas_f32 v99, v99, v102, v106
	v_div_fixup_f32 v98, v99, v98, 1.0
	v_mov_b32_e32 v102, v96
	v_mov_b32_e32 v103, v76
	v_mov_b32_e32 v76, v97
	v_pk_mul_f32 v[102:103], v[98:99], v[102:103] op_sel_hi:[0,1]
	v_pk_mul_f32 v[76:77], v[98:99], v[76:77] op_sel_hi:[0,1]
	v_pk_fma_f32 v[96:97], v[56:57], v[76:77], v[14:15]
	v_pk_fma_f32 v[76:77], v[58:59], v[102:103], v[12:13]
	v_mov_b32_e32 v102, v100
	v_mov_b32_e32 v103, v78
	v_mov_b32_e32 v78, v101
	v_pk_mul_f32 v[102:103], v[98:99], v[102:103] op_sel_hi:[0,1]
	v_pk_mul_f32 v[78:79], v[98:99], v[78:79] op_sel_hi:[0,1]
	v_pk_fma_f32 v[100:101], v[52:53], v[78:79], v[10:11]
	v_pk_fma_f32 v[78:79], v[54:55], v[102:103], v[8:9]
	v_cvt_pk_bf16_f32 v76, v76, v77
	v_cvt_pk_bf16_f32 v77, v96, v97
	v_cvt_pk_bf16_f32 v78, v78, v79
	v_cvt_pk_bf16_f32 v79, v100, v101
	v_lshl_add_u64 v[96:97], v[36:37], 0, s[64:65]
	global_store_dwordx4 v[96:97], v[76:79], off
	s_lshl_b64 s[64:65], s[0:1], 12
	s_nop 0
	v_mov_b32_e32 v77, v80
	v_mov_b32_e32 v80, v105
	v_mov_b32_e32 v76, v104
	v_pk_mul_f32 v[78:79], v[98:99], v[80:81] op_sel_hi:[0,1]
	v_mov_b32_e32 v80, v108
	v_mov_b32_e32 v81, v82
	v_mov_b32_e32 v82, v109
	v_pk_mul_f32 v[76:77], v[98:99], v[76:77] op_sel_hi:[0,1]
	v_pk_mul_f32 v[80:81], v[98:99], v[80:81] op_sel_hi:[0,1]
	v_pk_mul_f32 v[82:83], v[98:99], v[82:83] op_sel_hi:[0,1]
	v_pk_fma_f32 v[78:79], v[48:49], v[78:79], v[6:7]
	v_pk_fma_f32 v[76:77], v[50:51], v[76:77], v[4:5]
	v_pk_fma_f32 v[82:83], v[44:45], v[82:83], v[2:3]
	v_pk_fma_f32 v[80:81], v[46:47], v[80:81], v[0:1]
	v_cvt_pk_bf16_f32 v76, v76, v77
	v_cvt_pk_bf16_f32 v77, v78, v79
	v_cvt_pk_bf16_f32 v78, v80, v81
	v_cvt_pk_bf16_f32 v79, v82, v83
	global_store_dwordx4 v[96:97], v[76:79], off offset:1024
	v_pk_mul_f32 v[80:81], v[98:99], v[114:115] op_sel_hi:[0,1]
	v_pk_mul_f32 v[82:83], v[98:99], v[86:87] op_sel_hi:[0,1]
	v_pk_mul_f32 v[76:77], v[98:99], v[112:113] op_sel_hi:[0,1]
	v_pk_mul_f32 v[78:79], v[98:99], v[84:85] op_sel_hi:[0,1]
	v_pk_fma_f32 v[78:79], v[64:65], v[78:79], v[22:23]
	v_pk_fma_f32 v[76:77], v[66:67], v[76:77], v[20:21]
	v_pk_fma_f32 v[82:83], v[60:61], v[82:83], v[18:19]
	v_pk_fma_f32 v[80:81], v[62:63], v[80:81], v[16:17]
	v_cvt_pk_bf16_f32 v76, v76, v77
	v_cvt_pk_bf16_f32 v77, v78, v79
	v_cvt_pk_bf16_f32 v78, v80, v81
	v_cvt_pk_bf16_f32 v79, v82, v83
	global_store_dwordx4 v[96:97], v[76:79], off offset:2048
	v_pk_mul_f32 v[80:81], v[94:95], v[98:99] op_sel_hi:[1,0]
	v_pk_mul_f32 v[82:83], v[90:91], v[98:99] op_sel_hi:[1,0]
	v_pk_mul_f32 v[76:77], v[92:93], v[98:99] op_sel_hi:[1,0]
	v_pk_mul_f32 v[78:79], v[88:89], v[98:99] op_sel_hi:[1,0]
	v_pk_fma_f32 v[76:77], v[74:75], v[76:77], v[28:29]
	v_pk_fma_f32 v[78:79], v[72:73], v[78:79], v[30:31]
	v_pk_fma_f32 v[82:83], v[68:69], v[82:83], v[26:27]
	v_pk_fma_f32 v[80:81], v[70:71], v[80:81], v[24:25]
	v_cvt_pk_bf16_f32 v76, v76, v77
	v_cvt_pk_bf16_f32 v77, v78, v79
	v_cvt_pk_bf16_f32 v78, v80, v81
	v_cvt_pk_bf16_f32 v79, v82, v83
	global_store_dwordx4 v[96:97], v[76:79], off offset:3072
	s_waitcnt vmcnt(11)
	v_lshlrev_b32_e32 v97, 16, v195
	v_lshlrev_b32_e32 v96, 16, v194
	v_and_b32_e32 v77, 0xffff0000, v195
	v_and_b32_e32 v76, 0xffff0000, v194
	v_lshlrev_b32_e32 v101, 16, v197
	v_lshlrev_b32_e32 v100, 16, v196
	v_and_b32_e32 v79, 0xffff0000, v197
	v_and_b32_e32 v78, 0xffff0000, v196
	v_pk_mul_f32 v[98:99], v[76:77], v[76:77]
	v_pk_mul_f32 v[102:103], v[78:79], v[78:79]
	s_waitcnt vmcnt(8)
; __device__ __forceinline__ v4u pk8(f32x4 a, f32x4 b) { v4u w; w.x = pk2(a[0], a[1]); w.y = pk2(a[2], a[3]); w.z = pk2(b[0], b[1]); w.w = pk2(b[2], b[3]); return w; }
; __device__ __forceinline__ float ssq8(const f32x4& a, const f32x4& b) { return ((a[0] * a[0] + a[1] * a[1]) + (a[2] * a[2] + a[3] * a[3])) + ((b[0] * b[0] + b[1] * b[1]) + (b[2] * b[2] + b[3] * b[3])); }
; __device__ __forceinline__ float wave_sum(float v) {
; #pragma unroll
;     for (int o = 1; o < 64; o <<= 1) v += shfl_xor_f(v, o);
;     return v;
; template <int XF32> __device__ __forceinline__ void norm_mod_phase(const void* x, const float* modl, int ch_shift, int ch_scale, bf16* H, int gw, int NGW, int lane) {
;     ...
;             for (int j = 0; j < 4; ++j) s += ssq8(v[j][0], v[j][1]);
;             const float rstd = 1.f / sqrtf(wave_sum(s) * (1.f / DM) + EPS);
;             v4u* o = (v4u*)(H + (size_t)(r0 + rr) * DM);
; #pragma unroll
;             for (int j = 0; j < 4; ++j) o[lane + 64 * j] = pk8(v[j][0] * rstd * sc[j][0] + sh[j][0], v[j][1] * rstd * sc[j][1] + sh[j][1]);
	v_lshlrev_b32_e32 v92, 16, v206
	v_and_b32_e32 v93, 0xffff0000, v206
	v_pk_fma_f32 v[98:99], v[96:97], v[96:97], v[98:99]
	v_pk_fma_f32 v[102:103], v[100:101], v[100:101], v[102:103]
	v_lshlrev_b32_e32 v105, 16, v199
	v_lshlrev_b32_e32 v104, 16, v198
	v_and_b32_e32 v81, 0xffff0000, v199
	v_and_b32_e32 v80, 0xffff0000, v198
	v_lshlrev_b32_e32 v109, 16, v201
	v_lshlrev_b32_e32 v108, 16, v200
	v_and_b32_e32 v83, 0xffff0000, v201
	v_and_b32_e32 v82, 0xffff0000, v200
	v_pk_mul_f32 v[106:107], v[80:81], v[80:81]
	v_pk_mul_f32 v[110:111], v[82:83], v[82:83]
	v_mul_f32_e32 v116, v92, v92
	v_mul_f32_e32 v117, v93, v93
	v_pk_add_f32 v[98:99], v[98:99], v[98:99] op_sel:[0,1] op_sel_hi:[1,0]
	v_pk_add_f32 v[102:103], v[102:103], v[102:103] op_sel:[0,1] op_sel_hi:[1,0]
	v_lshlrev_b32_e32 v88, 16, v207
	v_and_b32_e32 v89, 0xffff0000, v207
	v_pk_fma_f32 v[106:107], v[104:105], v[104:105], v[106:107]
	v_pk_fma_f32 v[110:111], v[108:109], v[108:109], v[110:111]
	v_mov_b32_e32 v99, v116
	v_mov_b32_e32 v103, v117
	v_mul_f32_e32 v118, v88, v88
	v_mul_f32_e32 v119, v89, v89
	v_pk_add_f32 v[98:99], v[98:99], v[102:103]
	v_pk_add_f32 v[102:103], v[106:107], v[106:107] op_sel:[0,1] op_sel_hi:[1,0]
	v_pk_add_f32 v[106:107], v[110:111], v[110:111] op_sel:[0,1] op_sel_hi:[1,0]
	v_mov_b32_e32 v103, v118
	v_mov_b32_e32 v107, v119
	v_lshlrev_b32_e32 v112, 16, v202
	v_and_b32_e32 v113, 0xffff0000, v202
	v_lshlrev_b32_e32 v84, 16, v203
	v_and_b32_e32 v85, 0xffff0000, v203
	v_pk_add_f32 v[102:103], v[102:103], v[106:107]
	v_lshlrev_b32_e32 v94, 16, v208
	v_and_b32_e32 v95, 0xffff0000, v208
	v_pk_add_f32 v[98:99], v[98:99], v[102:103]
	v_mul_f32_e32 v102, v113, v113
	v_mul_f32_e32 v106, v85, v85
	v_mul_f32_e32 v120, v94, v94
	v_mul_f32_e32 v121, v95, v95
	v_pk_fma_f32 v[102:103], v[112:113], v[112:113], v[102:103] op_sel_hi:[1,1,0]
	v_pk_fma_f32 v[106:107], v[84:85], v[84:85], v[106:107] op_sel_hi:[1,1,0]
	v_lshlrev_b32_e32 v114, 16, v204
	v_and_b32_e32 v115, 0xffff0000, v204
	v_lshlrev_b32_e32 v86, 16, v205
	v_and_b32_e32 v87, 0xffff0000, v205
	v_mov_b32_e32 v103, v120
	v_mov_b32_e32 v107, v121
	v_lshlrev_b32_e32 v90, 16, v209
	v_and_b32_e32 v91, 0xffff0000, v209
	s_add_i32 s100, s8, -2
	s_ashr_i32 s101, s100, 31
	s_lshl_b64 s[100:101], s[100:101], 12
	v_lshl_add_u64 v[210:211], v[34:35], 0, s[100:101]
	s_nop 0
	global_load_dwordx4 v[194:197], v[210:211], off
	global_load_dwordx4 v[198:201], v[210:211], off offset:1024
	global_load_dwordx4 v[202:205], v[210:211], off offset:2048
	global_load_dwordx4 v[206:209], v[210:211], off offset:3072
	v_pk_add_f32 v[102:103], v[102:103], v[106:107]
	v_mul_f32_e32 v106, v115, v115
	v_mul_f32_e32 v110, v87, v87
	v_mul_f32_e32 v122, v90, v90
	v_mul_f32_e32 v123, v91, v91
	v_pk_fma_f32 v[106:107], v[114:115], v[114:115], v[106:107] op_sel_hi:[1,1,0]
	v_pk_fma_f32 v[110:111], v[86:87], v[86:87], v[110:111] op_sel_hi:[1,1,0]
	v_mov_b32_e32 v107, v122
	v_mov_b32_e32 v111, v123
	v_pk_add_f32 v[106:107], v[106:107], v[110:111]
	s_nop 0
	v_pk_add_f32 v[102:103], v[102:103], v[106:107]
	s_nop 0
	v_pk_add_f32 v[98:99], v[98:99], v[102:103]
	s_nop 0
	v_add_f32_e32 v98, v98, v99
	s_nop 1
	v_add_f32_dpp v98, v98, v98 quad_perm:[1,0,3,2] row_mask:0xf bank_mask:0xf
	s_nop 1
	v_add_f32_dpp v98, v98, v98 quad_perm:[2,3,0,1] row_mask:0xf bank_mask:0xf
	s_nop 1
	v_add_f32_dpp v98, v98, v98 row_half_mirror row_mask:0xf bank_mask:0xf
	s_nop 1
	v_add_f32_dpp v98, v98, v98 row_mirror row_mask:0xf bank_mask:0xf
	v_mov_b32_e32 v99, v98
	s_nop 1
	v_permlane16_swap_b32_e32 v99, v98
	s_nop 1
	v_add_f32_e32 v98, v98, v99
	v_mov_b32_e32 v99, v98
	s_nop 1
	v_permlane32_swap_b32_e32 v99, v98
	s_nop 1
	v_add_f32_e32 v98, v98, v99
	v_fmamk_f32 v98, v98, 0x3a000000, v224
	v_cmp_gt_f32_e32 vcc, s41, v98
	v_mul_f32_e32 v99, 0x4f800000, v98
	s_nop 0
	v_cndmask_b32_e32 v98, v98, v99, vcc
	v_sqrt_f32_e32 v99, v98
	s_nop 0
	v_add_u32_e32 v102, -1, v99
	v_fma_f32 v103, -v102, v99, v98
	v_cmp_ge_f32_e64 s[4:5], 0, v103
	v_add_u32_e32 v103, 1, v99
	s_nop 0
	v_cndmask_b32_e64 v102, v99, v102, s[4:5]
	v_fma_f32 v99, -v103, v99, v98
	v_cmp_lt_f32_e64 s[4:5], 0, v99
	s_nop 1
	v_cndmask_b32_e64 v99, v102, v103, s[4:5]
	v_mul_f32_e32 v102, 0x37800000, v99
	v_cndmask_b32_e32 v99, v99, v102, vcc
	v_cmp_class_f32_e32 vcc, v98, v225
	s_nop 1
	v_cndmask_b32_e32 v98, v99, v98, vcc
	v_div_scale_f32 v99, s[0:1], v98, v98, 1.0
	v_rcp_f32_e32 v102, v99
	s_add_i32 s0, s8, -3
	s_ashr_i32 s1, s0, 31
	v_fma_f32 v103, -v99, v102, 1.0
	v_fmac_f32_e32 v102, v103, v102
	v_div_scale_f32 v103, vcc, 1.0, v98, 1.0
	v_mul_f32_e32 v106, v103, v102
	v_fma_f32 v107, -v99, v106, v103
	v_fmac_f32_e32 v106, v107, v102
	v_fma_f32 v99, -v99, v106, v103
	v_div_fmas_f32 v99, v99, v102, v106
	v_div_fixup_f32 v98, v99, v98, 1.0
	v_mov_b32_e32 v102, v96
	v_mov_b32_e32 v103, v76
	v_mov_b32_e32 v76, v97
	v_pk_mul_f32 v[102:103], v[98:99], v[102:103] op_sel_hi:[0,1]
	v_pk_mul_f32 v[76:77], v[98:99], v[76:77] op_sel_hi:[0,1]
	v_pk_fma_f32 v[96:97], v[56:57], v[76:77], v[14:15]
	v_pk_fma_f32 v[76:77], v[58:59], v[102:103], v[12:13]
	v_mov_b32_e32 v102, v100
	v_mov_b32_e32 v103, v78
	v_mov_b32_e32 v78, v101
	v_pk_mul_f32 v[102:103], v[98:99], v[102:103] op_sel_hi:[0,1]
	v_pk_mul_f32 v[78:79], v[98:99], v[78:79] op_sel_hi:[0,1]
	v_pk_fma_f32 v[100:101], v[52:53], v[78:79], v[10:11]
	v_pk_fma_f32 v[78:79], v[54:55], v[102:103], v[8:9]
	v_cvt_pk_bf16_f32 v76, v76, v77
	v_cvt_pk_bf16_f32 v77, v96, v97
	v_cvt_pk_bf16_f32 v78, v78, v79
	v_cvt_pk_bf16_f32 v79, v100, v101
	v_lshl_add_u64 v[96:97], v[36:37], 0, s[64:65]
	global_store_dwordx4 v[96:97], v[76:79], off
	s_lshl_b64 s[64:65], s[0:1], 12
	s_nop 0
	v_mov_b32_e32 v77, v80
; __device__ __forceinline__ v4u pk8(f32x4 a, f32x4 b) { v4u w; w.x = pk2(a[0], a[1]); w.y = pk2(a[2], a[3]); w.z = pk2(b[0], b[1]); w.w = pk2(b[2], b[3]); return w; }
; __device__ __forceinline__ float ssq8(const f32x4& a, const f32x4& b) { return ((a[0] * a[0] + a[1] * a[1]) + (a[2] * a[2] + a[3] * a[3])) + ((b[0] * b[0] + b[1] * b[1]) + (b[2] * b[2] + b[3] * b[3])); }
; template <int XF32> __device__ __forceinline__ void norm_mod_phase(const void* x, const float* modl, int ch_shift, int ch_scale, bf16* H, int gw, int NGW, int lane) {
;     ...
;             const unsigned char* xr = (const unsigned char*)x + (size_t)(r0 + rr) * rowb; f32x4 v[4][2]; float s = 0.f;
; #pragma unroll
;             for (int j = 0; j < 4; ++j) ld_row8<XF32>(xr, lane, j, v[j][0], v[j][1]);
; #pragma unroll
;             for (int j = 0; j < 4; ++j) s += ssq8(v[j][0], v[j][1]);
;             const float rstd = 1.f / sqrtf(wave_sum(s) * (1.f / DM) + EPS);
;             v4u* o = (v4u*)(H + (size_t)(r0 + rr) * DM);
; #pragma unroll
;             for (int j = 0; j < 4; ++j) o[lane + 64 * j] = pk8(v[j][0] * rstd * sc[j][0] + sh[j][0], v[j][1] * rstd * sc[j][1] + sh[j][1]);
	v_mov_b32_e32 v80, v105
	v_mov_b32_e32 v76, v104
	v_pk_mul_f32 v[78:79], v[98:99], v[80:81] op_sel_hi:[0,1]
	v_mov_b32_e32 v80, v108
	v_mov_b32_e32 v81, v82
	v_mov_b32_e32 v82, v109
	v_pk_mul_f32 v[76:77], v[98:99], v[76:77] op_sel_hi:[0,1]
	v_pk_mul_f32 v[80:81], v[98:99], v[80:81] op_sel_hi:[0,1]
	v_pk_mul_f32 v[82:83], v[98:99], v[82:83] op_sel_hi:[0,1]
	v_pk_fma_f32 v[78:79], v[48:49], v[78:79], v[6:7]
	v_pk_fma_f32 v[76:77], v[50:51], v[76:77], v[4:5]
	v_pk_fma_f32 v[82:83], v[44:45], v[82:83], v[2:3]
	v_pk_fma_f32 v[80:81], v[46:47], v[80:81], v[0:1]
	v_cvt_pk_bf16_f32 v76, v76, v77
	v_cvt_pk_bf16_f32 v77, v78, v79
	v_cvt_pk_bf16_f32 v78, v80, v81
	v_cvt_pk_bf16_f32 v79, v82, v83
	global_store_dwordx4 v[96:97], v[76:79], off offset:1024
	v_pk_mul_f32 v[80:81], v[98:99], v[114:115] op_sel_hi:[0,1]
	v_pk_mul_f32 v[82:83], v[98:99], v[86:87] op_sel_hi:[0,1]
	v_pk_mul_f32 v[76:77], v[98:99], v[112:113] op_sel_hi:[0,1]
	v_pk_mul_f32 v[78:79], v[98:99], v[84:85] op_sel_hi:[0,1]
	v_pk_fma_f32 v[78:79], v[64:65], v[78:79], v[22:23]
	v_pk_fma_f32 v[76:77], v[66:67], v[76:77], v[20:21]
	v_pk_fma_f32 v[82:83], v[60:61], v[82:83], v[18:19]
	v_pk_fma_f32 v[80:81], v[62:63], v[80:81], v[16:17]
	v_cvt_pk_bf16_f32 v76, v76, v77
	v_cvt_pk_bf16_f32 v77, v78, v79
	v_cvt_pk_bf16_f32 v78, v80, v81
	v_cvt_pk_bf16_f32 v79, v82, v83
	global_store_dwordx4 v[96:97], v[76:79], off offset:2048
	v_pk_mul_f32 v[80:81], v[94:95], v[98:99] op_sel_hi:[1,0]
	v_pk_mul_f32 v[82:83], v[90:91], v[98:99] op_sel_hi:[1,0]
	v_pk_mul_f32 v[76:77], v[92:93], v[98:99] op_sel_hi:[1,0]
	v_pk_mul_f32 v[78:79], v[88:89], v[98:99] op_sel_hi:[1,0]
	v_pk_fma_f32 v[76:77], v[74:75], v[76:77], v[28:29]
	v_pk_fma_f32 v[78:79], v[72:73], v[78:79], v[30:31]
	v_pk_fma_f32 v[82:83], v[68:69], v[82:83], v[26:27]
	v_pk_fma_f32 v[80:81], v[70:71], v[80:81], v[24:25]
	v_cvt_pk_bf16_f32 v76, v76, v77
	v_cvt_pk_bf16_f32 v77, v78, v79
	v_cvt_pk_bf16_f32 v78, v80, v81
	v_cvt_pk_bf16_f32 v79, v82, v83
	global_store_dwordx4 v[96:97], v[76:79], off offset:3072
	s_waitcnt vmcnt(11)
	v_lshlrev_b32_e32 v97, 16, v179
	v_lshlrev_b32_e32 v96, 16, v178
	v_and_b32_e32 v77, 0xffff0000, v179
	v_and_b32_e32 v76, 0xffff0000, v178
	v_lshlrev_b32_e32 v101, 16, v181
	v_lshlrev_b32_e32 v100, 16, v180
	v_and_b32_e32 v79, 0xffff0000, v181
	v_and_b32_e32 v78, 0xffff0000, v180
	v_pk_mul_f32 v[98:99], v[76:77], v[76:77]
	v_pk_mul_f32 v[102:103], v[78:79], v[78:79]
	s_waitcnt vmcnt(8)
	v_lshlrev_b32_e32 v92, 16, v190
	v_and_b32_e32 v93, 0xffff0000, v190
	v_pk_fma_f32 v[98:99], v[96:97], v[96:97], v[98:99]
	v_pk_fma_f32 v[102:103], v[100:101], v[100:101], v[102:103]
	v_lshlrev_b32_e32 v105, 16, v183
	v_lshlrev_b32_e32 v104, 16, v182
	v_and_b32_e32 v81, 0xffff0000, v183
	v_and_b32_e32 v80, 0xffff0000, v182
	v_lshlrev_b32_e32 v109, 16, v185
	v_lshlrev_b32_e32 v108, 16, v184
	v_and_b32_e32 v83, 0xffff0000, v185
	v_and_b32_e32 v82, 0xffff0000, v184
	v_pk_mul_f32 v[106:107], v[80:81], v[80:81]
	v_pk_mul_f32 v[110:111], v[82:83], v[82:83]
	v_mul_f32_e32 v116, v92, v92
	v_mul_f32_e32 v117, v93, v93
	v_pk_add_f32 v[98:99], v[98:99], v[98:99] op_sel:[0,1] op_sel_hi:[1,0]
	v_pk_add_f32 v[102:103], v[102:103], v[102:103] op_sel:[0,1] op_sel_hi:[1,0]
	v_lshlrev_b32_e32 v88, 16, v191
	v_and_b32_e32 v89, 0xffff0000, v191
	v_pk_fma_f32 v[106:107], v[104:105], v[104:105], v[106:107]
	v_pk_fma_f32 v[110:111], v[108:109], v[108:109], v[110:111]
	v_mov_b32_e32 v99, v116
	v_mov_b32_e32 v103, v117
	v_mul_f32_e32 v118, v88, v88
	v_mul_f32_e32 v119, v89, v89
	v_pk_add_f32 v[98:99], v[98:99], v[102:103]
	v_pk_add_f32 v[102:103], v[106:107], v[106:107] op_sel:[0,1] op_sel_hi:[1,0]
	v_pk_add_f32 v[106:107], v[110:111], v[110:111] op_sel:[0,1] op_sel_hi:[1,0]
	v_mov_b32_e32 v103, v118
	v_mov_b32_e32 v107, v119
	v_lshlrev_b32_e32 v112, 16, v186
	v_and_b32_e32 v113, 0xffff0000, v186
	v_lshlrev_b32_e32 v84, 16, v187
	v_and_b32_e32 v85, 0xffff0000, v187
	v_pk_add_f32 v[102:103], v[102:103], v[106:107]
	v_lshlrev_b32_e32 v94, 16, v192
	v_and_b32_e32 v95, 0xffff0000, v192
	v_pk_add_f32 v[98:99], v[98:99], v[102:103]
	v_mul_f32_e32 v102, v113, v113
	v_mul_f32_e32 v106, v85, v85
	v_mul_f32_e32 v120, v94, v94
	v_mul_f32_e32 v121, v95, v95
	v_pk_fma_f32 v[102:103], v[112:113], v[112:113], v[102:103] op_sel_hi:[1,1,0]
	v_pk_fma_f32 v[106:107], v[84:85], v[84:85], v[106:107] op_sel_hi:[1,1,0]
	v_lshlrev_b32_e32 v114, 16, v188
	v_and_b32_e32 v115, 0xffff0000, v188
	v_lshlrev_b32_e32 v86, 16, v189
	v_and_b32_e32 v87, 0xffff0000, v189
	v_mov_b32_e32 v103, v120
	v_mov_b32_e32 v107, v121
	v_lshlrev_b32_e32 v90, 16, v193
	v_and_b32_e32 v91, 0xffff0000, v193
	s_add_i32 s100, s8, -1
	s_ashr_i32 s101, s100, 31
	s_lshl_b64 s[100:101], s[100:101], 12
	v_lshl_add_u64 v[210:211], v[34:35], 0, s[100:101]
	s_nop 0
	global_load_dwordx4 v[178:181], v[210:211], off
	global_load_dwordx4 v[182:185], v[210:211], off offset:1024
	global_load_dwordx4 v[186:189], v[210:211], off offset:2048
	global_load_dwordx4 v[190:193], v[210:211], off offset:3072
	v_pk_add_f32 v[102:103], v[102:103], v[106:107]
	v_mul_f32_e32 v106, v115, v115
	v_mul_f32_e32 v110, v87, v87
	v_mul_f32_e32 v122, v90, v90
	v_mul_f32_e32 v123, v91, v91
	v_pk_fma_f32 v[106:107], v[114:115], v[114:115], v[106:107] op_sel_hi:[1,1,0]
	v_pk_fma_f32 v[110:111], v[86:87], v[86:87], v[110:111] op_sel_hi:[1,1,0]
	v_mov_b32_e32 v107, v122
	v_mov_b32_e32 v111, v123
	v_pk_add_f32 v[106:107], v[106:107], v[110:111]
	s_nop 0
	v_pk_add_f32 v[102:103], v[102:103], v[106:107]
	s_nop 0
	v_pk_add_f32 v[98:99], v[98:99], v[102:103]
	s_nop 0
	v_add_f32_e32 v98, v98, v99
	s_nop 1
	v_add_f32_dpp v98, v98, v98 quad_perm:[1,0,3,2] row_mask:0xf bank_mask:0xf
; __device__ __forceinline__ v4u pk8(f32x4 a, f32x4 b) { v4u w; w.x = pk2(a[0], a[1]); w.y = pk2(a[2], a[3]); w.z = pk2(b[0], b[1]); w.w = pk2(b[2], b[3]); return w; }
; __device__ __forceinline__ float wave_sum(float v) {
; #pragma unroll
;     for (int o = 1; o < 64; o <<= 1) v += shfl_xor_f(v, o);
;     return v;
; template <int XF32> __device__ __forceinline__ void norm_mod_phase(const void* x, const float* modl, int ch_shift, int ch_scale, bf16* H, int gw, int NGW, int lane) {
;     ...
;             v4u* o = (v4u*)(H + (size_t)(r0 + rr) * DM);
; #pragma unroll
;             for (int j = 0; j < 4; ++j) o[lane + 64 * j] = pk8(v[j][0] * rstd * sc[j][0] + sh[j][0], v[j][1] * rstd * sc[j][1] + sh[j][1]);
	s_nop 1
	v_add_f32_dpp v98, v98, v98 quad_perm:[2,3,0,1] row_mask:0xf bank_mask:0xf
	s_nop 1
	v_add_f32_dpp v98, v98, v98 row_half_mirror row_mask:0xf bank_mask:0xf
	s_nop 1
	v_add_f32_dpp v98, v98, v98 row_mirror row_mask:0xf bank_mask:0xf
	v_mov_b32_e32 v99, v98
	s_nop 1
	v_permlane16_swap_b32_e32 v99, v98
	s_nop 1
	v_add_f32_e32 v98, v98, v99
	v_mov_b32_e32 v99, v98
	s_nop 1
	v_permlane32_swap_b32_e32 v99, v98
	s_nop 1
	v_add_f32_e32 v98, v98, v99
	v_fmamk_f32 v98, v98, 0x3a000000, v224
	v_cmp_gt_f32_e32 vcc, s41, v98
	v_mul_f32_e32 v99, 0x4f800000, v98
	s_nop 0
	v_cndmask_b32_e32 v98, v98, v99, vcc
	v_sqrt_f32_e32 v99, v98
	s_nop 0
	v_add_u32_e32 v102, -1, v99
	v_fma_f32 v103, -v102, v99, v98
	v_cmp_ge_f32_e64 s[4:5], 0, v103
	v_add_u32_e32 v103, 1, v99
	s_nop 0
	v_cndmask_b32_e64 v102, v99, v102, s[4:5]
	v_fma_f32 v99, -v103, v99, v98
	v_cmp_lt_f32_e64 s[4:5], 0, v99
	s_nop 1
	v_cndmask_b32_e64 v99, v102, v103, s[4:5]
	v_mul_f32_e32 v102, 0x37800000, v99
	v_cndmask_b32_e32 v99, v99, v102, vcc
	v_cmp_class_f32_e32 vcc, v98, v225
	s_nop 1
	v_cndmask_b32_e32 v98, v99, v98, vcc
	v_div_scale_f32 v99, s[0:1], v98, v98, 1.0
	v_rcp_f32_e32 v102, v99
	s_add_i32 s0, s8, -2
	s_ashr_i32 s1, s0, 31
	v_fma_f32 v103, -v99, v102, 1.0
	v_fmac_f32_e32 v102, v103, v102
	v_div_scale_f32 v103, vcc, 1.0, v98, 1.0
	v_mul_f32_e32 v106, v103, v102
	v_fma_f32 v107, -v99, v106, v103
	v_fmac_f32_e32 v106, v107, v102
	v_fma_f32 v99, -v99, v106, v103
	v_div_fmas_f32 v99, v99, v102, v106
	v_div_fixup_f32 v98, v99, v98, 1.0
	v_mov_b32_e32 v102, v96
	v_mov_b32_e32 v103, v76
	v_mov_b32_e32 v76, v97
	v_pk_mul_f32 v[102:103], v[98:99], v[102:103] op_sel_hi:[0,1]
	v_pk_mul_f32 v[76:77], v[98:99], v[76:77] op_sel_hi:[0,1]
	v_pk_fma_f32 v[96:97], v[56:57], v[76:77], v[14:15]
	v_pk_fma_f32 v[76:77], v[58:59], v[102:103], v[12:13]
	v_mov_b32_e32 v102, v100
	v_mov_b32_e32 v103, v78
	v_mov_b32_e32 v78, v101
	v_pk_mul_f32 v[102:103], v[98:99], v[102:103] op_sel_hi:[0,1]
	v_pk_mul_f32 v[78:79], v[98:99], v[78:79] op_sel_hi:[0,1]
	v_pk_fma_f32 v[100:101], v[52:53], v[78:79], v[10:11]
	v_pk_fma_f32 v[78:79], v[54:55], v[102:103], v[8:9]
	v_cvt_pk_bf16_f32 v76, v76, v77
	v_cvt_pk_bf16_f32 v77, v96, v97
	v_cvt_pk_bf16_f32 v78, v78, v79
	v_cvt_pk_bf16_f32 v79, v100, v101
	v_lshl_add_u64 v[96:97], v[36:37], 0, s[64:65]
	global_store_dwordx4 v[96:97], v[76:79], off
	s_lshl_b64 s[64:65], s[0:1], 12
	s_nop 0
	v_mov_b32_e32 v77, v80
	v_mov_b32_e32 v80, v105
	v_mov_b32_e32 v76, v104
	v_pk_mul_f32 v[78:79], v[98:99], v[80:81] op_sel_hi:[0,1]
	v_mov_b32_e32 v80, v108
	v_mov_b32_e32 v81, v82
	v_mov_b32_e32 v82, v109
	v_pk_mul_f32 v[76:77], v[98:99], v[76:77] op_sel_hi:[0,1]
	v_pk_mul_f32 v[80:81], v[98:99], v[80:81] op_sel_hi:[0,1]
	v_pk_mul_f32 v[82:83], v[98:99], v[82:83] op_sel_hi:[0,1]
	v_pk_fma_f32 v[78:79], v[48:49], v[78:79], v[6:7]
	v_pk_fma_f32 v[76:77], v[50:51], v[76:77], v[4:5]
	v_pk_fma_f32 v[82:83], v[44:45], v[82:83], v[2:3]
	v_pk_fma_f32 v[80:81], v[46:47], v[80:81], v[0:1]
	v_cvt_pk_bf16_f32 v76, v76, v77
	v_cvt_pk_bf16_f32 v77, v78, v79
	v_cvt_pk_bf16_f32 v78, v80, v81
	v_cvt_pk_bf16_f32 v79, v82, v83
	global_store_dwordx4 v[96:97], v[76:79], off offset:1024
	v_pk_mul_f32 v[80:81], v[98:99], v[114:115] op_sel_hi:[0,1]
	v_pk_mul_f32 v[82:83], v[98:99], v[86:87] op_sel_hi:[0,1]
	v_pk_mul_f32 v[76:77], v[98:99], v[112:113] op_sel_hi:[0,1]
	v_pk_mul_f32 v[78:79], v[98:99], v[84:85] op_sel_hi:[0,1]
	v_pk_fma_f32 v[78:79], v[64:65], v[78:79], v[22:23]
	v_pk_fma_f32 v[76:77], v[66:67], v[76:77], v[20:21]
	v_pk_fma_f32 v[82:83], v[60:61], v[82:83], v[18:19]
	v_pk_fma_f32 v[80:81], v[62:63], v[80:81], v[16:17]
	v_cvt_pk_bf16_f32 v76, v76, v77
	v_cvt_pk_bf16_f32 v77, v78, v79
	v_cvt_pk_bf16_f32 v78, v80, v81
	v_cvt_pk_bf16_f32 v79, v82, v83
	global_store_dwordx4 v[96:97], v[76:79], off offset:2048
	v_pk_mul_f32 v[80:81], v[94:95], v[98:99] op_sel_hi:[1,0]
	v_pk_mul_f32 v[82:83], v[90:91], v[98:99] op_sel_hi:[1,0]
	v_pk_mul_f32 v[76:77], v[92:93], v[98:99] op_sel_hi:[1,0]
	v_pk_mul_f32 v[78:79], v[88:89], v[98:99] op_sel_hi:[1,0]
	v_pk_fma_f32 v[76:77], v[74:75], v[76:77], v[28:29]
	v_pk_fma_f32 v[78:79], v[72:73], v[78:79], v[30:31]
	v_pk_fma_f32 v[82:83], v[68:69], v[82:83], v[26:27]
	v_pk_fma_f32 v[80:81], v[70:71], v[80:81], v[24:25]
	v_cvt_pk_bf16_f32 v76, v76, v77
	v_cvt_pk_bf16_f32 v77, v78, v79
	v_cvt_pk_bf16_f32 v78, v80, v81
	v_cvt_pk_bf16_f32 v79, v82, v83
	global_store_dwordx4 v[96:97], v[76:79], off offset:3072
	s_waitcnt vmcnt(11)
	v_lshlrev_b32_e32 v97, 16, v195
	v_lshlrev_b32_e32 v96, 16, v194
	v_and_b32_e32 v77, 0xffff0000, v195
	v_and_b32_e32 v76, 0xffff0000, v194
	v_lshlrev_b32_e32 v101, 16, v197
	v_lshlrev_b32_e32 v100, 16, v196
	v_and_b32_e32 v79, 0xffff0000, v197
	v_and_b32_e32 v78, 0xffff0000, v196
	v_pk_mul_f32 v[98:99], v[76:77], v[76:77]
	v_pk_mul_f32 v[102:103], v[78:79], v[78:79]
	s_waitcnt vmcnt(8)
; __device__ __forceinline__ v4u pk8(f32x4 a, f32x4 b) { v4u w; w.x = pk2(a[0], a[1]); w.y = pk2(a[2], a[3]); w.z = pk2(b[0], b[1]); w.w = pk2(b[2], b[3]); return w; }
; __device__ __forceinline__ float ssq8(const f32x4& a, const f32x4& b) { return ((a[0] * a[0] + a[1] * a[1]) + (a[2] * a[2] + a[3] * a[3])) + ((b[0] * b[0] + b[1] * b[1]) + (b[2] * b[2] + b[3] * b[3])); }
; __device__ __forceinline__ float wave_sum(float v) {
; #pragma unroll
;     for (int o = 1; o < 64; o <<= 1) v += shfl_xor_f(v, o);
;     return v;
; template <int XF32> __device__ __forceinline__ void norm_mod_phase(const void* x, const float* modl, int ch_shift, int ch_scale, bf16* H, int gw, int NGW, int lane) {
;     ...
;             for (int j = 0; j < 4; ++j) s += ssq8(v[j][0], v[j][1]);
;             const float rstd = 1.f / sqrtf(wave_sum(s) * (1.f / DM) + EPS);
;             v4u* o = (v4u*)(H + (size_t)(r0 + rr) * DM);
; #pragma unroll
;             for (int j = 0; j < 4; ++j) o[lane + 64 * j] = pk8(v[j][0] * rstd * sc[j][0] + sh[j][0], v[j][1] * rstd * sc[j][1] + sh[j][1]);
	v_lshlrev_b32_e32 v92, 16, v206
	v_and_b32_e32 v93, 0xffff0000, v206
	v_pk_fma_f32 v[98:99], v[96:97], v[96:97], v[98:99]
	v_pk_fma_f32 v[102:103], v[100:101], v[100:101], v[102:103]
	v_lshlrev_b32_e32 v105, 16, v199
	v_lshlrev_b32_e32 v104, 16, v198
	v_and_b32_e32 v81, 0xffff0000, v199
	v_and_b32_e32 v80, 0xffff0000, v198
	v_lshlrev_b32_e32 v109, 16, v201
	v_lshlrev_b32_e32 v108, 16, v200
	v_and_b32_e32 v83, 0xffff0000, v201
	v_and_b32_e32 v82, 0xffff0000, v200
	v_pk_mul_f32 v[106:107], v[80:81], v[80:81]
	v_pk_mul_f32 v[110:111], v[82:83], v[82:83]
	v_mul_f32_e32 v116, v92, v92
	v_mul_f32_e32 v117, v93, v93
	v_pk_add_f32 v[98:99], v[98:99], v[98:99] op_sel:[0,1] op_sel_hi:[1,0]
	v_pk_add_f32 v[102:103], v[102:103], v[102:103] op_sel:[0,1] op_sel_hi:[1,0]
	v_lshlrev_b32_e32 v88, 16, v207
	v_and_b32_e32 v89, 0xffff0000, v207
	v_pk_fma_f32 v[106:107], v[104:105], v[104:105], v[106:107]
	v_pk_fma_f32 v[110:111], v[108:109], v[108:109], v[110:111]
	v_mov_b32_e32 v99, v116
	v_mov_b32_e32 v103, v117
	v_mul_f32_e32 v118, v88, v88
	v_mul_f32_e32 v119, v89, v89
	v_pk_add_f32 v[98:99], v[98:99], v[102:103]
	v_pk_add_f32 v[102:103], v[106:107], v[106:107] op_sel:[0,1] op_sel_hi:[1,0]
	v_pk_add_f32 v[106:107], v[110:111], v[110:111] op_sel:[0,1] op_sel_hi:[1,0]
	v_mov_b32_e32 v103, v118
	v_mov_b32_e32 v107, v119
	v_lshlrev_b32_e32 v112, 16, v202
	v_and_b32_e32 v113, 0xffff0000, v202
	v_lshlrev_b32_e32 v84, 16, v203
	v_and_b32_e32 v85, 0xffff0000, v203
	v_pk_add_f32 v[102:103], v[102:103], v[106:107]
	v_lshlrev_b32_e32 v94, 16, v208
	v_and_b32_e32 v95, 0xffff0000, v208
	v_pk_add_f32 v[98:99], v[98:99], v[102:103]
	v_mul_f32_e32 v102, v113, v113
	v_mul_f32_e32 v106, v85, v85
	v_mul_f32_e32 v120, v94, v94
	v_mul_f32_e32 v121, v95, v95
	v_pk_fma_f32 v[102:103], v[112:113], v[112:113], v[102:103] op_sel_hi:[1,1,0]
	v_pk_fma_f32 v[106:107], v[84:85], v[84:85], v[106:107] op_sel_hi:[1,1,0]
	v_lshlrev_b32_e32 v114, 16, v204
	v_and_b32_e32 v115, 0xffff0000, v204
	v_lshlrev_b32_e32 v86, 16, v205
	v_and_b32_e32 v87, 0xffff0000, v205
	v_mov_b32_e32 v103, v120
	v_mov_b32_e32 v107, v121
	v_lshlrev_b32_e32 v90, 16, v209
	v_and_b32_e32 v91, 0xffff0000, v209
	s_add_i32 s100, s8, 0
	s_ashr_i32 s101, s100, 31
	s_lshl_b64 s[100:101], s[100:101], 12
	v_lshl_add_u64 v[210:211], v[34:35], 0, s[100:101]
	s_nop 0
	global_load_dwordx4 v[194:197], v[210:211], off
	global_load_dwordx4 v[198:201], v[210:211], off offset:1024
	global_load_dwordx4 v[202:205], v[210:211], off offset:2048
	global_load_dwordx4 v[206:209], v[210:211], off offset:3072
	v_pk_add_f32 v[102:103], v[102:103], v[106:107]
	v_mul_f32_e32 v106, v115, v115
	v_mul_f32_e32 v110, v87, v87
	v_mul_f32_e32 v122, v90, v90
	v_mul_f32_e32 v123, v91, v91
	v_pk_fma_f32 v[106:107], v[114:115], v[114:115], v[106:107] op_sel_hi:[1,1,0]
	v_pk_fma_f32 v[110:111], v[86:87], v[86:87], v[110:111] op_sel_hi:[1,1,0]
	v_mov_b32_e32 v107, v122
	v_mov_b32_e32 v111, v123
	v_pk_add_f32 v[106:107], v[106:107], v[110:111]
	s_nop 0
	v_pk_add_f32 v[102:103], v[102:103], v[106:107]
	s_nop 0
	v_pk_add_f32 v[98:99], v[98:99], v[102:103]
	s_nop 0
	v_add_f32_e32 v98, v98, v99
	s_nop 1
	v_add_f32_dpp v98, v98, v98 quad_perm:[1,0,3,2] row_mask:0xf bank_mask:0xf
	s_nop 1
	v_add_f32_dpp v98, v98, v98 quad_perm:[2,3,0,1] row_mask:0xf bank_mask:0xf
	s_nop 1
	v_add_f32_dpp v98, v98, v98 row_half_mirror row_mask:0xf bank_mask:0xf
	s_nop 1
	v_add_f32_dpp v98, v98, v98 row_mirror row_mask:0xf bank_mask:0xf
	v_mov_b32_e32 v99, v98
	s_nop 1
	v_permlane16_swap_b32_e32 v99, v98
	s_nop 1
	v_add_f32_e32 v98, v98, v99
	v_mov_b32_e32 v99, v98
	s_nop 1
	v_permlane32_swap_b32_e32 v99, v98
	s_nop 1
	v_add_f32_e32 v98, v98, v99
	v_fmamk_f32 v98, v98, 0x3a000000, v224
	v_cmp_gt_f32_e32 vcc, s41, v98
	v_mul_f32_e32 v99, 0x4f800000, v98
	s_nop 0
	v_cndmask_b32_e32 v98, v98, v99, vcc
	v_sqrt_f32_e32 v99, v98
	s_nop 0
	v_add_u32_e32 v102, -1, v99
	v_fma_f32 v103, -v102, v99, v98
	v_cmp_ge_f32_e64 s[4:5], 0, v103
	v_add_u32_e32 v103, 1, v99
	s_nop 0
	v_cndmask_b32_e64 v102, v99, v102, s[4:5]
	v_fma_f32 v99, -v103, v99, v98
	v_cmp_lt_f32_e64 s[4:5], 0, v99
	s_nop 1
	v_cndmask_b32_e64 v99, v102, v103, s[4:5]
	v_mul_f32_e32 v102, 0x37800000, v99
	v_cndmask_b32_e32 v99, v99, v102, vcc
	v_cmp_class_f32_e32 vcc, v98, v225
	s_nop 1
	v_cndmask_b32_e32 v98, v99, v98, vcc
	v_div_scale_f32 v99, s[0:1], v98, v98, 1.0
	v_rcp_f32_e32 v102, v99
	s_add_i32 s0, s8, -1
	s_ashr_i32 s1, s0, 31
	v_fma_f32 v103, -v99, v102, 1.0
	v_fmac_f32_e32 v102, v103, v102
	v_div_scale_f32 v103, vcc, 1.0, v98, 1.0
	v_mul_f32_e32 v106, v103, v102
	v_fma_f32 v107, -v99, v106, v103
	v_fmac_f32_e32 v106, v107, v102
	v_fma_f32 v99, -v99, v106, v103
	v_div_fmas_f32 v99, v99, v102, v106
	v_div_fixup_f32 v98, v99, v98, 1.0
	v_mov_b32_e32 v102, v96
	v_mov_b32_e32 v103, v76
	v_mov_b32_e32 v76, v97
	v_pk_mul_f32 v[102:103], v[98:99], v[102:103] op_sel_hi:[0,1]
	v_pk_mul_f32 v[76:77], v[98:99], v[76:77] op_sel_hi:[0,1]
	v_pk_fma_f32 v[96:97], v[56:57], v[76:77], v[14:15]
	v_pk_fma_f32 v[76:77], v[58:59], v[102:103], v[12:13]
	v_mov_b32_e32 v102, v100
	v_mov_b32_e32 v103, v78
	v_mov_b32_e32 v78, v101
	v_pk_mul_f32 v[102:103], v[98:99], v[102:103] op_sel_hi:[0,1]
	v_pk_mul_f32 v[78:79], v[98:99], v[78:79] op_sel_hi:[0,1]
	v_pk_fma_f32 v[100:101], v[52:53], v[78:79], v[10:11]
	v_pk_fma_f32 v[78:79], v[54:55], v[102:103], v[8:9]
	v_cvt_pk_bf16_f32 v76, v76, v77
	v_cvt_pk_bf16_f32 v77, v96, v97
	v_cvt_pk_bf16_f32 v78, v78, v79
	v_cvt_pk_bf16_f32 v79, v100, v101
	v_lshl_add_u64 v[96:97], v[36:37], 0, s[64:65]
	global_store_dwordx4 v[96:97], v[76:79], off
	s_lshl_b64 s[64:65], s[0:1], 12
	s_nop 0
	v_mov_b32_e32 v77, v80
; __device__ __forceinline__ v4u pk8(f32x4 a, f32x4 b) { v4u w; w.x = pk2(a[0], a[1]); w.y = pk2(a[2], a[3]); w.z = pk2(b[0], b[1]); w.w = pk2(b[2], b[3]); return w; }
; __device__ __forceinline__ float ssq8(const f32x4& a, const f32x4& b) { return ((a[0] * a[0] + a[1] * a[1]) + (a[2] * a[2] + a[3] * a[3])) + ((b[0] * b[0] + b[1] * b[1]) + (b[2] * b[2] + b[3] * b[3])); }
; __device__ __forceinline__ float wave_sum(float v) {
; #pragma unroll
;     for (int o = 1; o < 64; o <<= 1) v += shfl_xor_f(v, o);
;     return v;
; template <int XF32> __device__ __forceinline__ void norm_mod_phase(const void* x, const float* modl, int ch_shift, int ch_scale, bf16* H, int gw, int NGW, int lane) {
;     ...
;             const unsigned char* xr = (const unsigned char*)x + (size_t)(r0 + rr) * rowb; f32x4 v[4][2]; float s = 0.f;
; #pragma unroll
;             for (int j = 0; j < 4; ++j) ld_row8<XF32>(xr, lane, j, v[j][0], v[j][1]);
; #pragma unroll
;             for (int j = 0; j < 4; ++j) s += ssq8(v[j][0], v[j][1]);
;             const float rstd = 1.f / sqrtf(wave_sum(s) * (1.f / DM) + EPS);
;             v4u* o = (v4u*)(H + (size_t)(r0 + rr) * DM);
; #pragma unroll
;             for (int j = 0; j < 4; ++j) o[lane + 64 * j] = pk8(v[j][0] * rstd * sc[j][0] + sh[j][0], v[j][1] * rstd * sc[j][1] + sh[j][1]);
	v_mov_b32_e32 v80, v105
	v_mov_b32_e32 v76, v104
	v_pk_mul_f32 v[78:79], v[98:99], v[80:81] op_sel_hi:[0,1]
	v_mov_b32_e32 v80, v108
	v_mov_b32_e32 v81, v82
	v_mov_b32_e32 v82, v109
	v_pk_mul_f32 v[76:77], v[98:99], v[76:77] op_sel_hi:[0,1]
	v_pk_mul_f32 v[80:81], v[98:99], v[80:81] op_sel_hi:[0,1]
	v_pk_mul_f32 v[82:83], v[98:99], v[82:83] op_sel_hi:[0,1]
	v_pk_fma_f32 v[78:79], v[48:49], v[78:79], v[6:7]
	v_pk_fma_f32 v[76:77], v[50:51], v[76:77], v[4:5]
	v_pk_fma_f32 v[82:83], v[44:45], v[82:83], v[2:3]
	v_pk_fma_f32 v[80:81], v[46:47], v[80:81], v[0:1]
	v_cvt_pk_bf16_f32 v76, v76, v77
	v_cvt_pk_bf16_f32 v77, v78, v79
	v_cvt_pk_bf16_f32 v78, v80, v81
	v_cvt_pk_bf16_f32 v79, v82, v83
	global_store_dwordx4 v[96:97], v[76:79], off offset:1024
	v_pk_mul_f32 v[80:81], v[98:99], v[114:115] op_sel_hi:[0,1]
	v_pk_mul_f32 v[82:83], v[98:99], v[86:87] op_sel_hi:[0,1]
	v_pk_mul_f32 v[76:77], v[98:99], v[112:113] op_sel_hi:[0,1]
	v_pk_mul_f32 v[78:79], v[98:99], v[84:85] op_sel_hi:[0,1]
	v_pk_fma_f32 v[78:79], v[64:65], v[78:79], v[22:23]
	v_pk_fma_f32 v[76:77], v[66:67], v[76:77], v[20:21]
	v_pk_fma_f32 v[82:83], v[60:61], v[82:83], v[18:19]
	v_pk_fma_f32 v[80:81], v[62:63], v[80:81], v[16:17]
	v_cvt_pk_bf16_f32 v76, v76, v77
	v_cvt_pk_bf16_f32 v77, v78, v79
	v_cvt_pk_bf16_f32 v78, v80, v81
	v_cvt_pk_bf16_f32 v79, v82, v83
	global_store_dwordx4 v[96:97], v[76:79], off offset:2048
	v_pk_mul_f32 v[80:81], v[94:95], v[98:99] op_sel_hi:[1,0]
	v_pk_mul_f32 v[82:83], v[90:91], v[98:99] op_sel_hi:[1,0]
	v_pk_mul_f32 v[76:77], v[92:93], v[98:99] op_sel_hi:[1,0]
	v_pk_mul_f32 v[78:79], v[88:89], v[98:99] op_sel_hi:[1,0]
	v_pk_fma_f32 v[76:77], v[74:75], v[76:77], v[28:29]
	v_pk_fma_f32 v[78:79], v[72:73], v[78:79], v[30:31]
	v_pk_fma_f32 v[82:83], v[68:69], v[82:83], v[26:27]
	v_pk_fma_f32 v[80:81], v[70:71], v[80:81], v[24:25]
	v_cvt_pk_bf16_f32 v76, v76, v77
	v_cvt_pk_bf16_f32 v77, v78, v79
	v_cvt_pk_bf16_f32 v78, v80, v81
	v_cvt_pk_bf16_f32 v79, v82, v83
	global_store_dwordx4 v[96:97], v[76:79], off offset:3072
	s_waitcnt vmcnt(11)
	v_lshlrev_b32_e32 v97, 16, v179
	v_lshlrev_b32_e32 v96, 16, v178
	v_and_b32_e32 v77, 0xffff0000, v179
	v_and_b32_e32 v76, 0xffff0000, v178
	v_lshlrev_b32_e32 v101, 16, v181
	v_lshlrev_b32_e32 v100, 16, v180
	v_and_b32_e32 v79, 0xffff0000, v181
	v_and_b32_e32 v78, 0xffff0000, v180
	v_pk_mul_f32 v[98:99], v[76:77], v[76:77]
	v_pk_mul_f32 v[102:103], v[78:79], v[78:79]
	s_waitcnt vmcnt(8)
	v_lshlrev_b32_e32 v92, 16, v190
	v_and_b32_e32 v93, 0xffff0000, v190
	v_pk_fma_f32 v[98:99], v[96:97], v[96:97], v[98:99]
	v_pk_fma_f32 v[102:103], v[100:101], v[100:101], v[102:103]
	v_lshlrev_b32_e32 v105, 16, v183
	v_lshlrev_b32_e32 v104, 16, v182
	v_and_b32_e32 v81, 0xffff0000, v183
	v_and_b32_e32 v80, 0xffff0000, v182
	v_lshlrev_b32_e32 v109, 16, v185
	v_lshlrev_b32_e32 v108, 16, v184
	v_and_b32_e32 v83, 0xffff0000, v185
	v_and_b32_e32 v82, 0xffff0000, v184
	v_pk_mul_f32 v[106:107], v[80:81], v[80:81]
	v_pk_mul_f32 v[110:111], v[82:83], v[82:83]
	v_mul_f32_e32 v116, v92, v92
	v_mul_f32_e32 v117, v93, v93
	v_pk_add_f32 v[98:99], v[98:99], v[98:99] op_sel:[0,1] op_sel_hi:[1,0]
	v_pk_add_f32 v[102:103], v[102:103], v[102:103] op_sel:[0,1] op_sel_hi:[1,0]
	v_lshlrev_b32_e32 v88, 16, v191
	v_and_b32_e32 v89, 0xffff0000, v191
	v_pk_fma_f32 v[106:107], v[104:105], v[104:105], v[106:107]
	v_pk_fma_f32 v[110:111], v[108:109], v[108:109], v[110:111]
	v_mov_b32_e32 v99, v116
	v_mov_b32_e32 v103, v117
	v_mul_f32_e32 v118, v88, v88
	v_mul_f32_e32 v119, v89, v89
	v_pk_add_f32 v[98:99], v[98:99], v[102:103]
	v_pk_add_f32 v[102:103], v[106:107], v[106:107] op_sel:[0,1] op_sel_hi:[1,0]
	v_pk_add_f32 v[106:107], v[110:111], v[110:111] op_sel:[0,1] op_sel_hi:[1,0]
	v_mov_b32_e32 v103, v118
	v_mov_b32_e32 v107, v119
	v_lshlrev_b32_e32 v112, 16, v186
	v_and_b32_e32 v113, 0xffff0000, v186
	v_lshlrev_b32_e32 v84, 16, v187
	v_and_b32_e32 v85, 0xffff0000, v187
	v_pk_add_f32 v[102:103], v[102:103], v[106:107]
	v_lshlrev_b32_e32 v94, 16, v192
	v_and_b32_e32 v95, 0xffff0000, v192
	v_pk_add_f32 v[98:99], v[98:99], v[102:103]
	v_mul_f32_e32 v102, v113, v113
	v_mul_f32_e32 v106, v85, v85
	v_mul_f32_e32 v120, v94, v94
	v_mul_f32_e32 v121, v95, v95
	v_pk_fma_f32 v[102:103], v[112:113], v[112:113], v[102:103] op_sel_hi:[1,1,0]
	v_pk_fma_f32 v[106:107], v[84:85], v[84:85], v[106:107] op_sel_hi:[1,1,0]
	v_lshlrev_b32_e32 v114, 16, v188
	v_and_b32_e32 v115, 0xffff0000, v188
	v_lshlrev_b32_e32 v86, 16, v189
	v_and_b32_e32 v87, 0xffff0000, v189
	v_mov_b32_e32 v103, v120
	v_mov_b32_e32 v107, v121
	v_lshlrev_b32_e32 v90, 16, v193
	v_and_b32_e32 v91, 0xffff0000, v193
	v_pk_add_f32 v[102:103], v[102:103], v[106:107]
	v_mul_f32_e32 v106, v115, v115
	v_mul_f32_e32 v110, v87, v87
	v_mul_f32_e32 v122, v90, v90
	v_mul_f32_e32 v123, v91, v91
	v_pk_fma_f32 v[106:107], v[114:115], v[114:115], v[106:107] op_sel_hi:[1,1,0]
	v_pk_fma_f32 v[110:111], v[86:87], v[86:87], v[110:111] op_sel_hi:[1,1,0]
	v_mov_b32_e32 v107, v122
	v_mov_b32_e32 v111, v123
	v_pk_add_f32 v[106:107], v[106:107], v[110:111]
	s_nop 0
	v_pk_add_f32 v[102:103], v[102:103], v[106:107]
	s_nop 0
	v_pk_add_f32 v[98:99], v[98:99], v[102:103]
	s_nop 0
	v_add_f32_e32 v98, v98, v99
	s_nop 1
	v_add_f32_dpp v98, v98, v98 quad_perm:[1,0,3,2] row_mask:0xf bank_mask:0xf
	s_nop 1
	v_add_f32_dpp v98, v98, v98 quad_perm:[2,3,0,1] row_mask:0xf bank_mask:0xf
	s_nop 1
	v_add_f32_dpp v98, v98, v98 row_half_mirror row_mask:0xf bank_mask:0xf
	s_nop 1
	v_add_f32_dpp v98, v98, v98 row_mirror row_mask:0xf bank_mask:0xf
	v_mov_b32_e32 v99, v98
	s_nop 1
	v_permlane16_swap_b32_e32 v99, v98
	s_nop 1
	v_add_f32_e32 v98, v98, v99
	v_mov_b32_e32 v99, v98
; __device__ __forceinline__ v4u pk8(f32x4 a, f32x4 b) { v4u w; w.x = pk2(a[0], a[1]); w.y = pk2(a[2], a[3]); w.z = pk2(b[0], b[1]); w.w = pk2(b[2], b[3]); return w; }
; __device__ __forceinline__ float wave_sum(float v) {
; #pragma unroll
;     for (int o = 1; o < 64; o <<= 1) v += shfl_xor_f(v, o);
;     return v;
; template <int XF32> __device__ __forceinline__ void norm_mod_phase(const void* x, const float* modl, int ch_shift, int ch_scale, bf16* H, int gw, int NGW, int lane) {
;     ...
;             v4u* o = (v4u*)(H + (size_t)(r0 + rr) * DM);
; #pragma unroll
;             for (int j = 0; j < 4; ++j) o[lane + 64 * j] = pk8(v[j][0] * rstd * sc[j][0] + sh[j][0], v[j][1] * rstd * sc[j][1] + sh[j][1]);
	s_nop 1
	v_permlane32_swap_b32_e32 v99, v98
	s_nop 1
	v_add_f32_e32 v98, v98, v99
	v_fmamk_f32 v98, v98, 0x3a000000, v224
	v_cmp_gt_f32_e32 vcc, s41, v98
	v_mul_f32_e32 v99, 0x4f800000, v98
	s_nop 0
	v_cndmask_b32_e32 v98, v98, v99, vcc
	v_sqrt_f32_e32 v99, v98
	s_nop 0
	v_add_u32_e32 v102, -1, v99
	v_fma_f32 v103, -v102, v99, v98
	v_cmp_ge_f32_e64 s[4:5], 0, v103
	v_add_u32_e32 v103, 1, v99
	s_nop 0
	v_cndmask_b32_e64 v102, v99, v102, s[4:5]
	v_fma_f32 v99, -v103, v99, v98
	v_cmp_lt_f32_e64 s[4:5], 0, v99
	s_nop 1
	v_cndmask_b32_e64 v99, v102, v103, s[4:5]
	v_mul_f32_e32 v102, 0x37800000, v99
	v_cndmask_b32_e32 v99, v99, v102, vcc
	v_cmp_class_f32_e32 vcc, v98, v225
	s_nop 1
	v_cndmask_b32_e32 v98, v99, v98, vcc
	v_div_scale_f32 v99, s[0:1], v98, v98, 1.0
	v_rcp_f32_e32 v102, v99
	s_nop 0
	v_fma_f32 v103, -v99, v102, 1.0
	v_fmac_f32_e32 v102, v103, v102
	v_div_scale_f32 v103, vcc, 1.0, v98, 1.0
	v_mul_f32_e32 v106, v103, v102
	v_fma_f32 v107, -v99, v106, v103
	v_fmac_f32_e32 v106, v107, v102
	v_fma_f32 v99, -v99, v106, v103
	v_div_fmas_f32 v99, v99, v102, v106
	v_div_fixup_f32 v98, v99, v98, 1.0
	v_mov_b32_e32 v102, v96
	v_mov_b32_e32 v103, v76
	v_mov_b32_e32 v76, v97
	v_pk_mul_f32 v[102:103], v[98:99], v[102:103] op_sel_hi:[0,1]
	v_pk_mul_f32 v[76:77], v[98:99], v[76:77] op_sel_hi:[0,1]
	v_pk_fma_f32 v[96:97], v[56:57], v[76:77], v[14:15]
	v_pk_fma_f32 v[76:77], v[58:59], v[102:103], v[12:13]
	v_mov_b32_e32 v102, v100
	v_mov_b32_e32 v103, v78
	v_mov_b32_e32 v78, v101
	v_pk_mul_f32 v[102:103], v[98:99], v[102:103] op_sel_hi:[0,1]
	v_pk_mul_f32 v[78:79], v[98:99], v[78:79] op_sel_hi:[0,1]
	v_pk_fma_f32 v[100:101], v[52:53], v[78:79], v[10:11]
	v_pk_fma_f32 v[78:79], v[54:55], v[102:103], v[8:9]
	v_cvt_pk_bf16_f32 v76, v76, v77
	v_cvt_pk_bf16_f32 v77, v96, v97
	v_cvt_pk_bf16_f32 v78, v78, v79
	v_cvt_pk_bf16_f32 v79, v100, v101
	v_lshl_add_u64 v[96:97], v[36:37], 0, s[64:65]
	global_store_dwordx4 v[96:97], v[76:79], off
	s_lshl_b64 s[64:65], s[8:9], 12
	s_add_i32 s8, s8, s2
	v_mov_b32_e32 v77, v80
	v_mov_b32_e32 v80, v105
	v_mov_b32_e32 v76, v104
	v_pk_mul_f32 v[78:79], v[98:99], v[80:81] op_sel_hi:[0,1]
	v_mov_b32_e32 v80, v108
	v_mov_b32_e32 v81, v82
	v_mov_b32_e32 v82, v109
	v_pk_mul_f32 v[76:77], v[98:99], v[76:77] op_sel_hi:[0,1]
	v_pk_mul_f32 v[80:81], v[98:99], v[80:81] op_sel_hi:[0,1]
	v_pk_mul_f32 v[82:83], v[98:99], v[82:83] op_sel_hi:[0,1]
	v_pk_fma_f32 v[78:79], v[48:49], v[78:79], v[6:7]
	v_pk_fma_f32 v[76:77], v[50:51], v[76:77], v[4:5]
	v_pk_fma_f32 v[82:83], v[44:45], v[82:83], v[2:3]
	v_pk_fma_f32 v[80:81], v[46:47], v[80:81], v[0:1]
	v_cvt_pk_bf16_f32 v76, v76, v77
	v_cvt_pk_bf16_f32 v77, v78, v79
	v_cvt_pk_bf16_f32 v78, v80, v81
	v_cvt_pk_bf16_f32 v79, v82, v83
	global_store_dwordx4 v[96:97], v[76:79], off offset:1024
	v_pk_mul_f32 v[80:81], v[98:99], v[114:115] op_sel_hi:[0,1]
	v_pk_mul_f32 v[82:83], v[98:99], v[86:87] op_sel_hi:[0,1]
	v_pk_mul_f32 v[76:77], v[98:99], v[112:113] op_sel_hi:[0,1]
	v_pk_mul_f32 v[78:79], v[98:99], v[84:85] op_sel_hi:[0,1]
	v_pk_fma_f32 v[78:79], v[64:65], v[78:79], v[22:23]
	v_pk_fma_f32 v[76:77], v[66:67], v[76:77], v[20:21]
	v_pk_fma_f32 v[82:83], v[60:61], v[82:83], v[18:19]
	v_pk_fma_f32 v[80:81], v[62:63], v[80:81], v[16:17]
	v_cvt_pk_bf16_f32 v76, v76, v77
	v_cvt_pk_bf16_f32 v77, v78, v79
	v_cvt_pk_bf16_f32 v78, v80, v81
	v_cvt_pk_bf16_f32 v79, v82, v83
	global_store_dwordx4 v[96:97], v[76:79], off offset:2048
	v_pk_mul_f32 v[80:81], v[94:95], v[98:99] op_sel_hi:[1,0]
	v_pk_mul_f32 v[82:83], v[90:91], v[98:99] op_sel_hi:[1,0]
	v_pk_mul_f32 v[76:77], v[92:93], v[98:99] op_sel_hi:[1,0]
	v_pk_mul_f32 v[78:79], v[88:89], v[98:99] op_sel_hi:[1,0]
	v_pk_fma_f32 v[76:77], v[74:75], v[76:77], v[28:29]
	v_pk_fma_f32 v[78:79], v[72:73], v[78:79], v[30:31]
	v_pk_fma_f32 v[82:83], v[68:69], v[82:83], v[26:27]
	v_pk_fma_f32 v[80:81], v[70:71], v[80:81], v[24:25]
	v_cvt_pk_bf16_f32 v76, v76, v77
	v_cvt_pk_bf16_f32 v77, v78, v79
	v_cvt_pk_bf16_f32 v78, v80, v81
	v_cvt_pk_bf16_f32 v79, v82, v83
	global_store_dwordx4 v[96:97], v[76:79], off offset:3072
	s_cmpk_lt_i32 s3, 0x800
	s_waitcnt vmcnt(7)
	v_lshlrev_b32_e32 v97, 16, v195
	v_lshlrev_b32_e32 v96, 16, v194
	v_and_b32_e32 v77, 0xffff0000, v195
	v_and_b32_e32 v76, 0xffff0000, v194
	v_lshlrev_b32_e32 v101, 16, v197
	v_lshlrev_b32_e32 v100, 16, v196
	v_and_b32_e32 v79, 0xffff0000, v197
	v_and_b32_e32 v78, 0xffff0000, v196
	v_pk_mul_f32 v[98:99], v[76:77], v[76:77]
	v_pk_mul_f32 v[102:103], v[78:79], v[78:79]
	s_waitcnt vmcnt(4)
; __device__ __forceinline__ float ssq8(const f32x4& a, const f32x4& b) { return ((a[0] * a[0] + a[1] * a[1]) + (a[2] * a[2] + a[3] * a[3])) + ((b[0] * b[0] + b[1] * b[1]) + (b[2] * b[2] + b[3] * b[3])); }
; __device__ __forceinline__ float wave_sum(float v) {
; #pragma unroll
;     for (int o = 1; o < 64; o <<= 1) v += shfl_xor_f(v, o);
;     return v;
; template <int XF32> __device__ __forceinline__ void norm_mod_phase(const void* x, const float* modl, int ch_shift, int ch_scale, bf16* H, int gw, int NGW, int lane) {
;     ...
;             for (int j = 0; j < 4; ++j) s += ssq8(v[j][0], v[j][1]);
;             const float rstd = 1.f / sqrtf(wave_sum(s) * (1.f / DM) + EPS);
;             v4u* o = (v4u*)(H + (size_t)(r0 + rr) * DM);
; #pragma unroll
	v_lshlrev_b32_e32 v92, 16, v206
	v_and_b32_e32 v93, 0xffff0000, v206
	v_pk_fma_f32 v[98:99], v[96:97], v[96:97], v[98:99]
	v_pk_fma_f32 v[102:103], v[100:101], v[100:101], v[102:103]
	v_lshlrev_b32_e32 v105, 16, v199
	v_lshlrev_b32_e32 v104, 16, v198
	v_and_b32_e32 v81, 0xffff0000, v199
	v_and_b32_e32 v80, 0xffff0000, v198
	v_lshlrev_b32_e32 v109, 16, v201
	v_lshlrev_b32_e32 v108, 16, v200
	v_and_b32_e32 v83, 0xffff0000, v201
	v_and_b32_e32 v82, 0xffff0000, v200
	v_pk_mul_f32 v[106:107], v[80:81], v[80:81]
	v_pk_mul_f32 v[110:111], v[82:83], v[82:83]
	v_mul_f32_e32 v116, v92, v92
	v_mul_f32_e32 v117, v93, v93
	v_pk_add_f32 v[98:99], v[98:99], v[98:99] op_sel:[0,1] op_sel_hi:[1,0]
	v_pk_add_f32 v[102:103], v[102:103], v[102:103] op_sel:[0,1] op_sel_hi:[1,0]
	v_lshlrev_b32_e32 v88, 16, v207
	v_and_b32_e32 v89, 0xffff0000, v207
	v_pk_fma_f32 v[106:107], v[104:105], v[104:105], v[106:107]
	v_pk_fma_f32 v[110:111], v[108:109], v[108:109], v[110:111]
	v_mov_b32_e32 v99, v116
	v_mov_b32_e32 v103, v117
	v_mul_f32_e32 v118, v88, v88
	v_mul_f32_e32 v119, v89, v89
	v_pk_add_f32 v[98:99], v[98:99], v[102:103]
	v_pk_add_f32 v[102:103], v[106:107], v[106:107] op_sel:[0,1] op_sel_hi:[1,0]
	v_pk_add_f32 v[106:107], v[110:111], v[110:111] op_sel:[0,1] op_sel_hi:[1,0]
	v_mov_b32_e32 v103, v118
	v_mov_b32_e32 v107, v119
	v_lshlrev_b32_e32 v112, 16, v202
	v_and_b32_e32 v113, 0xffff0000, v202
	v_lshlrev_b32_e32 v84, 16, v203
	v_and_b32_e32 v85, 0xffff0000, v203
	v_pk_add_f32 v[102:103], v[102:103], v[106:107]
	v_lshlrev_b32_e32 v94, 16, v208
	v_and_b32_e32 v95, 0xffff0000, v208
	v_pk_add_f32 v[98:99], v[98:99], v[102:103]
	v_mul_f32_e32 v102, v113, v113
	v_mul_f32_e32 v106, v85, v85
	v_mul_f32_e32 v120, v94, v94
	v_mul_f32_e32 v121, v95, v95
	v_pk_fma_f32 v[102:103], v[112:113], v[112:113], v[102:103] op_sel_hi:[1,1,0]
	v_pk_fma_f32 v[106:107], v[84:85], v[84:85], v[106:107] op_sel_hi:[1,1,0]
	v_lshlrev_b32_e32 v114, 16, v204
	v_and_b32_e32 v115, 0xffff0000, v204
	v_lshlrev_b32_e32 v86, 16, v205
	v_and_b32_e32 v87, 0xffff0000, v205
	v_mov_b32_e32 v103, v120
	v_mov_b32_e32 v107, v121
	v_lshlrev_b32_e32 v90, 16, v209
	v_and_b32_e32 v91, 0xffff0000, v209
	v_pk_add_f32 v[102:103], v[102:103], v[106:107]
	v_mul_f32_e32 v106, v115, v115
	v_mul_f32_e32 v110, v87, v87
	v_mul_f32_e32 v122, v90, v90
	v_mul_f32_e32 v123, v91, v91
	v_pk_fma_f32 v[106:107], v[114:115], v[114:115], v[106:107] op_sel_hi:[1,1,0]
	v_pk_fma_f32 v[110:111], v[86:87], v[86:87], v[110:111] op_sel_hi:[1,1,0]
	v_mov_b32_e32 v107, v122
	v_mov_b32_e32 v111, v123
	v_pk_add_f32 v[106:107], v[106:107], v[110:111]
	s_nop 0
	v_pk_add_f32 v[102:103], v[102:103], v[106:107]
	s_nop 0
	v_pk_add_f32 v[98:99], v[98:99], v[102:103]
	s_nop 0
	v_add_f32_e32 v98, v98, v99
	s_nop 1
	v_add_f32_dpp v98, v98, v98 quad_perm:[1,0,3,2] row_mask:0xf bank_mask:0xf
	s_nop 1
	v_add_f32_dpp v98, v98, v98 quad_perm:[2,3,0,1] row_mask:0xf bank_mask:0xf
	s_nop 1
	v_add_f32_dpp v98, v98, v98 row_half_mirror row_mask:0xf bank_mask:0xf
	s_nop 1
	v_add_f32_dpp v98, v98, v98 row_mirror row_mask:0xf bank_mask:0xf
	v_mov_b32_e32 v99, v98
	s_nop 1
	v_permlane16_swap_b32_e32 v99, v98
	s_nop 1
	v_add_f32_e32 v98, v98, v99
	v_mov_b32_e32 v99, v98
	s_nop 1
	v_permlane32_swap_b32_e32 v99, v98
	s_nop 1
	v_add_f32_e32 v98, v98, v99
	v_fmamk_f32 v98, v98, 0x3a000000, v224
	v_cmp_gt_f32_e32 vcc, s41, v98
	v_mul_f32_e32 v99, 0x4f800000, v98
	s_nop 0
	v_cndmask_b32_e32 v98, v98, v99, vcc
	v_sqrt_f32_e32 v99, v98
	s_nop 0
	v_add_u32_e32 v102, -1, v99
	v_fma_f32 v103, -v102, v99, v98
	v_cmp_ge_f32_e64 s[4:5], 0, v103
; __device__ __forceinline__ v4u pk8(f32x4 a, f32x4 b) { v4u w; w.x = pk2(a[0], a[1]); w.y = pk2(a[2], a[3]); w.z = pk2(b[0], b[1]); w.w = pk2(b[2], b[3]); return w; }
; template <int XF32> __device__ __forceinline__ void norm_mod_phase(const void* x, const float* modl, int ch_shift, int ch_scale, bf16* H, int gw, int NGW, int lane) {
;     ...
;             const float rstd = 1.f / sqrtf(wave_sum(s) * (1.f / DM) + EPS);
;             v4u* o = (v4u*)(H + (size_t)(r0 + rr) * DM);
; #pragma unroll
;             for (int j = 0; j < 4; ++j) o[lane + 64 * j] = pk8(v[j][0] * rstd * sc[j][0] + sh[j][0], v[j][1] * rstd * sc[j][1] + sh[j][1]);
	v_add_u32_e32 v103, 1, v99
	s_nop 0
	v_cndmask_b32_e64 v102, v99, v102, s[4:5]
	v_fma_f32 v99, -v103, v99, v98
	v_cmp_lt_f32_e64 s[4:5], 0, v99
	s_nop 1
	v_cndmask_b32_e64 v99, v102, v103, s[4:5]
	v_mul_f32_e32 v102, 0x37800000, v99
	v_cndmask_b32_e32 v99, v99, v102, vcc
	v_cmp_class_f32_e32 vcc, v98, v225
	s_nop 1
	v_cndmask_b32_e32 v98, v99, v98, vcc
	v_div_scale_f32 v99, s[0:1], v98, v98, 1.0
	v_rcp_f32_e32 v102, v99
	s_nop 0
	v_fma_f32 v103, -v99, v102, 1.0
	v_fmac_f32_e32 v102, v103, v102
	v_div_scale_f32 v103, vcc, 1.0, v98, 1.0
	v_mul_f32_e32 v106, v103, v102
	v_fma_f32 v107, -v99, v106, v103
	v_fmac_f32_e32 v106, v107, v102
	v_fma_f32 v99, -v99, v106, v103
	v_div_fmas_f32 v99, v99, v102, v106
	v_div_fixup_f32 v98, v99, v98, 1.0
	v_mov_b32_e32 v103, v76
	v_mov_b32_e32 v76, v97
	v_mov_b32_e32 v102, v96
	v_pk_mul_f32 v[76:77], v[98:99], v[76:77] op_sel_hi:[0,1]
	v_pk_mul_f32 v[102:103], v[98:99], v[102:103] op_sel_hi:[0,1]
	v_pk_fma_f32 v[14:15], v[56:57], v[76:77], v[14:15]
	v_mov_b32_e32 v56, v100
	v_mov_b32_e32 v57, v78
	v_mov_b32_e32 v78, v101
	v_pk_fma_f32 v[12:13], v[58:59], v[102:103], v[12:13]
	v_pk_mul_f32 v[56:57], v[98:99], v[56:57] op_sel_hi:[0,1]
	v_pk_mul_f32 v[58:59], v[98:99], v[78:79] op_sel_hi:[0,1]
	v_pk_fma_f32 v[52:53], v[52:53], v[58:59], v[10:11]
	v_pk_fma_f32 v[10:11], v[54:55], v[56:57], v[8:9]
	v_cvt_pk_bf16_f32 v8, v12, v13
	v_cvt_pk_bf16_f32 v9, v14, v15
	v_cvt_pk_bf16_f32 v10, v10, v11
	v_cvt_pk_bf16_f32 v11, v52, v53
	v_lshl_add_u64 v[12:13], v[36:37], 0, s[64:65]
	global_store_dwordx4 v[12:13], v[8:11], off
	s_nop 1
	v_mov_b32_e32 v8, v104
	v_mov_b32_e32 v9, v80
	v_pk_mul_f32 v[8:9], v[98:99], v[8:9] op_sel_hi:[0,1]
	v_mov_b32_e32 v80, v105
	v_pk_mul_f32 v[10:11], v[98:99], v[80:81] op_sel_hi:[0,1]
	v_pk_fma_f32 v[4:5], v[50:51], v[8:9], v[4:5]
	v_mov_b32_e32 v8, v108
	v_mov_b32_e32 v9, v82
	v_mov_b32_e32 v82, v109
	v_pk_fma_f32 v[6:7], v[48:49], v[10:11], v[6:7]
	v_pk_mul_f32 v[8:9], v[98:99], v[8:9] op_sel_hi:[0,1]
	v_pk_mul_f32 v[10:11], v[98:99], v[82:83] op_sel_hi:[0,1]
	v_pk_fma_f32 v[10:11], v[44:45], v[10:11], v[2:3]
	v_pk_fma_f32 v[2:3], v[46:47], v[8:9], v[0:1]
	v_cvt_pk_bf16_f32 v0, v4, v5
	v_cvt_pk_bf16_f32 v1, v6, v7
	v_cvt_pk_bf16_f32 v2, v2, v3
	v_cvt_pk_bf16_f32 v3, v10, v11
	global_store_dwordx4 v[12:13], v[0:3], off offset:1024
	v_pk_mul_f32 v[4:5], v[98:99], v[114:115] op_sel_hi:[0,1]
	v_pk_mul_f32 v[6:7], v[98:99], v[86:87] op_sel_hi:[0,1]
	v_pk_mul_f32 v[0:1], v[98:99], v[112:113] op_sel_hi:[0,1]
	v_pk_mul_f32 v[2:3], v[98:99], v[84:85] op_sel_hi:[0,1]
	v_pk_fma_f32 v[2:3], v[64:65], v[2:3], v[22:23]
	v_pk_fma_f32 v[0:1], v[66:67], v[0:1], v[20:21]
	v_pk_fma_f32 v[6:7], v[60:61], v[6:7], v[18:19]
	v_pk_fma_f32 v[4:5], v[62:63], v[4:5], v[16:17]
	v_cvt_pk_bf16_f32 v0, v0, v1
	v_cvt_pk_bf16_f32 v1, v2, v3
	v_cvt_pk_bf16_f32 v2, v4, v5
	v_cvt_pk_bf16_f32 v3, v6, v7
	global_store_dwordx4 v[12:13], v[0:3], off offset:2048
	v_pk_mul_f32 v[4:5], v[94:95], v[98:99] op_sel_hi:[1,0]
	v_pk_mul_f32 v[6:7], v[90:91], v[98:99] op_sel_hi:[1,0]
	v_pk_mul_f32 v[0:1], v[92:93], v[98:99] op_sel_hi:[1,0]
	v_pk_mul_f32 v[2:3], v[88:89], v[98:99] op_sel_hi:[1,0]
	v_pk_fma_f32 v[0:1], v[74:75], v[0:1], v[28:29]
	v_pk_fma_f32 v[2:3], v[72:73], v[2:3], v[30:31]
	v_pk_fma_f32 v[6:7], v[68:69], v[6:7], v[26:27]
	v_pk_fma_f32 v[4:5], v[70:71], v[4:5], v[24:25]
	v_cvt_pk_bf16_f32 v0, v0, v1
	v_cvt_pk_bf16_f32 v1, v2, v3
	v_cvt_pk_bf16_f32 v2, v4, v5
	v_cvt_pk_bf16_f32 v3, v6, v7
	global_store_dwordx4 v[12:13], v[0:3], off offset:3072
	s_cbranch_scc1 .LBB0_161

; template <int XF32> __device__ __forceinline__ void norm_mod_phase(const void* x, const float* modl, int ch_shift, int ch_scale, bf16* H, int gw, int NGW, int lane) {
;     ...
;     for (int blk = gw; blk < M / 8; blk += NGW) {
;         const int r0 = blk * 8, b = r0 >> 12;
;         const f32x4* shp = (const f32x4*)(modl + (size_t)b * MODW + ch_shift * DM); const f32x4* scp = (const f32x4*)(modl + (size_t)b * MODW + ch_scale * DM);
;         f32x4 sh[4][2], sc[4][2];
; #pragma unroll
;         for (int j = 0; j < 4; ++j)
; #pragma unroll
;             for (int q = 0; q < 2; ++q) { sh[j][q] = shp[2 * (lane + 64 * j) + q]; sc[j][q] = scp[2 * (lane + 64 * j) + q] + 1.f; }
;         for (int rr = 0; rr < 8; ++rr) {
;             const unsigned char* xr = (const unsigned char*)x + (size_t)(r0 + rr) * rowb; f32x4 v[4][2]; float s = 0.f;
; #pragma unroll
;             for (int j = 0; j < 4; ++j) ld_row8<XF32>(xr, lane, j, v[j][0], v[j][1]);
.LBB0_166:
	s_ashr_i32 s2, s1, 9
	s_mul_hi_i32 s3, s2, 0x12000
	s_mul_i32 s2, s2, 0x12000
	s_add_u32 s2, s24, s2
	s_addc_u32 s3, s26, s3
	s_add_u32 s64, s2, 0x2000
	s_addc_u32 s65, s3, 0
	s_add_i32 s4, s8, -7
	s_ashr_i32 s5, s4, 31
	v_lshl_add_u64 v[0:1], s[2:3], 0, v[100:101]
	v_lshl_add_u64 v[8:9], s[2:3], 0, v[102:103]
	v_lshl_add_u64 v[28:29], s[2:3], 0, v[104:105]
	v_lshl_add_u64 v[32:33], s[64:65], 0, v[100:101]
	v_lshl_add_u64 v[34:35], v[96:97], 4, s[64:65]
	v_lshl_add_u64 v[40:41], s[64:65], 0, v[102:103]
	v_lshl_add_u64 v[42:43], s[64:65], 0, v[104:105]
	s_lshl_b64 s[2:3], s[4:5], 13
	global_load_dwordx4 v[12:15], v[0:1], off offset:16
	global_load_dwordx4 v[20:23], v[0:1], off
	global_load_dwordx4 v[4:7], v[0:1], off offset:2064
	global_load_dwordx4 v[16:19], v[0:1], off offset:2048
	s_nop 0
	global_load_dwordx4 v[0:3], v[8:9], off offset:16
	s_nop 0
	global_load_dwordx4 v[8:11], v[8:9], off
	s_nop 0
	global_load_dwordx4 v[24:27], v[28:29], off offset:16
	s_nop 0
	global_load_dwordx4 v[28:31], v[28:29], off
	s_nop 0
	global_load_dwordx4 v[60:63], v[32:33], off
	global_load_dwordx4 v[56:59], v[32:33], off offset:16
	global_load_dwordx4 v[52:55], v[34:35], off
	global_load_dwordx4 v[44:47], v[34:35], off offset:16
	global_load_dwordx4 v[36:39], v[40:41], off offset:16
	global_load_dwordx4 v[48:51], v[40:41], off
	s_nop 0
	global_load_dwordx4 v[32:35], v[42:43], off offset:16
	s_nop 0
	global_load_dwordx4 v[40:43], v[42:43], off
	s_add_u32 s64, s36, s2
	s_addc_u32 s65, s37, s3
	v_lshl_add_u64 v[64:65], s[64:65], 0, v[100:101]
	v_lshl_add_u64 v[66:67], s[64:65], 0, v[102:103]
	v_lshl_add_u64 v[72:73], s[64:65], 0, v[104:105]
	global_load_dwordx4 v[92:95], v[64:65], off
	global_load_dwordx4 v[88:91], v[64:65], off offset:16
	global_load_dwordx4 v[84:87], v[64:65], off offset:2048
	global_load_dwordx4 v[80:83], v[64:65], off offset:2064
	global_load_dwordx4 v[76:79], v[66:67], off
	global_load_dwordx4 v[68:71], v[66:67], off offset:16
	s_nop 0
	global_load_dwordx4 v[64:67], v[72:73], off offset:16
	s_nop 0
	global_load_dwordx4 v[72:75], v[72:73], off
	v_mbcnt_lo_u32_b32 v108, -1, 0
	v_mbcnt_hi_u32_b32 v108, -1, v108
	v_mbcnt_lo_u32_b32 v109, -1, 0
	v_mbcnt_hi_u32_b32 v109, -1, v109
	v_mbcnt_lo_u32_b32 v110, -1, 0
	v_mbcnt_hi_u32_b32 v110, -1, v110
	v_mbcnt_lo_u32_b32 v111, -1, 0
	v_mbcnt_hi_u32_b32 v111, -1, v111
	s_lshl_b64 s[66:67], s[4:5], 12
	v_lshlrev_b32_e32 v108, 2, v108
	v_xor_b32_e32 v214, 4, v108
	v_lshlrev_b32_e32 v109, 2, v109
	v_xor_b32_e32 v213, 8, v109
	v_lshlrev_b32_e32 v110, 2, v110
	v_xor_b32_e32 v212, 16, v110
	v_lshlrev_b32_e32 v111, 2, v111
	s_add_i32 s4, s8, -6
	v_xor_b32_e32 v211, 32, v111
	s_ashr_i32 s5, s4, 31
	s_lshl_b64 s[2:3], s[4:5], 13
	v_lshl_add_u64 v[106:107], v[98:99], 0, s[66:67]
	s_add_u32 s66, s36, s2
	v_mbcnt_lo_u32_b32 v112, -1, 0
	v_mbcnt_hi_u32_b32 v112, -1, v112
	s_addc_u32 s67, s37, s3
	s_add_i32 s64, s8, -5
	v_lshlrev_b32_e32 v112, 2, v112
	s_lshl_b64 s[2:3], s[4:5], 12
	s_ashr_i32 s65, s64, 31
	v_xor_b32_e32 v210, 64, v112
	v_lshl_add_u64 v[108:109], v[98:99], 0, s[2:3]
	s_lshl_b64 s[2:3], s[64:65], 13
	s_add_u32 s4, s36, s2
	s_addc_u32 s5, s37, s3
	s_lshl_b64 s[2:3], s[64:65], 12
	s_add_i32 s64, s8, -4
	s_ashr_i32 s65, s64, 31
	v_mbcnt_lo_u32_b32 v113, -1, 0
	v_mbcnt_hi_u32_b32 v113, -1, v113
	v_lshl_add_u64 v[116:117], v[98:99], 0, s[2:3]
	s_lshl_b64 s[2:3], s[64:65], 13
	v_lshlrev_b32_e32 v113, 2, v113
	v_lshl_add_u64 v[122:123], s[4:5], 0, v[100:101]
	v_lshl_add_u64 v[118:119], s[4:5], 0, v[102:103]
	v_lshl_add_u64 v[120:121], s[4:5], 0, v[104:105]
	s_add_u32 s4, s36, s2
	v_xor_b32_e32 v168, 0x80, v113
	s_addc_u32 s5, s37, s3
	s_lshl_b64 s[2:3], s[64:65], 12
	s_add_i32 s64, s8, -3
	s_ashr_i32 s65, s64, 31
	v_lshl_add_u64 v[158:159], v[98:99], 0, s[2:3]
	s_lshl_b64 s[2:3], s[64:65], 13
	v_lshl_add_u64 v[164:165], s[4:5], 0, v[100:101]
	v_lshl_add_u64 v[160:161], s[4:5], 0, v[102:103]
	v_lshl_add_u64 v[162:163], s[4:5], 0, v[104:105]
	s_add_u32 s4, s36, s2
	s_addc_u32 s5, s37, s3
	s_lshl_b64 s[2:3], s[64:65], 12
	s_add_i32 s64, s8, -2
	s_ashr_i32 s65, s64, 31
	v_lshl_add_u64 v[166:167], v[98:99], 0, s[2:3]
	s_lshl_b64 s[2:3], s[64:65], 13
	v_lshl_add_u64 v[186:187], s[4:5], 0, v[100:101]
	v_lshl_add_u64 v[182:183], s[4:5], 0, v[102:103]
	v_lshl_add_u64 v[184:185], s[4:5], 0, v[104:105]
	s_add_u32 s4, s36, s2
	s_addc_u32 s5, s37, s3
	s_lshl_b64 s[2:3], s[64:65], 12
	s_add_i32 s64, s8, -1
	s_ashr_i32 s65, s64, 31
	v_lshl_add_u64 v[188:189], v[98:99], 0, s[2:3]
	s_waitcnt vmcnt(15)
	v_pk_add_f32 v[126:127], v[62:63], 1.0 op_sel_hi:[1,0]
	s_waitcnt vmcnt(14)
	v_pk_add_f32 v[132:133], v[56:57], 1.0 op_sel_hi:[1,0]
	s_waitcnt vmcnt(13)
	v_pk_add_f32 v[134:135], v[54:55], 1.0 op_sel_hi:[1,0]
	s_waitcnt vmcnt(12)
	v_pk_add_f32 v[138:139], v[46:47], 1.0 op_sel_hi:[1,0]
	v_pk_add_f32 v[140:141], v[44:45], 1.0 op_sel_hi:[1,0]
	s_waitcnt vmcnt(11)
	v_pk_add_f32 v[146:147], v[38:39], 1.0 op_sel_hi:[1,0]
	v_pk_add_f32 v[148:149], v[36:37], 1.0 op_sel_hi:[1,0]
	s_waitcnt vmcnt(8)
	v_pk_add_f32 v[150:151], v[42:43], 1.0 op_sel_hi:[1,0]
	v_pk_add_f32 v[152:153], v[40:41], 1.0 op_sel_hi:[1,0]
	v_pk_add_f32 v[154:155], v[34:35], 1.0 op_sel_hi:[1,0]
	v_pk_add_f32 v[156:157], v[32:33], 1.0 op_sel_hi:[1,0]
	s_waitcnt vmcnt(7)
	v_pk_mul_f32 v[32:33], v[94:95], v[94:95]
	v_pk_mul_f32 v[34:35], v[92:93], v[92:93]
	s_waitcnt vmcnt(6)
	v_pk_mul_f32 v[36:37], v[90:91], v[90:91]
	v_pk_mul_f32 v[38:39], v[88:89], v[88:89]
	s_waitcnt vmcnt(5)
	v_pk_mul_f32 v[40:41], v[86:87], v[86:87]
	v_pk_mul_f32 v[42:43], v[84:85], v[84:85]
	s_waitcnt vmcnt(4)
; __device__ __forceinline__ v4u pk8(f32x4 a, f32x4 b) { v4u w; w.x = pk2(a[0], a[1]); w.y = pk2(a[2], a[3]); w.z = pk2(b[0], b[1]); w.w = pk2(b[2], b[3]); return w; }
; __device__ __forceinline__ float ssq8(const f32x4& a, const f32x4& b) { return ((a[0] * a[0] + a[1] * a[1]) + (a[2] * a[2] + a[3] * a[3])) + ((b[0] * b[0] + b[1] * b[1]) + (b[2] * b[2] + b[3] * b[3])); }
; __device__ __forceinline__ float wave_sum(float v) {
; #pragma unroll
;     for (int o = 1; o < 64; o <<= 1) v += shfl_xor_f(v, o);
;     return v;
; template <int XF32> __device__ __forceinline__ void norm_mod_phase(const void* x, const float* modl, int ch_shift, int ch_scale, bf16* H, int gw, int NGW, int lane) {
;     ...
;             for (int j = 0; j < 4; ++j) s += ssq8(v[j][0], v[j][1]);
;             const float rstd = 1.f / sqrtf(wave_sum(s) * (1.f / DM) + EPS);
;             v4u* o = (v4u*)(H + (size_t)(r0 + rr) * DM);
; #pragma unroll
;             for (int j = 0; j < 4; ++j) o[lane + 64 * j] = pk8(v[j][0] * rstd * sc[j][0] + sh[j][0], v[j][1] * rstd * sc[j][1] + sh[j][1]);
	v_pk_mul_f32 v[44:45], v[82:83], v[82:83]
	v_pk_mul_f32 v[46:47], v[80:81], v[80:81]
	v_pk_mov_b32 v[56:57], v[34:35], v[32:33] op_sel:[1,0]
	v_mov_b32_e32 v35, v33
	v_pk_mov_b32 v[32:33], v[38:39], v[36:37] op_sel:[1,0]
	v_mov_b32_e32 v39, v37
	v_pk_mov_b32 v[36:37], v[42:43], v[40:41] op_sel:[1,0]
	v_mov_b32_e32 v43, v41
	v_pk_mov_b32 v[40:41], v[46:47], v[44:45] op_sel:[1,0]
	v_mov_b32_e32 v47, v45
	v_pk_add_f32 v[136:137], v[52:53], 1.0 op_sel_hi:[1,0]
	v_pk_add_f32 v[142:143], v[50:51], 1.0 op_sel_hi:[1,0]
	v_pk_add_f32 v[144:145], v[48:49], 1.0 op_sel_hi:[1,0]
	s_waitcnt vmcnt(1)
	v_mul_f32_e32 v55, v64, v64
	v_mul_f32_e32 v48, v77, v77
	v_mul_f32_e32 v50, v79, v79
	v_mul_f32_e32 v52, v69, v69
	v_mul_f32_e32 v54, v71, v71
	v_pk_add_f32 v[34:35], v[56:57], v[34:35]
	v_pk_add_f32 v[32:33], v[32:33], v[38:39]
	v_pk_add_f32 v[36:37], v[36:37], v[42:43]
	v_pk_add_f32 v[38:39], v[40:41], v[46:47]
	v_pk_add_f32 v[128:129], v[60:61], 1.0 op_sel_hi:[1,0]
	v_pk_add_f32 v[130:131], v[58:59], 1.0 op_sel_hi:[1,0]
	v_mul_f32_e32 v58, v65, v65
	v_mul_f32_e32 v59, v66, v66
	v_mul_f32_e32 v60, v67, v67
	s_waitcnt vmcnt(0)
	v_mul_f32_e32 v61, v72, v72
	v_mul_f32_e32 v62, v73, v73
	v_mul_f32_e32 v63, v74, v74
	v_mul_f32_e32 v170, v75, v75
	v_pk_fma_f32 v[44:45], v[76:77], v[76:77], v[48:49] op_sel_hi:[1,1,0]
	v_pk_fma_f32 v[48:49], v[78:79], v[78:79], v[50:51] op_sel_hi:[1,1,0]
	v_pk_fma_f32 v[50:51], v[68:69], v[68:69], v[52:53] op_sel_hi:[1,1,0]
	v_pk_fma_f32 v[52:53], v[70:71], v[70:71], v[54:55] op_sel_hi:[1,1,0]
	v_pk_add_f32 v[34:35], v[34:35], v[34:35] op_sel:[0,1] op_sel_hi:[1,0]
	v_pk_add_f32 v[32:33], v[32:33], v[32:33] op_sel:[0,1] op_sel_hi:[1,0]
	v_pk_add_f32 v[36:37], v[36:37], v[36:37] op_sel:[0,1] op_sel_hi:[1,0]
	v_pk_add_f32 v[38:39], v[38:39], v[38:39] op_sel:[0,1] op_sel_hi:[1,0]
	v_mov_b32_e32 v45, v55
	v_mov_b32_e32 v49, v58
	v_mov_b32_e32 v51, v59
	v_mov_b32_e32 v53, v60
	v_mov_b32_e32 v35, v61
	v_mov_b32_e32 v33, v62
	v_mov_b32_e32 v37, v63
	v_mov_b32_e32 v39, v170
	v_pk_add_f32 v[40:41], v[44:45], v[48:49]
	v_pk_add_f32 v[42:43], v[50:51], v[52:53]
	v_pk_add_f32 v[32:33], v[34:35], v[32:33]
	v_pk_add_f32 v[34:35], v[36:37], v[38:39]
	v_pk_add_f32 v[40:41], v[40:41], v[42:43]
	v_pk_add_f32 v[32:33], v[32:33], v[34:35]
	s_lshl_b64 s[2:3], s[64:65], 13
	v_pk_add_f32 v[32:33], v[32:33], v[40:41]
	v_lshl_add_u64 v[194:195], s[4:5], 0, v[100:101]
	v_add_f32_e32 v32, v32, v33
	ds_bpermute_b32 v33, v214, v32
	v_lshl_add_u64 v[190:191], s[4:5], 0, v[102:103]
	v_lshl_add_u64 v[192:193], s[4:5], 0, v[104:105]
	s_add_u32 s4, s36, s2
	s_addc_u32 s5, s37, s3
	s_waitcnt lgkmcnt(0)
	v_add_f32_e32 v32, v32, v33
	ds_bpermute_b32 v33, v213, v32
	s_lshl_b64 s[2:3], s[64:65], 12
	s_ashr_i32 s9, s8, 31
	v_lshl_add_u64 v[196:197], v[98:99], 0, s[2:3]
	s_lshl_b64 s[2:3], s[8:9], 13
	s_waitcnt lgkmcnt(0)
	v_add_f32_e32 v32, v32, v33
	ds_bpermute_b32 v33, v212, v32
	v_lshl_add_u64 v[202:203], s[4:5], 0, v[100:101]
	v_lshl_add_u64 v[198:199], s[4:5], 0, v[102:103]
	v_lshl_add_u64 v[200:201], s[4:5], 0, v[104:105]
	s_add_u32 s4, s36, s2
	s_waitcnt lgkmcnt(0)
	v_add_f32_e32 v32, v32, v33
	ds_bpermute_b32 v33, v211, v32
	s_addc_u32 s5, s37, s3
	v_lshl_add_u64 v[208:209], s[4:5], 0, v[100:101]
	v_lshl_add_u64 v[204:205], s[4:5], 0, v[102:103]
	v_lshl_add_u64 v[206:207], s[4:5], 0, v[104:105]
	s_waitcnt lgkmcnt(0)
	v_add_f32_e32 v32, v32, v33
	ds_bpermute_b32 v33, v210, v32
	s_lshl_b64 s[2:3], s[8:9], 12
	v_lshl_add_u64 v[124:125], v[98:99], 0, s[2:3]
	v_lshl_add_u64 v[114:115], s[66:67], 0, v[100:101]
	v_lshl_add_u64 v[110:111], s[66:67], 0, v[102:103]
	s_waitcnt lgkmcnt(0)
	v_add_f32_e32 v32, v32, v33
	ds_bpermute_b32 v33, v168, v32
	v_lshl_add_u64 v[112:113], s[66:67], 0, v[104:105]
	s_add_i32 s1, s1, s58
	s_add_i32 s8, s8, s0
	s_cmpk_gt_i32 s1, 0x7ff
	s_waitcnt lgkmcnt(0)
	v_add_f32_e32 v32, v32, v33
	v_fmamk_f32 v32, v32, 0x3a000000, v224
	v_mul_f32_e32 v33, 0x4f800000, v32
	v_cmp_gt_f32_e32 vcc, s41, v32
	s_nop 1
	v_cndmask_b32_e32 v32, v32, v33, vcc
	v_sqrt_f32_e32 v33, v32
	s_nop 0
	v_add_u32_e32 v34, -1, v33
	v_add_u32_e32 v35, 1, v33
	v_fma_f32 v36, -v34, v33, v32
	v_fma_f32 v37, -v35, v33, v32
	v_cmp_ge_f32_e64 s[4:5], 0, v36
	s_nop 1
	v_cndmask_b32_e64 v33, v33, v34, s[4:5]
	v_cmp_lt_f32_e64 s[4:5], 0, v37
	s_nop 1
	v_cndmask_b32_e64 v33, v33, v35, s[4:5]
	v_mul_f32_e32 v34, 0x37800000, v33
	v_cndmask_b32_e32 v33, v33, v34, vcc
	v_cmp_class_f32_e32 vcc, v32, v225
	s_nop 1
	v_cndmask_b32_e32 v32, v33, v32, vcc
	v_div_scale_f32 v33, s[2:3], v32, v32, 1.0
	v_rcp_f32_e32 v35, v33
	v_div_scale_f32 v34, vcc, 1.0, v32, 1.0
	v_fma_f32 v36, -v33, v35, 1.0
	v_fmac_f32_e32 v35, v36, v35
	v_mul_f32_e32 v36, v34, v35
	v_fma_f32 v37, -v33, v36, v34
	v_fmac_f32_e32 v36, v37, v35
	v_fma_f32 v33, -v33, v36, v34
	v_div_fmas_f32 v33, v33, v35, v36
	v_div_fixup_f32 v32, v33, v32, 1.0
	v_pk_mul_f32 v[34:35], v[92:93], v[32:33] op_sel_hi:[1,0]
	v_pk_mul_f32 v[36:37], v[94:95], v[32:33] op_sel_hi:[1,0]
	v_pk_mul_f32 v[38:39], v[88:89], v[32:33] op_sel_hi:[1,0]
	v_pk_mul_f32 v[40:41], v[90:91], v[32:33] op_sel_hi:[1,0]
	v_pk_mul_f32 v[42:43], v[84:85], v[32:33] op_sel_hi:[1,0]
	v_pk_mul_f32 v[44:45], v[86:87], v[32:33] op_sel_hi:[1,0]
	v_pk_mul_f32 v[46:47], v[80:81], v[32:33] op_sel_hi:[1,0]
	v_pk_mul_f32 v[48:49], v[82:83], v[32:33] op_sel_hi:[1,0]
	v_pk_mul_f32 v[50:51], v[76:77], v[32:33] op_sel_hi:[1,0]
	v_pk_mul_f32 v[52:53], v[78:79], v[32:33] op_sel_hi:[1,0]
	v_pk_mul_f32 v[54:55], v[68:69], v[32:33] op_sel_hi:[1,0]
	v_pk_mul_f32 v[56:57], v[70:71], v[32:33] op_sel_hi:[1,0]
	v_pk_mul_f32 v[58:59], v[72:73], v[32:33] op_sel_hi:[1,0]
; __device__ __forceinline__ v4u pk8(f32x4 a, f32x4 b) { v4u w; w.x = pk2(a[0], a[1]); w.y = pk2(a[2], a[3]); w.z = pk2(b[0], b[1]); w.w = pk2(b[2], b[3]); return w; }
; __device__ __forceinline__ float ssq8(const f32x4& a, const f32x4& b) { return ((a[0] * a[0] + a[1] * a[1]) + (a[2] * a[2] + a[3] * a[3])) + ((b[0] * b[0] + b[1] * b[1]) + (b[2] * b[2] + b[3] * b[3])); }
; __device__ __forceinline__ float wave_sum(float v) {
; #pragma unroll
;     for (int o = 1; o < 64; o <<= 1) v += shfl_xor_f(v, o);
; template <int XF32> __device__ __forceinline__ void norm_mod_phase(const void* x, const float* modl, int ch_shift, int ch_scale, bf16* H, int gw, int NGW, int lane) {
;     ...
;             const unsigned char* xr = (const unsigned char*)x + (size_t)(r0 + rr) * rowb; f32x4 v[4][2]; float s = 0.f;
; #pragma unroll
;             for (int j = 0; j < 4; ++j) ld_row8<XF32>(xr, lane, j, v[j][0], v[j][1]);
; #pragma unroll
;             for (int j = 0; j < 4; ++j) s += ssq8(v[j][0], v[j][1]);
;             const float rstd = 1.f / sqrtf(wave_sum(s) * (1.f / DM) + EPS);
;             v4u* o = (v4u*)(H + (size_t)(r0 + rr) * DM);
; #pragma unroll
;             for (int j = 0; j < 4; ++j) o[lane + 64 * j] = pk8(v[j][0] * rstd * sc[j][0] + sh[j][0], v[j][1] * rstd * sc[j][1] + sh[j][1]);
	v_pk_mul_f32 v[60:61], v[74:75], v[32:33] op_sel_hi:[1,0]
	v_pk_mul_f32 v[62:63], v[64:65], v[32:33] op_sel_hi:[1,0]
	v_pk_mul_f32 v[32:33], v[66:67], v[32:33] op_sel_hi:[1,0]
	v_pk_fma_f32 v[36:37], v[126:127], v[36:37], v[22:23]
	v_pk_fma_f32 v[34:35], v[128:129], v[34:35], v[20:21]
	v_pk_fma_f32 v[40:41], v[130:131], v[40:41], v[14:15]
	v_pk_fma_f32 v[38:39], v[132:133], v[38:39], v[12:13]
	v_pk_fma_f32 v[44:45], v[134:135], v[44:45], v[18:19]
	v_pk_fma_f32 v[42:43], v[136:137], v[42:43], v[16:17]
	v_pk_fma_f32 v[48:49], v[138:139], v[48:49], v[6:7]
	v_pk_fma_f32 v[46:47], v[140:141], v[46:47], v[4:5]
	v_pk_fma_f32 v[52:53], v[142:143], v[52:53], v[10:11]
	v_pk_fma_f32 v[50:51], v[144:145], v[50:51], v[8:9]
	v_pk_fma_f32 v[56:57], v[146:147], v[56:57], v[2:3]
	v_pk_fma_f32 v[54:55], v[148:149], v[54:55], v[0:1]
	v_pk_fma_f32 v[60:61], v[150:151], v[60:61], v[30:31]
	v_pk_fma_f32 v[58:59], v[152:153], v[58:59], v[28:29]
	v_pk_fma_f32 v[64:65], v[154:155], v[32:33], v[26:27]
	v_pk_fma_f32 v[62:63], v[156:157], v[62:63], v[24:25]
	v_cvt_pk_bf16_f32 v32, v34, v35
	v_cvt_pk_bf16_f32 v33, v36, v37
	v_cvt_pk_bf16_f32 v34, v38, v39
	v_cvt_pk_bf16_f32 v35, v40, v41
	v_cvt_pk_bf16_f32 v36, v42, v43
	v_cvt_pk_bf16_f32 v37, v44, v45
	v_cvt_pk_bf16_f32 v38, v46, v47
	v_cvt_pk_bf16_f32 v39, v48, v49
	v_cvt_pk_bf16_f32 v40, v50, v51
	v_cvt_pk_bf16_f32 v41, v52, v53
	v_cvt_pk_bf16_f32 v42, v54, v55
	v_cvt_pk_bf16_f32 v43, v56, v57
	v_cvt_pk_bf16_f32 v44, v58, v59
	v_cvt_pk_bf16_f32 v45, v60, v61
	v_cvt_pk_bf16_f32 v46, v62, v63
	v_cvt_pk_bf16_f32 v47, v64, v65
	global_store_dwordx4 v[106:107], v[32:35], off
	global_store_dwordx4 v[106:107], v[36:39], off offset:1024
	global_store_dwordx4 v[106:107], v[40:43], off offset:2048
	global_store_dwordx4 v[106:107], v[44:47], off offset:3072
	global_load_dwordx4 v[32:35], v[114:115], off
	s_nop 0
	global_load_dwordx4 v[36:39], v[114:115], off offset:16
	global_load_dwordx4 v[40:43], v[114:115], off offset:2048
	global_load_dwordx4 v[44:47], v[114:115], off offset:2064
	global_load_dwordx4 v[48:51], v[112:113], off offset:16
	global_load_dwordx4 v[52:55], v[110:111], off
	global_load_dwordx4 v[56:59], v[110:111], off offset:16
	global_load_dwordx4 v[60:63], v[112:113], off
	v_mbcnt_lo_u32_b32 v64, -1, 0
	v_mbcnt_hi_u32_b32 v64, -1, v64
	v_mbcnt_lo_u32_b32 v65, -1, 0
	v_mbcnt_hi_u32_b32 v65, -1, v65
	v_mbcnt_lo_u32_b32 v66, -1, 0
	v_mbcnt_hi_u32_b32 v66, -1, v66
	v_mbcnt_lo_u32_b32 v67, -1, 0
	v_mbcnt_hi_u32_b32 v67, -1, v67
	v_mbcnt_lo_u32_b32 v68, -1, 0
	v_mbcnt_hi_u32_b32 v68, -1, v68
	v_mbcnt_lo_u32_b32 v69, -1, 0
	v_mbcnt_hi_u32_b32 v69, -1, v69
	s_nop 0
	v_lshlrev_b32_e32 v64, 2, v64
	v_lshlrev_b32_e32 v65, 2, v65
	v_lshlrev_b32_e32 v66, 2, v66
	v_lshlrev_b32_e32 v67, 2, v67
	v_lshlrev_b32_e32 v68, 2, v68
	v_lshlrev_b32_e32 v69, 2, v69
	v_xor_b32_e32 v87, 4, v64
	v_xor_b32_e32 v90, 8, v65
	v_xor_b32_e32 v91, 16, v66
	v_xor_b32_e32 v92, 32, v67
	v_xor_b32_e32 v93, 64, v68
	v_xor_b32_e32 v94, 0x80, v69
	s_waitcnt vmcnt(7)
	v_pk_mul_f32 v[64:65], v[34:35], v[34:35]
	v_pk_mul_f32 v[66:67], v[32:33], v[32:33]
	s_waitcnt vmcnt(6)
	v_pk_mul_f32 v[68:69], v[38:39], v[38:39]
	v_pk_mul_f32 v[70:71], v[36:37], v[36:37]
	s_waitcnt vmcnt(5)
	v_pk_mul_f32 v[72:73], v[42:43], v[42:43]
	v_pk_mul_f32 v[74:75], v[40:41], v[40:41]
	s_waitcnt vmcnt(4)
	v_pk_mul_f32 v[76:77], v[46:47], v[46:47]
	v_pk_mul_f32 v[78:79], v[44:45], v[44:45]
	v_pk_mov_b32 v[88:89], v[66:67], v[64:65] op_sel:[1,0]
	v_mov_b32_e32 v67, v65
	v_pk_mov_b32 v[64:65], v[70:71], v[68:69] op_sel:[1,0]
	v_mov_b32_e32 v71, v69
	v_pk_mov_b32 v[68:69], v[74:75], v[72:73] op_sel:[1,0]
	v_mov_b32_e32 v75, v73
	v_pk_mov_b32 v[72:73], v[78:79], v[76:77] op_sel:[1,0]
	v_mov_b32_e32 v79, v77
	s_waitcnt vmcnt(2)
	v_mul_f32_e32 v80, v53, v53
	v_mul_f32_e32 v82, v55, v55
	s_waitcnt vmcnt(1)
	v_mul_f32_e32 v84, v57, v57
	v_mul_f32_e32 v86, v59, v59
	v_pk_add_f32 v[66:67], v[88:89], v[66:67]
	v_pk_add_f32 v[64:65], v[64:65], v[70:71]
	v_pk_add_f32 v[68:69], v[68:69], v[74:75]
	v_pk_add_f32 v[70:71], v[72:73], v[78:79]
	v_mul_f32_e32 v95, v48, v48
	v_mul_f32_e32 v106, v49, v49
	v_mul_f32_e32 v107, v50, v50
	v_mul_f32_e32 v110, v51, v51
	s_waitcnt vmcnt(0)
	v_mul_f32_e32 v111, v60, v60
	v_mul_f32_e32 v112, v61, v61
	v_mul_f32_e32 v113, v62, v62
	v_mul_f32_e32 v114, v63, v63
	v_pk_fma_f32 v[76:77], v[52:53], v[52:53], v[80:81] op_sel_hi:[1,1,0]
	v_pk_fma_f32 v[80:81], v[54:55], v[54:55], v[82:83] op_sel_hi:[1,1,0]
	v_pk_fma_f32 v[82:83], v[56:57], v[56:57], v[84:85] op_sel_hi:[1,1,0]
	v_pk_fma_f32 v[84:85], v[58:59], v[58:59], v[86:87] op_sel_hi:[1,1,0]
	v_pk_add_f32 v[66:67], v[66:67], v[66:67] op_sel:[0,1] op_sel_hi:[1,0]
	v_pk_add_f32 v[64:65], v[64:65], v[64:65] op_sel:[0,1] op_sel_hi:[1,0]
	v_pk_add_f32 v[68:69], v[68:69], v[68:69] op_sel:[0,1] op_sel_hi:[1,0]
	v_pk_add_f32 v[70:71], v[70:71], v[70:71] op_sel:[0,1] op_sel_hi:[1,0]
	v_mov_b32_e32 v77, v95
	v_mov_b32_e32 v81, v106
	v_mov_b32_e32 v83, v107
	v_mov_b32_e32 v85, v110
	v_mov_b32_e32 v67, v111
	v_mov_b32_e32 v65, v112
	v_mov_b32_e32 v69, v113
	v_mov_b32_e32 v71, v114
	v_pk_add_f32 v[72:73], v[76:77], v[80:81]
	v_pk_add_f32 v[74:75], v[82:83], v[84:85]
	v_pk_add_f32 v[64:65], v[66:67], v[64:65]
	v_pk_add_f32 v[66:67], v[68:69], v[70:71]
	v_pk_add_f32 v[72:73], v[72:73], v[74:75]
	v_pk_add_f32 v[64:65], v[64:65], v[66:67]
	s_nop 0
	v_pk_add_f32 v[64:65], v[64:65], v[72:73]
	s_nop 0
	v_add_f32_e32 v64, v64, v65
	s_nop 1
	v_add_f32_dpp v64, v64, v64 quad_perm:[1,0,3,2] row_mask:0xf bank_mask:0xf
	s_nop 1
	v_add_f32_dpp v64, v64, v64 quad_perm:[2,3,0,1] row_mask:0xf bank_mask:0xf
	s_nop 1
; __device__ __forceinline__ v4u pk8(f32x4 a, f32x4 b) { v4u w; w.x = pk2(a[0], a[1]); w.y = pk2(a[2], a[3]); w.z = pk2(b[0], b[1]); w.w = pk2(b[2], b[3]); return w; }
; __device__ __forceinline__ float ssq8(const f32x4& a, const f32x4& b) { return ((a[0] * a[0] + a[1] * a[1]) + (a[2] * a[2] + a[3] * a[3])) + ((b[0] * b[0] + b[1] * b[1]) + (b[2] * b[2] + b[3] * b[3])); }
; __device__ __forceinline__ float shfl_xor_f(float v, int o) {
;     int l; asm volatile("v_mbcnt_lo_u32_b32 %0, -1, 0\n\tv_mbcnt_hi_u32_b32 %0, -1, %0" : "=v"(l));
;     return __builtin_bit_cast(float, __builtin_amdgcn_ds_bpermute((l ^ o) << 2, __builtin_bit_cast(int, v)));
; }
; __device__ __forceinline__ float wave_sum(float v) {
; #pragma unroll
;     for (int o = 1; o < 64; o <<= 1) v += shfl_xor_f(v, o);
;     return v;
; template <int XF32> __device__ __forceinline__ void norm_mod_phase(const void* x, const float* modl, int ch_shift, int ch_scale, bf16* H, int gw, int NGW, int lane) {
;     ...
;         for (int rr = 0; rr < 8; ++rr) {
;             const unsigned char* xr = (const unsigned char*)x + (size_t)(r0 + rr) * rowb; f32x4 v[4][2]; float s = 0.f;
; #pragma unroll
;             for (int j = 0; j < 4; ++j) ld_row8<XF32>(xr, lane, j, v[j][0], v[j][1]);
; #pragma unroll
;             for (int j = 0; j < 4; ++j) s += ssq8(v[j][0], v[j][1]);
;             const float rstd = 1.f / sqrtf(wave_sum(s) * (1.f / DM) + EPS);
;             v4u* o = (v4u*)(H + (size_t)(r0 + rr) * DM);
; #pragma unroll
;             for (int j = 0; j < 4; ++j) o[lane + 64 * j] = pk8(v[j][0] * rstd * sc[j][0] + sh[j][0], v[j][1] * rstd * sc[j][1] + sh[j][1]);
;         }
	v_add_f32_dpp v64, v64, v64 row_half_mirror row_mask:0xf bank_mask:0xf
	s_nop 1
	v_add_f32_dpp v64, v64, v64 row_mirror row_mask:0xf bank_mask:0xf
	v_mov_b32_e32 v65, v64
	s_nop 1
	v_permlane16_swap_b32_e32 v65, v64
	s_nop 1
	v_add_f32_e32 v64, v64, v65
	v_mov_b32_e32 v65, v64
	s_nop 1
	v_permlane32_swap_b32_e32 v65, v64
	s_nop 1
	v_add_f32_e32 v64, v64, v65
	v_fmamk_f32 v64, v64, 0x3a000000, v224
	v_mul_f32_e32 v65, 0x4f800000, v64
	v_cmp_gt_f32_e32 vcc, s41, v64
	s_nop 1
	v_cndmask_b32_e32 v64, v64, v65, vcc
	v_sqrt_f32_e32 v65, v64
	s_nop 0
	v_add_u32_e32 v66, -1, v65
	v_add_u32_e32 v67, 1, v65
	v_fma_f32 v68, -v66, v65, v64
	v_fma_f32 v69, -v67, v65, v64
	v_cmp_ge_f32_e64 s[4:5], 0, v68
	s_nop 1
	v_cndmask_b32_e64 v65, v65, v66, s[4:5]
	v_cmp_lt_f32_e64 s[4:5], 0, v69
	s_nop 1
	v_cndmask_b32_e64 v65, v65, v67, s[4:5]
	v_mul_f32_e32 v66, 0x37800000, v65
	v_cndmask_b32_e32 v65, v65, v66, vcc
	v_cmp_class_f32_e32 vcc, v64, v225
	s_nop 1
	v_cndmask_b32_e32 v64, v65, v64, vcc
	v_div_scale_f32 v65, s[2:3], v64, v64, 1.0
	v_rcp_f32_e32 v67, v65
	v_div_scale_f32 v66, vcc, 1.0, v64, 1.0
	v_fma_f32 v68, -v65, v67, 1.0
	v_fmac_f32_e32 v67, v68, v67
	v_mul_f32_e32 v68, v66, v67
	v_fma_f32 v69, -v65, v68, v66
	v_fmac_f32_e32 v68, v69, v67
	v_fma_f32 v65, -v65, v68, v66
	v_div_fmas_f32 v65, v65, v67, v68
	v_div_fixup_f32 v64, v65, v64, 1.0
	v_pk_mul_f32 v[32:33], v[32:33], v[64:65] op_sel_hi:[1,0]
	v_pk_mul_f32 v[34:35], v[34:35], v[64:65] op_sel_hi:[1,0]
	v_pk_mul_f32 v[36:37], v[36:37], v[64:65] op_sel_hi:[1,0]
	v_pk_mul_f32 v[38:39], v[38:39], v[64:65] op_sel_hi:[1,0]
	v_pk_mul_f32 v[40:41], v[40:41], v[64:65] op_sel_hi:[1,0]
	v_pk_mul_f32 v[42:43], v[42:43], v[64:65] op_sel_hi:[1,0]
	v_pk_mul_f32 v[44:45], v[44:45], v[64:65] op_sel_hi:[1,0]
	v_pk_mul_f32 v[46:47], v[46:47], v[64:65] op_sel_hi:[1,0]
	v_pk_mul_f32 v[52:53], v[52:53], v[64:65] op_sel_hi:[1,0]
	v_pk_mul_f32 v[54:55], v[54:55], v[64:65] op_sel_hi:[1,0]
	v_pk_mul_f32 v[56:57], v[56:57], v[64:65] op_sel_hi:[1,0]
	v_pk_mul_f32 v[58:59], v[58:59], v[64:65] op_sel_hi:[1,0]
	v_pk_mul_f32 v[60:61], v[60:61], v[64:65] op_sel_hi:[1,0]
	v_pk_mul_f32 v[62:63], v[62:63], v[64:65] op_sel_hi:[1,0]
	v_pk_mul_f32 v[48:49], v[48:49], v[64:65] op_sel_hi:[1,0]
	v_pk_mul_f32 v[50:51], v[50:51], v[64:65] op_sel_hi:[1,0]
	v_pk_fma_f32 v[34:35], v[126:127], v[34:35], v[22:23]
	v_pk_fma_f32 v[32:33], v[128:129], v[32:33], v[20:21]
	v_pk_fma_f32 v[38:39], v[130:131], v[38:39], v[14:15]
	v_pk_fma_f32 v[36:37], v[132:133], v[36:37], v[12:13]
	v_pk_fma_f32 v[42:43], v[134:135], v[42:43], v[18:19]
	v_pk_fma_f32 v[40:41], v[136:137], v[40:41], v[16:17]
	v_pk_fma_f32 v[46:47], v[138:139], v[46:47], v[6:7]
	v_pk_fma_f32 v[44:45], v[140:141], v[44:45], v[4:5]
	v_pk_fma_f32 v[54:55], v[142:143], v[54:55], v[10:11]
	v_pk_fma_f32 v[52:53], v[144:145], v[52:53], v[8:9]
	v_pk_fma_f32 v[58:59], v[146:147], v[58:59], v[2:3]
	v_pk_fma_f32 v[56:57], v[148:149], v[56:57], v[0:1]
	v_pk_fma_f32 v[62:63], v[150:151], v[62:63], v[30:31]
	v_pk_fma_f32 v[60:61], v[152:153], v[60:61], v[28:29]
	v_pk_fma_f32 v[50:51], v[154:155], v[50:51], v[26:27]
	v_pk_fma_f32 v[48:49], v[156:157], v[48:49], v[24:25]
	v_cvt_pk_bf16_f32 v32, v32, v33
	v_cvt_pk_bf16_f32 v33, v34, v35
	v_cvt_pk_bf16_f32 v34, v36, v37
	v_cvt_pk_bf16_f32 v35, v38, v39
	v_cvt_pk_bf16_f32 v36, v40, v41
	v_cvt_pk_bf16_f32 v37, v42, v43
	v_cvt_pk_bf16_f32 v38, v44, v45
	v_cvt_pk_bf16_f32 v39, v46, v47
	v_cvt_pk_bf16_f32 v40, v52, v53
	v_cvt_pk_bf16_f32 v41, v54, v55
	v_cvt_pk_bf16_f32 v42, v56, v57
	v_cvt_pk_bf16_f32 v43, v58, v59
	v_cvt_pk_bf16_f32 v44, v60, v61
	v_cvt_pk_bf16_f32 v45, v62, v63
	v_cvt_pk_bf16_f32 v46, v48, v49
	v_cvt_pk_bf16_f32 v47, v50, v51
	global_store_dwordx4 v[108:109], v[32:35], off
	global_store_dwordx4 v[108:109], v[36:39], off offset:1024
	global_store_dwordx4 v[108:109], v[40:43], off offset:2048
	global_store_dwordx4 v[108:109], v[44:47], off offset:3072
	global_load_dwordx4 v[32:35], v[122:123], off
	s_nop 0
	global_load_dwordx4 v[36:39], v[122:123], off offset:16
	global_load_dwordx4 v[40:43], v[122:123], off offset:2048
	global_load_dwordx4 v[44:47], v[122:123], off offset:2064
	global_load_dwordx4 v[48:51], v[120:121], off offset:16
	global_load_dwordx4 v[52:55], v[118:119], off
	global_load_dwordx4 v[56:59], v[118:119], off offset:16
	global_load_dwordx4 v[60:63], v[120:121], off
	v_mbcnt_lo_u32_b32 v64, -1, 0
	v_mbcnt_hi_u32_b32 v64, -1, v64
	v_mbcnt_lo_u32_b32 v65, -1, 0
	v_mbcnt_hi_u32_b32 v65, -1, v65
	v_mbcnt_lo_u32_b32 v66, -1, 0
	v_mbcnt_hi_u32_b32 v66, -1, v66
	v_mbcnt_lo_u32_b32 v67, -1, 0
	v_mbcnt_hi_u32_b32 v67, -1, v67
	v_mbcnt_lo_u32_b32 v68, -1, 0
	v_mbcnt_hi_u32_b32 v68, -1, v68
	v_mbcnt_lo_u32_b32 v69, -1, 0
	v_mbcnt_hi_u32_b32 v69, -1, v69
	s_nop 0
	v_lshlrev_b32_e32 v64, 2, v64
	v_lshlrev_b32_e32 v65, 2, v65
	v_lshlrev_b32_e32 v66, 2, v66
	v_lshlrev_b32_e32 v67, 2, v67
	v_lshlrev_b32_e32 v68, 2, v68
	v_lshlrev_b32_e32 v69, 2, v69
	v_xor_b32_e32 v87, 4, v64
	v_xor_b32_e32 v90, 8, v65
	v_xor_b32_e32 v91, 16, v66
	v_xor_b32_e32 v92, 32, v67
	v_xor_b32_e32 v93, 64, v68
	v_xor_b32_e32 v94, 0x80, v69
	s_waitcnt vmcnt(7)
	v_pk_mul_f32 v[64:65], v[34:35], v[34:35]
	v_pk_mul_f32 v[66:67], v[32:33], v[32:33]
	s_waitcnt vmcnt(6)
	v_pk_mul_f32 v[68:69], v[38:39], v[38:39]
	v_pk_mul_f32 v[70:71], v[36:37], v[36:37]
	s_waitcnt vmcnt(5)
	v_pk_mul_f32 v[72:73], v[42:43], v[42:43]
	v_pk_mul_f32 v[74:75], v[40:41], v[40:41]
	s_waitcnt vmcnt(4)
; __device__ __forceinline__ v4u pk8(f32x4 a, f32x4 b) { v4u w; w.x = pk2(a[0], a[1]); w.y = pk2(a[2], a[3]); w.z = pk2(b[0], b[1]); w.w = pk2(b[2], b[3]); return w; }
; __device__ __forceinline__ float ssq8(const f32x4& a, const f32x4& b) { return ((a[0] * a[0] + a[1] * a[1]) + (a[2] * a[2] + a[3] * a[3])) + ((b[0] * b[0] + b[1] * b[1]) + (b[2] * b[2] + b[3] * b[3])); }
; __device__ __forceinline__ float shfl_xor_f(float v, int o) {
;     int l; asm volatile("v_mbcnt_lo_u32_b32 %0, -1, 0\n\tv_mbcnt_hi_u32_b32 %0, -1, %0" : "=v"(l));
;     return __builtin_bit_cast(float, __builtin_amdgcn_ds_bpermute((l ^ o) << 2, __builtin_bit_cast(int, v)));
; }
; __device__ __forceinline__ float wave_sum(float v) {
; #pragma unroll
;     for (int o = 1; o < 64; o <<= 1) v += shfl_xor_f(v, o);
;     return v;
; template <int XF32> __device__ __forceinline__ void norm_mod_phase(const void* x, const float* modl, int ch_shift, int ch_scale, bf16* H, int gw, int NGW, int lane) {
;     ...
;         for (int rr = 0; rr < 8; ++rr) {
;             const unsigned char* xr = (const unsigned char*)x + (size_t)(r0 + rr) * rowb; f32x4 v[4][2]; float s = 0.f;
; #pragma unroll
;             for (int j = 0; j < 4; ++j) ld_row8<XF32>(xr, lane, j, v[j][0], v[j][1]);
; #pragma unroll
;             for (int j = 0; j < 4; ++j) s += ssq8(v[j][0], v[j][1]);
;             const float rstd = 1.f / sqrtf(wave_sum(s) * (1.f / DM) + EPS);
;             v4u* o = (v4u*)(H + (size_t)(r0 + rr) * DM);
; #pragma unroll
;             for (int j = 0; j < 4; ++j) o[lane + 64 * j] = pk8(v[j][0] * rstd * sc[j][0] + sh[j][0], v[j][1] * rstd * sc[j][1] + sh[j][1]);
;         }
	v_pk_mul_f32 v[76:77], v[46:47], v[46:47]
	v_pk_mul_f32 v[78:79], v[44:45], v[44:45]
	v_pk_mov_b32 v[88:89], v[66:67], v[64:65] op_sel:[1,0]
	v_mov_b32_e32 v67, v65
	v_pk_mov_b32 v[64:65], v[70:71], v[68:69] op_sel:[1,0]
	v_mov_b32_e32 v71, v69
	v_pk_mov_b32 v[68:69], v[74:75], v[72:73] op_sel:[1,0]
	v_mov_b32_e32 v75, v73
	v_pk_mov_b32 v[72:73], v[78:79], v[76:77] op_sel:[1,0]
	v_mov_b32_e32 v79, v77
	s_waitcnt vmcnt(2)
	v_mul_f32_e32 v80, v53, v53
	v_mul_f32_e32 v82, v55, v55
	s_waitcnt vmcnt(1)
	v_mul_f32_e32 v84, v57, v57
	v_mul_f32_e32 v86, v59, v59
	v_pk_add_f32 v[66:67], v[88:89], v[66:67]
	v_pk_add_f32 v[64:65], v[64:65], v[70:71]
	v_pk_add_f32 v[68:69], v[68:69], v[74:75]
	v_pk_add_f32 v[70:71], v[72:73], v[78:79]
	v_mul_f32_e32 v95, v48, v48
	v_mul_f32_e32 v106, v49, v49
	v_mul_f32_e32 v107, v50, v50
	v_mul_f32_e32 v108, v51, v51
	s_waitcnt vmcnt(0)
	v_mul_f32_e32 v109, v60, v60
	v_mul_f32_e32 v110, v61, v61
	v_mul_f32_e32 v111, v62, v62
	v_mul_f32_e32 v112, v63, v63
	v_pk_fma_f32 v[76:77], v[52:53], v[52:53], v[80:81] op_sel_hi:[1,1,0]
	v_pk_fma_f32 v[80:81], v[54:55], v[54:55], v[82:83] op_sel_hi:[1,1,0]
	v_pk_fma_f32 v[82:83], v[56:57], v[56:57], v[84:85] op_sel_hi:[1,1,0]
	v_pk_fma_f32 v[84:85], v[58:59], v[58:59], v[86:87] op_sel_hi:[1,1,0]
	v_pk_add_f32 v[66:67], v[66:67], v[66:67] op_sel:[0,1] op_sel_hi:[1,0]
	v_pk_add_f32 v[64:65], v[64:65], v[64:65] op_sel:[0,1] op_sel_hi:[1,0]
	v_pk_add_f32 v[68:69], v[68:69], v[68:69] op_sel:[0,1] op_sel_hi:[1,0]
	v_pk_add_f32 v[70:71], v[70:71], v[70:71] op_sel:[0,1] op_sel_hi:[1,0]
	v_mov_b32_e32 v77, v95
	v_mov_b32_e32 v81, v106
	v_mov_b32_e32 v83, v107
	v_mov_b32_e32 v85, v108
	v_mov_b32_e32 v67, v109
	v_mov_b32_e32 v65, v110
	v_mov_b32_e32 v69, v111
	v_mov_b32_e32 v71, v112
	v_pk_add_f32 v[72:73], v[76:77], v[80:81]
	v_pk_add_f32 v[74:75], v[82:83], v[84:85]
	v_pk_add_f32 v[64:65], v[66:67], v[64:65]
	v_pk_add_f32 v[66:67], v[68:69], v[70:71]
	v_pk_add_f32 v[72:73], v[72:73], v[74:75]
	v_pk_add_f32 v[64:65], v[64:65], v[66:67]
	s_nop 0
	v_pk_add_f32 v[64:65], v[64:65], v[72:73]
	s_nop 0
	v_add_f32_e32 v64, v64, v65
	s_nop 1
	v_add_f32_dpp v64, v64, v64 quad_perm:[1,0,3,2] row_mask:0xf bank_mask:0xf
	s_nop 1
	v_add_f32_dpp v64, v64, v64 quad_perm:[2,3,0,1] row_mask:0xf bank_mask:0xf
	s_nop 1
	v_add_f32_dpp v64, v64, v64 row_half_mirror row_mask:0xf bank_mask:0xf
	s_nop 1
	v_add_f32_dpp v64, v64, v64 row_mirror row_mask:0xf bank_mask:0xf
	v_mov_b32_e32 v65, v64
	s_nop 1
	v_permlane16_swap_b32_e32 v65, v64
	s_nop 1
	v_add_f32_e32 v64, v64, v65
	v_mov_b32_e32 v65, v64
	s_nop 1
	v_permlane32_swap_b32_e32 v65, v64
	s_nop 1
	v_add_f32_e32 v64, v64, v65
	v_fmamk_f32 v64, v64, 0x3a000000, v224
	v_mul_f32_e32 v65, 0x4f800000, v64
	v_cmp_gt_f32_e32 vcc, s41, v64
	s_nop 1
	v_cndmask_b32_e32 v64, v64, v65, vcc
	v_sqrt_f32_e32 v65, v64
	s_nop 0
	v_add_u32_e32 v66, -1, v65
	v_add_u32_e32 v67, 1, v65
	v_fma_f32 v68, -v66, v65, v64
	v_fma_f32 v69, -v67, v65, v64
	v_cmp_ge_f32_e64 s[4:5], 0, v68
	s_nop 1
	v_cndmask_b32_e64 v65, v65, v66, s[4:5]
	v_cmp_lt_f32_e64 s[4:5], 0, v69
	s_nop 1
	v_cndmask_b32_e64 v65, v65, v67, s[4:5]
	v_mul_f32_e32 v66, 0x37800000, v65
	v_cndmask_b32_e32 v65, v65, v66, vcc
	v_cmp_class_f32_e32 vcc, v64, v225
	s_nop 1
	v_cndmask_b32_e32 v64, v65, v64, vcc
	v_div_scale_f32 v65, s[2:3], v64, v64, 1.0
	v_rcp_f32_e32 v67, v65
	v_div_scale_f32 v66, vcc, 1.0, v64, 1.0
	v_fma_f32 v68, -v65, v67, 1.0
	v_fmac_f32_e32 v67, v68, v67
	v_mul_f32_e32 v68, v66, v67
	v_fma_f32 v69, -v65, v68, v66
	v_fmac_f32_e32 v68, v69, v67
	v_fma_f32 v65, -v65, v68, v66
	v_div_fmas_f32 v65, v65, v67, v68
	v_div_fixup_f32 v64, v65, v64, 1.0
	v_pk_mul_f32 v[32:33], v[32:33], v[64:65] op_sel_hi:[1,0]
	v_pk_mul_f32 v[34:35], v[34:35], v[64:65] op_sel_hi:[1,0]
	v_pk_mul_f32 v[36:37], v[36:37], v[64:65] op_sel_hi:[1,0]
	v_pk_mul_f32 v[38:39], v[38:39], v[64:65] op_sel_hi:[1,0]
	v_pk_mul_f32 v[40:41], v[40:41], v[64:65] op_sel_hi:[1,0]
	v_pk_mul_f32 v[42:43], v[42:43], v[64:65] op_sel_hi:[1,0]
	v_pk_mul_f32 v[44:45], v[44:45], v[64:65] op_sel_hi:[1,0]
	v_pk_mul_f32 v[46:47], v[46:47], v[64:65] op_sel_hi:[1,0]
	v_pk_mul_f32 v[52:53], v[52:53], v[64:65] op_sel_hi:[1,0]
	v_pk_mul_f32 v[54:55], v[54:55], v[64:65] op_sel_hi:[1,0]
	v_pk_mul_f32 v[56:57], v[56:57], v[64:65] op_sel_hi:[1,0]
	v_pk_mul_f32 v[58:59], v[58:59], v[64:65] op_sel_hi:[1,0]
	v_pk_mul_f32 v[60:61], v[60:61], v[64:65] op_sel_hi:[1,0]
	v_pk_mul_f32 v[62:63], v[62:63], v[64:65] op_sel_hi:[1,0]
	v_pk_mul_f32 v[48:49], v[48:49], v[64:65] op_sel_hi:[1,0]
	v_pk_mul_f32 v[50:51], v[50:51], v[64:65] op_sel_hi:[1,0]
	v_pk_fma_f32 v[34:35], v[126:127], v[34:35], v[22:23]
	v_pk_fma_f32 v[32:33], v[128:129], v[32:33], v[20:21]
	v_pk_fma_f32 v[38:39], v[130:131], v[38:39], v[14:15]
	v_pk_fma_f32 v[36:37], v[132:133], v[36:37], v[12:13]
	v_pk_fma_f32 v[42:43], v[134:135], v[42:43], v[18:19]
	v_pk_fma_f32 v[40:41], v[136:137], v[40:41], v[16:17]
	v_pk_fma_f32 v[46:47], v[138:139], v[46:47], v[6:7]
	v_pk_fma_f32 v[44:45], v[140:141], v[44:45], v[4:5]
	v_pk_fma_f32 v[54:55], v[142:143], v[54:55], v[10:11]
	v_pk_fma_f32 v[52:53], v[144:145], v[52:53], v[8:9]
	v_pk_fma_f32 v[58:59], v[146:147], v[58:59], v[2:3]
	v_pk_fma_f32 v[56:57], v[148:149], v[56:57], v[0:1]
	v_pk_fma_f32 v[62:63], v[150:151], v[62:63], v[30:31]
	v_pk_fma_f32 v[60:61], v[152:153], v[60:61], v[28:29]
	v_pk_fma_f32 v[50:51], v[154:155], v[50:51], v[26:27]
	v_pk_fma_f32 v[48:49], v[156:157], v[48:49], v[24:25]
	v_cvt_pk_bf16_f32 v32, v32, v33
	v_cvt_pk_bf16_f32 v33, v34, v35
	v_cvt_pk_bf16_f32 v34, v36, v37
	v_cvt_pk_bf16_f32 v35, v38, v39
	v_cvt_pk_bf16_f32 v36, v40, v41
	v_cvt_pk_bf16_f32 v37, v42, v43
; __device__ __forceinline__ v4u pk8(f32x4 a, f32x4 b) { v4u w; w.x = pk2(a[0], a[1]); w.y = pk2(a[2], a[3]); w.z = pk2(b[0], b[1]); w.w = pk2(b[2], b[3]); return w; }
; __device__ __forceinline__ float ssq8(const f32x4& a, const f32x4& b) { return ((a[0] * a[0] + a[1] * a[1]) + (a[2] * a[2] + a[3] * a[3])) + ((b[0] * b[0] + b[1] * b[1]) + (b[2] * b[2] + b[3] * b[3])); }
; __device__ __forceinline__ float shfl_xor_f(float v, int o) {
;     int l; asm volatile("v_mbcnt_lo_u32_b32 %0, -1, 0\n\tv_mbcnt_hi_u32_b32 %0, -1, %0" : "=v"(l));
;     return __builtin_bit_cast(float, __builtin_amdgcn_ds_bpermute((l ^ o) << 2, __builtin_bit_cast(int, v)));
; }
; __device__ __forceinline__ float wave_sum(float v) {
; #pragma unroll
;     for (int o = 1; o < 64; o <<= 1) v += shfl_xor_f(v, o);
;     return v;
; template <int XF32> __device__ __forceinline__ void norm_mod_phase(const void* x, const float* modl, int ch_shift, int ch_scale, bf16* H, int gw, int NGW, int lane) {
;     ...
;         for (int rr = 0; rr < 8; ++rr) {
;             const unsigned char* xr = (const unsigned char*)x + (size_t)(r0 + rr) * rowb; f32x4 v[4][2]; float s = 0.f;
; #pragma unroll
;             for (int j = 0; j < 4; ++j) ld_row8<XF32>(xr, lane, j, v[j][0], v[j][1]);
; #pragma unroll
;             for (int j = 0; j < 4; ++j) s += ssq8(v[j][0], v[j][1]);
;             const float rstd = 1.f / sqrtf(wave_sum(s) * (1.f / DM) + EPS);
;             v4u* o = (v4u*)(H + (size_t)(r0 + rr) * DM);
; #pragma unroll
;             for (int j = 0; j < 4; ++j) o[lane + 64 * j] = pk8(v[j][0] * rstd * sc[j][0] + sh[j][0], v[j][1] * rstd * sc[j][1] + sh[j][1]);
;         }
	v_cvt_pk_bf16_f32 v38, v44, v45
	v_cvt_pk_bf16_f32 v39, v46, v47
	v_cvt_pk_bf16_f32 v40, v52, v53
	v_cvt_pk_bf16_f32 v41, v54, v55
	v_cvt_pk_bf16_f32 v42, v56, v57
	v_cvt_pk_bf16_f32 v43, v58, v59
	v_cvt_pk_bf16_f32 v44, v60, v61
	v_cvt_pk_bf16_f32 v45, v62, v63
	v_cvt_pk_bf16_f32 v46, v48, v49
	v_cvt_pk_bf16_f32 v47, v50, v51
	global_store_dwordx4 v[116:117], v[32:35], off
	global_store_dwordx4 v[116:117], v[36:39], off offset:1024
	global_store_dwordx4 v[116:117], v[40:43], off offset:2048
	global_store_dwordx4 v[116:117], v[44:47], off offset:3072
	global_load_dwordx4 v[32:35], v[164:165], off
	s_nop 0
	global_load_dwordx4 v[36:39], v[164:165], off offset:16
	global_load_dwordx4 v[40:43], v[164:165], off offset:2048
	global_load_dwordx4 v[44:47], v[164:165], off offset:2064
	global_load_dwordx4 v[48:51], v[162:163], off offset:16
	global_load_dwordx4 v[52:55], v[160:161], off
	global_load_dwordx4 v[56:59], v[160:161], off offset:16
	global_load_dwordx4 v[60:63], v[162:163], off
	v_mbcnt_lo_u32_b32 v64, -1, 0
	v_mbcnt_hi_u32_b32 v64, -1, v64
	v_mbcnt_lo_u32_b32 v65, -1, 0
	v_mbcnt_hi_u32_b32 v65, -1, v65
	v_mbcnt_lo_u32_b32 v66, -1, 0
	v_mbcnt_hi_u32_b32 v66, -1, v66
	v_mbcnt_lo_u32_b32 v67, -1, 0
	v_mbcnt_hi_u32_b32 v67, -1, v67
	v_mbcnt_lo_u32_b32 v68, -1, 0
	v_mbcnt_hi_u32_b32 v68, -1, v68
	v_mbcnt_lo_u32_b32 v69, -1, 0
	v_mbcnt_hi_u32_b32 v69, -1, v69
	s_nop 0
	v_lshlrev_b32_e32 v64, 2, v64
	v_lshlrev_b32_e32 v65, 2, v65
	v_lshlrev_b32_e32 v66, 2, v66
	v_lshlrev_b32_e32 v67, 2, v67
	v_lshlrev_b32_e32 v68, 2, v68
	v_lshlrev_b32_e32 v69, 2, v69
	v_xor_b32_e32 v87, 4, v64
	v_xor_b32_e32 v90, 8, v65
	v_xor_b32_e32 v91, 16, v66
	v_xor_b32_e32 v92, 32, v67
	v_xor_b32_e32 v93, 64, v68
	v_xor_b32_e32 v94, 0x80, v69
	s_waitcnt vmcnt(7)
	v_pk_mul_f32 v[64:65], v[34:35], v[34:35]
	v_pk_mul_f32 v[66:67], v[32:33], v[32:33]
	s_waitcnt vmcnt(6)
	v_pk_mul_f32 v[68:69], v[38:39], v[38:39]
	v_pk_mul_f32 v[70:71], v[36:37], v[36:37]
	s_waitcnt vmcnt(5)
	v_pk_mul_f32 v[72:73], v[42:43], v[42:43]
	v_pk_mul_f32 v[74:75], v[40:41], v[40:41]
	s_waitcnt vmcnt(4)
	v_pk_mul_f32 v[76:77], v[46:47], v[46:47]
	v_pk_mul_f32 v[78:79], v[44:45], v[44:45]
	v_pk_mov_b32 v[88:89], v[66:67], v[64:65] op_sel:[1,0]
	v_mov_b32_e32 v67, v65
	v_pk_mov_b32 v[64:65], v[70:71], v[68:69] op_sel:[1,0]
	v_mov_b32_e32 v71, v69
	v_pk_mov_b32 v[68:69], v[74:75], v[72:73] op_sel:[1,0]
	v_mov_b32_e32 v75, v73
	v_pk_mov_b32 v[72:73], v[78:79], v[76:77] op_sel:[1,0]
	v_mov_b32_e32 v79, v77
	s_waitcnt vmcnt(2)
	v_mul_f32_e32 v80, v53, v53
	v_mul_f32_e32 v82, v55, v55
	s_waitcnt vmcnt(1)
	v_mul_f32_e32 v84, v57, v57
	v_mul_f32_e32 v86, v59, v59
	v_pk_add_f32 v[66:67], v[88:89], v[66:67]
	v_pk_add_f32 v[64:65], v[64:65], v[70:71]
	v_pk_add_f32 v[68:69], v[68:69], v[74:75]
	v_pk_add_f32 v[70:71], v[72:73], v[78:79]
	v_mul_f32_e32 v95, v48, v48
	v_mul_f32_e32 v106, v49, v49
	v_mul_f32_e32 v107, v50, v50
	v_mul_f32_e32 v108, v51, v51
	s_waitcnt vmcnt(0)
	v_mul_f32_e32 v109, v60, v60
	v_mul_f32_e32 v110, v61, v61
	v_mul_f32_e32 v111, v62, v62
	v_mul_f32_e32 v112, v63, v63
	v_pk_fma_f32 v[76:77], v[52:53], v[52:53], v[80:81] op_sel_hi:[1,1,0]
	v_pk_fma_f32 v[80:81], v[54:55], v[54:55], v[82:83] op_sel_hi:[1,1,0]
	v_pk_fma_f32 v[82:83], v[56:57], v[56:57], v[84:85] op_sel_hi:[1,1,0]
	v_pk_fma_f32 v[84:85], v[58:59], v[58:59], v[86:87] op_sel_hi:[1,1,0]
	v_pk_add_f32 v[66:67], v[66:67], v[66:67] op_sel:[0,1] op_sel_hi:[1,0]
	v_pk_add_f32 v[64:65], v[64:65], v[64:65] op_sel:[0,1] op_sel_hi:[1,0]
	v_pk_add_f32 v[68:69], v[68:69], v[68:69] op_sel:[0,1] op_sel_hi:[1,0]
	v_pk_add_f32 v[70:71], v[70:71], v[70:71] op_sel:[0,1] op_sel_hi:[1,0]
	v_mov_b32_e32 v77, v95
	v_mov_b32_e32 v81, v106
	v_mov_b32_e32 v83, v107
	v_mov_b32_e32 v85, v108
	v_mov_b32_e32 v67, v109
	v_mov_b32_e32 v65, v110
	v_mov_b32_e32 v69, v111
	v_mov_b32_e32 v71, v112
	v_pk_add_f32 v[72:73], v[76:77], v[80:81]
	v_pk_add_f32 v[74:75], v[82:83], v[84:85]
	v_pk_add_f32 v[64:65], v[66:67], v[64:65]
	v_pk_add_f32 v[66:67], v[68:69], v[70:71]
	v_pk_add_f32 v[72:73], v[72:73], v[74:75]
	v_pk_add_f32 v[64:65], v[64:65], v[66:67]
	s_nop 0
	v_pk_add_f32 v[64:65], v[64:65], v[72:73]
	s_nop 0
	v_add_f32_e32 v64, v64, v65
	s_nop 1
	v_add_f32_dpp v64, v64, v64 quad_perm:[1,0,3,2] row_mask:0xf bank_mask:0xf
	s_nop 1
	v_add_f32_dpp v64, v64, v64 quad_perm:[2,3,0,1] row_mask:0xf bank_mask:0xf
	s_nop 1
	v_add_f32_dpp v64, v64, v64 row_half_mirror row_mask:0xf bank_mask:0xf
	s_nop 1
	v_add_f32_dpp v64, v64, v64 row_mirror row_mask:0xf bank_mask:0xf
	v_mov_b32_e32 v65, v64
	s_nop 1
	v_permlane16_swap_b32_e32 v65, v64
	s_nop 1
	v_add_f32_e32 v64, v64, v65
	v_mov_b32_e32 v65, v64
	s_nop 1
	v_permlane32_swap_b32_e32 v65, v64
	s_nop 1
	v_add_f32_e32 v64, v64, v65
	v_fmamk_f32 v64, v64, 0x3a000000, v224
	v_mul_f32_e32 v65, 0x4f800000, v64
	v_cmp_gt_f32_e32 vcc, s41, v64
	s_nop 1
	v_cndmask_b32_e32 v64, v64, v65, vcc
	v_sqrt_f32_e32 v65, v64
	s_nop 0
	v_add_u32_e32 v66, -1, v65
	v_add_u32_e32 v67, 1, v65
	v_fma_f32 v68, -v66, v65, v64
	v_fma_f32 v69, -v67, v65, v64
	v_cmp_ge_f32_e64 s[4:5], 0, v68
	s_nop 1
	v_cndmask_b32_e64 v65, v65, v66, s[4:5]
	v_cmp_lt_f32_e64 s[4:5], 0, v69
	s_nop 1
	v_cndmask_b32_e64 v65, v65, v67, s[4:5]
	v_mul_f32_e32 v66, 0x37800000, v65
	v_cndmask_b32_e32 v65, v65, v66, vcc
	v_cmp_class_f32_e32 vcc, v64, v225
	s_nop 1
	v_cndmask_b32_e32 v64, v65, v64, vcc
	v_div_scale_f32 v65, s[2:3], v64, v64, 1.0
	v_rcp_f32_e32 v67, v65
	v_div_scale_f32 v66, vcc, 1.0, v64, 1.0
	v_fma_f32 v68, -v65, v67, 1.0
	v_fmac_f32_e32 v67, v68, v67
	v_mul_f32_e32 v68, v66, v67
	v_fma_f32 v69, -v65, v68, v66
	v_fmac_f32_e32 v68, v69, v67
	v_fma_f32 v65, -v65, v68, v66
; __device__ __forceinline__ v4u pk8(f32x4 a, f32x4 b) { v4u w; w.x = pk2(a[0], a[1]); w.y = pk2(a[2], a[3]); w.z = pk2(b[0], b[1]); w.w = pk2(b[2], b[3]); return w; }
; __device__ __forceinline__ float ssq8(const f32x4& a, const f32x4& b) { return ((a[0] * a[0] + a[1] * a[1]) + (a[2] * a[2] + a[3] * a[3])) + ((b[0] * b[0] + b[1] * b[1]) + (b[2] * b[2] + b[3] * b[3])); }
; template <int XF32> __device__ __forceinline__ void norm_mod_phase(const void* x, const float* modl, int ch_shift, int ch_scale, bf16* H, int gw, int NGW, int lane) {
;     ...
;         for (int rr = 0; rr < 8; ++rr) {
;             const unsigned char* xr = (const unsigned char*)x + (size_t)(r0 + rr) * rowb; f32x4 v[4][2]; float s = 0.f;
; #pragma unroll
;             for (int j = 0; j < 4; ++j) ld_row8<XF32>(xr, lane, j, v[j][0], v[j][1]);
; #pragma unroll
;             for (int j = 0; j < 4; ++j) s += ssq8(v[j][0], v[j][1]);
;             const float rstd = 1.f / sqrtf(wave_sum(s) * (1.f / DM) + EPS);
;             v4u* o = (v4u*)(H + (size_t)(r0 + rr) * DM);
; #pragma unroll
;             for (int j = 0; j < 4; ++j) o[lane + 64 * j] = pk8(v[j][0] * rstd * sc[j][0] + sh[j][0], v[j][1] * rstd * sc[j][1] + sh[j][1]);
;         }
	v_div_fmas_f32 v65, v65, v67, v68
	v_div_fixup_f32 v64, v65, v64, 1.0
	v_pk_mul_f32 v[32:33], v[32:33], v[64:65] op_sel_hi:[1,0]
	v_pk_mul_f32 v[34:35], v[34:35], v[64:65] op_sel_hi:[1,0]
	v_pk_mul_f32 v[36:37], v[36:37], v[64:65] op_sel_hi:[1,0]
	v_pk_mul_f32 v[38:39], v[38:39], v[64:65] op_sel_hi:[1,0]
	v_pk_mul_f32 v[40:41], v[40:41], v[64:65] op_sel_hi:[1,0]
	v_pk_mul_f32 v[42:43], v[42:43], v[64:65] op_sel_hi:[1,0]
	v_pk_mul_f32 v[44:45], v[44:45], v[64:65] op_sel_hi:[1,0]
	v_pk_mul_f32 v[46:47], v[46:47], v[64:65] op_sel_hi:[1,0]
	v_pk_mul_f32 v[52:53], v[52:53], v[64:65] op_sel_hi:[1,0]
	v_pk_mul_f32 v[54:55], v[54:55], v[64:65] op_sel_hi:[1,0]
	v_pk_mul_f32 v[56:57], v[56:57], v[64:65] op_sel_hi:[1,0]
	v_pk_mul_f32 v[58:59], v[58:59], v[64:65] op_sel_hi:[1,0]
	v_pk_mul_f32 v[60:61], v[60:61], v[64:65] op_sel_hi:[1,0]
	v_pk_mul_f32 v[62:63], v[62:63], v[64:65] op_sel_hi:[1,0]
	v_pk_mul_f32 v[48:49], v[48:49], v[64:65] op_sel_hi:[1,0]
	v_pk_mul_f32 v[50:51], v[50:51], v[64:65] op_sel_hi:[1,0]
	v_pk_fma_f32 v[34:35], v[126:127], v[34:35], v[22:23]
	v_pk_fma_f32 v[32:33], v[128:129], v[32:33], v[20:21]
	v_pk_fma_f32 v[38:39], v[130:131], v[38:39], v[14:15]
	v_pk_fma_f32 v[36:37], v[132:133], v[36:37], v[12:13]
	v_pk_fma_f32 v[42:43], v[134:135], v[42:43], v[18:19]
	v_pk_fma_f32 v[40:41], v[136:137], v[40:41], v[16:17]
	v_pk_fma_f32 v[46:47], v[138:139], v[46:47], v[6:7]
	v_pk_fma_f32 v[44:45], v[140:141], v[44:45], v[4:5]
	v_pk_fma_f32 v[54:55], v[142:143], v[54:55], v[10:11]
	v_pk_fma_f32 v[52:53], v[144:145], v[52:53], v[8:9]
	v_pk_fma_f32 v[58:59], v[146:147], v[58:59], v[2:3]
	v_pk_fma_f32 v[56:57], v[148:149], v[56:57], v[0:1]
	v_pk_fma_f32 v[62:63], v[150:151], v[62:63], v[30:31]
	v_pk_fma_f32 v[60:61], v[152:153], v[60:61], v[28:29]
	v_pk_fma_f32 v[50:51], v[154:155], v[50:51], v[26:27]
	v_pk_fma_f32 v[48:49], v[156:157], v[48:49], v[24:25]
	v_cvt_pk_bf16_f32 v32, v32, v33
	v_cvt_pk_bf16_f32 v33, v34, v35
	v_cvt_pk_bf16_f32 v34, v36, v37
	v_cvt_pk_bf16_f32 v35, v38, v39
	v_cvt_pk_bf16_f32 v36, v40, v41
	v_cvt_pk_bf16_f32 v37, v42, v43
	v_cvt_pk_bf16_f32 v38, v44, v45
	v_cvt_pk_bf16_f32 v39, v46, v47
	v_cvt_pk_bf16_f32 v40, v52, v53
	v_cvt_pk_bf16_f32 v41, v54, v55
	v_cvt_pk_bf16_f32 v42, v56, v57
	v_cvt_pk_bf16_f32 v43, v58, v59
	v_cvt_pk_bf16_f32 v44, v60, v61
	v_cvt_pk_bf16_f32 v45, v62, v63
	v_cvt_pk_bf16_f32 v46, v48, v49
	v_cvt_pk_bf16_f32 v47, v50, v51
	global_store_dwordx4 v[158:159], v[32:35], off
	global_store_dwordx4 v[158:159], v[36:39], off offset:1024
	global_store_dwordx4 v[158:159], v[40:43], off offset:2048
	global_store_dwordx4 v[158:159], v[44:47], off offset:3072
	global_load_dwordx4 v[32:35], v[186:187], off
	s_nop 0
	global_load_dwordx4 v[36:39], v[186:187], off offset:16
	global_load_dwordx4 v[40:43], v[186:187], off offset:2048
	global_load_dwordx4 v[44:47], v[186:187], off offset:2064
	global_load_dwordx4 v[48:51], v[184:185], off offset:16
	global_load_dwordx4 v[52:55], v[182:183], off
	global_load_dwordx4 v[56:59], v[182:183], off offset:16
	global_load_dwordx4 v[60:63], v[184:185], off
	v_mbcnt_lo_u32_b32 v64, -1, 0
	v_mbcnt_hi_u32_b32 v64, -1, v64
	v_mbcnt_lo_u32_b32 v65, -1, 0
	v_mbcnt_hi_u32_b32 v65, -1, v65
	v_mbcnt_lo_u32_b32 v66, -1, 0
	v_mbcnt_hi_u32_b32 v66, -1, v66
	v_mbcnt_lo_u32_b32 v67, -1, 0
	v_mbcnt_hi_u32_b32 v67, -1, v67
	v_mbcnt_lo_u32_b32 v68, -1, 0
	v_mbcnt_hi_u32_b32 v68, -1, v68
	v_mbcnt_lo_u32_b32 v69, -1, 0
	v_mbcnt_hi_u32_b32 v69, -1, v69
	s_nop 0
	v_lshlrev_b32_e32 v64, 2, v64
	v_lshlrev_b32_e32 v65, 2, v65
	v_lshlrev_b32_e32 v66, 2, v66
	v_lshlrev_b32_e32 v67, 2, v67
	v_lshlrev_b32_e32 v68, 2, v68
	v_lshlrev_b32_e32 v69, 2, v69
	v_xor_b32_e32 v87, 4, v64
	v_xor_b32_e32 v90, 8, v65
	v_xor_b32_e32 v91, 16, v66
	v_xor_b32_e32 v92, 32, v67
	v_xor_b32_e32 v93, 64, v68
	v_xor_b32_e32 v94, 0x80, v69
	s_waitcnt vmcnt(7)
	v_pk_mul_f32 v[64:65], v[34:35], v[34:35]
	v_pk_mul_f32 v[66:67], v[32:33], v[32:33]
	s_waitcnt vmcnt(6)
	v_pk_mul_f32 v[68:69], v[38:39], v[38:39]
	v_pk_mul_f32 v[70:71], v[36:37], v[36:37]
	s_waitcnt vmcnt(5)
	v_pk_mul_f32 v[72:73], v[42:43], v[42:43]
	v_pk_mul_f32 v[74:75], v[40:41], v[40:41]
	s_waitcnt vmcnt(4)
	v_pk_mul_f32 v[76:77], v[46:47], v[46:47]
	v_pk_mul_f32 v[78:79], v[44:45], v[44:45]
	v_pk_mov_b32 v[88:89], v[66:67], v[64:65] op_sel:[1,0]
	v_mov_b32_e32 v67, v65
	v_pk_mov_b32 v[64:65], v[70:71], v[68:69] op_sel:[1,0]
	v_mov_b32_e32 v71, v69
	v_pk_mov_b32 v[68:69], v[74:75], v[72:73] op_sel:[1,0]
	v_mov_b32_e32 v75, v73
	v_pk_mov_b32 v[72:73], v[78:79], v[76:77] op_sel:[1,0]
	v_mov_b32_e32 v79, v77
	s_waitcnt vmcnt(2)
	v_mul_f32_e32 v80, v53, v53
	v_mul_f32_e32 v82, v55, v55
	s_waitcnt vmcnt(1)
	v_mul_f32_e32 v84, v57, v57
	v_mul_f32_e32 v86, v59, v59
	v_pk_add_f32 v[66:67], v[88:89], v[66:67]
	v_pk_add_f32 v[64:65], v[64:65], v[70:71]
	v_pk_add_f32 v[68:69], v[68:69], v[74:75]
	v_pk_add_f32 v[70:71], v[72:73], v[78:79]
	v_mul_f32_e32 v95, v48, v48
	v_mul_f32_e32 v106, v49, v49
	v_mul_f32_e32 v107, v50, v50
	v_mul_f32_e32 v108, v51, v51
	s_waitcnt vmcnt(0)
; __device__ __forceinline__ v4u pk8(f32x4 a, f32x4 b) { v4u w; w.x = pk2(a[0], a[1]); w.y = pk2(a[2], a[3]); w.z = pk2(b[0], b[1]); w.w = pk2(b[2], b[3]); return w; }
; __device__ __forceinline__ float ssq8(const f32x4& a, const f32x4& b) { return ((a[0] * a[0] + a[1] * a[1]) + (a[2] * a[2] + a[3] * a[3])) + ((b[0] * b[0] + b[1] * b[1]) + (b[2] * b[2] + b[3] * b[3])); }
; __device__ __forceinline__ float shfl_xor_f(float v, int o) {
;     int l; asm volatile("v_mbcnt_lo_u32_b32 %0, -1, 0\n\tv_mbcnt_hi_u32_b32 %0, -1, %0" : "=v"(l));
;     return __builtin_bit_cast(float, __builtin_amdgcn_ds_bpermute((l ^ o) << 2, __builtin_bit_cast(int, v)));
; }
; __device__ __forceinline__ float wave_sum(float v) {
; #pragma unroll
;     for (int o = 1; o < 64; o <<= 1) v += shfl_xor_f(v, o);
;     return v;
; template <int XF32> __device__ __forceinline__ void norm_mod_phase(const void* x, const float* modl, int ch_shift, int ch_scale, bf16* H, int gw, int NGW, int lane) {
;     ...
;         for (int rr = 0; rr < 8; ++rr) {
;             const unsigned char* xr = (const unsigned char*)x + (size_t)(r0 + rr) * rowb; f32x4 v[4][2]; float s = 0.f;
; #pragma unroll
;             for (int j = 0; j < 4; ++j) ld_row8<XF32>(xr, lane, j, v[j][0], v[j][1]);
; #pragma unroll
;             for (int j = 0; j < 4; ++j) s += ssq8(v[j][0], v[j][1]);
;             const float rstd = 1.f / sqrtf(wave_sum(s) * (1.f / DM) + EPS);
;             v4u* o = (v4u*)(H + (size_t)(r0 + rr) * DM);
; #pragma unroll
;             for (int j = 0; j < 4; ++j) o[lane + 64 * j] = pk8(v[j][0] * rstd * sc[j][0] + sh[j][0], v[j][1] * rstd * sc[j][1] + sh[j][1]);
;         }
	v_mul_f32_e32 v109, v60, v60
	v_mul_f32_e32 v110, v61, v61
	v_mul_f32_e32 v111, v62, v62
	v_mul_f32_e32 v112, v63, v63
	v_pk_fma_f32 v[76:77], v[52:53], v[52:53], v[80:81] op_sel_hi:[1,1,0]
	v_pk_fma_f32 v[80:81], v[54:55], v[54:55], v[82:83] op_sel_hi:[1,1,0]
	v_pk_fma_f32 v[82:83], v[56:57], v[56:57], v[84:85] op_sel_hi:[1,1,0]
	v_pk_fma_f32 v[84:85], v[58:59], v[58:59], v[86:87] op_sel_hi:[1,1,0]
	v_pk_add_f32 v[66:67], v[66:67], v[66:67] op_sel:[0,1] op_sel_hi:[1,0]
	v_pk_add_f32 v[64:65], v[64:65], v[64:65] op_sel:[0,1] op_sel_hi:[1,0]
	v_pk_add_f32 v[68:69], v[68:69], v[68:69] op_sel:[0,1] op_sel_hi:[1,0]
	v_pk_add_f32 v[70:71], v[70:71], v[70:71] op_sel:[0,1] op_sel_hi:[1,0]
	v_mov_b32_e32 v77, v95
	v_mov_b32_e32 v81, v106
	v_mov_b32_e32 v83, v107
	v_mov_b32_e32 v85, v108
	v_mov_b32_e32 v67, v109
	v_mov_b32_e32 v65, v110
	v_mov_b32_e32 v69, v111
	v_mov_b32_e32 v71, v112
	v_pk_add_f32 v[72:73], v[76:77], v[80:81]
	v_pk_add_f32 v[74:75], v[82:83], v[84:85]
	v_pk_add_f32 v[64:65], v[66:67], v[64:65]
	v_pk_add_f32 v[66:67], v[68:69], v[70:71]
	v_pk_add_f32 v[72:73], v[72:73], v[74:75]
	v_pk_add_f32 v[64:65], v[64:65], v[66:67]
	s_nop 0
	v_pk_add_f32 v[64:65], v[64:65], v[72:73]
	s_nop 0
	v_add_f32_e32 v64, v64, v65
	s_nop 1
	v_add_f32_dpp v64, v64, v64 quad_perm:[1,0,3,2] row_mask:0xf bank_mask:0xf
	s_nop 1
	v_add_f32_dpp v64, v64, v64 quad_perm:[2,3,0,1] row_mask:0xf bank_mask:0xf
	s_nop 1
	v_add_f32_dpp v64, v64, v64 row_half_mirror row_mask:0xf bank_mask:0xf
	s_nop 1
	v_add_f32_dpp v64, v64, v64 row_mirror row_mask:0xf bank_mask:0xf
	v_mov_b32_e32 v65, v64
	s_nop 1
	v_permlane16_swap_b32_e32 v65, v64
	s_nop 1
	v_add_f32_e32 v64, v64, v65
	v_mov_b32_e32 v65, v64
	s_nop 1
	v_permlane32_swap_b32_e32 v65, v64
	s_nop 1
	v_add_f32_e32 v64, v64, v65
	v_fmamk_f32 v64, v64, 0x3a000000, v224
	v_mul_f32_e32 v65, 0x4f800000, v64
	v_cmp_gt_f32_e32 vcc, s41, v64
	s_nop 1
	v_cndmask_b32_e32 v64, v64, v65, vcc
	v_sqrt_f32_e32 v65, v64
	s_nop 0
	v_add_u32_e32 v66, -1, v65
	v_add_u32_e32 v67, 1, v65
	v_fma_f32 v68, -v66, v65, v64
	v_fma_f32 v69, -v67, v65, v64
	v_cmp_ge_f32_e64 s[4:5], 0, v68
	s_nop 1
	v_cndmask_b32_e64 v65, v65, v66, s[4:5]
	v_cmp_lt_f32_e64 s[4:5], 0, v69
	s_nop 1
	v_cndmask_b32_e64 v65, v65, v67, s[4:5]
	v_mul_f32_e32 v66, 0x37800000, v65
	v_cndmask_b32_e32 v65, v65, v66, vcc
	v_cmp_class_f32_e32 vcc, v64, v225
	s_nop 1
	v_cndmask_b32_e32 v64, v65, v64, vcc
	v_div_scale_f32 v65, s[2:3], v64, v64, 1.0
	v_rcp_f32_e32 v67, v65
	v_div_scale_f32 v66, vcc, 1.0, v64, 1.0
	v_fma_f32 v68, -v65, v67, 1.0
	v_fmac_f32_e32 v67, v68, v67
	v_mul_f32_e32 v68, v66, v67
	v_fma_f32 v69, -v65, v68, v66
	v_fmac_f32_e32 v68, v69, v67
	v_fma_f32 v65, -v65, v68, v66
	v_div_fmas_f32 v65, v65, v67, v68
	v_div_fixup_f32 v64, v65, v64, 1.0
	v_pk_mul_f32 v[32:33], v[32:33], v[64:65] op_sel_hi:[1,0]
	v_pk_mul_f32 v[34:35], v[34:35], v[64:65] op_sel_hi:[1,0]
	v_pk_mul_f32 v[36:37], v[36:37], v[64:65] op_sel_hi:[1,0]
	v_pk_mul_f32 v[38:39], v[38:39], v[64:65] op_sel_hi:[1,0]
	v_pk_mul_f32 v[40:41], v[40:41], v[64:65] op_sel_hi:[1,0]
	v_pk_mul_f32 v[42:43], v[42:43], v[64:65] op_sel_hi:[1,0]
	v_pk_mul_f32 v[44:45], v[44:45], v[64:65] op_sel_hi:[1,0]
	v_pk_mul_f32 v[46:47], v[46:47], v[64:65] op_sel_hi:[1,0]
	v_pk_mul_f32 v[52:53], v[52:53], v[64:65] op_sel_hi:[1,0]
	v_pk_mul_f32 v[54:55], v[54:55], v[64:65] op_sel_hi:[1,0]
	v_pk_mul_f32 v[56:57], v[56:57], v[64:65] op_sel_hi:[1,0]
	v_pk_mul_f32 v[58:59], v[58:59], v[64:65] op_sel_hi:[1,0]
	v_pk_mul_f32 v[60:61], v[60:61], v[64:65] op_sel_hi:[1,0]
	v_pk_mul_f32 v[62:63], v[62:63], v[64:65] op_sel_hi:[1,0]
	v_pk_mul_f32 v[48:49], v[48:49], v[64:65] op_sel_hi:[1,0]
	v_pk_mul_f32 v[50:51], v[50:51], v[64:65] op_sel_hi:[1,0]
	v_pk_fma_f32 v[34:35], v[126:127], v[34:35], v[22:23]
	v_pk_fma_f32 v[32:33], v[128:129], v[32:33], v[20:21]
	v_pk_fma_f32 v[38:39], v[130:131], v[38:39], v[14:15]
	v_pk_fma_f32 v[36:37], v[132:133], v[36:37], v[12:13]
	v_pk_fma_f32 v[42:43], v[134:135], v[42:43], v[18:19]
	v_pk_fma_f32 v[40:41], v[136:137], v[40:41], v[16:17]
	v_pk_fma_f32 v[46:47], v[138:139], v[46:47], v[6:7]
	v_pk_fma_f32 v[44:45], v[140:141], v[44:45], v[4:5]
	v_pk_fma_f32 v[54:55], v[142:143], v[54:55], v[10:11]
	v_pk_fma_f32 v[52:53], v[144:145], v[52:53], v[8:9]
	v_pk_fma_f32 v[58:59], v[146:147], v[58:59], v[2:3]
	v_pk_fma_f32 v[56:57], v[148:149], v[56:57], v[0:1]
	v_pk_fma_f32 v[62:63], v[150:151], v[62:63], v[30:31]
	v_pk_fma_f32 v[60:61], v[152:153], v[60:61], v[28:29]
	v_pk_fma_f32 v[50:51], v[154:155], v[50:51], v[26:27]
	v_pk_fma_f32 v[48:49], v[156:157], v[48:49], v[24:25]
	v_cvt_pk_bf16_f32 v32, v32, v33
	v_cvt_pk_bf16_f32 v33, v34, v35
	v_cvt_pk_bf16_f32 v34, v36, v37
	v_cvt_pk_bf16_f32 v35, v38, v39
	v_cvt_pk_bf16_f32 v36, v40, v41
	v_cvt_pk_bf16_f32 v37, v42, v43
	v_cvt_pk_bf16_f32 v38, v44, v45
	v_cvt_pk_bf16_f32 v39, v46, v47
	v_cvt_pk_bf16_f32 v40, v52, v53
	v_cvt_pk_bf16_f32 v41, v54, v55
	v_cvt_pk_bf16_f32 v42, v56, v57
	v_cvt_pk_bf16_f32 v43, v58, v59
	v_cvt_pk_bf16_f32 v44, v60, v61
	v_cvt_pk_bf16_f32 v45, v62, v63
	v_cvt_pk_bf16_f32 v46, v48, v49
	v_cvt_pk_bf16_f32 v47, v50, v51
	global_store_dwordx4 v[166:167], v[32:35], off
	global_store_dwordx4 v[166:167], v[36:39], off offset:1024
	global_store_dwordx4 v[166:167], v[40:43], off offset:2048
	global_store_dwordx4 v[166:167], v[44:47], off offset:3072
	global_load_dwordx4 v[32:35], v[194:195], off
	s_nop 0
	global_load_dwordx4 v[36:39], v[194:195], off offset:16
	global_load_dwordx4 v[40:43], v[194:195], off offset:2048
	global_load_dwordx4 v[44:47], v[194:195], off offset:2064
	global_load_dwordx4 v[48:51], v[192:193], off offset:16
	global_load_dwordx4 v[52:55], v[190:191], off
	global_load_dwordx4 v[56:59], v[190:191], off offset:16
	global_load_dwordx4 v[60:63], v[192:193], off
	v_mbcnt_lo_u32_b32 v64, -1, 0
	v_mbcnt_hi_u32_b32 v64, -1, v64
	v_mbcnt_lo_u32_b32 v65, -1, 0
	v_mbcnt_hi_u32_b32 v65, -1, v65
	v_mbcnt_lo_u32_b32 v66, -1, 0
	v_mbcnt_hi_u32_b32 v66, -1, v66
	v_mbcnt_lo_u32_b32 v67, -1, 0
	v_mbcnt_hi_u32_b32 v67, -1, v67
	v_mbcnt_lo_u32_b32 v68, -1, 0
	v_mbcnt_hi_u32_b32 v68, -1, v68
	v_mbcnt_lo_u32_b32 v69, -1, 0
	v_mbcnt_hi_u32_b32 v69, -1, v69
	s_nop 0
	v_lshlrev_b32_e32 v64, 2, v64
	v_lshlrev_b32_e32 v65, 2, v65
	v_lshlrev_b32_e32 v66, 2, v66
	v_lshlrev_b32_e32 v67, 2, v67
	v_lshlrev_b32_e32 v68, 2, v68
	v_lshlrev_b32_e32 v69, 2, v69
	v_xor_b32_e32 v87, 4, v64
	v_xor_b32_e32 v90, 8, v65
	v_xor_b32_e32 v91, 16, v66
	v_xor_b32_e32 v92, 32, v67
	v_xor_b32_e32 v93, 64, v68
	v_xor_b32_e32 v94, 0x80, v69
	s_waitcnt vmcnt(7)
; __device__ __forceinline__ v4u pk8(f32x4 a, f32x4 b) { v4u w; w.x = pk2(a[0], a[1]); w.y = pk2(a[2], a[3]); w.z = pk2(b[0], b[1]); w.w = pk2(b[2], b[3]); return w; }
; __device__ __forceinline__ float ssq8(const f32x4& a, const f32x4& b) { return ((a[0] * a[0] + a[1] * a[1]) + (a[2] * a[2] + a[3] * a[3])) + ((b[0] * b[0] + b[1] * b[1]) + (b[2] * b[2] + b[3] * b[3])); }
; __device__ __forceinline__ float shfl_xor_f(float v, int o) {
;     int l; asm volatile("v_mbcnt_lo_u32_b32 %0, -1, 0\n\tv_mbcnt_hi_u32_b32 %0, -1, %0" : "=v"(l));
;     return __builtin_bit_cast(float, __builtin_amdgcn_ds_bpermute((l ^ o) << 2, __builtin_bit_cast(int, v)));
; }
; __device__ __forceinline__ float wave_sum(float v) {
; #pragma unroll
;     for (int o = 1; o < 64; o <<= 1) v += shfl_xor_f(v, o);
;     return v;
; template <int XF32> __device__ __forceinline__ void norm_mod_phase(const void* x, const float* modl, int ch_shift, int ch_scale, bf16* H, int gw, int NGW, int lane) {
;     ...
;         for (int rr = 0; rr < 8; ++rr) {
;             const unsigned char* xr = (const unsigned char*)x + (size_t)(r0 + rr) * rowb; f32x4 v[4][2]; float s = 0.f;
; #pragma unroll
;             for (int j = 0; j < 4; ++j) ld_row8<XF32>(xr, lane, j, v[j][0], v[j][1]);
; #pragma unroll
;             for (int j = 0; j < 4; ++j) s += ssq8(v[j][0], v[j][1]);
;             const float rstd = 1.f / sqrtf(wave_sum(s) * (1.f / DM) + EPS);
;             v4u* o = (v4u*)(H + (size_t)(r0 + rr) * DM);
; #pragma unroll
;             for (int j = 0; j < 4; ++j) o[lane + 64 * j] = pk8(v[j][0] * rstd * sc[j][0] + sh[j][0], v[j][1] * rstd * sc[j][1] + sh[j][1]);
;         }
	v_pk_mul_f32 v[64:65], v[34:35], v[34:35]
	v_pk_mul_f32 v[66:67], v[32:33], v[32:33]
	s_waitcnt vmcnt(6)
	v_pk_mul_f32 v[68:69], v[38:39], v[38:39]
	v_pk_mul_f32 v[70:71], v[36:37], v[36:37]
	s_waitcnt vmcnt(5)
	v_pk_mul_f32 v[72:73], v[42:43], v[42:43]
	v_pk_mul_f32 v[74:75], v[40:41], v[40:41]
	s_waitcnt vmcnt(4)
	v_pk_mul_f32 v[76:77], v[46:47], v[46:47]
	v_pk_mul_f32 v[78:79], v[44:45], v[44:45]
	v_pk_mov_b32 v[88:89], v[66:67], v[64:65] op_sel:[1,0]
	v_mov_b32_e32 v67, v65
	v_pk_mov_b32 v[64:65], v[70:71], v[68:69] op_sel:[1,0]
	v_mov_b32_e32 v71, v69
	v_pk_mov_b32 v[68:69], v[74:75], v[72:73] op_sel:[1,0]
	v_mov_b32_e32 v75, v73
	v_pk_mov_b32 v[72:73], v[78:79], v[76:77] op_sel:[1,0]
	v_mov_b32_e32 v79, v77
	s_waitcnt vmcnt(2)
	v_mul_f32_e32 v80, v53, v53
	v_mul_f32_e32 v82, v55, v55
	s_waitcnt vmcnt(1)
	v_mul_f32_e32 v84, v57, v57
	v_mul_f32_e32 v86, v59, v59
	v_pk_add_f32 v[66:67], v[88:89], v[66:67]
	v_pk_add_f32 v[64:65], v[64:65], v[70:71]
	v_pk_add_f32 v[68:69], v[68:69], v[74:75]
	v_pk_add_f32 v[70:71], v[72:73], v[78:79]
	v_mul_f32_e32 v95, v48, v48
	v_mul_f32_e32 v106, v49, v49
	v_mul_f32_e32 v107, v50, v50
	v_mul_f32_e32 v108, v51, v51
	s_waitcnt vmcnt(0)
	v_mul_f32_e32 v109, v60, v60
	v_mul_f32_e32 v110, v61, v61
	v_mul_f32_e32 v111, v62, v62
	v_mul_f32_e32 v112, v63, v63
	v_pk_fma_f32 v[76:77], v[52:53], v[52:53], v[80:81] op_sel_hi:[1,1,0]
	v_pk_fma_f32 v[80:81], v[54:55], v[54:55], v[82:83] op_sel_hi:[1,1,0]
	v_pk_fma_f32 v[82:83], v[56:57], v[56:57], v[84:85] op_sel_hi:[1,1,0]
	v_pk_fma_f32 v[84:85], v[58:59], v[58:59], v[86:87] op_sel_hi:[1,1,0]
	v_pk_add_f32 v[66:67], v[66:67], v[66:67] op_sel:[0,1] op_sel_hi:[1,0]
	v_pk_add_f32 v[64:65], v[64:65], v[64:65] op_sel:[0,1] op_sel_hi:[1,0]
	v_pk_add_f32 v[68:69], v[68:69], v[68:69] op_sel:[0,1] op_sel_hi:[1,0]
	v_pk_add_f32 v[70:71], v[70:71], v[70:71] op_sel:[0,1] op_sel_hi:[1,0]
	v_mov_b32_e32 v77, v95
	v_mov_b32_e32 v81, v106
	v_mov_b32_e32 v83, v107
	v_mov_b32_e32 v85, v108
	v_mov_b32_e32 v67, v109
	v_mov_b32_e32 v65, v110
	v_mov_b32_e32 v69, v111
	v_mov_b32_e32 v71, v112
	v_pk_add_f32 v[72:73], v[76:77], v[80:81]
	v_pk_add_f32 v[74:75], v[82:83], v[84:85]
	v_pk_add_f32 v[64:65], v[66:67], v[64:65]
	v_pk_add_f32 v[66:67], v[68:69], v[70:71]
	v_pk_add_f32 v[72:73], v[72:73], v[74:75]
	v_pk_add_f32 v[64:65], v[64:65], v[66:67]
	s_nop 0
	v_pk_add_f32 v[64:65], v[64:65], v[72:73]
	s_nop 0
	v_add_f32_e32 v64, v64, v65
	s_nop 1
	v_add_f32_dpp v64, v64, v64 quad_perm:[1,0,3,2] row_mask:0xf bank_mask:0xf
	s_nop 1
	v_add_f32_dpp v64, v64, v64 quad_perm:[2,3,0,1] row_mask:0xf bank_mask:0xf
	s_nop 1
	v_add_f32_dpp v64, v64, v64 row_half_mirror row_mask:0xf bank_mask:0xf
	s_nop 1
	v_add_f32_dpp v64, v64, v64 row_mirror row_mask:0xf bank_mask:0xf
	v_mov_b32_e32 v65, v64
	s_nop 1
	v_permlane16_swap_b32_e32 v65, v64
	s_nop 1
	v_add_f32_e32 v64, v64, v65
	v_mov_b32_e32 v65, v64
	s_nop 1
	v_permlane32_swap_b32_e32 v65, v64
	s_nop 1
	v_add_f32_e32 v64, v64, v65
	v_fmamk_f32 v64, v64, 0x3a000000, v224
	v_mul_f32_e32 v65, 0x4f800000, v64
	v_cmp_gt_f32_e32 vcc, s41, v64
	s_nop 1
	v_cndmask_b32_e32 v64, v64, v65, vcc
	v_sqrt_f32_e32 v65, v64
	s_nop 0
	v_add_u32_e32 v66, -1, v65
	v_add_u32_e32 v67, 1, v65
	v_fma_f32 v68, -v66, v65, v64
	v_fma_f32 v69, -v67, v65, v64
	v_cmp_ge_f32_e64 s[4:5], 0, v68
	s_nop 1
	v_cndmask_b32_e64 v65, v65, v66, s[4:5]
	v_cmp_lt_f32_e64 s[4:5], 0, v69
	s_nop 1
	v_cndmask_b32_e64 v65, v65, v67, s[4:5]
	v_mul_f32_e32 v66, 0x37800000, v65
	v_cndmask_b32_e32 v65, v65, v66, vcc
	v_cmp_class_f32_e32 vcc, v64, v225
	s_nop 1
	v_cndmask_b32_e32 v64, v65, v64, vcc
	v_div_scale_f32 v65, s[2:3], v64, v64, 1.0
	v_rcp_f32_e32 v67, v65
	v_div_scale_f32 v66, vcc, 1.0, v64, 1.0
	v_fma_f32 v68, -v65, v67, 1.0
	v_fmac_f32_e32 v67, v68, v67
	v_mul_f32_e32 v68, v66, v67
	v_fma_f32 v69, -v65, v68, v66
	v_fmac_f32_e32 v68, v69, v67
	v_fma_f32 v65, -v65, v68, v66
	v_div_fmas_f32 v65, v65, v67, v68
	v_div_fixup_f32 v64, v65, v64, 1.0
	v_pk_mul_f32 v[32:33], v[32:33], v[64:65] op_sel_hi:[1,0]
	v_pk_mul_f32 v[34:35], v[34:35], v[64:65] op_sel_hi:[1,0]
	v_pk_mul_f32 v[36:37], v[36:37], v[64:65] op_sel_hi:[1,0]
	v_pk_mul_f32 v[38:39], v[38:39], v[64:65] op_sel_hi:[1,0]
	v_pk_mul_f32 v[40:41], v[40:41], v[64:65] op_sel_hi:[1,0]
	v_pk_mul_f32 v[42:43], v[42:43], v[64:65] op_sel_hi:[1,0]
	v_pk_mul_f32 v[44:45], v[44:45], v[64:65] op_sel_hi:[1,0]
	v_pk_mul_f32 v[46:47], v[46:47], v[64:65] op_sel_hi:[1,0]
	v_pk_mul_f32 v[52:53], v[52:53], v[64:65] op_sel_hi:[1,0]
	v_pk_mul_f32 v[54:55], v[54:55], v[64:65] op_sel_hi:[1,0]
	v_pk_mul_f32 v[56:57], v[56:57], v[64:65] op_sel_hi:[1,0]
	v_pk_mul_f32 v[58:59], v[58:59], v[64:65] op_sel_hi:[1,0]
	v_pk_mul_f32 v[60:61], v[60:61], v[64:65] op_sel_hi:[1,0]
	v_pk_mul_f32 v[62:63], v[62:63], v[64:65] op_sel_hi:[1,0]
	v_pk_mul_f32 v[48:49], v[48:49], v[64:65] op_sel_hi:[1,0]
	v_pk_mul_f32 v[50:51], v[50:51], v[64:65] op_sel_hi:[1,0]
	v_pk_fma_f32 v[34:35], v[126:127], v[34:35], v[22:23]
	v_pk_fma_f32 v[32:33], v[128:129], v[32:33], v[20:21]
	v_pk_fma_f32 v[38:39], v[130:131], v[38:39], v[14:15]
	v_pk_fma_f32 v[36:37], v[132:133], v[36:37], v[12:13]
	v_pk_fma_f32 v[42:43], v[134:135], v[42:43], v[18:19]
	v_pk_fma_f32 v[40:41], v[136:137], v[40:41], v[16:17]
	v_pk_fma_f32 v[46:47], v[138:139], v[46:47], v[6:7]
	v_pk_fma_f32 v[44:45], v[140:141], v[44:45], v[4:5]
	v_pk_fma_f32 v[54:55], v[142:143], v[54:55], v[10:11]
	v_pk_fma_f32 v[52:53], v[144:145], v[52:53], v[8:9]
	v_pk_fma_f32 v[58:59], v[146:147], v[58:59], v[2:3]
	v_pk_fma_f32 v[56:57], v[148:149], v[56:57], v[0:1]
	v_pk_fma_f32 v[62:63], v[150:151], v[62:63], v[30:31]
	v_pk_fma_f32 v[60:61], v[152:153], v[60:61], v[28:29]
; __device__ __forceinline__ v4u pk8(f32x4 a, f32x4 b) { v4u w; w.x = pk2(a[0], a[1]); w.y = pk2(a[2], a[3]); w.z = pk2(b[0], b[1]); w.w = pk2(b[2], b[3]); return w; }
; __device__ __forceinline__ float ssq8(const f32x4& a, const f32x4& b) { return ((a[0] * a[0] + a[1] * a[1]) + (a[2] * a[2] + a[3] * a[3])) + ((b[0] * b[0] + b[1] * b[1]) + (b[2] * b[2] + b[3] * b[3])); }
; __device__ __forceinline__ float shfl_xor_f(float v, int o) {
;     int l; asm volatile("v_mbcnt_lo_u32_b32 %0, -1, 0\n\tv_mbcnt_hi_u32_b32 %0, -1, %0" : "=v"(l));
;     return __builtin_bit_cast(float, __builtin_amdgcn_ds_bpermute((l ^ o) << 2, __builtin_bit_cast(int, v)));
; }
; __device__ __forceinline__ float wave_sum(float v) {
; #pragma unroll
;     for (int o = 1; o < 64; o <<= 1) v += shfl_xor_f(v, o);
;     return v;
; template <int XF32> __device__ __forceinline__ void norm_mod_phase(const void* x, const float* modl, int ch_shift, int ch_scale, bf16* H, int gw, int NGW, int lane) {
;     ...
;         for (int rr = 0; rr < 8; ++rr) {
;             const unsigned char* xr = (const unsigned char*)x + (size_t)(r0 + rr) * rowb; f32x4 v[4][2]; float s = 0.f;
; #pragma unroll
;             for (int j = 0; j < 4; ++j) ld_row8<XF32>(xr, lane, j, v[j][0], v[j][1]);
; #pragma unroll
;             for (int j = 0; j < 4; ++j) s += ssq8(v[j][0], v[j][1]);
;             const float rstd = 1.f / sqrtf(wave_sum(s) * (1.f / DM) + EPS);
;             v4u* o = (v4u*)(H + (size_t)(r0 + rr) * DM);
; #pragma unroll
;             for (int j = 0; j < 4; ++j) o[lane + 64 * j] = pk8(v[j][0] * rstd * sc[j][0] + sh[j][0], v[j][1] * rstd * sc[j][1] + sh[j][1]);
;         }
	v_pk_fma_f32 v[50:51], v[154:155], v[50:51], v[26:27]
	v_pk_fma_f32 v[48:49], v[156:157], v[48:49], v[24:25]
	v_cvt_pk_bf16_f32 v32, v32, v33
	v_cvt_pk_bf16_f32 v33, v34, v35
	v_cvt_pk_bf16_f32 v34, v36, v37
	v_cvt_pk_bf16_f32 v35, v38, v39
	v_cvt_pk_bf16_f32 v36, v40, v41
	v_cvt_pk_bf16_f32 v37, v42, v43
	v_cvt_pk_bf16_f32 v38, v44, v45
	v_cvt_pk_bf16_f32 v39, v46, v47
	v_cvt_pk_bf16_f32 v40, v52, v53
	v_cvt_pk_bf16_f32 v41, v54, v55
	v_cvt_pk_bf16_f32 v42, v56, v57
	v_cvt_pk_bf16_f32 v43, v58, v59
	v_cvt_pk_bf16_f32 v44, v60, v61
	v_cvt_pk_bf16_f32 v45, v62, v63
	v_cvt_pk_bf16_f32 v46, v48, v49
	v_cvt_pk_bf16_f32 v47, v50, v51
	global_store_dwordx4 v[188:189], v[32:35], off
	global_store_dwordx4 v[188:189], v[36:39], off offset:1024
	global_store_dwordx4 v[188:189], v[40:43], off offset:2048
	global_store_dwordx4 v[188:189], v[44:47], off offset:3072
	global_load_dwordx4 v[32:35], v[202:203], off
	s_nop 0
	global_load_dwordx4 v[36:39], v[202:203], off offset:16
	global_load_dwordx4 v[40:43], v[202:203], off offset:2048
	global_load_dwordx4 v[44:47], v[202:203], off offset:2064
	global_load_dwordx4 v[48:51], v[200:201], off offset:16
	global_load_dwordx4 v[52:55], v[198:199], off
	global_load_dwordx4 v[56:59], v[198:199], off offset:16
	global_load_dwordx4 v[60:63], v[200:201], off
	v_mbcnt_lo_u32_b32 v64, -1, 0
	v_mbcnt_hi_u32_b32 v64, -1, v64
	v_mbcnt_lo_u32_b32 v65, -1, 0
	v_mbcnt_hi_u32_b32 v65, -1, v65
	v_mbcnt_lo_u32_b32 v66, -1, 0
	v_mbcnt_hi_u32_b32 v66, -1, v66
	v_mbcnt_lo_u32_b32 v67, -1, 0
	v_mbcnt_hi_u32_b32 v67, -1, v67
	v_mbcnt_lo_u32_b32 v68, -1, 0
	v_mbcnt_hi_u32_b32 v68, -1, v68
	v_mbcnt_lo_u32_b32 v69, -1, 0
	v_mbcnt_hi_u32_b32 v69, -1, v69
	s_nop 0
	v_lshlrev_b32_e32 v64, 2, v64
	v_lshlrev_b32_e32 v65, 2, v65
	v_lshlrev_b32_e32 v66, 2, v66
	v_lshlrev_b32_e32 v67, 2, v67
	v_lshlrev_b32_e32 v68, 2, v68
	v_lshlrev_b32_e32 v69, 2, v69
	v_xor_b32_e32 v87, 4, v64
	v_xor_b32_e32 v90, 8, v65
	v_xor_b32_e32 v91, 16, v66
	v_xor_b32_e32 v92, 32, v67
	v_xor_b32_e32 v93, 64, v68
	v_xor_b32_e32 v94, 0x80, v69
	s_waitcnt vmcnt(7)
	v_pk_mul_f32 v[64:65], v[34:35], v[34:35]
	v_pk_mul_f32 v[66:67], v[32:33], v[32:33]
	s_waitcnt vmcnt(6)
	v_pk_mul_f32 v[68:69], v[38:39], v[38:39]
	v_pk_mul_f32 v[70:71], v[36:37], v[36:37]
	s_waitcnt vmcnt(5)
	v_pk_mul_f32 v[72:73], v[42:43], v[42:43]
	v_pk_mul_f32 v[74:75], v[40:41], v[40:41]
	s_waitcnt vmcnt(4)
	v_pk_mul_f32 v[76:77], v[46:47], v[46:47]
	v_pk_mul_f32 v[78:79], v[44:45], v[44:45]
	v_pk_mov_b32 v[88:89], v[66:67], v[64:65] op_sel:[1,0]
	v_mov_b32_e32 v67, v65
	v_pk_mov_b32 v[64:65], v[70:71], v[68:69] op_sel:[1,0]
	v_mov_b32_e32 v71, v69
	v_pk_mov_b32 v[68:69], v[74:75], v[72:73] op_sel:[1,0]
	v_mov_b32_e32 v75, v73
	v_pk_mov_b32 v[72:73], v[78:79], v[76:77] op_sel:[1,0]
	v_mov_b32_e32 v79, v77
	s_waitcnt vmcnt(2)
	v_mul_f32_e32 v80, v53, v53
	v_mul_f32_e32 v82, v55, v55
	s_waitcnt vmcnt(1)
	v_mul_f32_e32 v84, v57, v57
	v_mul_f32_e32 v86, v59, v59
	v_pk_add_f32 v[66:67], v[88:89], v[66:67]
	v_pk_add_f32 v[64:65], v[64:65], v[70:71]
	v_pk_add_f32 v[68:69], v[68:69], v[74:75]
	v_pk_add_f32 v[70:71], v[72:73], v[78:79]
	v_mul_f32_e32 v95, v48, v48
	v_mul_f32_e32 v106, v49, v49
	v_mul_f32_e32 v107, v50, v50
	v_mul_f32_e32 v108, v51, v51
	s_waitcnt vmcnt(0)
	v_mul_f32_e32 v109, v60, v60
	v_mul_f32_e32 v110, v61, v61
	v_mul_f32_e32 v111, v62, v62
	v_mul_f32_e32 v112, v63, v63
	v_pk_fma_f32 v[76:77], v[52:53], v[52:53], v[80:81] op_sel_hi:[1,1,0]
	v_pk_fma_f32 v[80:81], v[54:55], v[54:55], v[82:83] op_sel_hi:[1,1,0]
	v_pk_fma_f32 v[82:83], v[56:57], v[56:57], v[84:85] op_sel_hi:[1,1,0]
	v_pk_fma_f32 v[84:85], v[58:59], v[58:59], v[86:87] op_sel_hi:[1,1,0]
	v_pk_add_f32 v[66:67], v[66:67], v[66:67] op_sel:[0,1] op_sel_hi:[1,0]
	v_pk_add_f32 v[64:65], v[64:65], v[64:65] op_sel:[0,1] op_sel_hi:[1,0]
	v_pk_add_f32 v[68:69], v[68:69], v[68:69] op_sel:[0,1] op_sel_hi:[1,0]
	v_pk_add_f32 v[70:71], v[70:71], v[70:71] op_sel:[0,1] op_sel_hi:[1,0]
	v_mov_b32_e32 v77, v95
	v_mov_b32_e32 v81, v106
	v_mov_b32_e32 v83, v107
	v_mov_b32_e32 v85, v108
	v_mov_b32_e32 v67, v109
	v_mov_b32_e32 v65, v110
	v_mov_b32_e32 v69, v111
	v_mov_b32_e32 v71, v112
	v_pk_add_f32 v[72:73], v[76:77], v[80:81]
	v_pk_add_f32 v[74:75], v[82:83], v[84:85]
	v_pk_add_f32 v[64:65], v[66:67], v[64:65]
	v_pk_add_f32 v[66:67], v[68:69], v[70:71]
	v_pk_add_f32 v[72:73], v[72:73], v[74:75]
	v_pk_add_f32 v[64:65], v[64:65], v[66:67]
	s_nop 0
	v_pk_add_f32 v[64:65], v[64:65], v[72:73]
	s_nop 0
	v_add_f32_e32 v64, v64, v65
	s_nop 1
	v_add_f32_dpp v64, v64, v64 quad_perm:[1,0,3,2] row_mask:0xf bank_mask:0xf
	s_nop 1
	v_add_f32_dpp v64, v64, v64 quad_perm:[2,3,0,1] row_mask:0xf bank_mask:0xf
	s_nop 1
	v_add_f32_dpp v64, v64, v64 row_half_mirror row_mask:0xf bank_mask:0xf
	s_nop 1
	v_add_f32_dpp v64, v64, v64 row_mirror row_mask:0xf bank_mask:0xf
	v_mov_b32_e32 v65, v64
	s_nop 1
	v_permlane16_swap_b32_e32 v65, v64
	s_nop 1
	v_add_f32_e32 v64, v64, v65
	v_mov_b32_e32 v65, v64
	s_nop 1
	v_permlane32_swap_b32_e32 v65, v64
	s_nop 1
	v_add_f32_e32 v64, v64, v65
	v_fmamk_f32 v64, v64, 0x3a000000, v224
	v_mul_f32_e32 v65, 0x4f800000, v64
	v_cmp_gt_f32_e32 vcc, s41, v64
	s_nop 1
	v_cndmask_b32_e32 v64, v64, v65, vcc
	v_sqrt_f32_e32 v65, v64
	s_nop 0
	v_add_u32_e32 v66, -1, v65
	v_add_u32_e32 v67, 1, v65
	v_fma_f32 v68, -v66, v65, v64
	v_fma_f32 v69, -v67, v65, v64
	v_cmp_ge_f32_e64 s[4:5], 0, v68
	s_nop 1
	v_cndmask_b32_e64 v65, v65, v66, s[4:5]
	v_cmp_lt_f32_e64 s[4:5], 0, v69
	s_nop 1
	v_cndmask_b32_e64 v65, v65, v67, s[4:5]
	v_mul_f32_e32 v66, 0x37800000, v65
	v_cndmask_b32_e32 v65, v65, v66, vcc
	v_cmp_class_f32_e32 vcc, v64, v225
	s_nop 1
; __device__ __forceinline__ v4u pk8(f32x4 a, f32x4 b) { v4u w; w.x = pk2(a[0], a[1]); w.y = pk2(a[2], a[3]); w.z = pk2(b[0], b[1]); w.w = pk2(b[2], b[3]); return w; }
; __device__ __forceinline__ float ssq8(const f32x4& a, const f32x4& b) { return ((a[0] * a[0] + a[1] * a[1]) + (a[2] * a[2] + a[3] * a[3])) + ((b[0] * b[0] + b[1] * b[1]) + (b[2] * b[2] + b[3] * b[3])); }
; template <int XF32> __device__ __forceinline__ void norm_mod_phase(const void* x, const float* modl, int ch_shift, int ch_scale, bf16* H, int gw, int NGW, int lane) {
;     ...
;         for (int rr = 0; rr < 8; ++rr) {
;             const unsigned char* xr = (const unsigned char*)x + (size_t)(r0 + rr) * rowb; f32x4 v[4][2]; float s = 0.f;
; #pragma unroll
;             for (int j = 0; j < 4; ++j) ld_row8<XF32>(xr, lane, j, v[j][0], v[j][1]);
; #pragma unroll
;             for (int j = 0; j < 4; ++j) s += ssq8(v[j][0], v[j][1]);
;             const float rstd = 1.f / sqrtf(wave_sum(s) * (1.f / DM) + EPS);
;             v4u* o = (v4u*)(H + (size_t)(r0 + rr) * DM);
; #pragma unroll
;             for (int j = 0; j < 4; ++j) o[lane + 64 * j] = pk8(v[j][0] * rstd * sc[j][0] + sh[j][0], v[j][1] * rstd * sc[j][1] + sh[j][1]);
;         }
	v_cndmask_b32_e32 v64, v65, v64, vcc
	v_div_scale_f32 v65, s[2:3], v64, v64, 1.0
	v_rcp_f32_e32 v67, v65
	v_div_scale_f32 v66, vcc, 1.0, v64, 1.0
	v_fma_f32 v68, -v65, v67, 1.0
	v_fmac_f32_e32 v67, v68, v67
	v_mul_f32_e32 v68, v66, v67
	v_fma_f32 v69, -v65, v68, v66
	v_fmac_f32_e32 v68, v69, v67
	v_fma_f32 v65, -v65, v68, v66
	v_div_fmas_f32 v65, v65, v67, v68
	v_div_fixup_f32 v64, v65, v64, 1.0
	v_pk_mul_f32 v[32:33], v[32:33], v[64:65] op_sel_hi:[1,0]
	v_pk_mul_f32 v[34:35], v[34:35], v[64:65] op_sel_hi:[1,0]
	v_pk_mul_f32 v[36:37], v[36:37], v[64:65] op_sel_hi:[1,0]
	v_pk_mul_f32 v[38:39], v[38:39], v[64:65] op_sel_hi:[1,0]
	v_pk_mul_f32 v[40:41], v[40:41], v[64:65] op_sel_hi:[1,0]
	v_pk_mul_f32 v[42:43], v[42:43], v[64:65] op_sel_hi:[1,0]
	v_pk_mul_f32 v[44:45], v[44:45], v[64:65] op_sel_hi:[1,0]
	v_pk_mul_f32 v[46:47], v[46:47], v[64:65] op_sel_hi:[1,0]
	v_pk_mul_f32 v[52:53], v[52:53], v[64:65] op_sel_hi:[1,0]
	v_pk_mul_f32 v[54:55], v[54:55], v[64:65] op_sel_hi:[1,0]
	v_pk_mul_f32 v[56:57], v[56:57], v[64:65] op_sel_hi:[1,0]
	v_pk_mul_f32 v[58:59], v[58:59], v[64:65] op_sel_hi:[1,0]
	v_pk_mul_f32 v[60:61], v[60:61], v[64:65] op_sel_hi:[1,0]
	v_pk_mul_f32 v[62:63], v[62:63], v[64:65] op_sel_hi:[1,0]
	v_pk_mul_f32 v[48:49], v[48:49], v[64:65] op_sel_hi:[1,0]
	v_pk_mul_f32 v[50:51], v[50:51], v[64:65] op_sel_hi:[1,0]
	v_pk_fma_f32 v[34:35], v[126:127], v[34:35], v[22:23]
	v_pk_fma_f32 v[32:33], v[128:129], v[32:33], v[20:21]
	v_pk_fma_f32 v[38:39], v[130:131], v[38:39], v[14:15]
	v_pk_fma_f32 v[36:37], v[132:133], v[36:37], v[12:13]
	v_pk_fma_f32 v[42:43], v[134:135], v[42:43], v[18:19]
	v_pk_fma_f32 v[40:41], v[136:137], v[40:41], v[16:17]
	v_pk_fma_f32 v[46:47], v[138:139], v[46:47], v[6:7]
	v_pk_fma_f32 v[44:45], v[140:141], v[44:45], v[4:5]
	v_pk_fma_f32 v[54:55], v[142:143], v[54:55], v[10:11]
	v_pk_fma_f32 v[52:53], v[144:145], v[52:53], v[8:9]
	v_pk_fma_f32 v[58:59], v[146:147], v[58:59], v[2:3]
	v_pk_fma_f32 v[56:57], v[148:149], v[56:57], v[0:1]
	v_pk_fma_f32 v[62:63], v[150:151], v[62:63], v[30:31]
	v_pk_fma_f32 v[60:61], v[152:153], v[60:61], v[28:29]
	v_pk_fma_f32 v[50:51], v[154:155], v[50:51], v[26:27]
	v_pk_fma_f32 v[48:49], v[156:157], v[48:49], v[24:25]
	v_cvt_pk_bf16_f32 v32, v32, v33
	v_cvt_pk_bf16_f32 v33, v34, v35
	v_cvt_pk_bf16_f32 v34, v36, v37
	v_cvt_pk_bf16_f32 v35, v38, v39
	v_cvt_pk_bf16_f32 v36, v40, v41
	v_cvt_pk_bf16_f32 v37, v42, v43
	v_cvt_pk_bf16_f32 v38, v44, v45
	v_cvt_pk_bf16_f32 v39, v46, v47
	v_cvt_pk_bf16_f32 v40, v52, v53
	v_cvt_pk_bf16_f32 v41, v54, v55
	v_cvt_pk_bf16_f32 v42, v56, v57
	v_cvt_pk_bf16_f32 v43, v58, v59
	v_cvt_pk_bf16_f32 v44, v60, v61
	v_cvt_pk_bf16_f32 v45, v62, v63
	v_cvt_pk_bf16_f32 v46, v48, v49
	v_cvt_pk_bf16_f32 v47, v50, v51
	global_store_dwordx4 v[196:197], v[32:35], off
	global_store_dwordx4 v[196:197], v[36:39], off offset:1024
	global_store_dwordx4 v[196:197], v[40:43], off offset:2048
	global_store_dwordx4 v[196:197], v[44:47], off offset:3072
	global_load_dwordx4 v[60:63], v[208:209], off
	global_load_dwordx4 v[56:59], v[208:209], off offset:16
	global_load_dwordx4 v[52:55], v[208:209], off offset:2048
	s_nop 0
	global_load_dwordx4 v[44:47], v[208:209], off offset:2064
	global_load_dwordx4 v[32:35], v[206:207], off offset:16
	global_load_dwordx4 v[48:51], v[204:205], off
	global_load_dwordx4 v[40:43], v[204:205], off offset:16
	global_load_dwordx4 v[36:39], v[206:207], off
	v_mbcnt_lo_u32_b32 v64, -1, 0
	v_mbcnt_hi_u32_b32 v64, -1, v64
	v_mbcnt_lo_u32_b32 v65, -1, 0
	v_mbcnt_hi_u32_b32 v65, -1, v65
	v_mbcnt_lo_u32_b32 v66, -1, 0
	v_mbcnt_hi_u32_b32 v66, -1, v66
	v_mbcnt_lo_u32_b32 v67, -1, 0
	v_mbcnt_hi_u32_b32 v67, -1, v67
	v_mbcnt_lo_u32_b32 v68, -1, 0
	v_mbcnt_hi_u32_b32 v68, -1, v68
	v_mbcnt_lo_u32_b32 v69, -1, 0
	v_mbcnt_hi_u32_b32 v69, -1, v69
	s_nop 0
	v_lshlrev_b32_e32 v64, 2, v64
	v_lshlrev_b32_e32 v65, 2, v65
	v_lshlrev_b32_e32 v66, 2, v66
	v_lshlrev_b32_e32 v67, 2, v67
	v_lshlrev_b32_e32 v68, 2, v68
	v_lshlrev_b32_e32 v69, 2, v69
	v_xor_b32_e32 v87, 4, v64
	v_xor_b32_e32 v90, 8, v65
	v_xor_b32_e32 v91, 16, v66
	v_xor_b32_e32 v92, 32, v67
	v_xor_b32_e32 v93, 64, v68
	v_xor_b32_e32 v94, 0x80, v69
	s_waitcnt vmcnt(7)
	v_pk_mul_f32 v[64:65], v[62:63], v[62:63]
	v_pk_mul_f32 v[66:67], v[60:61], v[60:61]
	s_waitcnt vmcnt(6)
	v_pk_mul_f32 v[68:69], v[58:59], v[58:59]
	v_pk_mul_f32 v[70:71], v[56:57], v[56:57]
	s_waitcnt vmcnt(5)
	v_pk_mul_f32 v[72:73], v[54:55], v[54:55]
	v_pk_mul_f32 v[74:75], v[52:53], v[52:53]
	s_waitcnt vmcnt(4)
	v_pk_mul_f32 v[76:77], v[46:47], v[46:47]
	v_pk_mul_f32 v[78:79], v[44:45], v[44:45]
	v_pk_mov_b32 v[88:89], v[66:67], v[64:65] op_sel:[1,0]
	v_mov_b32_e32 v67, v65
	v_pk_mov_b32 v[64:65], v[70:71], v[68:69] op_sel:[1,0]
	v_mov_b32_e32 v71, v69
	v_pk_mov_b32 v[68:69], v[74:75], v[72:73] op_sel:[1,0]
	v_mov_b32_e32 v75, v73
	v_pk_mov_b32 v[72:73], v[78:79], v[76:77] op_sel:[1,0]
	v_mov_b32_e32 v79, v77
	s_waitcnt vmcnt(2)
	v_mul_f32_e32 v80, v49, v49
	v_mul_f32_e32 v82, v51, v51
	s_waitcnt vmcnt(1)
	v_mul_f32_e32 v84, v41, v41
	v_mul_f32_e32 v86, v43, v43
	v_pk_add_f32 v[66:67], v[88:89], v[66:67]
	v_pk_add_f32 v[64:65], v[64:65], v[70:71]
	v_pk_add_f32 v[68:69], v[68:69], v[74:75]
	v_pk_add_f32 v[70:71], v[72:73], v[78:79]
	v_mul_f32_e32 v95, v32, v32
	v_mul_f32_e32 v106, v33, v33
	v_mul_f32_e32 v107, v34, v34
	v_mul_f32_e32 v108, v35, v35
	s_waitcnt vmcnt(0)
; __device__ __forceinline__ v4u pk8(f32x4 a, f32x4 b) { v4u w; w.x = pk2(a[0], a[1]); w.y = pk2(a[2], a[3]); w.z = pk2(b[0], b[1]); w.w = pk2(b[2], b[3]); return w; }
; __device__ __forceinline__ float ssq8(const f32x4& a, const f32x4& b) { return ((a[0] * a[0] + a[1] * a[1]) + (a[2] * a[2] + a[3] * a[3])) + ((b[0] * b[0] + b[1] * b[1]) + (b[2] * b[2] + b[3] * b[3])); }
; __device__ __forceinline__ float shfl_xor_f(float v, int o) {
;     int l; asm volatile("v_mbcnt_lo_u32_b32 %0, -1, 0\n\tv_mbcnt_hi_u32_b32 %0, -1, %0" : "=v"(l));
;     return __builtin_bit_cast(float, __builtin_amdgcn_ds_bpermute((l ^ o) << 2, __builtin_bit_cast(int, v)));
; }
; __device__ __forceinline__ float wave_sum(float v) {
; #pragma unroll
;     for (int o = 1; o < 64; o <<= 1) v += shfl_xor_f(v, o);
;     return v;
; template <int XF32> __device__ __forceinline__ void norm_mod_phase(const void* x, const float* modl, int ch_shift, int ch_scale, bf16* H, int gw, int NGW, int lane) {
;     ...
;         for (int rr = 0; rr < 8; ++rr) {
;             const unsigned char* xr = (const unsigned char*)x + (size_t)(r0 + rr) * rowb; f32x4 v[4][2]; float s = 0.f;
; #pragma unroll
;             for (int j = 0; j < 4; ++j) ld_row8<XF32>(xr, lane, j, v[j][0], v[j][1]);
; #pragma unroll
;             for (int j = 0; j < 4; ++j) s += ssq8(v[j][0], v[j][1]);
;             const float rstd = 1.f / sqrtf(wave_sum(s) * (1.f / DM) + EPS);
;             v4u* o = (v4u*)(H + (size_t)(r0 + rr) * DM);
; #pragma unroll
;             for (int j = 0; j < 4; ++j) o[lane + 64 * j] = pk8(v[j][0] * rstd * sc[j][0] + sh[j][0], v[j][1] * rstd * sc[j][1] + sh[j][1]);
;         }
	v_mul_f32_e32 v109, v36, v36
	v_mul_f32_e32 v110, v37, v37
	v_mul_f32_e32 v111, v38, v38
	v_mul_f32_e32 v112, v39, v39
	v_pk_fma_f32 v[76:77], v[48:49], v[48:49], v[80:81] op_sel_hi:[1,1,0]
	v_pk_fma_f32 v[80:81], v[50:51], v[50:51], v[82:83] op_sel_hi:[1,1,0]
	v_pk_fma_f32 v[82:83], v[40:41], v[40:41], v[84:85] op_sel_hi:[1,1,0]
	v_pk_fma_f32 v[84:85], v[42:43], v[42:43], v[86:87] op_sel_hi:[1,1,0]
	v_pk_add_f32 v[66:67], v[66:67], v[66:67] op_sel:[0,1] op_sel_hi:[1,0]
	v_pk_add_f32 v[64:65], v[64:65], v[64:65] op_sel:[0,1] op_sel_hi:[1,0]
	v_pk_add_f32 v[68:69], v[68:69], v[68:69] op_sel:[0,1] op_sel_hi:[1,0]
	v_pk_add_f32 v[70:71], v[70:71], v[70:71] op_sel:[0,1] op_sel_hi:[1,0]
	v_mov_b32_e32 v77, v95
	v_mov_b32_e32 v81, v106
	v_mov_b32_e32 v83, v107
	v_mov_b32_e32 v85, v108
	v_mov_b32_e32 v67, v109
	v_mov_b32_e32 v65, v110
	v_mov_b32_e32 v69, v111
	v_mov_b32_e32 v71, v112
	v_pk_add_f32 v[72:73], v[76:77], v[80:81]
	v_pk_add_f32 v[74:75], v[82:83], v[84:85]
	v_pk_add_f32 v[64:65], v[66:67], v[64:65]
	v_pk_add_f32 v[66:67], v[68:69], v[70:71]
	v_pk_add_f32 v[72:73], v[72:73], v[74:75]
	v_pk_add_f32 v[64:65], v[64:65], v[66:67]
	s_nop 0
	v_pk_add_f32 v[64:65], v[64:65], v[72:73]
	s_nop 0
	v_add_f32_e32 v64, v64, v65
	s_nop 1
	v_add_f32_dpp v64, v64, v64 quad_perm:[1,0,3,2] row_mask:0xf bank_mask:0xf
	s_nop 1
	v_add_f32_dpp v64, v64, v64 quad_perm:[2,3,0,1] row_mask:0xf bank_mask:0xf
	s_nop 1
	v_add_f32_dpp v64, v64, v64 row_half_mirror row_mask:0xf bank_mask:0xf
	s_nop 1
	v_add_f32_dpp v64, v64, v64 row_mirror row_mask:0xf bank_mask:0xf
	v_mov_b32_e32 v65, v64
	s_nop 1
	v_permlane16_swap_b32_e32 v65, v64
	s_nop 1
	v_add_f32_e32 v64, v64, v65
	v_mov_b32_e32 v65, v64
	s_nop 1
	v_permlane32_swap_b32_e32 v65, v64
	s_nop 1
	v_add_f32_e32 v64, v64, v65
	v_fmamk_f32 v64, v64, 0x3a000000, v224
	v_mul_f32_e32 v65, 0x4f800000, v64
	v_cmp_gt_f32_e32 vcc, s41, v64
	s_nop 1
	v_cndmask_b32_e32 v64, v64, v65, vcc
	v_sqrt_f32_e32 v65, v64
	s_nop 0
	v_add_u32_e32 v66, -1, v65
	v_add_u32_e32 v67, 1, v65
	v_fma_f32 v68, -v66, v65, v64
	v_fma_f32 v69, -v67, v65, v64
	v_cmp_ge_f32_e64 s[4:5], 0, v68
	s_nop 1
	v_cndmask_b32_e64 v65, v65, v66, s[4:5]
	v_cmp_lt_f32_e64 s[4:5], 0, v69
	s_nop 1
	v_cndmask_b32_e64 v65, v65, v67, s[4:5]
	v_mul_f32_e32 v66, 0x37800000, v65
	v_cndmask_b32_e32 v65, v65, v66, vcc
	v_cmp_class_f32_e32 vcc, v64, v225
	s_nop 1
	v_cndmask_b32_e32 v64, v65, v64, vcc
	v_div_scale_f32 v65, s[2:3], v64, v64, 1.0
	v_rcp_f32_e32 v67, v65
	v_div_scale_f32 v66, vcc, 1.0, v64, 1.0
	v_fma_f32 v68, -v65, v67, 1.0
	v_fmac_f32_e32 v67, v68, v67
	v_mul_f32_e32 v68, v66, v67
	v_fma_f32 v69, -v65, v68, v66
	v_fmac_f32_e32 v68, v69, v67
	v_fma_f32 v65, -v65, v68, v66
	v_div_fmas_f32 v65, v65, v67, v68
	v_div_fixup_f32 v64, v65, v64, 1.0
	v_pk_mul_f32 v[60:61], v[60:61], v[64:65] op_sel_hi:[1,0]
	v_pk_mul_f32 v[62:63], v[62:63], v[64:65] op_sel_hi:[1,0]
	v_pk_mul_f32 v[56:57], v[56:57], v[64:65] op_sel_hi:[1,0]
	v_pk_mul_f32 v[58:59], v[58:59], v[64:65] op_sel_hi:[1,0]
	v_pk_mul_f32 v[52:53], v[52:53], v[64:65] op_sel_hi:[1,0]
	v_pk_mul_f32 v[54:55], v[54:55], v[64:65] op_sel_hi:[1,0]
	v_pk_mul_f32 v[44:45], v[44:45], v[64:65] op_sel_hi:[1,0]
	v_pk_mul_f32 v[46:47], v[46:47], v[64:65] op_sel_hi:[1,0]
	v_pk_mul_f32 v[48:49], v[48:49], v[64:65] op_sel_hi:[1,0]
	v_pk_mul_f32 v[50:51], v[50:51], v[64:65] op_sel_hi:[1,0]
	v_pk_mul_f32 v[40:41], v[40:41], v[64:65] op_sel_hi:[1,0]
	v_pk_mul_f32 v[42:43], v[42:43], v[64:65] op_sel_hi:[1,0]
	v_pk_mul_f32 v[36:37], v[36:37], v[64:65] op_sel_hi:[1,0]
	v_pk_mul_f32 v[38:39], v[38:39], v[64:65] op_sel_hi:[1,0]
	v_pk_mul_f32 v[32:33], v[32:33], v[64:65] op_sel_hi:[1,0]
	v_pk_mul_f32 v[34:35], v[34:35], v[64:65] op_sel_hi:[1,0]
	v_pk_fma_f32 v[22:23], v[126:127], v[62:63], v[22:23]
	v_pk_fma_f32 v[20:21], v[128:129], v[60:61], v[20:21]
	v_pk_fma_f32 v[14:15], v[130:131], v[58:59], v[14:15]
	v_pk_fma_f32 v[12:13], v[132:133], v[56:57], v[12:13]
	v_pk_fma_f32 v[18:19], v[134:135], v[54:55], v[18:19]
	v_pk_fma_f32 v[16:17], v[136:137], v[52:53], v[16:17]
	v_pk_fma_f32 v[46:47], v[138:139], v[46:47], v[6:7]
	v_pk_fma_f32 v[6:7], v[140:141], v[44:45], v[4:5]
	v_pk_fma_f32 v[10:11], v[142:143], v[50:51], v[10:11]
	v_pk_fma_f32 v[8:9], v[144:145], v[48:49], v[8:9]
	v_pk_fma_f32 v[42:43], v[146:147], v[42:43], v[2:3]
	v_pk_fma_f32 v[40:41], v[148:149], v[40:41], v[0:1]
	v_pk_fma_f32 v[30:31], v[150:151], v[38:39], v[30:31]
	v_pk_fma_f32 v[28:29], v[152:153], v[36:37], v[28:29]
	v_pk_fma_f32 v[26:27], v[154:155], v[34:35], v[26:27]
	v_pk_fma_f32 v[24:25], v[156:157], v[32:33], v[24:25]
	v_cvt_pk_bf16_f32 v0, v20, v21
	v_cvt_pk_bf16_f32 v1, v22, v23
	v_cvt_pk_bf16_f32 v2, v12, v13
	v_cvt_pk_bf16_f32 v3, v14, v15
	v_cvt_pk_bf16_f32 v4, v16, v17
	v_cvt_pk_bf16_f32 v5, v18, v19
	v_cvt_pk_bf16_f32 v6, v6, v7
	v_cvt_pk_bf16_f32 v7, v46, v47
	v_cvt_pk_bf16_f32 v8, v8, v9
	v_cvt_pk_bf16_f32 v9, v10, v11
	v_cvt_pk_bf16_f32 v10, v40, v41
	v_cvt_pk_bf16_f32 v11, v42, v43
	v_cvt_pk_bf16_f32 v12, v28, v29
	v_cvt_pk_bf16_f32 v13, v30, v31
	v_cvt_pk_bf16_f32 v14, v24, v25
	v_cvt_pk_bf16_f32 v15, v26, v27
	global_store_dwordx4 v[124:125], v[0:3], off
	global_store_dwordx4 v[124:125], v[4:7], off offset:1024
	global_store_dwordx4 v[124:125], v[8:11], off offset:2048
	global_store_dwordx4 v[124:125], v[12:15], off offset:3072
	s_cbranch_scc0 .LBB0_166

; __device__ __forceinline__ void norm_mod_fold_phase(const bf16* x, const float* modl, int ch_shift, int ch_scale, bf16* H, bf16* HE, bf16* HO, int gw, int NGW, int lane) {
;     ...
;         const int b = blk >> 9, t0 = (blk & 511) * 4;
;         const f32x4* shp = (const f32x4*)(modl + (size_t)b * MODW + ch_shift * DM); const f32x4* scp = (const f32x4*)(modl + (size_t)b * MODW + ch_scale * DM);
;         f32x4 sh[4][2], sc[4][2];
; #pragma unroll
;         for (int j = 0; j < 4; ++j)
; #pragma unroll
;             for (int q = 0; q < 2; ++q) { sh[j][q] = shp[2 * (lane + 64 * j) + q]; sc[j][q] = scp[2 * (lane + 64 * j) + q] + 1.f; }
.LBB0_407:
	s_bfe_u32 s2, s0, 0x90002
	s_lshl_b32 s9, s2, 2
	s_lshl_b32 s10, s2, 14
	s_ashr_i32 s2, s8, 9
	s_sub_i32 s18, 0x1000, s9
	s_mul_i32 s4, s2, 0x12000
	s_mul_hi_i32 s3, s2, 0x12000
	s_add_u32 s4, s24, s4
	s_addc_u32 s3, s26, s3
	s_add_u32 s6, s4, 0x6000
	s_addc_u32 s7, s3, 0
	s_add_u32 s4, s4, 0x8000
	s_addc_u32 s5, s3, 0
	v_lshl_add_u64 v[4:5], s[6:7], 0, v[62:63]
	v_lshl_add_u64 v[12:13], s[4:5], 0, v[62:63]
	global_load_dwordx4 v[0:3], v[4:5], off offset:16
	s_nop 0
	global_load_dwordx4 v[4:7], v[4:5], off
	s_nop 0
	global_load_dwordx4 v[188:191], v[12:13], off offset:16
	s_nop 0
	global_load_dwordx4 v[192:195], v[12:13], off
	v_lshl_add_u64 v[20:21], s[4:5], 0, v[64:65]
	v_lshl_add_u64 v[28:29], s[4:5], 0, v[66:67]
	v_lshl_add_u64 v[36:37], s[4:5], 0, v[68:69]
	s_lshl_b32 s19, s2, 12
	s_lshl_b32 s20, s2, 11
	s_or_b32 s2, s19, s9
	s_ashr_i32 s3, s2, 31
	s_lshl_b64 s[2:3], s[2:3], 12
	v_lshl_add_u64 v[102:103], v[60:61], 0, s[2:3]
	s_mov_b64 s[72:73], 0
	s_mov_b32 s21, 0
	v_lshl_add_u64 v[12:13], s[6:7], 0, v[64:65]
	global_load_dwordx4 v[8:11], v[12:13], off offset:16
	s_nop 0
	global_load_dwordx4 v[12:15], v[12:13], off
	s_nop 0
	global_load_dwordx4 v[196:199], v[20:21], off offset:16
	s_nop 0
	global_load_dwordx4 v[200:203], v[20:21], off
	v_lshl_add_u64 v[20:21], s[6:7], 0, v[66:67]
	global_load_dwordx4 v[16:19], v[20:21], off offset:16
	s_nop 0
	global_load_dwordx4 v[20:23], v[20:21], off
	s_nop 0
	global_load_dwordx4 v[204:207], v[28:29], off offset:16
	s_nop 0
	global_load_dwordx4 v[208:211], v[28:29], off
	v_lshl_add_u64 v[28:29], s[6:7], 0, v[68:69]
	global_load_dwordx4 v[24:27], v[28:29], off offset:16
	s_nop 0
	global_load_dwordx4 v[28:31], v[28:29], off
	s_nop 0
	global_load_dwordx4 v[212:215], v[36:37], off offset:16
	s_nop 0
	global_load_dwordx4 v[216:219], v[36:37], off
	s_waitcnt vmcnt(0)
	v_pk_add_f32 v[74:75], v[190:191], 1.0 op_sel_hi:[1,0]
	v_pk_add_f32 v[72:73], v[192:193], 1.0 op_sel_hi:[1,0]
	v_pk_add_f32 v[70:71], v[194:195], 1.0 op_sel_hi:[1,0]
	v_pk_add_f32 v[76:77], v[188:189], 1.0 op_sel_hi:[1,0]
	v_pk_add_f32 v[82:83], v[198:199], 1.0 op_sel_hi:[1,0]
	v_pk_add_f32 v[80:81], v[200:201], 1.0 op_sel_hi:[1,0]
	v_pk_add_f32 v[78:79], v[202:203], 1.0 op_sel_hi:[1,0]
	v_pk_add_f32 v[84:85], v[196:197], 1.0 op_sel_hi:[1,0]
	v_pk_add_f32 v[90:91], v[206:207], 1.0 op_sel_hi:[1,0]
	v_pk_add_f32 v[88:89], v[208:209], 1.0 op_sel_hi:[1,0]
	v_pk_add_f32 v[86:87], v[210:211], 1.0 op_sel_hi:[1,0]
	v_pk_add_f32 v[92:93], v[204:205], 1.0 op_sel_hi:[1,0]
	v_pk_add_f32 v[98:99], v[214:215], 1.0 op_sel_hi:[1,0]
	v_pk_add_f32 v[94:95], v[218:219], 1.0 op_sel_hi:[1,0]
	v_pk_add_f32 v[96:97], v[216:217], 1.0 op_sel_hi:[1,0]
	v_pk_add_f32 v[100:101], v[212:213], 1.0 op_sel_hi:[1,0]
	s_branch .LBB0_410

; __device__ __forceinline__ float ssq8(const f32x4& a, const f32x4& b) { return ((a[0] * a[0] + a[1] * a[1]) + (a[2] * a[2] + a[3] * a[3])) + ((b[0] * b[0] + b[1] * b[1]) + (b[2] * b[2] + b[3] * b[3])); }
; __device__ __forceinline__ void norm_mod_fold_phase(const bf16* x, const float* modl, int ch_shift, int ch_scale, bf16* H, bf16* HE, bf16* HO, int gw, int NGW, int lane) {
;     ...
;         for (int tt = 0; tt < 4; ++tt) {
;             const int t = t0 + tt, ra = t, rb = t ? SEQ - t : SEQ / 2;
;             const bf16* xa = x + (size_t)(b * SEQ + ra) * DM; const bf16* xb = x + (size_t)(b * SEQ + rb) * DM;
;             f32x4 va[4][2], vb[4][2]; float sa = 0.f, sb = 0.f;
; #pragma unroll
;             for (int j = 0; j < 4; ++j) { ld_row8<0>(xa, lane, j, va[j][0], va[j][1]); ld_row8<0>(xb, lane, j, vb[j][0], vb[j][1]); }
; #pragma unroll
;             for (int j = 0; j < 4; ++j) { sa += ssq8(va[j][0], va[j][1]); sb += ssq8(vb[j][0], vb[j][1]); }
.LBB0_410:
	s_add_i32 s2, s10, s72
	s_cmp_lg_u32 s2, 0
	s_cselect_b64 s[74:75], -1, 0
	s_cmp_eq_u32 s2, 0
	s_cselect_b64 s[2:3], -1, 0
	v_lshl_add_u64 v[120:121], v[102:103], 0, s[72:73]
	s_mov_b32 s6, 0x18800000
	s_and_b64 s[4:5], s[2:3], exec
	v_add_co_u32_e32 v104, vcc, s6, v120
	s_cselect_b32 s2, 0x800, s18
	s_nop 0
	v_addc_co_u32_e32 v105, vcc, 0, v121, vcc
	s_add_i32 s2, s2, s19
	global_load_dwordx4 v[122:125], v[104:105], off
	s_ashr_i32 s3, s2, 31
	s_lshl_b64 s[76:77], s[2:3], 12
	v_lshl_add_u64 v[112:113], v[52:53], 0, s[76:77]
	global_load_dwordx4 v[48:51], v[112:113], off
	global_load_dwordx4 v[44:47], v[104:105], off offset:1024
	global_load_dwordx4 v[40:43], v[112:113], off offset:1024
	global_load_dwordx4 v[36:39], v[104:105], off offset:2048
	global_load_dwordx4 v[32:35], v[112:113], off offset:2048
	s_nop 0
	global_load_dwordx4 v[104:107], v[104:105], off offset:3072
	s_waitcnt vmcnt(5)
	v_and_b32_e32 v135, 0xffff0000, v49
	global_load_dwordx4 v[126:129], v[112:113], off offset:3072
	v_and_b32_e32 v139, 0xffff0000, v123
	v_and_b32_e32 v138, 0xffff0000, v122
	v_lshlrev_b32_e32 v141, 16, v123
	v_lshlrev_b32_e32 v140, 16, v122
	v_pk_mul_f32 v[122:123], v[138:139], v[138:139]
	v_and_b32_e32 v143, 0xffff0000, v125
	v_and_b32_e32 v142, 0xffff0000, v124
	v_pk_fma_f32 v[162:163], v[140:141], v[140:141], v[122:123]
	v_lshlrev_b32_e32 v145, 16, v125
	v_lshlrev_b32_e32 v144, 16, v124
	v_pk_mul_f32 v[122:123], v[142:143], v[142:143]
	v_and_b32_e32 v134, 0xffff0000, v48
	v_pk_fma_f32 v[164:165], v[144:145], v[144:145], v[122:123]
	s_waitcnt vmcnt(4)
	v_and_b32_e32 v123, 0xffff0000, v41
	v_and_b32_e32 v122, 0xffff0000, v40
	s_waitcnt vmcnt(1)
	v_lshlrev_b32_e32 v108, 16, v104
	v_lshlrev_b32_e32 v137, 16, v49
	v_lshlrev_b32_e32 v136, 16, v48
	v_pk_mul_f32 v[48:49], v[134:135], v[134:135]
	v_lshlrev_b32_e32 v133, 16, v51
	v_lshlrev_b32_e32 v132, 16, v50
	v_and_b32_e32 v131, 0xffff0000, v51
	v_and_b32_e32 v130, 0xffff0000, v50
	v_and_b32_e32 v51, 0xffff0000, v43
	v_and_b32_e32 v50, 0xffff0000, v42
	v_and_b32_e32 v109, 0xffff0000, v104
	v_pk_fma_f32 v[158:159], v[136:137], v[136:137], v[48:49]
	v_pk_mul_f32 v[48:49], v[130:131], v[130:131]
	v_and_b32_e32 v125, 0xffff0000, v45
	v_and_b32_e32 v124, 0xffff0000, v44
	v_lshlrev_b32_e32 v146, 16, v32
	v_and_b32_e32 v147, 0xffff0000, v32
	v_lshlrev_b32_e32 v154, 16, v33
	v_and_b32_e32 v155, 0xffff0000, v33
	v_lshlrev_b32_e32 v148, 16, v34
	v_and_b32_e32 v149, 0xffff0000, v34
	v_mul_f32_e32 v34, v108, v108
	v_pk_add_f32 v[32:33], v[162:163], v[162:163] op_sel:[0,1] op_sel_hi:[1,0]
	v_pk_fma_f32 v[160:161], v[132:133], v[132:133], v[48:49]
	v_lshlrev_b32_e32 v49, 16, v45
	v_lshlrev_b32_e32 v48, 16, v44
	v_pk_mul_f32 v[44:45], v[124:125], v[124:125]
	v_lshlrev_b32_e32 v156, 16, v35
	v_and_b32_e32 v157, 0xffff0000, v35
	v_mov_b32_e32 v33, v34
	v_pk_add_f32 v[34:35], v[164:165], v[164:165] op_sel:[0,1] op_sel_hi:[1,0]
	v_lshlrev_b32_e32 v110, 16, v105
	v_pk_fma_f32 v[184:185], v[48:49], v[48:49], v[44:45]
	v_and_b32_e32 v111, 0xffff0000, v105
	v_lshlrev_b32_e32 v150, 16, v38
	v_and_b32_e32 v151, 0xffff0000, v38
	v_mul_f32_e32 v38, v111, v111
	v_lshlrev_b32_e32 v104, 16, v106
	v_and_b32_e32 v105, 0xffff0000, v106
	v_lshlrev_b32_e32 v152, 16, v39
	v_and_b32_e32 v153, 0xffff0000, v39
	v_mul_f32_e32 v39, v104, v104
	v_mul_f32_e32 v168, v105, v105
	v_lshlrev_b32_e32 v106, 16, v107
	v_and_b32_e32 v107, 0xffff0000, v107
	v_mul_f32_e32 v170, v106, v106
	v_mul_f32_e32 v171, v107, v107
	s_waitcnt vmcnt(0)
	v_lshlrev_b32_e32 v114, 16, v126
	v_and_b32_e32 v115, 0xffff0000, v126
	v_lshlrev_b32_e32 v118, 16, v127
	v_and_b32_e32 v119, 0xffff0000, v127
	v_lshlrev_b32_e32 v112, 16, v128
	v_and_b32_e32 v113, 0xffff0000, v128
	v_lshlrev_b32_e32 v116, 16, v129
	v_and_b32_e32 v117, 0xffff0000, v129
	v_lshlrev_b32_e32 v127, 16, v47
	v_lshlrev_b32_e32 v126, 16, v46
	v_and_b32_e32 v129, 0xffff0000, v47
	v_and_b32_e32 v128, 0xffff0000, v46
	v_lshlrev_b32_e32 v47, 16, v41
	v_lshlrev_b32_e32 v46, 16, v40
	v_pk_mul_f32 v[40:41], v[122:123], v[122:123]
	v_pk_mul_f32 v[44:45], v[128:129], v[128:129]
	v_pk_fma_f32 v[166:167], v[46:47], v[46:47], v[40:41]
	v_lshlrev_b32_e32 v41, 16, v43
	v_lshlrev_b32_e32 v40, 16, v42
	v_pk_mul_f32 v[42:43], v[50:51], v[50:51]
	v_pk_fma_f32 v[186:187], v[126:127], v[126:127], v[44:45]
	v_pk_fma_f32 v[182:183], v[40:41], v[40:41], v[42:43]
	v_lshlrev_b32_e32 v42, 16, v36
	v_and_b32_e32 v43, 0xffff0000, v36
	v_mul_f32_e32 v36, v109, v109
	v_mov_b32_e32 v35, v36
	v_lshlrev_b32_e32 v44, 16, v37
	v_and_b32_e32 v45, 0xffff0000, v37
	v_mul_f32_e32 v37, v110, v110
	v_pk_add_f32 v[32:33], v[32:33], v[34:35]
	v_pk_add_f32 v[34:35], v[184:185], v[184:185] op_sel:[0,1] op_sel_hi:[1,0]
	v_mul_f32_e32 v163, v113, v113
	v_mov_b32_e32 v35, v37
	v_pk_add_f32 v[36:37], v[186:187], v[186:187] op_sel:[0,1] op_sel_hi:[1,0]
	v_mul_f32_e32 v164, v116, v116
	v_mov_b32_e32 v37, v38
	v_pk_add_f32 v[34:35], v[34:35], v[36:37]
	v_mul_f32_e32 v36, v45, v45
	v_pk_add_f32 v[32:33], v[32:33], v[34:35]
	v_mul_f32_e32 v34, v43, v43
	v_pk_fma_f32 v[34:35], v[42:43], v[42:43], v[34:35] op_sel_hi:[1,1,0]
	v_pk_fma_f32 v[36:37], v[44:45], v[44:45], v[36:37] op_sel_hi:[1,1,0]
	v_mov_b32_e32 v35, v39
	v_mov_b32_e32 v37, v168
	v_pk_add_f32 v[34:35], v[34:35], v[36:37]
	v_mul_f32_e32 v36, v151, v151
	v_mul_f32_e32 v38, v153, v153
	v_pk_fma_f32 v[36:37], v[150:151], v[150:151], v[36:37] op_sel_hi:[1,1,0]
	v_pk_fma_f32 v[38:39], v[152:153], v[152:153], v[38:39] op_sel_hi:[1,1,0]
	v_mov_b32_e32 v37, v170
	v_mov_b32_e32 v39, v171
	v_pk_add_f32 v[36:37], v[36:37], v[38:39]
	v_mul_f32_e32 v38, v119, v119
	v_pk_add_f32 v[34:35], v[34:35], v[36:37]
; __device__ __forceinline__ float ssq8(const f32x4& a, const f32x4& b) { return ((a[0] * a[0] + a[1] * a[1]) + (a[2] * a[2] + a[3] * a[3])) + ((b[0] * b[0] + b[1] * b[1]) + (b[2] * b[2] + b[3] * b[3])); }
; __device__ __forceinline__ float shfl_xor_f(float v, int o) {
;     int l; asm volatile("v_mbcnt_lo_u32_b32 %0, -1, 0\n\tv_mbcnt_hi_u32_b32 %0, -1, %0" : "=v"(l));
;     return __builtin_bit_cast(float, __builtin_amdgcn_ds_bpermute((l ^ o) << 2, __builtin_bit_cast(int, v)));
; }
; __device__ __forceinline__ float wave_sum(float v) {
; #pragma unroll
;     for (int o = 1; o < 64; o <<= 1) v += shfl_xor_f(v, o);
;     return v;
; __device__ __forceinline__ void norm_mod_fold_phase(const bf16* x, const float* modl, int ch_shift, int ch_scale, bf16* H, bf16* HE, bf16* HO, int gw, int NGW, int lane) {
;     ...
;             for (int j = 0; j < 4; ++j) { sa += ssq8(va[j][0], va[j][1]); sb += ssq8(vb[j][0], vb[j][1]); }
;             const float ra_ = 1.f / sqrtf(wave_sum(sa) * (1.f / DM) + EPS), rb_ = 1.f / sqrtf(wave_sum(sb) * (1.f / DM) + EPS);
	v_mul_f32_e32 v36, v115, v115
	v_pk_add_f32 v[32:33], v[32:33], v[34:35]
	v_mul_f32_e32 v34, v114, v114
	v_add_f32_e32 v162, v32, v33
	v_pk_add_f32 v[32:33], v[158:159], v[158:159] op_sel:[0,1] op_sel_hi:[1,0]
	v_mul_f32_e32 v37, v118, v118
	v_mov_b32_e32 v33, v34
	v_pk_add_f32 v[34:35], v[160:161], v[160:161] op_sel:[0,1] op_sel_hi:[1,0]
	v_mul_f32_e32 v39, v112, v112
	v_mov_b32_e32 v35, v36
	v_pk_add_f32 v[32:33], v[32:33], v[34:35]
	v_pk_add_f32 v[34:35], v[166:167], v[166:167] op_sel:[0,1] op_sel_hi:[1,0]
	v_mul_f32_e32 v165, v117, v117
	v_mov_b32_e32 v35, v37
	v_pk_add_f32 v[36:37], v[182:183], v[182:183] op_sel:[0,1] op_sel_hi:[1,0]
	s_nop 0
	v_mov_b32_e32 v37, v38
	v_pk_add_f32 v[34:35], v[34:35], v[36:37]
	v_mul_f32_e32 v36, v155, v155
	v_pk_add_f32 v[32:33], v[32:33], v[34:35]
	v_mul_f32_e32 v34, v147, v147
	v_pk_fma_f32 v[34:35], v[146:147], v[146:147], v[34:35] op_sel_hi:[1,1,0]
	v_pk_fma_f32 v[36:37], v[154:155], v[154:155], v[36:37] op_sel_hi:[1,1,0]
	v_mov_b32_e32 v35, v39
	v_mov_b32_e32 v37, v163
	v_pk_add_f32 v[34:35], v[34:35], v[36:37]
	v_mul_f32_e32 v36, v149, v149
	v_mul_f32_e32 v38, v157, v157
	v_pk_fma_f32 v[36:37], v[148:149], v[148:149], v[36:37] op_sel_hi:[1,1,0]
	v_pk_fma_f32 v[38:39], v[156:157], v[156:157], v[38:39] op_sel_hi:[1,1,0]
	v_mov_b32_e32 v37, v164
	v_mov_b32_e32 v39, v165
	v_pk_add_f32 v[36:37], v[36:37], v[38:39]
	s_nop 0
	v_pk_add_f32 v[34:35], v[34:35], v[36:37]
	s_nop 0
	v_pk_add_f32 v[32:33], v[32:33], v[34:35]
	s_nop 0
	v_add_f32_e32 v32, v32, v33
	v_mbcnt_lo_u32_b32 v33, -1, 0
	v_mbcnt_hi_u32_b32 v33, -1, v33
	v_mbcnt_lo_u32_b32 v34, -1, 0
	v_mbcnt_hi_u32_b32 v34, -1, v34
	s_nop 0
	v_lshlrev_b32_e32 v33, 2, v33
	v_xor_b32_e32 v33, 4, v33
	ds_bpermute_b32 v33, v33, v162
	v_lshlrev_b32_e32 v34, 2, v34
	v_xor_b32_e32 v34, 8, v34
	s_waitcnt lgkmcnt(0)
	v_add_f32_e32 v33, v162, v33
	ds_bpermute_b32 v34, v34, v33
	s_waitcnt lgkmcnt(0)
	v_add_f32_e32 v33, v33, v34
	v_mbcnt_lo_u32_b32 v34, -1, 0
	v_mbcnt_hi_u32_b32 v34, -1, v34
	s_nop 0
	v_lshlrev_b32_e32 v34, 2, v34
	v_xor_b32_e32 v34, 16, v34
	ds_bpermute_b32 v34, v34, v33
	s_waitcnt lgkmcnt(0)
	v_add_f32_e32 v33, v33, v34
	v_mbcnt_lo_u32_b32 v34, -1, 0
	v_mbcnt_hi_u32_b32 v34, -1, v34
	s_nop 0
	v_lshlrev_b32_e32 v34, 2, v34
	v_xor_b32_e32 v34, 32, v34
	ds_bpermute_b32 v34, v34, v33
	s_waitcnt lgkmcnt(0)
	v_add_f32_e32 v33, v33, v34
	v_mbcnt_lo_u32_b32 v34, -1, 0
	v_mbcnt_hi_u32_b32 v34, -1, v34
	s_nop 0
	v_lshlrev_b32_e32 v34, 2, v34
	v_xor_b32_e32 v34, 64, v34
	ds_bpermute_b32 v34, v34, v33
	s_waitcnt lgkmcnt(0)
	v_add_f32_e32 v33, v33, v34
	v_mbcnt_lo_u32_b32 v34, -1, 0
	v_mbcnt_hi_u32_b32 v34, -1, v34
	s_nop 0
	v_lshlrev_b32_e32 v34, 2, v34
	v_xor_b32_e32 v34, 0x80, v34
	ds_bpermute_b32 v34, v34, v33
	s_waitcnt lgkmcnt(0)
; __device__ __forceinline__ v4u pk8(f32x4 a, f32x4 b) { v4u w; w.x = pk2(a[0], a[1]); w.y = pk2(a[2], a[3]); w.z = pk2(b[0], b[1]); w.w = pk2(b[2], b[3]); return w; }
; __device__ __forceinline__ void norm_mod_fold_phase(const bf16* x, const float* modl, int ch_shift, int ch_scale, bf16* H, bf16* HE, bf16* HO, int gw, int NGW, int lane) {
;     ...
;             const float ra_ = 1.f / sqrtf(wave_sum(sa) * (1.f / DM) + EPS), rb_ = 1.f / sqrtf(wave_sum(sb) * (1.f / DM) + EPS);
;             v4u* oa = (v4u*)(H + (size_t)(b * SEQ + ra) * DM); v4u* ob = (v4u*)(H + (size_t)(b * SEQ + rb) * DM);
;             const int fr_ = b * 2048 + (t & 1) * 1024 + (t >> 1);
;             v4u* oe = (v4u*)(HE + (size_t)fr_ * DM); v4u* oo = (v4u*)(HO + (size_t)fr_ * DM);
;             const f32x4 z4 = {0.f, 0.f, 0.f, 0.f};
; #pragma unroll
;             for (int j = 0; j < 4; ++j) { const f32x4 ya0 = va[j][0] * ra_ * sc[j][0] + sh[j][0], ya1 = va[j][1] * ra_ * sc[j][1] + sh[j][1], yb0 = vb[j][0] * rb_ * sc[j][0] + sh[j][0], yb1 = vb[j][1] * rb_ * sc[j][1] + sh[j][1];
;                 oa[lane + 64 * j] = pk8(ya0, ya1); ob[lane + 64 * j] = pk8(yb0, yb1);
;                 oe[lane + 64 * j] = t ? pk8(ya0 + yb0, ya1 + yb1) : pk8(ya0, ya1);
;                 oo[lane + 64 * j] = t ? pk8(ya0 - yb0, ya1 - yb1) : pk8(z4, z4); }
	v_add_f32_e32 v33, v33, v34
	v_fmamk_f32 v33, v33, 0x3a000000, v224
	v_cmp_gt_f32_e32 vcc, s41, v33
	v_mul_f32_e32 v34, 0x4f800000, v33
	s_nop 0
	v_cndmask_b32_e32 v33, v33, v34, vcc
	v_sqrt_f32_e32 v34, v33
	s_nop 0
	v_add_u32_e32 v35, -1, v34
	v_fma_f32 v36, -v35, v34, v33
	v_cmp_ge_f32_e64 s[6:7], 0, v36
	v_add_u32_e32 v36, 1, v34
	s_nop 0
	v_cndmask_b32_e64 v35, v34, v35, s[6:7]
	v_fma_f32 v34, -v36, v34, v33
	v_cmp_lt_f32_e64 s[6:7], 0, v34
	s_nop 1
	v_cndmask_b32_e64 v34, v35, v36, s[6:7]
	v_mul_f32_e32 v35, 0x37800000, v34
	v_cndmask_b32_e32 v34, v34, v35, vcc
	v_cmp_class_f32_e32 vcc, v33, v225
	s_nop 1
	v_cndmask_b32_e32 v33, v34, v33, vcc
	v_div_scale_f32 v34, s[2:3], v33, v33, 1.0
	v_rcp_f32_e32 v35, v34
	s_nop 0
	v_fma_f32 v36, -v34, v35, 1.0
	v_fmac_f32_e32 v35, v36, v35
	v_div_scale_f32 v36, vcc, 1.0, v33, 1.0
	v_mul_f32_e32 v37, v36, v35
	v_fma_f32 v38, -v34, v37, v36
	v_fmac_f32_e32 v37, v38, v35
	v_fma_f32 v34, -v34, v37, v36
	v_div_fmas_f32 v34, v34, v35, v37
	v_div_fixup_f32 v158, v34, v33, 1.0
	s_nop 1
	v_add_f32_dpp v32, v32, v32 quad_perm:[1,0,3,2] row_mask:0xf bank_mask:0xf
	s_nop 1
	v_add_f32_dpp v32, v32, v32 quad_perm:[2,3,0,1] row_mask:0xf bank_mask:0xf
	s_nop 1
	v_add_f32_dpp v32, v32, v32 row_half_mirror row_mask:0xf bank_mask:0xf
	s_nop 1
	v_add_f32_dpp v32, v32, v32 row_mirror row_mask:0xf bank_mask:0xf
	v_mov_b32_e32 v33, v32
	s_nop 1
	v_permlane16_swap_b32_e32 v33, v32
	s_nop 1
	v_add_f32_e32 v32, v32, v33
	v_mov_b32_e32 v33, v32
	s_nop 1
	v_permlane32_swap_b32_e32 v33, v32
	s_nop 1
	v_add_f32_e32 v32, v32, v33
	v_fmamk_f32 v32, v32, 0x3a000000, v224
	v_cmp_gt_f32_e32 vcc, s41, v32
	v_mul_f32_e32 v33, 0x4f800000, v32
	s_nop 0
	v_cndmask_b32_e32 v32, v32, v33, vcc
	v_sqrt_f32_e32 v33, v32
	s_nop 0
	v_add_u32_e32 v34, -1, v33
	v_fma_f32 v35, -v34, v33, v32
	v_cmp_ge_f32_e64 s[6:7], 0, v35
	v_add_u32_e32 v35, 1, v33
	s_nop 0
	v_cndmask_b32_e64 v34, v33, v34, s[6:7]
	v_fma_f32 v33, -v35, v33, v32
	v_cmp_lt_f32_e64 s[6:7], 0, v33
	s_nop 1
	v_cndmask_b32_e64 v33, v34, v35, s[6:7]
	v_mul_f32_e32 v34, 0x37800000, v33
	v_cndmask_b32_e32 v33, v33, v34, vcc
	v_cmp_class_f32_e32 vcc, v32, v225
	s_nop 1
	v_cndmask_b32_e32 v32, v33, v32, vcc
	v_div_scale_f32 v33, s[2:3], v32, v32, 1.0
	v_rcp_f32_e32 v34, v33
	s_mov_b32 s2, 0x20800000
	v_fma_f32 v35, -v33, v34, 1.0
	v_fmac_f32_e32 v34, v35, v34
	v_div_scale_f32 v35, vcc, 1.0, v32, 1.0
	v_mul_f32_e32 v36, v35, v34
	v_fma_f32 v37, -v33, v36, v35
	v_fmac_f32_e32 v36, v37, v34
	v_fma_f32 v33, -v33, v36, v35
	v_div_fmas_f32 v33, v33, v34, v36
	v_div_fixup_f32 v160, v33, v32, 1.0
	v_mov_b32_e32 v32, v140
	v_mov_b32_e32 v33, v138
	v_pk_mul_f32 v[32:33], v[158:159], v[32:33] op_sel_hi:[0,1]
	v_pk_fma_f32 v[36:37], v[72:73], v[32:33], v[4:5]
	v_mov_b32_e32 v32, v144
	v_mov_b32_e32 v33, v142
	v_mov_b32_e32 v138, v141
	v_pk_mul_f32 v[32:33], v[158:159], v[32:33] op_sel_hi:[0,1]
	v_pk_mul_f32 v[34:35], v[158:159], v[138:139] op_sel_hi:[0,1]
	v_mov_b32_e32 v142, v145
	v_pk_fma_f32 v[138:139], v[76:77], v[32:33], v[0:1]
	v_mov_b32_e32 v32, v136
	v_mov_b32_e32 v33, v134
	v_pk_fma_f32 v[38:39], v[70:71], v[34:35], v[6:7]
	v_pk_mul_f32 v[34:35], v[158:159], v[142:143] op_sel_hi:[0,1]
	v_pk_mul_f32 v[32:33], v[160:161], v[32:33] op_sel_hi:[0,1]
	v_mov_b32_e32 v134, v137
	v_pk_fma_f32 v[140:141], v[74:75], v[34:35], v[2:3]
	v_pk_mul_f32 v[34:35], v[160:161], v[134:135] op_sel_hi:[0,1]
	v_pk_fma_f32 v[134:135], v[72:73], v[32:33], v[4:5]
	v_mov_b32_e32 v32, v132
	v_mov_b32_e32 v33, v130
	v_mov_b32_e32 v130, v133
	v_pk_fma_f32 v[136:137], v[70:71], v[34:35], v[6:7]
	v_pk_mul_f32 v[32:33], v[160:161], v[32:33] op_sel_hi:[0,1]
	v_pk_mul_f32 v[34:35], v[160:161], v[130:131] op_sel_hi:[0,1]
	v_add_co_u32_e32 v120, vcc, s2, v120
	v_pk_fma_f32 v[142:143], v[74:75], v[34:35], v[2:3]
	v_pk_fma_f32 v[132:133], v[76:77], v[32:33], v[0:1]
	v_addc_co_u32_e32 v121, vcc, 0, v121, vcc
	v_cvt_pk_bf16_f32 v32, v36, v37
	v_cvt_pk_bf16_f32 v33, v38, v39
	v_cvt_pk_bf16_f32 v34, v138, v139
	v_cvt_pk_bf16_f32 v35, v140, v141
	v_cvt_pk_bf16_f32 v162, v134, v135
	v_cvt_pk_bf16_f32 v163, v136, v137
	v_cvt_pk_bf16_f32 v164, v132, v133
	v_cvt_pk_bf16_f32 v165, v142, v143
	v_lshl_add_u64 v[130:131], v[54:55], 0, s[76:77]
	s_mov_b64 vcc, s[4:5]
	global_store_dwordx4 v[120:121], v[32:35], off
	global_store_dwordx4 v[130:131], v[162:165], off
	s_cbranch_vccnz .LBB0_412
	v_pk_add_f32 v[34:35], v[38:39], v[136:137]
	v_pk_add_f32 v[32:33], v[36:37], v[134:135]
	v_pk_add_f32 v[144:145], v[140:141], v[142:143]
	v_pk_add_f32 v[162:163], v[138:139], v[132:133]
	v_sub_f32_e32 v39, v39, v137
	v_sub_f32_e32 v38, v38, v136
	v_sub_f32_e32 v37, v37, v135
	v_sub_f32_e32 v36, v36, v134
	v_sub_f32_e32 v134, v141, v143
	v_sub_f32_e32 v135, v140, v142
	v_sub_f32_e32 v133, v139, v133
	v_sub_f32_e32 v132, v138, v132
	v_cvt_pk_bf16_f32 v32, v32, v33
	v_cvt_pk_bf16_f32 v33, v34, v35
	v_cvt_pk_bf16_f32 v34, v162, v163
	v_cvt_pk_bf16_f32 v35, v144, v145
	v_cvt_pk_bf16_f32 v36, v36, v37
	v_cvt_pk_bf16_f32 v37, v38, v39
	v_cvt_pk_bf16_f32 v38, v132, v133
	v_cvt_pk_bf16_f32 v39, v135, v134
	s_branch .LBB0_413

; __device__ __forceinline__ void nyq_phase(const bf16* H, const bf16* WfT, float* nyq, int gw, int NGW, int lane) {
;     for (int ch = gw; ch < 1024; ch += NGW) {
;         const v4u* wp = (const v4u*)(WfT + (size_t)ch * DM) + lane; v4u wv[4];
; #pragma unroll
;         for (int j = 0; j < 4; ++j) wv[j] = wp[64 * j];
; #pragma unroll
;         for (int b = 0; b < 4; ++b) { const v4u* hp = (const v4u*)(H + (size_t)(b * SEQ + SEQ / 2) * DM) + lane; float s = 0.f;
; #pragma unroll
;             for (int j = 0; j < 4; ++j) { const v4u hv = hp[64 * j];
; #pragma unroll
;                 for (int e = 0; e < 4; ++e) s += bflo(wv[j][e]) * bflo(hv[e]) + bfhi(wv[j][e]) * bfhi(hv[e]); }
;             s = wave_sum(s); if (lane == 0) nyq[b * 1024 + ch] = s; }
.LBB0_524:
	s_waitcnt lgkmcnt(0)
	v_lshl_add_u64 v[0:1], v[16:17], 0, s[60:61]
	global_load_dwordx4 v[22:25], v[0:1], off offset:-2048
	global_load_dwordx4 v[30:33], v[0:1], off offset:-1024
	global_load_dwordx4 v[4:7], v[0:1], off
	s_nop 0
	global_load_dwordx4 v[0:3], v[0:1], off offset:1024
	s_nop 0
	global_load_dwordx4 v[26:29], v[8:9], off
	global_load_dwordx4 v[34:37], v[8:9], off offset:1024
	global_load_dwordx4 v[40:43], v[8:9], off offset:2048
	global_load_dwordx4 v[48:51], v[8:9], off offset:3072
	global_load_dwordx4 v[52:55], v[10:11], off
	global_load_dwordx4 v[56:59], v[10:11], off offset:1024
	global_load_dwordx4 v[60:63], v[10:11], off offset:2048
	global_load_dwordx4 v[64:67], v[10:11], off offset:3072
	global_load_dwordx4 v[68:71], v[12:13], off
	global_load_dwordx4 v[72:75], v[12:13], off offset:1024
	global_load_dwordx4 v[76:79], v[12:13], off offset:2048
	global_load_dwordx4 v[80:83], v[12:13], off offset:3072
	global_load_dwordx4 v[84:87], v[14:15], off
	global_load_dwordx4 v[88:91], v[14:15], off offset:1024
	global_load_dwordx4 v[92:95], v[14:15], off offset:2048
	global_load_dwordx4 v[96:99], v[14:15], off offset:3072
	s_waitcnt vmcnt(13)
	v_and_b32_e32 v20, 0xffff0000, v22
	v_lshlrev_b32_e32 v18, 16, v22
	v_and_b32_e32 v22, 0xffff0000, v23
	v_and_b32_e32 v38, 0xffff0000, v5
	v_and_b32_e32 v21, 0xffff0000, v26
	v_lshlrev_b32_e32 v19, 16, v26
	v_mul_f32_e32 v21, v20, v21
	v_fmac_f32_e32 v21, v18, v19
	v_lshlrev_b32_e32 v19, 16, v23
	v_and_b32_e32 v23, 0xffff0000, v27
	v_lshlrev_b32_e32 v26, 16, v27
	v_mul_f32_e32 v23, v22, v23
	v_add_f32_e32 v21, 0, v21
	v_fmac_f32_e32 v23, v19, v26
	v_add_f32_e32 v23, v23, v21
	v_lshlrev_b32_e32 v21, 16, v24
	v_and_b32_e32 v24, 0xffff0000, v24
	v_and_b32_e32 v27, 0xffff0000, v28
	v_lshlrev_b32_e32 v26, 16, v28
	v_mul_f32_e32 v27, v24, v27
	v_fmac_f32_e32 v27, v21, v26
	v_add_f32_e32 v26, v27, v23
	v_lshlrev_b32_e32 v23, 16, v25
	v_and_b32_e32 v25, 0xffff0000, v25
	v_and_b32_e32 v28, 0xffff0000, v29
	v_lshlrev_b32_e32 v27, 16, v29
	v_mul_f32_e32 v28, v25, v28
	v_fmac_f32_e32 v28, v23, v27
	v_add_f32_e32 v27, v28, v26
	v_lshlrev_b32_e32 v26, 16, v30
	v_and_b32_e32 v28, 0xffff0000, v30
	v_and_b32_e32 v30, 0xffff0000, v34
	v_lshlrev_b32_e32 v29, 16, v34
	v_mul_f32_e32 v30, v28, v30
	v_fmac_f32_e32 v30, v26, v29
	v_add_f32_e32 v29, v30, v27
	v_lshlrev_b32_e32 v27, 16, v31
	v_and_b32_e32 v30, 0xffff0000, v31
	v_and_b32_e32 v31, 0xffff0000, v35
	v_lshlrev_b32_e32 v34, 16, v35
	v_mul_f32_e32 v31, v30, v31
	v_fmac_f32_e32 v31, v27, v34
	v_add_f32_e32 v31, v31, v29
	v_lshlrev_b32_e32 v29, 16, v32
	v_and_b32_e32 v32, 0xffff0000, v32
	v_and_b32_e32 v35, 0xffff0000, v36
	v_lshlrev_b32_e32 v34, 16, v36
	v_mul_f32_e32 v35, v32, v35
	v_fmac_f32_e32 v35, v29, v34
	v_add_f32_e32 v34, v35, v31
	v_lshlrev_b32_e32 v31, 16, v33
	v_and_b32_e32 v33, 0xffff0000, v33
	v_and_b32_e32 v36, 0xffff0000, v37
	v_lshlrev_b32_e32 v35, 16, v37
	v_mul_f32_e32 v36, v33, v36
	v_fmac_f32_e32 v36, v31, v35
	v_add_f32_e32 v35, v36, v34
	v_lshlrev_b32_e32 v34, 16, v4
	v_and_b32_e32 v36, 0xffff0000, v4
	v_and_b32_e32 v4, 0xffff0000, v40
	v_lshlrev_b32_e32 v37, 16, v40
	v_mul_f32_e32 v4, v36, v4
	v_fmac_f32_e32 v4, v34, v37
	v_add_f32_e32 v4, v4, v35
	v_lshlrev_b32_e32 v35, 16, v5
	v_and_b32_e32 v5, 0xffff0000, v41
	v_lshlrev_b32_e32 v37, 16, v41
	v_mul_f32_e32 v5, v38, v5
	v_fmac_f32_e32 v5, v35, v37
	v_lshlrev_b32_e32 v37, 16, v6
	v_and_b32_e32 v40, 0xffff0000, v6
	v_and_b32_e32 v6, 0xffff0000, v42
	v_add_f32_e32 v4, v5, v4
	v_lshlrev_b32_e32 v5, 16, v42
	v_mul_f32_e32 v6, v40, v6
	v_fmac_f32_e32 v6, v37, v5
	v_add_f32_e32 v4, v6, v4
	v_and_b32_e32 v41, 0xffff0000, v7
	v_and_b32_e32 v6, 0xffff0000, v43
	v_lshlrev_b32_e32 v39, 16, v7
	v_lshlrev_b32_e32 v5, 16, v43
	v_mul_f32_e32 v6, v41, v6
	v_fmac_f32_e32 v6, v39, v5
	v_add_f32_e32 v43, v6, v4
	v_lshlrev_b32_e32 v42, 16, v0
	v_and_b32_e32 v0, 0xffff0000, v0
	s_waitcnt vmcnt(12)
	v_lshlrev_b32_e32 v44, 16, v48
	v_and_b32_e32 v4, 0xffff0000, v48
	v_mul_f32_e32 v4, v0, v4
	v_fmac_f32_e32 v4, v42, v44
	v_add_f32_e32 v43, v4, v43
	v_lshlrev_b32_e32 v4, 16, v1
	v_lshlrev_b32_e32 v44, 16, v49
	v_and_b32_e32 v1, 0xffff0000, v1
	v_and_b32_e32 v5, 0xffff0000, v49
	v_mul_f32_e32 v5, v1, v5
	v_fmac_f32_e32 v5, v4, v44
	v_add_f32_e32 v43, v5, v43
	v_lshlrev_b32_e32 v5, 16, v2
	v_lshlrev_b32_e32 v44, 16, v50
	v_and_b32_e32 v2, 0xffff0000, v2
	v_and_b32_e32 v6, 0xffff0000, v50
	v_mul_f32_e32 v6, v2, v6
	v_fmac_f32_e32 v6, v5, v44
	v_add_f32_e32 v43, v6, v43
	v_lshlrev_b32_e32 v6, 16, v3
	v_lshlrev_b32_e32 v44, 16, v51
	v_and_b32_e32 v3, 0xffff0000, v3
	v_and_b32_e32 v7, 0xffff0000, v51
	v_mul_f32_e32 v7, v3, v7
	v_fmac_f32_e32 v7, v6, v44
	v_add_f32_e32 v7, v7, v43
	s_nop 1
	v_add_f32_dpp v7, v7, v7 quad_perm:[1,0,3,2] row_mask:0xf bank_mask:0xf
	s_nop 1
	v_add_f32_dpp v7, v7, v7 quad_perm:[2,3,0,1] row_mask:0xf bank_mask:0xf
	s_nop 1
	v_add_f32_dpp v7, v7, v7 row_half_mirror row_mask:0xf bank_mask:0xf
	s_nop 1
	v_add_f32_dpp v7, v7, v7 row_mirror row_mask:0xf bank_mask:0xf
	v_mov_b32_e32 v43, v7
	s_nop 1
	v_permlane16_swap_b32_e32 v43, v7
	s_nop 1
	v_add_f32_e32 v7, v7, v43
	v_mov_b32_e32 v43, v7
	s_nop 1
	v_permlane32_swap_b32_e32 v43, v7
	s_nop 1
	s_and_saveexec_b64 s[70:71], vcc
	s_cbranch_execz .LBB0_526
	s_add_u32 s2, s0, s60
	s_waitcnt lgkmcnt(0)
	v_add_f32_e32 v7, v7, v43
	s_addc_u32 s3, s1, 0
	v_mov_b32_e32 v43, 0x780000
	global_store_dword v43, v7, s[2:3]

; __device__ __forceinline__ void ld16(const unsigned short* p, f32x4 (&v)[4]) { const v4u a = ((const v4u*)p)[0], b = ((const v4u*)p)[1]; v[0] = uph4(a.x, a.y); v[1] = uph4(a.z, a.w); v[2] = uph4(b.x, b.y); v[3] = uph4(b.z, b.w); }
; __device__ __forceinline__ void combine_phase(const unsigned short* PQ4, const float* nyq, const float* yE, const float* yO, const bf16* OP, const float* LSE, bf16* Y, int gw, int NGW, int lane) {
;     for (int t = gw; t < BATCH * 1025; t += NGW) {
;         const int b = t / 1025, k = t - b * 1025;
;         f32x4 ep[4], op[4], eq[4], oq[4], n[4];
;         const float sg = (k & 1) ? -1.f / 64.f : 1.f / 64.f;
; #pragma unroll
;         for (int q = 0; q < 4; ++q) n[q] = *(const f32x4*)(nyq + b * 1024 + 16 * lane + 4 * q) * sg;
;         if (k < 1024) { const size_t off = (size_t)k * 4096 + b * 1024 + 16 * lane;
;             ld16(PQ4 + off, ep); ld16(PQ4 + (size_t)1024 * 4096 + off, op); ld16(PQ4 + (size_t)2 * 1024 * 4096 + off, eq); ld16(PQ4 + (size_t)3 * 1024 * 4096 + off, oq);
;         } else {
; #pragma unroll
;             for (int q = 0; q < 4; ++q) { ep[q] = *(const f32x4*)(yE + b * 1024 + 16 * lane + 4 * q); oq[q] = *(const f32x4*)(yO + b * 1024 + 16 * lane + 4 * q); op[q] = (f32x4){0.f, 0.f, 0.f, 0.f}; eq[q] = op[q]; } }
;         f32x4 y[4];
; #pragma unroll
;         for (int q = 0; q < 4; ++q) y[q] = (ep[q] + op[q]) - (eq[q] + oq[q]) + n[q];
;         st_row_norm(Y, b * SEQ + k, lane, y);
.LBB0_776:
	s_bitcmp0_b32 s72, 0
	s_cselect_b64 vcc, -1, 0
	v_mov_b32_e32 v90, 0xbc800000
	v_mov_b32_e32 v91, 0x3c800000
	v_cndmask_b32_e32 v124, v90, v91, vcc
	s_waitcnt vmcnt(7)
	v_pk_add_f32 v[90:91], v[70:71], v[12:13]
	v_pk_add_f32 v[92:93], v[74:75], v[14:15]
	s_waitcnt vmcnt(0)
	v_pk_add_f32 v[94:95], v[86:87], v[28:29]
	v_pk_add_f32 v[96:97], v[88:89], v[30:31]
	v_sub_f32_e32 v101, v91, v95
	v_sub_f32_e32 v99, v93, v97
	v_sub_f32_e32 v98, v92, v96
	v_sub_f32_e32 v100, v90, v94
	v_pk_fma_f32 v[126:127], v[44:45], v[124:125], v[100:101] op_sel_hi:[1,0,1]
	v_pk_fma_f32 v[128:129], v[46:47], v[124:125], v[98:99] op_sel_hi:[1,0,1]
	v_pk_add_f32 v[100:101], v[68:69], v[10:11]
	v_pk_add_f32 v[104:105], v[84:85], v[26:27]
	v_pk_add_f32 v[98:99], v[66:67], v[8:9]
	v_pk_add_f32 v[102:103], v[82:83], v[24:25]
	v_sub_f32_e32 v107, v101, v105
	v_sub_f32_e32 v106, v100, v104
	v_pk_mul_f32 v[142:143], v[128:129], v[128:129]
	v_pk_mul_f32 v[144:145], v[126:127], v[126:127]
	v_sub_f32_e32 v109, v99, v103
	v_sub_f32_e32 v108, v98, v102
	v_pk_fma_f32 v[132:133], v[42:43], v[124:125], v[106:107] op_sel_hi:[1,0,1]
	v_pk_add_f32 v[106:107], v[62:63], v[4:5]
	v_pk_add_f32 v[110:111], v[78:79], v[20:21]
	v_pk_mov_b32 v[146:147], v[144:145], v[142:143] op_sel:[1,0]
	v_mov_b32_e32 v145, v143
	v_pk_fma_f32 v[130:131], v[40:41], v[124:125], v[108:109] op_sel_hi:[1,0,1]
	v_pk_add_f32 v[108:109], v[64:65], v[6:7]
	v_pk_add_f32 v[112:113], v[80:81], v[22:23]
	v_sub_f32_e32 v115, v107, v111
	v_sub_f32_e32 v114, v106, v110
	v_pk_add_f32 v[142:143], v[146:147], v[144:145]
	v_sub_f32_e32 v117, v109, v113
	v_sub_f32_e32 v116, v108, v112
	v_pk_fma_f32 v[136:137], v[36:37], v[124:125], v[114:115] op_sel_hi:[1,0,1]
	v_pk_add_f32 v[142:143], v[142:143], v[142:143] op_sel_hi:[0,1]
	v_pk_mul_f32 v[144:145], v[132:133], v[132:133]
	v_pk_mul_f32 v[146:147], v[130:131], v[130:131]
	v_pk_fma_f32 v[134:135], v[38:39], v[124:125], v[116:117] op_sel_hi:[1,0,1]
	v_pk_add_f32 v[114:115], v[58:59], v[0:1]
	v_pk_add_f32 v[116:117], v[60:61], v[2:3]
	v_pk_add_f32 v[118:119], v[72:73], v[16:17]
	v_pk_add_f32 v[120:121], v[76:77], v[18:19]
	v_pk_mov_b32 v[148:149], v[146:147], v[144:145] op_sel:[1,0]
	v_mov_b32_e32 v147, v145
	v_mul_f32_e32 v142, v136, v136
	v_sub_f32_e32 v139, v115, v119
	v_sub_f32_e32 v138, v114, v118
	v_sub_f32_e32 v141, v117, v121
	v_sub_f32_e32 v140, v116, v120
	v_pk_add_f32 v[144:145], v[148:149], v[146:147]
	v_pk_fma_f32 v[146:147], v[136:137], v[136:137], v[142:143] op_sel_hi:[1,1,0]
	v_mul_f32_e32 v142, v134, v134
	v_pk_fma_f32 v[140:141], v[34:35], v[124:125], v[140:141] op_sel_hi:[1,0,1]
	v_pk_fma_f32 v[138:139], v[32:33], v[124:125], v[138:139] op_sel_hi:[1,0,1]
	v_pk_add_f32 v[144:145], v[144:145], v[144:145] op_sel_hi:[0,1]
	v_pk_fma_f32 v[148:149], v[134:135], v[134:135], v[142:143] op_sel_hi:[1,1,0]
	v_mul_f32_e32 v146, v138, v138
	v_mul_f32_e32 v148, v139, v139
	v_mul_f32_e32 v142, v140, v140
	v_mul_f32_e32 v144, v141, v141
	v_pk_add_f32 v[146:147], v[146:147], v[148:149]
	v_pk_add_f32 v[142:143], v[142:143], v[144:145]
	v_mbcnt_lo_u32_b32 v125, -1, 0
	v_mbcnt_hi_u32_b32 v125, -1, v125
	s_mul_i32 s3, s2, 0xbff
	v_pk_add_f32 v[142:143], v[146:147], v[142:143]
	v_lshlrev_b32_e32 v125, 2, v125
	v_add_f32_e32 v123, v142, v143
	v_xor_b32_e32 v125, 4, v125
	ds_bpermute_b32 v125, v125, v123
	s_add_i32 s76, s1, s3
	s_ashr_i32 s77, s76, 31
	s_mulk_i32 s2, 0x1401
	s_waitcnt lgkmcnt(0)
	v_add_f32_e32 v123, v123, v125
	v_mbcnt_lo_u32_b32 v125, -1, 0
	v_mbcnt_hi_u32_b32 v125, -1, v125
	s_nop 0
	v_lshlrev_b32_e32 v125, 2, v125
	v_xor_b32_e32 v125, 8, v125
	ds_bpermute_b32 v125, v125, v123
	s_waitcnt lgkmcnt(0)
	v_add_f32_e32 v123, v123, v125
	v_mbcnt_lo_u32_b32 v125, -1, 0
	v_mbcnt_hi_u32_b32 v125, -1, v125
	s_nop 0
	v_lshlrev_b32_e32 v125, 2, v125
	v_xor_b32_e32 v125, 16, v125
	ds_bpermute_b32 v125, v125, v123
	s_waitcnt lgkmcnt(0)
	v_add_f32_e32 v123, v123, v125
	v_mbcnt_lo_u32_b32 v125, -1, 0
	v_mbcnt_hi_u32_b32 v125, -1, v125
	s_nop 0
	v_lshlrev_b32_e32 v125, 2, v125
	v_xor_b32_e32 v125, 32, v125
	ds_bpermute_b32 v125, v125, v123
	s_waitcnt lgkmcnt(0)
	v_add_f32_e32 v123, v123, v125
	v_mbcnt_lo_u32_b32 v125, -1, 0
	v_mbcnt_hi_u32_b32 v125, -1, v125
	s_nop 0
	v_lshlrev_b32_e32 v125, 2, v125
	v_xor_b32_e32 v125, 64, v125
	ds_bpermute_b32 v125, v125, v123
	s_waitcnt lgkmcnt(0)
	v_add_f32_e32 v123, v123, v125
	v_mbcnt_lo_u32_b32 v125, -1, 0
	v_mbcnt_hi_u32_b32 v125, -1, v125
	s_nop 0
	v_lshlrev_b32_e32 v125, 2, v125
	v_xor_b32_e32 v125, 0x80, v125
	ds_bpermute_b32 v125, v125, v123
	s_waitcnt lgkmcnt(0)
; __device__ __forceinline__ v4u pk8(f32x4 a, f32x4 b) { v4u w; w.x = pk2(a[0], a[1]); w.y = pk2(a[2], a[3]); w.z = pk2(b[0], b[1]); w.w = pk2(b[2], b[3]); return w; }
; __device__ __forceinline__ void st_row_norm(bf16* Y, int row, int lane, const f32x4 (&y)[4]) {
;     float ss = 0.f;
; #pragma unroll
;     for (int q = 0; q < 4; ++q) ss += (y[q][0] * y[q][0] + y[q][1] * y[q][1]) + (y[q][2] * y[q][2] + y[q][3] * y[q][3]);
;     const float rs = 1.f / sqrtf(wave_sum(ss) * (1.f / 1024.f) + EPS);
;     v4u* o = (v4u*)(Y + (size_t)row * 2048 + 16 * lane); o[0] = pk8(y[0] * rs, y[1] * rs); o[1] = pk8(y[2] * rs, y[3] * rs);
; __device__ __forceinline__ void combine_phase(const unsigned short* PQ4, const float* nyq, const float* yE, const float* yO, const bf16* OP, const float* LSE, bf16* Y, int gw, int NGW, int lane) {
;     ...
;         const float sg = (k & 1) ? -1.f / 64.f : 1.f / 64.f;
; #pragma unroll
;         for (int q = 0; q < 4; ++q) n[q] = *(const f32x4*)(nyq + b * 1024 + 16 * lane + 4 * q) * sg;
	v_add_f32_e32 v123, v123, v125
	v_fmamk_f32 v123, v123, 0x3a800000, v224
	v_pk_mul_f32 v[46:47], v[46:47], v[124:125] op_sel_hi:[1,0]
	v_pk_mul_f32 v[44:45], v[44:45], v[124:125] op_sel_hi:[1,0]
	v_pk_mul_f32 v[42:43], v[42:43], v[124:125] op_sel_hi:[1,0]
	v_pk_mul_f32 v[40:41], v[40:41], v[124:125] op_sel_hi:[1,0]
	v_mul_f32_e32 v125, 0x4f800000, v123
	v_cmp_gt_f32_e32 vcc, s41, v123
	s_nop 1
	v_cndmask_b32_e32 v123, v123, v125, vcc
	v_sqrt_f32_e32 v125, v123
	s_nop 0
	v_add_u32_e32 v142, -1, v125
	v_fma_f32 v143, -v142, v125, v123
	v_cmp_ge_f32_e64 s[4:5], 0, v143
	v_add_u32_e32 v143, 1, v125
	v_pk_mul_f32 v[38:39], v[38:39], v[124:125] op_sel_hi:[1,0]
	v_pk_mul_f32 v[36:37], v[36:37], v[124:125] op_sel_hi:[1,0]
	v_pk_mul_f32 v[34:35], v[34:35], v[124:125] op_sel_hi:[1,0]
	v_cndmask_b32_e64 v142, v125, v142, s[4:5]
	v_fma_f32 v125, -v143, v125, v123
	v_cmp_lt_f32_e64 s[4:5], 0, v125
	s_nop 1
	v_cndmask_b32_e64 v125, v142, v143, s[4:5]
	v_mul_f32_e32 v142, 0x37800000, v125
	v_cndmask_b32_e32 v125, v125, v142, vcc
	v_cmp_class_f32_e32 vcc, v123, v225
	s_nop 1
	v_cndmask_b32_e32 v123, v125, v123, vcc
	v_div_scale_f32 v125, s[4:5], v123, v123, 1.0
	v_rcp_f32_e32 v142, v125
	v_pk_mul_f32 v[32:33], v[32:33], v[124:125] op_sel_hi:[1,0]
	s_lshl_b64 s[4:5], s[76:77], 12
	s_cmp_lt_i32 s72, 1
	v_fma_f32 v124, -v125, v142, 1.0
	v_fmac_f32_e32 v142, v124, v142
	v_div_scale_f32 v124, vcc, 1.0, v123, 1.0
	v_mul_f32_e32 v143, v124, v142
	v_fma_f32 v144, -v125, v143, v124
	v_fmac_f32_e32 v143, v144, v142
	v_fma_f32 v124, -v125, v143, v124
	v_div_fmas_f32 v124, v124, v142, v143
	v_div_fixup_f32 v142, v124, v123, 1.0
	v_pk_mul_f32 v[128:129], v[128:129], v[142:143] op_sel_hi:[1,0]
	v_pk_mul_f32 v[124:125], v[126:127], v[142:143] op_sel_hi:[1,0]
	v_pk_mul_f32 v[132:133], v[132:133], v[142:143] op_sel_hi:[1,0]
	v_pk_mul_f32 v[126:127], v[130:131], v[142:143] op_sel_hi:[1,0]
	v_lshl_add_u64 v[144:145], v[56:57], 0, s[4:5]
	v_cvt_pk_bf16_f32 v124, v124, v125
	v_cvt_pk_bf16_f32 v125, v128, v129
	v_cvt_pk_bf16_f32 v126, v126, v127
	v_cvt_pk_bf16_f32 v127, v132, v133
	global_store_dwordx4 v[144:145], v[124:127], off
	v_pk_mul_f32 v[128:129], v[140:141], v[142:143] op_sel_hi:[1,0]
	v_pk_mul_f32 v[130:131], v[138:139], v[142:143] op_sel_hi:[1,0]
	v_pk_mul_f32 v[126:127], v[134:135], v[142:143] op_sel_hi:[1,0]
	v_pk_mul_f32 v[124:125], v[136:137], v[142:143] op_sel_hi:[1,0]
	s_nop 0
	v_cvt_pk_bf16_f32 v124, v124, v125
	v_cvt_pk_bf16_f32 v125, v126, v127
	v_cvt_pk_bf16_f32 v126, v130, v131
	v_cvt_pk_bf16_f32 v127, v128, v129
	global_store_dwordx4 v[144:145], v[124:127], off offset:16
	s_cbranch_scc1 .LBB0_778
; __device__ __forceinline__ v4u pk8(f32x4 a, f32x4 b) { v4u w; w.x = pk2(a[0], a[1]); w.y = pk2(a[2], a[3]); w.z = pk2(b[0], b[1]); w.w = pk2(b[2], b[3]); return w; }
; __device__ __forceinline__ void st_row_norm(bf16* Y, int row, int lane, const f32x4 (&y)[4]) {
;     float ss = 0.f;
; #pragma unroll
;     for (int q = 0; q < 4; ++q) ss += (y[q][0] * y[q][0] + y[q][1] * y[q][1]) + (y[q][2] * y[q][2] + y[q][3] * y[q][3]);
;     const float rs = 1.f / sqrtf(wave_sum(ss) * (1.f / 1024.f) + EPS);
;     v4u* o = (v4u*)(Y + (size_t)row * 2048 + 16 * lane); o[0] = pk8(y[0] * rs, y[1] * rs); o[1] = pk8(y[2] * rs, y[3] * rs);
; __device__ __forceinline__ void combine_phase(const unsigned short* PQ4, const float* nyq, const float* yE, const float* yO, const bf16* OP, const float* LSE, bf16* Y, int gw, int NGW, int lane) {
;     ...
;         if (k > 0) {
; #pragma unroll
;             for (int q = 0; q < 4; ++q) y[q] = (ep[q] + op[q]) + (eq[q] + oq[q]) + n[q];
;             st_row_norm(Y, b * SEQ + SEQ - k, lane, y); }
	v_pk_add_f32 v[92:93], v[96:97], v[92:93]
	v_pk_add_f32 v[90:91], v[94:95], v[90:91]
	v_pk_add_f32 v[92:93], v[46:47], v[92:93]
	v_pk_add_f32 v[90:91], v[44:45], v[90:91]
	v_pk_add_f32 v[94:95], v[104:105], v[100:101]
	v_pk_add_f32 v[96:97], v[102:103], v[98:99]
	v_pk_add_f32 v[98:99], v[112:113], v[108:109]
	v_pk_add_f32 v[100:101], v[110:111], v[106:107]
	v_pk_mul_f32 v[106:107], v[92:93], v[92:93]
	v_pk_mul_f32 v[108:109], v[90:91], v[90:91]
	v_pk_add_f32 v[94:95], v[42:43], v[94:95]
	v_pk_mov_b32 v[110:111], v[108:109], v[106:107] op_sel:[1,0]
	v_mov_b32_e32 v109, v107
	v_pk_add_f32 v[96:97], v[40:41], v[96:97]
	v_pk_add_f32 v[106:107], v[110:111], v[108:109]
	v_pk_add_f32 v[100:101], v[36:37], v[100:101]
	v_pk_add_f32 v[106:107], v[106:107], v[106:107] op_sel_hi:[0,1]
	v_pk_mul_f32 v[108:109], v[94:95], v[94:95]
	v_pk_mul_f32 v[110:111], v[96:97], v[96:97]
	v_pk_add_f32 v[98:99], v[38:39], v[98:99]
	v_pk_mov_b32 v[112:113], v[110:111], v[108:109] op_sel:[1,0]
	v_mov_b32_e32 v111, v109
	v_mul_f32_e32 v106, v100, v100
	v_pk_add_f32 v[102:103], v[120:121], v[116:117]
	v_pk_add_f32 v[104:105], v[118:119], v[114:115]
	v_pk_add_f32 v[108:109], v[112:113], v[110:111]
	v_pk_fma_f32 v[110:111], v[100:101], v[100:101], v[106:107] op_sel_hi:[1,1,0]
	v_mul_f32_e32 v106, v98, v98
	v_pk_add_f32 v[102:103], v[34:35], v[102:103]
	v_pk_add_f32 v[104:105], v[32:33], v[104:105]
	v_pk_add_f32 v[108:109], v[108:109], v[108:109] op_sel_hi:[0,1]
	v_pk_fma_f32 v[112:113], v[98:99], v[98:99], v[106:107] op_sel_hi:[1,1,0]
	v_mul_f32_e32 v110, v104, v104
	v_mul_f32_e32 v112, v105, v105
	v_mul_f32_e32 v106, v102, v102
	v_mul_f32_e32 v108, v103, v103
	v_pk_add_f32 v[110:111], v[110:111], v[112:113]
	v_pk_add_f32 v[106:107], v[106:107], v[108:109]
	s_add_i32 s3, s0, s2
	v_pk_add_f32 v[106:107], v[110:111], v[106:107]
	s_nop 0
	v_add_f32_e32 v106, v106, v107
	s_nop 1
	v_add_f32_dpp v106, v106, v106 quad_perm:[1,0,3,2] row_mask:0xf bank_mask:0xf
	s_nop 1
	v_add_f32_dpp v106, v106, v106 quad_perm:[2,3,0,1] row_mask:0xf bank_mask:0xf
	s_nop 1
	v_add_f32_dpp v106, v106, v106 row_half_mirror row_mask:0xf bank_mask:0xf
	s_nop 1
	v_add_f32_dpp v106, v106, v106 row_mirror row_mask:0xf bank_mask:0xf
	v_mov_b32_e32 v107, v106
	s_nop 1
	v_permlane16_swap_b32_e32 v107, v106
	s_nop 1
	v_add_f32_e32 v106, v106, v107
	v_mov_b32_e32 v107, v106
	s_nop 1
	v_permlane32_swap_b32_e32 v107, v106
	s_nop 1
	v_add_f32_e32 v106, v106, v107
	v_fmamk_f32 v106, v106, 0x3a800000, v224
	v_mul_f32_e32 v107, 0x4f800000, v106
	v_cmp_gt_f32_e32 vcc, s41, v106
	s_nop 1
	v_cndmask_b32_e32 v106, v106, v107, vcc
	v_sqrt_f32_e32 v107, v106
	s_nop 0
	v_add_u32_e32 v108, -1, v107
	v_fma_f32 v109, -v108, v107, v106
	v_cmp_ge_f32_e64 s[4:5], 0, v109
	v_add_u32_e32 v109, 1, v107
	s_nop 0
	v_cndmask_b32_e64 v108, v107, v108, s[4:5]
	v_fma_f32 v107, -v109, v107, v106
	v_cmp_lt_f32_e64 s[4:5], 0, v107
	s_nop 1
	v_cndmask_b32_e64 v107, v108, v109, s[4:5]
	v_mul_f32_e32 v108, 0x37800000, v107
	v_cndmask_b32_e32 v107, v107, v108, vcc
	v_cmp_class_f32_e32 vcc, v106, v225
	s_nop 1
	v_cndmask_b32_e32 v106, v107, v106, vcc
	v_div_scale_f32 v107, s[4:5], v106, v106, 1.0
	v_rcp_f32_e32 v108, v107
	s_add_i32 s4, s3, 0x800
	s_ashr_i32 s5, s4, 31
	s_lshl_b64 s[4:5], s[4:5], 12
	v_fma_f32 v109, -v107, v108, 1.0
	v_fmac_f32_e32 v108, v109, v108
	v_div_scale_f32 v109, vcc, 1.0, v106, 1.0
	v_mul_f32_e32 v110, v109, v108
	v_fma_f32 v111, -v107, v110, v109
	v_fmac_f32_e32 v110, v111, v108
	v_fma_f32 v107, -v107, v110, v109
	v_div_fmas_f32 v107, v107, v108, v110
	v_div_fixup_f32 v106, v107, v106, 1.0
	v_pk_mul_f32 v[92:93], v[92:93], v[106:107] op_sel_hi:[1,0]
	v_pk_mul_f32 v[90:91], v[90:91], v[106:107] op_sel_hi:[1,0]
	v_pk_mul_f32 v[94:95], v[94:95], v[106:107] op_sel_hi:[1,0]
	v_pk_mul_f32 v[96:97], v[96:97], v[106:107] op_sel_hi:[1,0]
	v_lshl_add_u64 v[108:109], v[56:57], 0, s[4:5]
	v_cvt_pk_bf16_f32 v90, v90, v91
	v_cvt_pk_bf16_f32 v91, v92, v93
	v_cvt_pk_bf16_f32 v92, v96, v97
	v_cvt_pk_bf16_f32 v93, v94, v95
	global_store_dwordx4 v[108:109], v[90:93], off
	v_pk_mul_f32 v[94:95], v[102:103], v[106:107] op_sel_hi:[1,0]
	v_pk_mul_f32 v[96:97], v[104:105], v[106:107] op_sel_hi:[1,0]
	v_pk_mul_f32 v[92:93], v[98:99], v[106:107] op_sel_hi:[1,0]
	v_pk_mul_f32 v[90:91], v[100:101], v[106:107] op_sel_hi:[1,0]
	s_nop 0
	v_cvt_pk_bf16_f32 v90, v90, v91
	v_cvt_pk_bf16_f32 v91, v92, v93
	v_cvt_pk_bf16_f32 v92, v96, v97
	v_cvt_pk_bf16_f32 v93, v94, v95
	global_store_dwordx4 v[108:109], v[90:93], off offset:16

; __device__ __forceinline__ v4u pk8(f32x4 a, f32x4 b) { v4u w; w.x = pk2(a[0], a[1]); w.y = pk2(a[2], a[3]); w.z = pk2(b[0], b[1]); w.w = pk2(b[2], b[3]); return w; }
; __device__ __forceinline__ void st_row_norm(bf16* Y, int row, int lane, const f32x4 (&y)[4]) {
;     float ss = 0.f;
; #pragma unroll
;     for (int q = 0; q < 4; ++q) ss += (y[q][0] * y[q][0] + y[q][1] * y[q][1]) + (y[q][2] * y[q][2] + y[q][3] * y[q][3]);
;     const float rs = 1.f / sqrtf(wave_sum(ss) * (1.f / 1024.f) + EPS);
;     v4u* o = (v4u*)(Y + (size_t)row * 2048 + 16 * lane); o[0] = pk8(y[0] * rs, y[1] * rs); o[1] = pk8(y[2] * rs, y[3] * rs);
; __device__ __forceinline__ void combine_phase(const unsigned short* PQ4, const float* nyq, const float* yE, const float* yO, const bf16* OP, const float* LSE, bf16* Y, int gw, int NGW, int lane) {
;     ...
;         if (k < 1024) {
; #pragma unroll
;             for (int q = 0; q < 4; ++q) y[q] = (ep[q] - op[q]) - (oq[q] - eq[q]) + n[q];
;             st_row_norm(Y, b * SEQ + SEQ / 2 - k, lane, y); }
;         if (k > 0 && k < 1024) {
; #pragma unroll
;             for (int q = 0; q < 4; ++q) y[q] = (ep[q] - op[q]) + (oq[q] - eq[q]) + n[q];
;             st_row_norm(Y, b * SEQ + SEQ / 2 + k, lane, y); }
.LBB0_781:
	v_pk_add_f32 v[16:17], v[30:31], v[90:91]
	v_pk_add_f32 v[18:19], v[74:75], v[70:71]
	v_pk_add_f32 v[16:17], v[46:47], v[16:17]
	v_pk_add_f32 v[18:19], v[44:45], v[18:19]
	v_pk_add_f32 v[0:1], v[0:1], v[2:3]
	v_pk_add_f32 v[14:15], v[20:21], v[14:15]
	v_pk_add_f32 v[4:5], v[10:11], v[4:5]
	v_pk_add_f32 v[10:11], v[34:35], v[0:1]
	v_pk_mul_f32 v[0:1], v[16:17], v[16:17]
	v_pk_mul_f32 v[2:3], v[18:19], v[18:19]
	v_pk_add_f32 v[22:23], v[26:27], v[28:29]
	v_pk_add_f32 v[12:13], v[24:25], v[12:13]
	v_pk_add_f32 v[6:7], v[8:9], v[6:7]
	v_pk_add_f32 v[8:9], v[36:37], v[14:15]
	v_pk_mov_b32 v[14:15], v[2:3], v[0:1] op_sel:[1,0]
	v_mov_b32_e32 v3, v1
	v_pk_add_f32 v[12:13], v[40:41], v[12:13]
	v_pk_add_f32 v[22:23], v[42:43], v[22:23]
	v_pk_add_f32 v[0:1], v[14:15], v[2:3]
	v_pk_mul_f32 v[2:3], v[22:23], v[22:23]
	v_pk_add_f32 v[0:1], v[0:1], v[0:1] op_sel_hi:[0,1]
	v_pk_mul_f32 v[14:15], v[12:13], v[12:13]
	v_pk_add_f32 v[6:7], v[38:39], v[6:7]
	v_pk_mov_b32 v[20:21], v[14:15], v[2:3] op_sel:[1,0]
	v_mov_b32_e32 v15, v3
	v_mul_f32_e32 v0, v8, v8
	v_pk_add_f32 v[2:3], v[20:21], v[14:15]
	v_pk_fma_f32 v[14:15], v[8:9], v[8:9], v[0:1] op_sel_hi:[1,1,0]
	v_mul_f32_e32 v0, v6, v6
	v_pk_add_f32 v[4:5], v[32:33], v[4:5]
	v_pk_add_f32 v[2:3], v[2:3], v[2:3] op_sel_hi:[0,1]
	v_pk_fma_f32 v[20:21], v[6:7], v[6:7], v[0:1] op_sel_hi:[1,1,0]
	v_mul_f32_e32 v14, v4, v4
	v_mul_f32_e32 v20, v5, v5
	v_mul_f32_e32 v0, v10, v10
	v_mul_f32_e32 v2, v11, v11
	v_pk_add_f32 v[14:15], v[14:15], v[20:21]
	v_pk_add_f32 v[0:1], v[0:1], v[2:3]
	s_nop 0
	v_pk_add_f32 v[0:1], v[14:15], v[0:1]
	s_nop 0
	v_add_f32_e32 v0, v0, v1
	s_nop 1
	v_add_f32_dpp v0, v0, v0 quad_perm:[1,0,3,2] row_mask:0xf bank_mask:0xf
	s_nop 1
	v_add_f32_dpp v0, v0, v0 quad_perm:[2,3,0,1] row_mask:0xf bank_mask:0xf
	s_nop 1
	v_add_f32_dpp v0, v0, v0 row_half_mirror row_mask:0xf bank_mask:0xf
	s_nop 1
	v_add_f32_dpp v0, v0, v0 row_mirror row_mask:0xf bank_mask:0xf
	v_mov_b32_e32 v1, v0
	s_nop 1
	v_permlane16_swap_b32_e32 v1, v0
	s_nop 1
	v_add_f32_e32 v0, v0, v1
	v_mov_b32_e32 v1, v0
	s_nop 1
	v_permlane32_swap_b32_e32 v1, v0
	s_nop 1
	v_add_f32_e32 v0, v0, v1
	v_fmamk_f32 v0, v0, 0x3a800000, v224
	v_mul_f32_e32 v1, 0x4f800000, v0
	v_cmp_gt_f32_e32 vcc, s41, v0
	s_nop 1
	v_cndmask_b32_e32 v0, v0, v1, vcc
	v_sqrt_f32_e32 v1, v0
	s_nop 0
	v_add_u32_e32 v2, -1, v1
	v_fma_f32 v3, -v2, v1, v0
	v_cmp_ge_f32_e64 s[4:5], 0, v3
	v_add_u32_e32 v3, 1, v1
	s_nop 0
	v_cndmask_b32_e64 v2, v1, v2, s[4:5]
	v_fma_f32 v1, -v3, v1, v0
	v_cmp_lt_f32_e64 s[4:5], 0, v1
	s_nop 1
	v_cndmask_b32_e64 v1, v2, v3, s[4:5]
	v_mul_f32_e32 v2, 0x37800000, v1
	v_cndmask_b32_e32 v1, v1, v2, vcc
	v_cmp_class_f32_e32 vcc, v0, v225
	s_nop 1
	v_cndmask_b32_e32 v0, v1, v0, vcc
	v_div_scale_f32 v1, s[2:3], v0, v0, 1.0
	v_rcp_f32_e32 v2, v1
	s_add_i32 s2, s76, 0x800
	s_ashr_i32 s3, s2, 31
	s_lshl_b64 s[2:3], s[2:3], 12
	v_fma_f32 v3, -v1, v2, 1.0
	v_fmac_f32_e32 v2, v3, v2
	v_div_scale_f32 v3, vcc, 1.0, v0, 1.0
	v_mul_f32_e32 v14, v3, v2
	v_fma_f32 v15, -v1, v14, v3
	v_fmac_f32_e32 v14, v15, v2
	v_fma_f32 v1, -v1, v14, v3
	v_div_fmas_f32 v1, v1, v2, v14
	v_div_fixup_f32 v14, v1, v0, 1.0
	v_pk_mul_f32 v[2:3], v[16:17], v[14:15] op_sel_hi:[1,0]
	v_pk_mul_f32 v[0:1], v[18:19], v[14:15] op_sel_hi:[1,0]
	v_pk_mul_f32 v[16:17], v[22:23], v[14:15] op_sel_hi:[1,0]
	v_pk_mul_f32 v[12:13], v[12:13], v[14:15] op_sel_hi:[1,0]
	v_lshl_add_u64 v[20:21], v[56:57], 0, s[2:3]
	v_cvt_pk_bf16_f32 v0, v0, v1
	v_cvt_pk_bf16_f32 v1, v2, v3
	v_cvt_pk_bf16_f32 v2, v12, v13
	v_cvt_pk_bf16_f32 v3, v16, v17
	global_store_dwordx4 v[20:21], v[0:3], off
	v_pk_mul_f32 v[4:5], v[4:5], v[14:15] op_sel_hi:[1,0]
	s_nop 0
	v_pk_mul_f32 v[2:3], v[6:7], v[14:15] op_sel_hi:[1,0]
	v_pk_mul_f32 v[0:1], v[8:9], v[14:15] op_sel_hi:[1,0]
	v_pk_mul_f32 v[6:7], v[10:11], v[14:15] op_sel_hi:[1,0]
	v_cvt_pk_bf16_f32 v0, v0, v1
	v_cvt_pk_bf16_f32 v1, v2, v3
	v_cvt_pk_bf16_f32 v2, v4, v5
	v_cvt_pk_bf16_f32 v3, v6, v7
	global_store_dwordx4 v[20:21], v[0:3], off offset:16
	s_branch .LBB0_771

; __device__ __forceinline__ void combine_phase(const unsigned short* PQ4, const float* nyq, const float* yE, const float* yO, const bf16* OP, const float* LSE, bf16* Y, int gw, int NGW, int lane) {
;     ...
;     for (int tok = gw; tok < M; tok += NGW) {
;         const int h = lane >> 3;
;         float l0 = LSE[(size_t)tok * 8 + h], l1 = LSE[(size_t)M * 8 + (size_t)tok * 8 + h], l2 = LSE[(size_t)2 * M * 8 + (size_t)tok * 8 + h];
;         const v4u* a = (const v4u*)(OP + (size_t)tok * 1024 + 16 * lane); const v4u* bq = (const v4u*)(OP + (size_t)M * 1024 + (size_t)tok * 1024 + 16 * lane); const v4u* cq = (const v4u*)(OP + (size_t)2 * M * 1024 + (size_t)tok * 1024 + 16 * lane);
;         const v4u a0 = a[0], a1 = a[1], b0 = bq[0], b1 = bq[1], c0 = cq[0], c1 = cq[1];
;         const float lm = fmaxf(l0, fmaxf(l1, l2)); l0 = __builtin_amdgcn_exp2f(l0 - lm); l1 = __builtin_amdgcn_exp2f(l1 - lm); l2 = __builtin_amdgcn_exp2f(l2 - lm);
;         const float iw = 1.f / (l0 + l1 + l2); l0 *= iw; l1 *= iw; l2 *= iw;
.LBB0_784:
	v_lshl_add_u64 v[0:1], v[12:13], 0, s[60:61]
	v_add_co_u32_e32 v2, vcc, 0x600000, v0
	v_lshl_add_u64 v[22:23], v[10:11], 0, s[60:61]
	s_nop 0
	v_addc_co_u32_e32 v3, vcc, 0, v1, vcc
	global_load_dword v30, v[2:3], off
	v_add_co_u32_e32 v2, vcc, 0x680000, v0
	s_mov_b64 s[2:3], 0x3d800000
	s_nop 0
	v_addc_co_u32_e32 v3, vcc, 0, v1, vcc
	v_add_co_u32_e32 v0, vcc, 0x700000, v0
	global_load_dword v32, v[2:3], off
	s_nop 0
	v_addc_co_u32_e32 v1, vcc, 0, v1, vcc
	global_load_dword v33, v[0:1], off
	v_add_co_u32_e32 v0, vcc, 0x3d800000, v22
	v_lshl_add_u64 v[4:5], v[22:23], 0, s[2:3]
	s_nop 0
	v_addc_co_u32_e32 v1, vcc, 0, v23, vcc
	s_mov_b64 s[2:3], 0x3f800000
	v_add_co_u32_e32 v14, vcc, 1.0, v22
	v_lshl_add_u64 v[18:19], v[22:23], 0, s[2:3]
	s_nop 0
	v_addc_co_u32_e32 v15, vcc, 0, v23, vcc
	s_mov_b64 s[2:3], 0x41800000
	global_load_dwordx4 v[0:3], v[0:1], off
	s_nop 0
	global_load_dwordx4 v[4:7], v[4:5], off offset:16
	s_nop 0
	global_load_dwordx4 v[14:17], v[14:15], off
	s_nop 0
	global_load_dwordx4 v[18:21], v[18:19], off offset:16
	s_mov_b32 s1, 0x41800000
	v_lshl_add_u64 v[26:27], v[22:23], 0, s[2:3]
	v_add_co_u32_e32 v22, vcc, s1, v22
	s_add_i32 s0, s0, s58
	s_nop 0
	v_addc_co_u32_e32 v23, vcc, 0, v23, vcc
	global_load_dwordx4 v[22:25], v[22:23], off
	s_nop 0
	global_load_dwordx4 v[26:29], v[26:27], off offset:16
	v_lshl_add_u64 v[10:11], v[10:11], 0, s[62:63]
	v_lshl_add_u64 v[12:13], v[12:13], 0, s[70:71]
	s_cmpk_lt_i32 s0, 0x4000
	s_waitcnt vmcnt(6)
	v_max3_f32 v34, v30, v32, v33
	v_sub_f32_e32 v30, v30, v34
	v_exp_f32_e32 v31, v30
	v_sub_f32_e32 v30, v32, v34
	v_exp_f32_e32 v30, v30
	v_sub_f32_e32 v32, v33, v34
	v_exp_f32_e32 v33, v32
	v_add_f32_e32 v32, v31, v30
	v_add_f32_e32 v32, v33, v32
	v_div_scale_f32 v34, s[2:3], v32, v32, 1.0
	v_rcp_f32_e32 v35, v34
	s_waitcnt vmcnt(4)
	v_and_b32_e32 v39, 0xffff0000, v6
	v_lshlrev_b32_e32 v6, 16, v6
	v_fma_f32 v36, -v34, v35, 1.0
	v_fmac_f32_e32 v35, v36, v35
	v_div_scale_f32 v36, vcc, 1.0, v32, 1.0
	v_mul_f32_e32 v37, v36, v35
	v_fma_f32 v38, -v34, v37, v36
	v_fmac_f32_e32 v37, v38, v35
	v_fma_f32 v34, -v34, v37, v36
	v_div_fmas_f32 v34, v34, v35, v37
	v_div_fixup_f32 v32, v34, v32, 1.0
	v_mul_f32_e32 v34, v33, v32
	v_mbcnt_lo_u32_b32 v33, -1, 0
	v_mbcnt_hi_u32_b32 v33, -1, v33
	v_lshlrev_b32_e32 v36, 16, v7
	v_lshlrev_b32_e32 v33, 2, v33
	v_xor_b32_e32 v35, 4, v33
	v_mbcnt_lo_u32_b32 v33, -1, 0
	v_mbcnt_hi_u32_b32 v33, -1, v33
	s_waitcnt vmcnt(2)
	v_and_b32_e32 v37, 0xffff0000, v21
	v_lshlrev_b32_e32 v33, 2, v33
	v_xor_b32_e32 v46, 8, v33
	v_mbcnt_lo_u32_b32 v33, -1, 0
	v_mbcnt_hi_u32_b32 v33, -1, v33
	v_lshlrev_b32_e32 v38, 16, v20
	v_lshlrev_b32_e32 v33, 2, v33
	v_xor_b32_e32 v47, 16, v33
	v_mbcnt_lo_u32_b32 v33, -1, 0
	v_mbcnt_hi_u32_b32 v33, -1, v33
	s_waitcnt vmcnt(0)
; __device__ __forceinline__ unsigned pk2(float lo, float hi) { f32x2_t v = {lo, hi}; bf16x2_t b = __builtin_convertvector(v, bf16x2_t); return __builtin_bit_cast(unsigned, b); }
; __device__ __forceinline__ void combine_phase(const unsigned short* PQ4, const float* nyq, const float* yE, const float* yO, const bf16* OP, const float* LSE, bf16* Y, int gw, int NGW, int lane) {
;     ...
;         float y[16]; float ss = 0.f;
; #pragma unroll
;         for (int j = 0; j < 4; ++j) { y[2 * j] = l0 * bflo(a0[j]) + l1 * bflo(b0[j]) + l2 * bflo(c0[j]); y[2 * j + 1] = l0 * bfhi(a0[j]) + l1 * bfhi(b0[j]) + l2 * bfhi(c0[j]);
;             y[8 + 2 * j] = l0 * bflo(a1[j]) + l1 * bflo(b1[j]) + l2 * bflo(c1[j]); y[8 + 2 * j + 1] = l0 * bfhi(a1[j]) + l1 * bfhi(b1[j]) + l2 * bfhi(c1[j]); }
; #pragma unroll
;         for (int j = 0; j < 16; ++j) ss += y[j] * y[j];
;         const float rs = 1.f / sqrtf(wave_sum(ss) * (1.f / 1024.f) + EPS);
;         v4u o0, o1; o0.x = pk2(y[0] * rs, y[1] * rs); o0.y = pk2(y[2] * rs, y[3] * rs); o0.z = pk2(y[4] * rs, y[5] * rs); o0.w = pk2(y[6] * rs, y[7] * rs);
;         o1.x = pk2(y[8] * rs, y[9] * rs); o1.y = pk2(y[10] * rs, y[11] * rs); o1.z = pk2(y[12] * rs, y[13] * rs); o1.w = pk2(y[14] * rs, y[15] * rs);
;         v4u* o = (v4u*)(Y + (size_t)tok * 2048 + 1024 + 16 * lane); o[0] = o0; o[1] = o1;
	v_lshlrev_b32_e32 v40, 16, v27
	v_lshlrev_b32_e32 v33, 2, v33
	v_xor_b32_e32 v48, 32, v33
	v_mbcnt_lo_u32_b32 v33, -1, 0
	v_mbcnt_hi_u32_b32 v33, -1, v33
	v_and_b32_e32 v41, 0xffff0000, v27
	v_lshlrev_b32_e32 v33, 2, v33
	v_xor_b32_e32 v49, 64, v33
	v_mbcnt_lo_u32_b32 v33, -1, 0
	v_mbcnt_hi_u32_b32 v33, -1, v33
	v_and_b32_e32 v27, 0xffff0000, v3
	v_lshlrev_b32_e32 v33, 2, v33
	v_xor_b32_e32 v50, 0x80, v33
	v_pk_mul_f32 v[30:31], v[30:31], v[32:33] op_sel_hi:[1,0]
	v_and_b32_e32 v33, 0xffff0000, v7
	v_and_b32_e32 v7, 0xffff0000, v20
	v_pk_mul_f32 v[6:7], v[30:31], v[6:7] op_sel:[1,0] op_sel_hi:[0,1]
	v_lshlrev_b32_e32 v32, 16, v21
	v_pk_mul_f32 v[36:37], v[30:31], v[36:37] op_sel:[1,0] op_sel_hi:[0,1]
	v_pk_fma_f32 v[6:7], v[30:31], v[38:39], v[6:7]
	v_lshlrev_b32_e32 v38, 16, v5
	v_and_b32_e32 v39, 0xffff0000, v19
	v_pk_fma_f32 v[32:33], v[30:31], v[32:33], v[36:37]
	v_lshlrev_b32_e32 v36, 16, v29
	v_and_b32_e32 v37, 0xffff0000, v29
	v_lshlrev_b32_e32 v20, 16, v28
	v_and_b32_e32 v21, 0xffff0000, v28
	v_lshlrev_b32_e32 v28, 16, v19
	v_and_b32_e32 v29, 0xffff0000, v5
	v_pk_mul_f32 v[38:39], v[30:31], v[38:39] op_sel:[1,0] op_sel_hi:[0,1]
	v_pk_fma_f32 v[28:29], v[30:31], v[28:29], v[38:39]
	v_and_b32_e32 v5, 0xffff0000, v18
	v_pk_fma_f32 v[28:29], v[34:35], v[40:41], v[28:29] op_sel_hi:[0,1,1]
	v_and_b32_e32 v41, 0xffff0000, v4
	v_lshlrev_b32_e32 v4, 16, v4
	v_lshlrev_b32_e32 v40, 16, v18
	v_pk_mul_f32 v[4:5], v[30:31], v[4:5] op_sel:[1,0] op_sel_hi:[0,1]
	v_pk_fma_f32 v[4:5], v[30:31], v[40:41], v[4:5]
	v_lshlrev_b32_e32 v40, 16, v3
	v_and_b32_e32 v41, 0xffff0000, v17
	v_lshlrev_b32_e32 v18, 16, v26
	v_and_b32_e32 v19, 0xffff0000, v26
	v_lshlrev_b32_e32 v26, 16, v17
	v_pk_mul_f32 v[40:41], v[30:31], v[40:41] op_sel:[1,0] op_sel_hi:[0,1]
	v_lshlrev_b32_e32 v42, 16, v25
	v_and_b32_e32 v43, 0xffff0000, v25
	v_pk_fma_f32 v[26:27], v[30:31], v[26:27], v[40:41]
	v_and_b32_e32 v3, 0xffff0000, v16
	v_pk_fma_f32 v[26:27], v[34:35], v[42:43], v[26:27] op_sel_hi:[0,1,1]
	v_and_b32_e32 v43, 0xffff0000, v2
	v_lshlrev_b32_e32 v2, 16, v2
	v_lshlrev_b32_e32 v42, 16, v16
	v_pk_mul_f32 v[2:3], v[30:31], v[2:3] op_sel:[1,0] op_sel_hi:[0,1]
	v_pk_fma_f32 v[2:3], v[30:31], v[42:43], v[2:3]
	v_lshlrev_b32_e32 v42, 16, v1
	v_and_b32_e32 v43, 0xffff0000, v15
	v_lshlrev_b32_e32 v16, 16, v24
	v_and_b32_e32 v17, 0xffff0000, v24
	v_lshlrev_b32_e32 v24, 16, v15
	v_and_b32_e32 v25, 0xffff0000, v1
	v_pk_mul_f32 v[42:43], v[30:31], v[42:43] op_sel:[1,0] op_sel_hi:[0,1]
	v_lshlrev_b32_e32 v44, 16, v23
	v_and_b32_e32 v45, 0xffff0000, v23
	v_pk_fma_f32 v[24:25], v[30:31], v[24:25], v[42:43]
	v_and_b32_e32 v1, 0xffff0000, v14
	v_pk_fma_f32 v[24:25], v[34:35], v[44:45], v[24:25] op_sel_hi:[0,1,1]
	v_and_b32_e32 v45, 0xffff0000, v0
	v_lshlrev_b32_e32 v0, 16, v0
	v_lshlrev_b32_e32 v44, 16, v14
	v_pk_mul_f32 v[0:1], v[30:31], v[0:1] op_sel:[1,0] op_sel_hi:[0,1]
	v_lshlrev_b32_e32 v14, 16, v22
	v_and_b32_e32 v15, 0xffff0000, v22
	v_pk_fma_f32 v[0:1], v[30:31], v[44:45], v[0:1]
	v_pk_mul_f32 v[42:43], v[24:25], v[24:25]
	v_pk_fma_f32 v[0:1], v[34:35], v[14:15], v[0:1] op_sel_hi:[0,1,1]
	v_pk_mul_f32 v[14:15], v[0:1], v[0:1]
	v_pk_fma_f32 v[2:3], v[34:35], v[16:17], v[2:3] op_sel_hi:[0,1,1]
	v_add_f32_e32 v14, v14, v15
	v_add_f32_e32 v14, v42, v14
	v_pk_mul_f32 v[16:17], v[2:3], v[2:3]
	v_add_f32_e32 v14, v43, v14
	v_add_f32_e32 v14, v16, v14
	v_pk_mul_f32 v[40:41], v[26:27], v[26:27]
	v_add_f32_e32 v14, v17, v14
	v_pk_fma_f32 v[4:5], v[34:35], v[18:19], v[4:5] op_sel_hi:[0,1,1]
	v_add_f32_e32 v14, v40, v14
	v_pk_mul_f32 v[18:19], v[4:5], v[4:5]
	v_add_f32_e32 v14, v41, v14
	v_add_f32_e32 v14, v18, v14
	v_pk_mul_f32 v[38:39], v[28:29], v[28:29]
	v_add_f32_e32 v14, v19, v14
	v_pk_fma_f32 v[6:7], v[34:35], v[20:21], v[6:7] op_sel_hi:[0,1,1]
	v_add_f32_e32 v14, v38, v14
	v_pk_mul_f32 v[20:21], v[6:7], v[6:7]
	v_add_f32_e32 v14, v39, v14
	v_pk_fma_f32 v[32:33], v[34:35], v[36:37], v[32:33] op_sel_hi:[0,1,1]
	v_add_f32_e32 v14, v20, v14
	v_pk_mul_f32 v[36:37], v[32:33], v[32:33]
	v_add_f32_e32 v14, v21, v14
	v_add_f32_e32 v14, v36, v14
	v_add_f32_e32 v14, v37, v14
	s_nop 1
	v_add_f32_dpp v14, v14, v14 quad_perm:[1,0,3,2] row_mask:0xf bank_mask:0xf
	s_nop 1
	v_add_f32_dpp v14, v14, v14 quad_perm:[2,3,0,1] row_mask:0xf bank_mask:0xf
	s_nop 1
	v_add_f32_dpp v14, v14, v14 row_half_mirror row_mask:0xf bank_mask:0xf
	s_nop 1
	v_add_f32_dpp v14, v14, v14 row_mirror row_mask:0xf bank_mask:0xf
	v_mov_b32_e32 v15, v14
	s_nop 1
	v_permlane16_swap_b32_e32 v15, v14
	s_nop 1
	v_add_f32_e32 v14, v14, v15
	v_mov_b32_e32 v15, v14
	s_nop 1
	v_permlane32_swap_b32_e32 v15, v14
	s_nop 1
	v_add_f32_e32 v14, v14, v15
	v_fmamk_f32 v14, v14, 0x3a800000, v224
	v_cmp_gt_f32_e32 vcc, s41, v14
	v_mul_f32_e32 v15, 0x4f800000, v14
	s_nop 0
	v_cndmask_b32_e32 v14, v14, v15, vcc
	v_sqrt_f32_e32 v15, v14
	s_nop 0
	v_add_u32_e32 v16, -1, v15
	v_fma_f32 v17, -v16, v15, v14
	v_cmp_ge_f32_e64 s[4:5], 0, v17
	v_add_u32_e32 v17, 1, v15
	s_nop 0
	v_cndmask_b32_e64 v16, v15, v16, s[4:5]
	v_fma_f32 v15, -v17, v15, v14
	v_cmp_lt_f32_e64 s[4:5], 0, v15
	s_nop 1
	v_cndmask_b32_e64 v15, v16, v17, s[4:5]
	v_mul_f32_e32 v16, 0x37800000, v15
	v_cndmask_b32_e32 v15, v15, v16, vcc
	v_cmp_class_f32_e32 vcc, v14, v225
	s_nop 1
	v_cndmask_b32_e32 v14, v15, v14, vcc
	v_div_scale_f32 v15, s[2:3], v14, v14, 1.0
	v_rcp_f32_e32 v16, v15
	s_nop 0
	v_fma_f32 v17, -v15, v16, 1.0
	v_fmac_f32_e32 v16, v17, v16
	v_div_scale_f32 v17, vcc, 1.0, v14, 1.0
	v_mul_f32_e32 v18, v17, v16
	v_fma_f32 v19, -v15, v18, v17
	v_fmac_f32_e32 v18, v19, v16
	v_fma_f32 v15, -v15, v18, v17
	v_div_fmas_f32 v15, v15, v16, v18
	v_div_fixup_f32 v14, v15, v14, 1.0
	v_pk_mul_f32 v[0:1], v[0:1], v[14:15] op_sel_hi:[1,0]
	v_pk_mul_f32 v[16:17], v[24:25], v[14:15] op_sel_hi:[1,0]
	v_cvt_pk_bf16_f32 v0, v0, v1
	v_cvt_pk_bf16_f32 v1, v16, v17
	v_pk_mul_f32 v[2:3], v[2:3], v[14:15] op_sel_hi:[1,0]
	v_pk_mul_f32 v[16:17], v[26:27], v[14:15] op_sel_hi:[1,0]
	v_cvt_pk_bf16_f32 v2, v2, v3
	v_cvt_pk_bf16_f32 v3, v16, v17
	v_pk_mul_f32 v[4:5], v[4:5], v[14:15] op_sel_hi:[1,0]
	v_pk_mul_f32 v[16:17], v[28:29], v[14:15] op_sel_hi:[1,0]
	v_pk_mul_f32 v[6:7], v[6:7], v[14:15] op_sel_hi:[1,0]
	v_pk_mul_f32 v[14:15], v[32:33], v[14:15] op_sel_hi:[1,0]
	v_cvt_pk_bf16_f32 v6, v6, v7
	v_cvt_pk_bf16_f32 v7, v14, v15
	v_lshl_add_u64 v[14:15], v[8:9], 0, s[60:61]
	v_add_co_u32_e32 v14, vcc, 0x39800000, v14
	v_lshl_add_u64 v[8:9], v[8:9], 0, s[6:7]
	s_nop 0
	v_addc_co_u32_e32 v15, vcc, 0, v15, vcc
	v_cvt_pk_bf16_f32 v4, v4, v5
	v_cvt_pk_bf16_f32 v5, v16, v17
	global_store_dwordx4 v[14:15], v[0:3], off offset:2048
	global_store_dwordx4 v[14:15], v[4:7], off offset:2064
	s_cbranch_scc1 .LBB0_784

; __device__ __forceinline__ float ssq8(const f32x4& a, const f32x4& b) { return ((a[0] * a[0] + a[1] * a[1]) + (a[2] * a[2] + a[3] * a[3])) + ((b[0] * b[0] + b[1] * b[1]) + (b[2] * b[2] + b[3] * b[3])); }
; template <int XF32> __device__ __forceinline__ void norm_mod_phase(const void* x, const float* modl, int ch_shift, int ch_scale, bf16* H, int gw, int NGW, int lane) {
;     ...
;     for (int blk = gw; blk < M / 8; blk += NGW) {
;         const int r0 = blk * 8, b = r0 >> 12;
;         const f32x4* shp = (const f32x4*)(modl + (size_t)b * MODW + ch_shift * DM); const f32x4* scp = (const f32x4*)(modl + (size_t)b * MODW + ch_scale * DM);
;         f32x4 sh[4][2], sc[4][2];
; #pragma unroll
;         for (int j = 0; j < 4; ++j)
; #pragma unroll
;             for (int q = 0; q < 2; ++q) { sh[j][q] = shp[2 * (lane + 64 * j) + q]; sc[j][q] = scp[2 * (lane + 64 * j) + q] + 1.f; }
;         for (int rr = 0; rr < 8; ++rr) {
;             const unsigned char* xr = (const unsigned char*)x + (size_t)(r0 + rr) * rowb; f32x4 v[4][2]; float s = 0.f;
; #pragma unroll
;             for (int j = 0; j < 4; ++j) ld_row8<XF32>(xr, lane, j, v[j][0], v[j][1]);
; #pragma unroll
;             for (int j = 0; j < 4; ++j) s += ssq8(v[j][0], v[j][1]);
.LBB0_919:
	s_ashr_i32 s0, s56, 9
	s_mul_hi_i32 s1, s0, 0x12000
	s_mul_i32 s0, s0, 0x12000
	s_add_u32 s0, s24, s0
	s_addc_u32 s1, s26, s1
	s_add_u32 s60, s0, 0xc000
	s_addc_u32 s61, s1, 0
	s_add_u32 s0, s0, 0xe000
	s_addc_u32 s1, s1, 0
	v_lshl_add_u64 v[4:5], s[60:61], 0, v[36:37]
	v_lshl_add_u64 v[12:13], s[0:1], 0, v[36:37]
	global_load_dwordx4 v[0:3], v[4:5], off offset:16
	s_nop 0
	global_load_dwordx4 v[4:7], v[4:5], off
	s_nop 0
	global_load_dwordx4 v[178:181], v[12:13], off offset:16
	s_nop 0
	global_load_dwordx4 v[182:185], v[12:13], off
	v_lshl_add_u64 v[20:21], s[0:1], 0, v[38:39]
	v_lshl_add_u64 v[28:29], s[0:1], 0, v[40:41]
	v_lshl_add_u64 v[68:69], s[0:1], 0, v[42:43]
	s_add_i32 s0, s4, -7
	s_ashr_i32 s1, s0, 31
	s_ashr_i32 s5, s4, 31
	s_add_i32 s56, s56, s58
	v_lshl_add_u64 v[12:13], s[60:61], 0, v[38:39]
	global_load_dwordx4 v[8:11], v[12:13], off offset:16
	s_nop 0
	global_load_dwordx4 v[12:15], v[12:13], off
	s_nop 0
	global_load_dwordx4 v[186:189], v[20:21], off offset:16
	s_nop 0
	global_load_dwordx4 v[190:193], v[20:21], off
	v_lshl_add_u64 v[20:21], s[60:61], 0, v[40:41]
	global_load_dwordx4 v[16:19], v[20:21], off offset:16
	s_nop 0
	global_load_dwordx4 v[20:23], v[20:21], off
	s_nop 0
	global_load_dwordx4 v[194:197], v[28:29], off offset:16
	s_nop 0
	global_load_dwordx4 v[198:201], v[28:29], off
	v_lshl_add_u64 v[28:29], s[60:61], 0, v[42:43]
	global_load_dwordx4 v[24:27], v[28:29], off offset:16
	s_nop 0
	global_load_dwordx4 v[28:31], v[28:29], off
	s_nop 0
	global_load_dwordx4 v[202:205], v[68:69], off offset:16
	s_nop 0
	global_load_dwordx4 v[206:209], v[68:69], off
	s_lshl_b64 s[60:61], s[0:1], 12
	v_lshl_add_u64 v[88:89], v[32:33], 0, s[60:61]
	global_load_dwordx4 v[76:79], v[88:89], off
	global_load_dwordx4 v[80:83], v[88:89], off offset:1024
	global_load_dwordx4 v[84:87], v[88:89], off offset:2048
	s_nop 0
	global_load_dwordx4 v[88:91], v[88:89], off offset:3072
	s_waitcnt vmcnt(4)
	v_pk_add_f32 v[44:45], v[180:181], 1.0 op_sel_hi:[1,0]
	v_pk_add_f32 v[50:51], v[182:183], 1.0 op_sel_hi:[1,0]
	v_pk_add_f32 v[48:49], v[184:185], 1.0 op_sel_hi:[1,0]
	v_pk_add_f32 v[46:47], v[178:179], 1.0 op_sel_hi:[1,0]
	v_pk_add_f32 v[52:53], v[188:189], 1.0 op_sel_hi:[1,0]
	v_pk_add_f32 v[58:59], v[190:191], 1.0 op_sel_hi:[1,0]
	v_pk_add_f32 v[56:57], v[192:193], 1.0 op_sel_hi:[1,0]
	v_pk_add_f32 v[54:55], v[186:187], 1.0 op_sel_hi:[1,0]
	v_pk_add_f32 v[60:61], v[196:197], 1.0 op_sel_hi:[1,0]
	v_pk_add_f32 v[66:67], v[198:199], 1.0 op_sel_hi:[1,0]
	v_pk_add_f32 v[64:65], v[200:201], 1.0 op_sel_hi:[1,0]
	v_pk_add_f32 v[62:63], v[194:195], 1.0 op_sel_hi:[1,0]
	v_pk_add_f32 v[72:73], v[208:209], 1.0 op_sel_hi:[1,0]
	v_pk_add_f32 v[74:75], v[206:207], 1.0 op_sel_hi:[1,0]
	v_pk_add_f32 v[68:69], v[204:205], 1.0 op_sel_hi:[1,0]
	v_pk_add_f32 v[70:71], v[202:203], 1.0 op_sel_hi:[1,0]
	s_add_i32 s100, s4, -6
	s_ashr_i32 s101, s100, 31
	s_lshl_b64 s[100:101], s[100:101], 12
	v_lshl_add_u64 v[210:211], v[32:33], 0, s[100:101]
	s_nop 0
	global_load_dwordx4 v[194:197], v[210:211], off
	global_load_dwordx4 v[198:201], v[210:211], off offset:1024
	global_load_dwordx4 v[202:205], v[210:211], off offset:2048
	global_load_dwordx4 v[206:209], v[210:211], off offset:3072
	s_waitcnt vmcnt(7)
	v_lshlrev_b32_e32 v97, 16, v77
	v_lshlrev_b32_e32 v96, 16, v76
	v_and_b32_e32 v77, 0xffff0000, v77
	v_and_b32_e32 v76, 0xffff0000, v76
	v_lshlrev_b32_e32 v101, 16, v79
	v_lshlrev_b32_e32 v100, 16, v78
	v_and_b32_e32 v79, 0xffff0000, v79
	v_and_b32_e32 v78, 0xffff0000, v78
	v_pk_mul_f32 v[98:99], v[76:77], v[76:77]
	v_pk_mul_f32 v[102:103], v[78:79], v[78:79]
	s_waitcnt vmcnt(4)
	v_lshlrev_b32_e32 v92, 16, v88
	v_and_b32_e32 v93, 0xffff0000, v88
	v_pk_fma_f32 v[98:99], v[96:97], v[96:97], v[98:99]
	v_pk_fma_f32 v[102:103], v[100:101], v[100:101], v[102:103]
	v_lshlrev_b32_e32 v105, 16, v81
	v_lshlrev_b32_e32 v104, 16, v80
	v_and_b32_e32 v81, 0xffff0000, v81
	v_and_b32_e32 v80, 0xffff0000, v80
	v_lshlrev_b32_e32 v109, 16, v83
	v_lshlrev_b32_e32 v108, 16, v82
	v_and_b32_e32 v83, 0xffff0000, v83
	v_and_b32_e32 v82, 0xffff0000, v82
	v_pk_mul_f32 v[106:107], v[80:81], v[80:81]
	v_pk_mul_f32 v[110:111], v[82:83], v[82:83]
	v_mul_f32_e32 v116, v92, v92
	v_mul_f32_e32 v117, v93, v93
	v_pk_add_f32 v[98:99], v[98:99], v[98:99] op_sel:[0,1] op_sel_hi:[1,0]
	v_pk_add_f32 v[102:103], v[102:103], v[102:103] op_sel:[0,1] op_sel_hi:[1,0]
	v_lshlrev_b32_e32 v88, 16, v89
	v_and_b32_e32 v89, 0xffff0000, v89
	v_pk_fma_f32 v[106:107], v[104:105], v[104:105], v[106:107]
	v_pk_fma_f32 v[110:111], v[108:109], v[108:109], v[110:111]
	v_mov_b32_e32 v99, v116
	v_mov_b32_e32 v103, v117
	v_mul_f32_e32 v118, v88, v88
	v_mul_f32_e32 v119, v89, v89
	v_pk_add_f32 v[98:99], v[98:99], v[102:103]
	v_pk_add_f32 v[102:103], v[106:107], v[106:107] op_sel:[0,1] op_sel_hi:[1,0]
	v_pk_add_f32 v[106:107], v[110:111], v[110:111] op_sel:[0,1] op_sel_hi:[1,0]
	v_mov_b32_e32 v103, v118
	v_mov_b32_e32 v107, v119
	v_lshlrev_b32_e32 v112, 16, v84
	v_and_b32_e32 v113, 0xffff0000, v84
	v_lshlrev_b32_e32 v84, 16, v85
	v_and_b32_e32 v85, 0xffff0000, v85
	v_pk_add_f32 v[102:103], v[102:103], v[106:107]
	v_lshlrev_b32_e32 v94, 16, v90
	v_and_b32_e32 v95, 0xffff0000, v90
	v_pk_add_f32 v[98:99], v[98:99], v[102:103]
	v_mul_f32_e32 v102, v113, v113
	v_mul_f32_e32 v106, v85, v85
	v_mul_f32_e32 v120, v94, v94
	v_mul_f32_e32 v121, v95, v95
	v_pk_fma_f32 v[102:103], v[112:113], v[112:113], v[102:103] op_sel_hi:[1,1,0]
	v_pk_fma_f32 v[106:107], v[84:85], v[84:85], v[106:107] op_sel_hi:[1,1,0]
	v_lshlrev_b32_e32 v114, 16, v86
	v_and_b32_e32 v115, 0xffff0000, v86
	v_lshlrev_b32_e32 v86, 16, v87
	v_and_b32_e32 v87, 0xffff0000, v87
; __device__ __forceinline__ v4u pk8(f32x4 a, f32x4 b) { v4u w; w.x = pk2(a[0], a[1]); w.y = pk2(a[2], a[3]); w.z = pk2(b[0], b[1]); w.w = pk2(b[2], b[3]); return w; }
; __device__ __forceinline__ float ssq8(const f32x4& a, const f32x4& b) { return ((a[0] * a[0] + a[1] * a[1]) + (a[2] * a[2] + a[3] * a[3])) + ((b[0] * b[0] + b[1] * b[1]) + (b[2] * b[2] + b[3] * b[3])); }
; template <int XF32> __device__ __forceinline__ void norm_mod_phase(const void* x, const float* modl, int ch_shift, int ch_scale, bf16* H, int gw, int NGW, int lane) {
;     ...
;         for (int rr = 0; rr < 8; ++rr) {
;             const unsigned char* xr = (const unsigned char*)x + (size_t)(r0 + rr) * rowb; f32x4 v[4][2]; float s = 0.f;
; #pragma unroll
;             for (int j = 0; j < 4; ++j) ld_row8<XF32>(xr, lane, j, v[j][0], v[j][1]);
; #pragma unroll
;             for (int j = 0; j < 4; ++j) s += ssq8(v[j][0], v[j][1]);
;             const float rstd = 1.f / sqrtf(wave_sum(s) * (1.f / DM) + EPS);
;             v4u* o = (v4u*)(H + (size_t)(r0 + rr) * DM);
; #pragma unroll
;             for (int j = 0; j < 4; ++j) o[lane + 64 * j] = pk8(v[j][0] * rstd * sc[j][0] + sh[j][0], v[j][1] * rstd * sc[j][1] + sh[j][1]);
	v_mov_b32_e32 v103, v120
	v_mov_b32_e32 v107, v121
	v_lshlrev_b32_e32 v90, 16, v91
	v_and_b32_e32 v91, 0xffff0000, v91
	s_add_i32 s100, s4, -5
	s_ashr_i32 s101, s100, 31
	s_lshl_b64 s[100:101], s[100:101], 12
	v_lshl_add_u64 v[210:211], v[32:33], 0, s[100:101]
	s_nop 0
	global_load_dwordx4 v[178:181], v[210:211], off
	global_load_dwordx4 v[182:185], v[210:211], off offset:1024
	global_load_dwordx4 v[186:189], v[210:211], off offset:2048
	global_load_dwordx4 v[190:193], v[210:211], off offset:3072
	v_pk_add_f32 v[102:103], v[102:103], v[106:107]
	v_mul_f32_e32 v106, v115, v115
	v_mul_f32_e32 v110, v87, v87
	v_mul_f32_e32 v122, v90, v90
	v_mul_f32_e32 v123, v91, v91
	v_pk_fma_f32 v[106:107], v[114:115], v[114:115], v[106:107] op_sel_hi:[1,1,0]
	v_pk_fma_f32 v[110:111], v[86:87], v[86:87], v[110:111] op_sel_hi:[1,1,0]
	v_mov_b32_e32 v107, v122
	v_mov_b32_e32 v111, v123
	v_pk_add_f32 v[106:107], v[106:107], v[110:111]
	s_nop 0
	v_pk_add_f32 v[102:103], v[102:103], v[106:107]
	s_nop 0
	v_pk_add_f32 v[98:99], v[98:99], v[102:103]
	s_nop 0
	v_add_f32_e32 v98, v98, v99
	s_nop 1
	v_add_f32_dpp v98, v98, v98 quad_perm:[1,0,3,2] row_mask:0xf bank_mask:0xf
	s_nop 1
	v_add_f32_dpp v98, v98, v98 quad_perm:[2,3,0,1] row_mask:0xf bank_mask:0xf
	s_nop 1
	v_add_f32_dpp v98, v98, v98 row_half_mirror row_mask:0xf bank_mask:0xf
	s_nop 1
	v_add_f32_dpp v98, v98, v98 row_mirror row_mask:0xf bank_mask:0xf
	v_mov_b32_e32 v99, v98
	s_nop 1
	v_permlane16_swap_b32_e32 v99, v98
	s_nop 1
	v_add_f32_e32 v98, v98, v99
	v_mov_b32_e32 v99, v98
	s_nop 1
	v_permlane32_swap_b32_e32 v99, v98
	s_nop 1
	v_add_f32_e32 v98, v98, v99
	v_fmamk_f32 v98, v98, 0x3a000000, v224
	v_cmp_gt_f32_e32 vcc, s41, v98
	v_mul_f32_e32 v99, 0x4f800000, v98
	s_nop 0
	v_cndmask_b32_e32 v98, v98, v99, vcc
	v_sqrt_f32_e32 v99, v98
	s_nop 0
	v_add_u32_e32 v102, -1, v99
	v_fma_f32 v103, -v102, v99, v98
	v_cmp_ge_f32_e64 s[0:1], 0, v103
	v_add_u32_e32 v103, 1, v99
	s_nop 0
	v_cndmask_b32_e64 v102, v99, v102, s[0:1]
	v_fma_f32 v99, -v103, v99, v98
	v_cmp_lt_f32_e64 s[0:1], 0, v99
	s_nop 1
	v_cndmask_b32_e64 v99, v102, v103, s[0:1]
	v_mul_f32_e32 v102, 0x37800000, v99
	v_cndmask_b32_e32 v99, v99, v102, vcc
	v_cmp_class_f32_e32 vcc, v98, v225
	s_nop 1
	v_cndmask_b32_e32 v98, v99, v98, vcc
	v_div_scale_f32 v99, s[0:1], v98, v98, 1.0
	v_rcp_f32_e32 v102, v99
	s_add_i32 s0, s4, -6
	s_ashr_i32 s1, s0, 31
	v_fma_f32 v103, -v99, v102, 1.0
	v_fmac_f32_e32 v102, v103, v102
	v_div_scale_f32 v103, vcc, 1.0, v98, 1.0
	v_mul_f32_e32 v106, v103, v102
	v_fma_f32 v107, -v99, v106, v103
	v_fmac_f32_e32 v106, v107, v102
	v_fma_f32 v99, -v99, v106, v103
	v_div_fmas_f32 v99, v99, v102, v106
	v_div_fixup_f32 v98, v99, v98, 1.0
	v_mov_b32_e32 v102, v96
	v_mov_b32_e32 v103, v76
	v_mov_b32_e32 v76, v97
	v_pk_mul_f32 v[102:103], v[98:99], v[102:103] op_sel_hi:[0,1]
	v_pk_mul_f32 v[76:77], v[98:99], v[76:77] op_sel_hi:[0,1]
	v_pk_fma_f32 v[96:97], v[48:49], v[76:77], v[6:7]
	v_pk_fma_f32 v[76:77], v[50:51], v[102:103], v[4:5]
	v_mov_b32_e32 v102, v100
	v_mov_b32_e32 v103, v78
	v_mov_b32_e32 v78, v101
	v_pk_mul_f32 v[102:103], v[98:99], v[102:103] op_sel_hi:[0,1]
	v_pk_mul_f32 v[78:79], v[98:99], v[78:79] op_sel_hi:[0,1]
	v_pk_fma_f32 v[100:101], v[44:45], v[78:79], v[2:3]
	v_pk_fma_f32 v[78:79], v[46:47], v[102:103], v[0:1]
	v_cvt_pk_bf16_f32 v76, v76, v77
	v_cvt_pk_bf16_f32 v77, v96, v97
	v_cvt_pk_bf16_f32 v78, v78, v79
	v_cvt_pk_bf16_f32 v79, v100, v101
	v_lshl_add_u64 v[96:97], v[34:35], 0, s[60:61]
	global_store_dwordx4 v[96:97], v[76:79], off
	s_lshl_b64 s[60:61], s[0:1], 12
	s_nop 0
	v_mov_b32_e32 v77, v80
	v_mov_b32_e32 v80, v105
	v_mov_b32_e32 v76, v104
	v_pk_mul_f32 v[78:79], v[98:99], v[80:81] op_sel_hi:[0,1]
	v_mov_b32_e32 v80, v108
	v_mov_b32_e32 v81, v82
	v_mov_b32_e32 v82, v109
	v_pk_mul_f32 v[76:77], v[98:99], v[76:77] op_sel_hi:[0,1]
	v_pk_mul_f32 v[80:81], v[98:99], v[80:81] op_sel_hi:[0,1]
	v_pk_mul_f32 v[82:83], v[98:99], v[82:83] op_sel_hi:[0,1]
	v_pk_fma_f32 v[78:79], v[56:57], v[78:79], v[14:15]
	v_pk_fma_f32 v[76:77], v[58:59], v[76:77], v[12:13]
	v_pk_fma_f32 v[82:83], v[52:53], v[82:83], v[10:11]
	v_pk_fma_f32 v[80:81], v[54:55], v[80:81], v[8:9]
	v_cvt_pk_bf16_f32 v76, v76, v77
	v_cvt_pk_bf16_f32 v77, v78, v79
	v_cvt_pk_bf16_f32 v78, v80, v81
	v_cvt_pk_bf16_f32 v79, v82, v83
	global_store_dwordx4 v[96:97], v[76:79], off offset:1024
	v_pk_mul_f32 v[80:81], v[98:99], v[114:115] op_sel_hi:[0,1]
	v_pk_mul_f32 v[82:83], v[98:99], v[86:87] op_sel_hi:[0,1]
	v_pk_mul_f32 v[76:77], v[98:99], v[112:113] op_sel_hi:[0,1]
	v_pk_mul_f32 v[78:79], v[98:99], v[84:85] op_sel_hi:[0,1]
	v_pk_fma_f32 v[78:79], v[64:65], v[78:79], v[22:23]
	v_pk_fma_f32 v[76:77], v[66:67], v[76:77], v[20:21]
	v_pk_fma_f32 v[82:83], v[60:61], v[82:83], v[18:19]
	v_pk_fma_f32 v[80:81], v[62:63], v[80:81], v[16:17]
	v_cvt_pk_bf16_f32 v76, v76, v77
	v_cvt_pk_bf16_f32 v77, v78, v79
	v_cvt_pk_bf16_f32 v78, v80, v81
	v_cvt_pk_bf16_f32 v79, v82, v83
	global_store_dwordx4 v[96:97], v[76:79], off offset:2048
	v_pk_mul_f32 v[80:81], v[94:95], v[98:99] op_sel_hi:[1,0]
	v_pk_mul_f32 v[82:83], v[90:91], v[98:99] op_sel_hi:[1,0]
	v_pk_mul_f32 v[76:77], v[92:93], v[98:99] op_sel_hi:[1,0]
	v_pk_mul_f32 v[78:79], v[88:89], v[98:99] op_sel_hi:[1,0]
	v_pk_fma_f32 v[76:77], v[74:75], v[76:77], v[28:29]
	v_pk_fma_f32 v[78:79], v[72:73], v[78:79], v[30:31]
	v_pk_fma_f32 v[82:83], v[68:69], v[82:83], v[26:27]
	v_pk_fma_f32 v[80:81], v[70:71], v[80:81], v[24:25]
	v_cvt_pk_bf16_f32 v76, v76, v77
	v_cvt_pk_bf16_f32 v77, v78, v79
	v_cvt_pk_bf16_f32 v78, v80, v81
	v_cvt_pk_bf16_f32 v79, v82, v83
	global_store_dwordx4 v[96:97], v[76:79], off offset:3072
	s_waitcnt vmcnt(11)
; __device__ __forceinline__ v4u pk8(f32x4 a, f32x4 b) { v4u w; w.x = pk2(a[0], a[1]); w.y = pk2(a[2], a[3]); w.z = pk2(b[0], b[1]); w.w = pk2(b[2], b[3]); return w; }
; __device__ __forceinline__ float ssq8(const f32x4& a, const f32x4& b) { return ((a[0] * a[0] + a[1] * a[1]) + (a[2] * a[2] + a[3] * a[3])) + ((b[0] * b[0] + b[1] * b[1]) + (b[2] * b[2] + b[3] * b[3])); }
; __device__ __forceinline__ float shfl_xor_f(float v, int o) {
;     int l; asm volatile("v_mbcnt_lo_u32_b32 %0, -1, 0\n\tv_mbcnt_hi_u32_b32 %0, -1, %0" : "=v"(l));
;     return __builtin_bit_cast(float, __builtin_amdgcn_ds_bpermute((l ^ o) << 2, __builtin_bit_cast(int, v)));
; }
; __device__ __forceinline__ float wave_sum(float v) {
; #pragma unroll
;     for (int o = 1; o < 64; o <<= 1) v += shfl_xor_f(v, o);
;     return v;
; template <int XF32> __device__ __forceinline__ void norm_mod_phase(const void* x, const float* modl, int ch_shift, int ch_scale, bf16* H, int gw, int NGW, int lane) {
;     ...
;         for (int rr = 0; rr < 8; ++rr) {
;             const unsigned char* xr = (const unsigned char*)x + (size_t)(r0 + rr) * rowb; f32x4 v[4][2]; float s = 0.f;
; #pragma unroll
;             for (int j = 0; j < 4; ++j) ld_row8<XF32>(xr, lane, j, v[j][0], v[j][1]);
; #pragma unroll
;             for (int j = 0; j < 4; ++j) s += ssq8(v[j][0], v[j][1]);
;             const float rstd = 1.f / sqrtf(wave_sum(s) * (1.f / DM) + EPS);
;             v4u* o = (v4u*)(H + (size_t)(r0 + rr) * DM);
; #pragma unroll
;             for (int j = 0; j < 4; ++j) o[lane + 64 * j] = pk8(v[j][0] * rstd * sc[j][0] + sh[j][0], v[j][1] * rstd * sc[j][1] + sh[j][1]);
;         }
	v_lshlrev_b32_e32 v97, 16, v195
	v_lshlrev_b32_e32 v96, 16, v194
	v_and_b32_e32 v77, 0xffff0000, v195
	v_and_b32_e32 v76, 0xffff0000, v194
	v_lshlrev_b32_e32 v101, 16, v197
	v_lshlrev_b32_e32 v100, 16, v196
	v_and_b32_e32 v79, 0xffff0000, v197
	v_and_b32_e32 v78, 0xffff0000, v196
	v_pk_mul_f32 v[98:99], v[76:77], v[76:77]
	v_pk_mul_f32 v[102:103], v[78:79], v[78:79]
	s_waitcnt vmcnt(8)
	v_lshlrev_b32_e32 v92, 16, v206
	v_and_b32_e32 v93, 0xffff0000, v206
	v_pk_fma_f32 v[98:99], v[96:97], v[96:97], v[98:99]
	v_pk_fma_f32 v[102:103], v[100:101], v[100:101], v[102:103]
	v_lshlrev_b32_e32 v105, 16, v199
	v_lshlrev_b32_e32 v104, 16, v198
	v_and_b32_e32 v81, 0xffff0000, v199
	v_and_b32_e32 v80, 0xffff0000, v198
	v_lshlrev_b32_e32 v109, 16, v201
	v_lshlrev_b32_e32 v108, 16, v200
	v_and_b32_e32 v83, 0xffff0000, v201
	v_and_b32_e32 v82, 0xffff0000, v200
	v_pk_mul_f32 v[106:107], v[80:81], v[80:81]
	v_pk_mul_f32 v[110:111], v[82:83], v[82:83]
	v_mul_f32_e32 v116, v92, v92
	v_mul_f32_e32 v117, v93, v93
	v_pk_add_f32 v[98:99], v[98:99], v[98:99] op_sel:[0,1] op_sel_hi:[1,0]
	v_pk_add_f32 v[102:103], v[102:103], v[102:103] op_sel:[0,1] op_sel_hi:[1,0]
	v_lshlrev_b32_e32 v88, 16, v207
	v_and_b32_e32 v89, 0xffff0000, v207
	v_pk_fma_f32 v[106:107], v[104:105], v[104:105], v[106:107]
	v_pk_fma_f32 v[110:111], v[108:109], v[108:109], v[110:111]
	v_mov_b32_e32 v99, v116
	v_mov_b32_e32 v103, v117
	v_mul_f32_e32 v118, v88, v88
	v_mul_f32_e32 v119, v89, v89
	v_pk_add_f32 v[98:99], v[98:99], v[102:103]
	v_pk_add_f32 v[102:103], v[106:107], v[106:107] op_sel:[0,1] op_sel_hi:[1,0]
	v_pk_add_f32 v[106:107], v[110:111], v[110:111] op_sel:[0,1] op_sel_hi:[1,0]
	v_mov_b32_e32 v103, v118
	v_mov_b32_e32 v107, v119
	v_lshlrev_b32_e32 v112, 16, v202
	v_and_b32_e32 v113, 0xffff0000, v202
	v_lshlrev_b32_e32 v84, 16, v203
	v_and_b32_e32 v85, 0xffff0000, v203
	v_pk_add_f32 v[102:103], v[102:103], v[106:107]
	v_lshlrev_b32_e32 v94, 16, v208
	v_and_b32_e32 v95, 0xffff0000, v208
	v_pk_add_f32 v[98:99], v[98:99], v[102:103]
	v_mul_f32_e32 v102, v113, v113
	v_mul_f32_e32 v106, v85, v85
	v_mul_f32_e32 v120, v94, v94
	v_mul_f32_e32 v121, v95, v95
	v_pk_fma_f32 v[102:103], v[112:113], v[112:113], v[102:103] op_sel_hi:[1,1,0]
	v_pk_fma_f32 v[106:107], v[84:85], v[84:85], v[106:107] op_sel_hi:[1,1,0]
	v_lshlrev_b32_e32 v114, 16, v204
	v_and_b32_e32 v115, 0xffff0000, v204
	v_lshlrev_b32_e32 v86, 16, v205
	v_and_b32_e32 v87, 0xffff0000, v205
	v_mov_b32_e32 v103, v120
	v_mov_b32_e32 v107, v121
	v_lshlrev_b32_e32 v90, 16, v209
	v_and_b32_e32 v91, 0xffff0000, v209
	s_add_i32 s100, s4, -4
	s_ashr_i32 s101, s100, 31
	s_lshl_b64 s[100:101], s[100:101], 12
	v_lshl_add_u64 v[210:211], v[32:33], 0, s[100:101]
	s_nop 0
	global_load_dwordx4 v[194:197], v[210:211], off
	global_load_dwordx4 v[198:201], v[210:211], off offset:1024
	global_load_dwordx4 v[202:205], v[210:211], off offset:2048
	global_load_dwordx4 v[206:209], v[210:211], off offset:3072
	v_pk_add_f32 v[102:103], v[102:103], v[106:107]
	v_mul_f32_e32 v106, v115, v115
	v_mul_f32_e32 v110, v87, v87
	v_mul_f32_e32 v122, v90, v90
	v_mul_f32_e32 v123, v91, v91
	v_pk_fma_f32 v[106:107], v[114:115], v[114:115], v[106:107] op_sel_hi:[1,1,0]
	v_pk_fma_f32 v[110:111], v[86:87], v[86:87], v[110:111] op_sel_hi:[1,1,0]
	v_mov_b32_e32 v107, v122
	v_mov_b32_e32 v111, v123
	v_pk_add_f32 v[106:107], v[106:107], v[110:111]
	s_nop 0
	v_pk_add_f32 v[102:103], v[102:103], v[106:107]
	s_nop 0
	v_pk_add_f32 v[98:99], v[98:99], v[102:103]
	s_nop 0
	v_add_f32_e32 v98, v98, v99
	s_nop 1
	v_add_f32_dpp v98, v98, v98 quad_perm:[1,0,3,2] row_mask:0xf bank_mask:0xf
	s_nop 1
	v_add_f32_dpp v98, v98, v98 quad_perm:[2,3,0,1] row_mask:0xf bank_mask:0xf
	s_nop 1
	v_add_f32_dpp v98, v98, v98 row_half_mirror row_mask:0xf bank_mask:0xf
	s_nop 1
	v_add_f32_dpp v98, v98, v98 row_mirror row_mask:0xf bank_mask:0xf
	v_mov_b32_e32 v99, v98
	s_nop 1
	v_permlane16_swap_b32_e32 v99, v98
	s_nop 1
	v_add_f32_e32 v98, v98, v99
	v_mov_b32_e32 v99, v98
	s_nop 1
	v_permlane32_swap_b32_e32 v99, v98
	s_nop 1
	v_add_f32_e32 v98, v98, v99
	v_fmamk_f32 v98, v98, 0x3a000000, v224
	v_cmp_gt_f32_e32 vcc, s41, v98
	v_mul_f32_e32 v99, 0x4f800000, v98
	s_nop 0
	v_cndmask_b32_e32 v98, v98, v99, vcc
	v_sqrt_f32_e32 v99, v98
	s_nop 0
	v_add_u32_e32 v102, -1, v99
	v_fma_f32 v103, -v102, v99, v98
	v_cmp_ge_f32_e64 s[0:1], 0, v103
	v_add_u32_e32 v103, 1, v99
	s_nop 0
	v_cndmask_b32_e64 v102, v99, v102, s[0:1]
	v_fma_f32 v99, -v103, v99, v98
	v_cmp_lt_f32_e64 s[0:1], 0, v99
	s_nop 1
	v_cndmask_b32_e64 v99, v102, v103, s[0:1]
	v_mul_f32_e32 v102, 0x37800000, v99
	v_cndmask_b32_e32 v99, v99, v102, vcc
	v_cmp_class_f32_e32 vcc, v98, v225
	s_nop 1
	v_cndmask_b32_e32 v98, v99, v98, vcc
	v_div_scale_f32 v99, s[0:1], v98, v98, 1.0
	v_rcp_f32_e32 v102, v99
	s_add_i32 s0, s4, -5
	s_ashr_i32 s1, s0, 31
	v_fma_f32 v103, -v99, v102, 1.0
	v_fmac_f32_e32 v102, v103, v102
	v_div_scale_f32 v103, vcc, 1.0, v98, 1.0
	v_mul_f32_e32 v106, v103, v102
	v_fma_f32 v107, -v99, v106, v103
	v_fmac_f32_e32 v106, v107, v102
	v_fma_f32 v99, -v99, v106, v103
	v_div_fmas_f32 v99, v99, v102, v106
	v_div_fixup_f32 v98, v99, v98, 1.0
	v_mov_b32_e32 v102, v96
	v_mov_b32_e32 v103, v76
	v_mov_b32_e32 v76, v97
	v_pk_mul_f32 v[102:103], v[98:99], v[102:103] op_sel_hi:[0,1]
	v_pk_mul_f32 v[76:77], v[98:99], v[76:77] op_sel_hi:[0,1]
	v_pk_fma_f32 v[96:97], v[48:49], v[76:77], v[6:7]
	v_pk_fma_f32 v[76:77], v[50:51], v[102:103], v[4:5]
	v_mov_b32_e32 v102, v100
	v_mov_b32_e32 v103, v78
	v_mov_b32_e32 v78, v101
	v_pk_mul_f32 v[102:103], v[98:99], v[102:103] op_sel_hi:[0,1]
	v_pk_mul_f32 v[78:79], v[98:99], v[78:79] op_sel_hi:[0,1]
; __device__ __forceinline__ v4u pk8(f32x4 a, f32x4 b) { v4u w; w.x = pk2(a[0], a[1]); w.y = pk2(a[2], a[3]); w.z = pk2(b[0], b[1]); w.w = pk2(b[2], b[3]); return w; }
; __device__ __forceinline__ float ssq8(const f32x4& a, const f32x4& b) { return ((a[0] * a[0] + a[1] * a[1]) + (a[2] * a[2] + a[3] * a[3])) + ((b[0] * b[0] + b[1] * b[1]) + (b[2] * b[2] + b[3] * b[3])); }
; template <int XF32> __device__ __forceinline__ void norm_mod_phase(const void* x, const float* modl, int ch_shift, int ch_scale, bf16* H, int gw, int NGW, int lane) {
;     ...
;         for (int rr = 0; rr < 8; ++rr) {
;             const unsigned char* xr = (const unsigned char*)x + (size_t)(r0 + rr) * rowb; f32x4 v[4][2]; float s = 0.f;
; #pragma unroll
;             for (int j = 0; j < 4; ++j) ld_row8<XF32>(xr, lane, j, v[j][0], v[j][1]);
; #pragma unroll
;             for (int j = 0; j < 4; ++j) s += ssq8(v[j][0], v[j][1]);
;             const float rstd = 1.f / sqrtf(wave_sum(s) * (1.f / DM) + EPS);
;             v4u* o = (v4u*)(H + (size_t)(r0 + rr) * DM);
; #pragma unroll
;             for (int j = 0; j < 4; ++j) o[lane + 64 * j] = pk8(v[j][0] * rstd * sc[j][0] + sh[j][0], v[j][1] * rstd * sc[j][1] + sh[j][1]);
;         }
	v_pk_fma_f32 v[100:101], v[44:45], v[78:79], v[2:3]
	v_pk_fma_f32 v[78:79], v[46:47], v[102:103], v[0:1]
	v_cvt_pk_bf16_f32 v76, v76, v77
	v_cvt_pk_bf16_f32 v77, v96, v97
	v_cvt_pk_bf16_f32 v78, v78, v79
	v_cvt_pk_bf16_f32 v79, v100, v101
	v_lshl_add_u64 v[96:97], v[34:35], 0, s[60:61]
	global_store_dwordx4 v[96:97], v[76:79], off
	s_lshl_b64 s[60:61], s[0:1], 12
	s_nop 0
	v_mov_b32_e32 v77, v80
	v_mov_b32_e32 v80, v105
	v_mov_b32_e32 v76, v104
	v_pk_mul_f32 v[78:79], v[98:99], v[80:81] op_sel_hi:[0,1]
	v_mov_b32_e32 v80, v108
	v_mov_b32_e32 v81, v82
	v_mov_b32_e32 v82, v109
	v_pk_mul_f32 v[76:77], v[98:99], v[76:77] op_sel_hi:[0,1]
	v_pk_mul_f32 v[80:81], v[98:99], v[80:81] op_sel_hi:[0,1]
	v_pk_mul_f32 v[82:83], v[98:99], v[82:83] op_sel_hi:[0,1]
	v_pk_fma_f32 v[78:79], v[56:57], v[78:79], v[14:15]
	v_pk_fma_f32 v[76:77], v[58:59], v[76:77], v[12:13]
	v_pk_fma_f32 v[82:83], v[52:53], v[82:83], v[10:11]
	v_pk_fma_f32 v[80:81], v[54:55], v[80:81], v[8:9]
	v_cvt_pk_bf16_f32 v76, v76, v77
	v_cvt_pk_bf16_f32 v77, v78, v79
	v_cvt_pk_bf16_f32 v78, v80, v81
	v_cvt_pk_bf16_f32 v79, v82, v83
	global_store_dwordx4 v[96:97], v[76:79], off offset:1024
	v_pk_mul_f32 v[80:81], v[98:99], v[114:115] op_sel_hi:[0,1]
	v_pk_mul_f32 v[82:83], v[98:99], v[86:87] op_sel_hi:[0,1]
	v_pk_mul_f32 v[76:77], v[98:99], v[112:113] op_sel_hi:[0,1]
	v_pk_mul_f32 v[78:79], v[98:99], v[84:85] op_sel_hi:[0,1]
	v_pk_fma_f32 v[78:79], v[64:65], v[78:79], v[22:23]
	v_pk_fma_f32 v[76:77], v[66:67], v[76:77], v[20:21]
	v_pk_fma_f32 v[82:83], v[60:61], v[82:83], v[18:19]
	v_pk_fma_f32 v[80:81], v[62:63], v[80:81], v[16:17]
	v_cvt_pk_bf16_f32 v76, v76, v77
	v_cvt_pk_bf16_f32 v77, v78, v79
	v_cvt_pk_bf16_f32 v78, v80, v81
	v_cvt_pk_bf16_f32 v79, v82, v83
	global_store_dwordx4 v[96:97], v[76:79], off offset:2048
	v_pk_mul_f32 v[80:81], v[94:95], v[98:99] op_sel_hi:[1,0]
	v_pk_mul_f32 v[82:83], v[90:91], v[98:99] op_sel_hi:[1,0]
	v_pk_mul_f32 v[76:77], v[92:93], v[98:99] op_sel_hi:[1,0]
	v_pk_mul_f32 v[78:79], v[88:89], v[98:99] op_sel_hi:[1,0]
	v_pk_fma_f32 v[76:77], v[74:75], v[76:77], v[28:29]
	v_pk_fma_f32 v[78:79], v[72:73], v[78:79], v[30:31]
	v_pk_fma_f32 v[82:83], v[68:69], v[82:83], v[26:27]
	v_pk_fma_f32 v[80:81], v[70:71], v[80:81], v[24:25]
	v_cvt_pk_bf16_f32 v76, v76, v77
	v_cvt_pk_bf16_f32 v77, v78, v79
	v_cvt_pk_bf16_f32 v78, v80, v81
	v_cvt_pk_bf16_f32 v79, v82, v83
	global_store_dwordx4 v[96:97], v[76:79], off offset:3072
	s_waitcnt vmcnt(11)
	v_lshlrev_b32_e32 v97, 16, v179
	v_lshlrev_b32_e32 v96, 16, v178
	v_and_b32_e32 v77, 0xffff0000, v179
	v_and_b32_e32 v76, 0xffff0000, v178
	v_lshlrev_b32_e32 v101, 16, v181
	v_lshlrev_b32_e32 v100, 16, v180
	v_and_b32_e32 v79, 0xffff0000, v181
	v_and_b32_e32 v78, 0xffff0000, v180
	v_pk_mul_f32 v[98:99], v[76:77], v[76:77]
	v_pk_mul_f32 v[102:103], v[78:79], v[78:79]
	s_waitcnt vmcnt(8)
	v_lshlrev_b32_e32 v92, 16, v190
	v_and_b32_e32 v93, 0xffff0000, v190
	v_pk_fma_f32 v[98:99], v[96:97], v[96:97], v[98:99]
	v_pk_fma_f32 v[102:103], v[100:101], v[100:101], v[102:103]
	v_lshlrev_b32_e32 v105, 16, v183
	v_lshlrev_b32_e32 v104, 16, v182
	v_and_b32_e32 v81, 0xffff0000, v183
	v_and_b32_e32 v80, 0xffff0000, v182
	v_lshlrev_b32_e32 v109, 16, v185
	v_lshlrev_b32_e32 v108, 16, v184
	v_and_b32_e32 v83, 0xffff0000, v185
	v_and_b32_e32 v82, 0xffff0000, v184
	v_pk_mul_f32 v[106:107], v[80:81], v[80:81]
	v_pk_mul_f32 v[110:111], v[82:83], v[82:83]
	v_mul_f32_e32 v116, v92, v92
	v_mul_f32_e32 v117, v93, v93
	v_pk_add_f32 v[98:99], v[98:99], v[98:99] op_sel:[0,1] op_sel_hi:[1,0]
	v_pk_add_f32 v[102:103], v[102:103], v[102:103] op_sel:[0,1] op_sel_hi:[1,0]
	v_lshlrev_b32_e32 v88, 16, v191
	v_and_b32_e32 v89, 0xffff0000, v191
	v_pk_fma_f32 v[106:107], v[104:105], v[104:105], v[106:107]
	v_pk_fma_f32 v[110:111], v[108:109], v[108:109], v[110:111]
	v_mov_b32_e32 v99, v116
	v_mov_b32_e32 v103, v117
	v_mul_f32_e32 v118, v88, v88
	v_mul_f32_e32 v119, v89, v89
	v_pk_add_f32 v[98:99], v[98:99], v[102:103]
	v_pk_add_f32 v[102:103], v[106:107], v[106:107] op_sel:[0,1] op_sel_hi:[1,0]
	v_pk_add_f32 v[106:107], v[110:111], v[110:111] op_sel:[0,1] op_sel_hi:[1,0]
	v_mov_b32_e32 v103, v118
	v_mov_b32_e32 v107, v119
	v_lshlrev_b32_e32 v112, 16, v186
	v_and_b32_e32 v113, 0xffff0000, v186
	v_lshlrev_b32_e32 v84, 16, v187
	v_and_b32_e32 v85, 0xffff0000, v187
	v_pk_add_f32 v[102:103], v[102:103], v[106:107]
	v_lshlrev_b32_e32 v94, 16, v192
	v_and_b32_e32 v95, 0xffff0000, v192
	v_pk_add_f32 v[98:99], v[98:99], v[102:103]
	v_mul_f32_e32 v102, v113, v113
	v_mul_f32_e32 v106, v85, v85
	v_mul_f32_e32 v120, v94, v94
	v_mul_f32_e32 v121, v95, v95
	v_pk_fma_f32 v[102:103], v[112:113], v[112:113], v[102:103] op_sel_hi:[1,1,0]
	v_pk_fma_f32 v[106:107], v[84:85], v[84:85], v[106:107] op_sel_hi:[1,1,0]
	v_lshlrev_b32_e32 v114, 16, v188
	v_and_b32_e32 v115, 0xffff0000, v188
	v_lshlrev_b32_e32 v86, 16, v189
	v_and_b32_e32 v87, 0xffff0000, v189
	v_mov_b32_e32 v103, v120
	v_mov_b32_e32 v107, v121
	v_lshlrev_b32_e32 v90, 16, v193
	v_and_b32_e32 v91, 0xffff0000, v193
	s_add_i32 s100, s4, -3
	s_ashr_i32 s101, s100, 31
	s_lshl_b64 s[100:101], s[100:101], 12
	v_lshl_add_u64 v[210:211], v[32:33], 0, s[100:101]
	s_nop 0
	global_load_dwordx4 v[178:181], v[210:211], off
	global_load_dwordx4 v[182:185], v[210:211], off offset:1024
	global_load_dwordx4 v[186:189], v[210:211], off offset:2048
	global_load_dwordx4 v[190:193], v[210:211], off offset:3072
	v_pk_add_f32 v[102:103], v[102:103], v[106:107]
	v_mul_f32_e32 v106, v115, v115
	v_mul_f32_e32 v110, v87, v87
	v_mul_f32_e32 v122, v90, v90
	v_mul_f32_e32 v123, v91, v91
	v_pk_fma_f32 v[106:107], v[114:115], v[114:115], v[106:107] op_sel_hi:[1,1,0]
; __device__ __forceinline__ v4u pk8(f32x4 a, f32x4 b) { v4u w; w.x = pk2(a[0], a[1]); w.y = pk2(a[2], a[3]); w.z = pk2(b[0], b[1]); w.w = pk2(b[2], b[3]); return w; }
; __device__ __forceinline__ float ssq8(const f32x4& a, const f32x4& b) { return ((a[0] * a[0] + a[1] * a[1]) + (a[2] * a[2] + a[3] * a[3])) + ((b[0] * b[0] + b[1] * b[1]) + (b[2] * b[2] + b[3] * b[3])); }
; __device__ __forceinline__ float shfl_xor_f(float v, int o) {
;     int l; asm volatile("v_mbcnt_lo_u32_b32 %0, -1, 0\n\tv_mbcnt_hi_u32_b32 %0, -1, %0" : "=v"(l));
;     return __builtin_bit_cast(float, __builtin_amdgcn_ds_bpermute((l ^ o) << 2, __builtin_bit_cast(int, v)));
; }
; __device__ __forceinline__ float wave_sum(float v) {
; #pragma unroll
;     for (int o = 1; o < 64; o <<= 1) v += shfl_xor_f(v, o);
;     return v;
; template <int XF32> __device__ __forceinline__ void norm_mod_phase(const void* x, const float* modl, int ch_shift, int ch_scale, bf16* H, int gw, int NGW, int lane) {
;     ...
;         for (int rr = 0; rr < 8; ++rr) {
;             const unsigned char* xr = (const unsigned char*)x + (size_t)(r0 + rr) * rowb; f32x4 v[4][2]; float s = 0.f;
; #pragma unroll
;             for (int j = 0; j < 4; ++j) ld_row8<XF32>(xr, lane, j, v[j][0], v[j][1]);
; #pragma unroll
;             for (int j = 0; j < 4; ++j) s += ssq8(v[j][0], v[j][1]);
;             const float rstd = 1.f / sqrtf(wave_sum(s) * (1.f / DM) + EPS);
;             v4u* o = (v4u*)(H + (size_t)(r0 + rr) * DM);
; #pragma unroll
;             for (int j = 0; j < 4; ++j) o[lane + 64 * j] = pk8(v[j][0] * rstd * sc[j][0] + sh[j][0], v[j][1] * rstd * sc[j][1] + sh[j][1]);
;         }
	v_pk_fma_f32 v[110:111], v[86:87], v[86:87], v[110:111] op_sel_hi:[1,1,0]
	v_mov_b32_e32 v107, v122
	v_mov_b32_e32 v111, v123
	v_pk_add_f32 v[106:107], v[106:107], v[110:111]
	s_nop 0
	v_pk_add_f32 v[102:103], v[102:103], v[106:107]
	s_nop 0
	v_pk_add_f32 v[98:99], v[98:99], v[102:103]
	s_nop 0
	v_add_f32_e32 v98, v98, v99
	s_nop 1
	v_add_f32_dpp v98, v98, v98 quad_perm:[1,0,3,2] row_mask:0xf bank_mask:0xf
	s_nop 1
	v_add_f32_dpp v98, v98, v98 quad_perm:[2,3,0,1] row_mask:0xf bank_mask:0xf
	s_nop 1
	v_add_f32_dpp v98, v98, v98 row_half_mirror row_mask:0xf bank_mask:0xf
	s_nop 1
	v_add_f32_dpp v98, v98, v98 row_mirror row_mask:0xf bank_mask:0xf
	v_mov_b32_e32 v99, v98
	s_nop 1
	v_permlane16_swap_b32_e32 v99, v98
	s_nop 1
	v_add_f32_e32 v98, v98, v99
	v_mov_b32_e32 v99, v98
	s_nop 1
	v_permlane32_swap_b32_e32 v99, v98
	s_nop 1
	v_add_f32_e32 v98, v98, v99
	v_fmamk_f32 v98, v98, 0x3a000000, v224
	v_cmp_gt_f32_e32 vcc, s41, v98
	v_mul_f32_e32 v99, 0x4f800000, v98
	s_nop 0
	v_cndmask_b32_e32 v98, v98, v99, vcc
	v_sqrt_f32_e32 v99, v98
	s_nop 0
	v_add_u32_e32 v102, -1, v99
	v_fma_f32 v103, -v102, v99, v98
	v_cmp_ge_f32_e64 s[0:1], 0, v103
	v_add_u32_e32 v103, 1, v99
	s_nop 0
	v_cndmask_b32_e64 v102, v99, v102, s[0:1]
	v_fma_f32 v99, -v103, v99, v98
	v_cmp_lt_f32_e64 s[0:1], 0, v99
	s_nop 1
	v_cndmask_b32_e64 v99, v102, v103, s[0:1]
	v_mul_f32_e32 v102, 0x37800000, v99
	v_cndmask_b32_e32 v99, v99, v102, vcc
	v_cmp_class_f32_e32 vcc, v98, v225
	s_nop 1
	v_cndmask_b32_e32 v98, v99, v98, vcc
	v_div_scale_f32 v99, s[0:1], v98, v98, 1.0
	v_rcp_f32_e32 v102, v99
	s_add_i32 s0, s4, -4
	s_ashr_i32 s1, s0, 31
	v_fma_f32 v103, -v99, v102, 1.0
	v_fmac_f32_e32 v102, v103, v102
	v_div_scale_f32 v103, vcc, 1.0, v98, 1.0
	v_mul_f32_e32 v106, v103, v102
	v_fma_f32 v107, -v99, v106, v103
	v_fmac_f32_e32 v106, v107, v102
	v_fma_f32 v99, -v99, v106, v103
	v_div_fmas_f32 v99, v99, v102, v106
	v_div_fixup_f32 v98, v99, v98, 1.0
	v_mov_b32_e32 v102, v96
	v_mov_b32_e32 v103, v76
	v_mov_b32_e32 v76, v97
	v_pk_mul_f32 v[102:103], v[98:99], v[102:103] op_sel_hi:[0,1]
	v_pk_mul_f32 v[76:77], v[98:99], v[76:77] op_sel_hi:[0,1]
	v_pk_fma_f32 v[96:97], v[48:49], v[76:77], v[6:7]
	v_pk_fma_f32 v[76:77], v[50:51], v[102:103], v[4:5]
	v_mov_b32_e32 v102, v100
	v_mov_b32_e32 v103, v78
	v_mov_b32_e32 v78, v101
	v_pk_mul_f32 v[102:103], v[98:99], v[102:103] op_sel_hi:[0,1]
	v_pk_mul_f32 v[78:79], v[98:99], v[78:79] op_sel_hi:[0,1]
	v_pk_fma_f32 v[100:101], v[44:45], v[78:79], v[2:3]
	v_pk_fma_f32 v[78:79], v[46:47], v[102:103], v[0:1]
	v_cvt_pk_bf16_f32 v76, v76, v77
	v_cvt_pk_bf16_f32 v77, v96, v97
	v_cvt_pk_bf16_f32 v78, v78, v79
	v_cvt_pk_bf16_f32 v79, v100, v101
	v_lshl_add_u64 v[96:97], v[34:35], 0, s[60:61]
	global_store_dwordx4 v[96:97], v[76:79], off
	s_lshl_b64 s[60:61], s[0:1], 12
	s_nop 0
	v_mov_b32_e32 v77, v80
	v_mov_b32_e32 v80, v105
	v_mov_b32_e32 v76, v104
	v_pk_mul_f32 v[78:79], v[98:99], v[80:81] op_sel_hi:[0,1]
	v_mov_b32_e32 v80, v108
	v_mov_b32_e32 v81, v82
	v_mov_b32_e32 v82, v109
	v_pk_mul_f32 v[76:77], v[98:99], v[76:77] op_sel_hi:[0,1]
	v_pk_mul_f32 v[80:81], v[98:99], v[80:81] op_sel_hi:[0,1]
	v_pk_mul_f32 v[82:83], v[98:99], v[82:83] op_sel_hi:[0,1]
	v_pk_fma_f32 v[78:79], v[56:57], v[78:79], v[14:15]
	v_pk_fma_f32 v[76:77], v[58:59], v[76:77], v[12:13]
	v_pk_fma_f32 v[82:83], v[52:53], v[82:83], v[10:11]
	v_pk_fma_f32 v[80:81], v[54:55], v[80:81], v[8:9]
	v_cvt_pk_bf16_f32 v76, v76, v77
	v_cvt_pk_bf16_f32 v77, v78, v79
	v_cvt_pk_bf16_f32 v78, v80, v81
	v_cvt_pk_bf16_f32 v79, v82, v83
	global_store_dwordx4 v[96:97], v[76:79], off offset:1024
	v_pk_mul_f32 v[80:81], v[98:99], v[114:115] op_sel_hi:[0,1]
	v_pk_mul_f32 v[82:83], v[98:99], v[86:87] op_sel_hi:[0,1]
	v_pk_mul_f32 v[76:77], v[98:99], v[112:113] op_sel_hi:[0,1]
	v_pk_mul_f32 v[78:79], v[98:99], v[84:85] op_sel_hi:[0,1]
	v_pk_fma_f32 v[78:79], v[64:65], v[78:79], v[22:23]
	v_pk_fma_f32 v[76:77], v[66:67], v[76:77], v[20:21]
	v_pk_fma_f32 v[82:83], v[60:61], v[82:83], v[18:19]
	v_pk_fma_f32 v[80:81], v[62:63], v[80:81], v[16:17]
	v_cvt_pk_bf16_f32 v76, v76, v77
	v_cvt_pk_bf16_f32 v77, v78, v79
	v_cvt_pk_bf16_f32 v78, v80, v81
	v_cvt_pk_bf16_f32 v79, v82, v83
	global_store_dwordx4 v[96:97], v[76:79], off offset:2048
	v_pk_mul_f32 v[80:81], v[94:95], v[98:99] op_sel_hi:[1,0]
	v_pk_mul_f32 v[82:83], v[90:91], v[98:99] op_sel_hi:[1,0]
	v_pk_mul_f32 v[76:77], v[92:93], v[98:99] op_sel_hi:[1,0]
	v_pk_mul_f32 v[78:79], v[88:89], v[98:99] op_sel_hi:[1,0]
	v_pk_fma_f32 v[76:77], v[74:75], v[76:77], v[28:29]
	v_pk_fma_f32 v[78:79], v[72:73], v[78:79], v[30:31]
	v_pk_fma_f32 v[82:83], v[68:69], v[82:83], v[26:27]
	v_pk_fma_f32 v[80:81], v[70:71], v[80:81], v[24:25]
	v_cvt_pk_bf16_f32 v76, v76, v77
	v_cvt_pk_bf16_f32 v77, v78, v79
	v_cvt_pk_bf16_f32 v78, v80, v81
	v_cvt_pk_bf16_f32 v79, v82, v83
	global_store_dwordx4 v[96:97], v[76:79], off offset:3072
	s_waitcnt vmcnt(11)
	v_lshlrev_b32_e32 v97, 16, v195
	v_lshlrev_b32_e32 v96, 16, v194
	v_and_b32_e32 v77, 0xffff0000, v195
	v_and_b32_e32 v76, 0xffff0000, v194
	v_lshlrev_b32_e32 v101, 16, v197
	v_lshlrev_b32_e32 v100, 16, v196
	v_and_b32_e32 v79, 0xffff0000, v197
	v_and_b32_e32 v78, 0xffff0000, v196
	v_pk_mul_f32 v[98:99], v[76:77], v[76:77]
	v_pk_mul_f32 v[102:103], v[78:79], v[78:79]
	s_waitcnt vmcnt(8)
; __device__ __forceinline__ v4u pk8(f32x4 a, f32x4 b) { v4u w; w.x = pk2(a[0], a[1]); w.y = pk2(a[2], a[3]); w.z = pk2(b[0], b[1]); w.w = pk2(b[2], b[3]); return w; }
; __device__ __forceinline__ float ssq8(const f32x4& a, const f32x4& b) { return ((a[0] * a[0] + a[1] * a[1]) + (a[2] * a[2] + a[3] * a[3])) + ((b[0] * b[0] + b[1] * b[1]) + (b[2] * b[2] + b[3] * b[3])); }
; __device__ __forceinline__ float shfl_xor_f(float v, int o) {
;     int l; asm volatile("v_mbcnt_lo_u32_b32 %0, -1, 0\n\tv_mbcnt_hi_u32_b32 %0, -1, %0" : "=v"(l));
;     return __builtin_bit_cast(float, __builtin_amdgcn_ds_bpermute((l ^ o) << 2, __builtin_bit_cast(int, v)));
; }
; __device__ __forceinline__ float wave_sum(float v) {
; #pragma unroll
;     for (int o = 1; o < 64; o <<= 1) v += shfl_xor_f(v, o);
;     return v;
; template <int XF32> __device__ __forceinline__ void norm_mod_phase(const void* x, const float* modl, int ch_shift, int ch_scale, bf16* H, int gw, int NGW, int lane) {
;     ...
;         for (int rr = 0; rr < 8; ++rr) {
;             const unsigned char* xr = (const unsigned char*)x + (size_t)(r0 + rr) * rowb; f32x4 v[4][2]; float s = 0.f;
; #pragma unroll
;             for (int j = 0; j < 4; ++j) ld_row8<XF32>(xr, lane, j, v[j][0], v[j][1]);
; #pragma unroll
;             for (int j = 0; j < 4; ++j) s += ssq8(v[j][0], v[j][1]);
;             const float rstd = 1.f / sqrtf(wave_sum(s) * (1.f / DM) + EPS);
;             v4u* o = (v4u*)(H + (size_t)(r0 + rr) * DM);
; #pragma unroll
;             for (int j = 0; j < 4; ++j) o[lane + 64 * j] = pk8(v[j][0] * rstd * sc[j][0] + sh[j][0], v[j][1] * rstd * sc[j][1] + sh[j][1]);
;         }
	v_lshlrev_b32_e32 v92, 16, v206
	v_and_b32_e32 v93, 0xffff0000, v206
	v_pk_fma_f32 v[98:99], v[96:97], v[96:97], v[98:99]
	v_pk_fma_f32 v[102:103], v[100:101], v[100:101], v[102:103]
	v_lshlrev_b32_e32 v105, 16, v199
	v_lshlrev_b32_e32 v104, 16, v198
	v_and_b32_e32 v81, 0xffff0000, v199
	v_and_b32_e32 v80, 0xffff0000, v198
	v_lshlrev_b32_e32 v109, 16, v201
	v_lshlrev_b32_e32 v108, 16, v200
	v_and_b32_e32 v83, 0xffff0000, v201
	v_and_b32_e32 v82, 0xffff0000, v200
	v_pk_mul_f32 v[106:107], v[80:81], v[80:81]
	v_pk_mul_f32 v[110:111], v[82:83], v[82:83]
	v_mul_f32_e32 v116, v92, v92
	v_mul_f32_e32 v117, v93, v93
	v_pk_add_f32 v[98:99], v[98:99], v[98:99] op_sel:[0,1] op_sel_hi:[1,0]
	v_pk_add_f32 v[102:103], v[102:103], v[102:103] op_sel:[0,1] op_sel_hi:[1,0]
	v_lshlrev_b32_e32 v88, 16, v207
	v_and_b32_e32 v89, 0xffff0000, v207
	v_pk_fma_f32 v[106:107], v[104:105], v[104:105], v[106:107]
	v_pk_fma_f32 v[110:111], v[108:109], v[108:109], v[110:111]
	v_mov_b32_e32 v99, v116
	v_mov_b32_e32 v103, v117
	v_mul_f32_e32 v118, v88, v88
	v_mul_f32_e32 v119, v89, v89
	v_pk_add_f32 v[98:99], v[98:99], v[102:103]
	v_pk_add_f32 v[102:103], v[106:107], v[106:107] op_sel:[0,1] op_sel_hi:[1,0]
	v_pk_add_f32 v[106:107], v[110:111], v[110:111] op_sel:[0,1] op_sel_hi:[1,0]
	v_mov_b32_e32 v103, v118
	v_mov_b32_e32 v107, v119
	v_lshlrev_b32_e32 v112, 16, v202
	v_and_b32_e32 v113, 0xffff0000, v202
	v_lshlrev_b32_e32 v84, 16, v203
	v_and_b32_e32 v85, 0xffff0000, v203
	v_pk_add_f32 v[102:103], v[102:103], v[106:107]
	v_lshlrev_b32_e32 v94, 16, v208
	v_and_b32_e32 v95, 0xffff0000, v208
	v_pk_add_f32 v[98:99], v[98:99], v[102:103]
	v_mul_f32_e32 v102, v113, v113
	v_mul_f32_e32 v106, v85, v85
	v_mul_f32_e32 v120, v94, v94
	v_mul_f32_e32 v121, v95, v95
	v_pk_fma_f32 v[102:103], v[112:113], v[112:113], v[102:103] op_sel_hi:[1,1,0]
	v_pk_fma_f32 v[106:107], v[84:85], v[84:85], v[106:107] op_sel_hi:[1,1,0]
	v_lshlrev_b32_e32 v114, 16, v204
	v_and_b32_e32 v115, 0xffff0000, v204
	v_lshlrev_b32_e32 v86, 16, v205
	v_and_b32_e32 v87, 0xffff0000, v205
	v_mov_b32_e32 v103, v120
	v_mov_b32_e32 v107, v121
	v_lshlrev_b32_e32 v90, 16, v209
	v_and_b32_e32 v91, 0xffff0000, v209
	s_add_i32 s100, s4, -2
	s_ashr_i32 s101, s100, 31
	s_lshl_b64 s[100:101], s[100:101], 12
	v_lshl_add_u64 v[210:211], v[32:33], 0, s[100:101]
	s_nop 0
	global_load_dwordx4 v[194:197], v[210:211], off
	global_load_dwordx4 v[198:201], v[210:211], off offset:1024
	global_load_dwordx4 v[202:205], v[210:211], off offset:2048
	global_load_dwordx4 v[206:209], v[210:211], off offset:3072
	v_pk_add_f32 v[102:103], v[102:103], v[106:107]
	v_mul_f32_e32 v106, v115, v115
	v_mul_f32_e32 v110, v87, v87
	v_mul_f32_e32 v122, v90, v90
	v_mul_f32_e32 v123, v91, v91
	v_pk_fma_f32 v[106:107], v[114:115], v[114:115], v[106:107] op_sel_hi:[1,1,0]
	v_pk_fma_f32 v[110:111], v[86:87], v[86:87], v[110:111] op_sel_hi:[1,1,0]
	v_mov_b32_e32 v107, v122
	v_mov_b32_e32 v111, v123
	v_pk_add_f32 v[106:107], v[106:107], v[110:111]
	s_nop 0
	v_pk_add_f32 v[102:103], v[102:103], v[106:107]
	s_nop 0
	v_pk_add_f32 v[98:99], v[98:99], v[102:103]
	s_nop 0
	v_add_f32_e32 v98, v98, v99
	s_nop 1
	v_add_f32_dpp v98, v98, v98 quad_perm:[1,0,3,2] row_mask:0xf bank_mask:0xf
	s_nop 1
	v_add_f32_dpp v98, v98, v98 quad_perm:[2,3,0,1] row_mask:0xf bank_mask:0xf
	s_nop 1
	v_add_f32_dpp v98, v98, v98 row_half_mirror row_mask:0xf bank_mask:0xf
	s_nop 1
	v_add_f32_dpp v98, v98, v98 row_mirror row_mask:0xf bank_mask:0xf
	v_mov_b32_e32 v99, v98
	s_nop 1
	v_permlane16_swap_b32_e32 v99, v98
	s_nop 1
	v_add_f32_e32 v98, v98, v99
	v_mov_b32_e32 v99, v98
	s_nop 1
	v_permlane32_swap_b32_e32 v99, v98
	s_nop 1
	v_add_f32_e32 v98, v98, v99
	v_fmamk_f32 v98, v98, 0x3a000000, v224
	v_cmp_gt_f32_e32 vcc, s41, v98
	v_mul_f32_e32 v99, 0x4f800000, v98
	s_nop 0
	v_cndmask_b32_e32 v98, v98, v99, vcc
	v_sqrt_f32_e32 v99, v98
	s_nop 0
	v_add_u32_e32 v102, -1, v99
	v_fma_f32 v103, -v102, v99, v98
	v_cmp_ge_f32_e64 s[0:1], 0, v103
	v_add_u32_e32 v103, 1, v99
	s_nop 0
	v_cndmask_b32_e64 v102, v99, v102, s[0:1]
	v_fma_f32 v99, -v103, v99, v98
	v_cmp_lt_f32_e64 s[0:1], 0, v99
	s_nop 1
	v_cndmask_b32_e64 v99, v102, v103, s[0:1]
	v_mul_f32_e32 v102, 0x37800000, v99
	v_cndmask_b32_e32 v99, v99, v102, vcc
	v_cmp_class_f32_e32 vcc, v98, v225
	s_nop 1
	v_cndmask_b32_e32 v98, v99, v98, vcc
	v_div_scale_f32 v99, s[0:1], v98, v98, 1.0
	v_rcp_f32_e32 v102, v99
	s_add_i32 s0, s4, -3
	s_ashr_i32 s1, s0, 31
	v_fma_f32 v103, -v99, v102, 1.0
	v_fmac_f32_e32 v102, v103, v102
	v_div_scale_f32 v103, vcc, 1.0, v98, 1.0
	v_mul_f32_e32 v106, v103, v102
	v_fma_f32 v107, -v99, v106, v103
	v_fmac_f32_e32 v106, v107, v102
	v_fma_f32 v99, -v99, v106, v103
	v_div_fmas_f32 v99, v99, v102, v106
	v_div_fixup_f32 v98, v99, v98, 1.0
	v_mov_b32_e32 v102, v96
	v_mov_b32_e32 v103, v76
	v_mov_b32_e32 v76, v97
	v_pk_mul_f32 v[102:103], v[98:99], v[102:103] op_sel_hi:[0,1]
	v_pk_mul_f32 v[76:77], v[98:99], v[76:77] op_sel_hi:[0,1]
	v_pk_fma_f32 v[96:97], v[48:49], v[76:77], v[6:7]
	v_pk_fma_f32 v[76:77], v[50:51], v[102:103], v[4:5]
	v_mov_b32_e32 v102, v100
	v_mov_b32_e32 v103, v78
	v_mov_b32_e32 v78, v101
	v_pk_mul_f32 v[102:103], v[98:99], v[102:103] op_sel_hi:[0,1]
	v_pk_mul_f32 v[78:79], v[98:99], v[78:79] op_sel_hi:[0,1]
	v_pk_fma_f32 v[100:101], v[44:45], v[78:79], v[2:3]
	v_pk_fma_f32 v[78:79], v[46:47], v[102:103], v[0:1]
	v_cvt_pk_bf16_f32 v76, v76, v77
	v_cvt_pk_bf16_f32 v77, v96, v97
	v_cvt_pk_bf16_f32 v78, v78, v79
	v_cvt_pk_bf16_f32 v79, v100, v101
	v_lshl_add_u64 v[96:97], v[34:35], 0, s[60:61]
	global_store_dwordx4 v[96:97], v[76:79], off
	s_lshl_b64 s[60:61], s[0:1], 12
	s_nop 0
	v_mov_b32_e32 v77, v80
; __device__ __forceinline__ v4u pk8(f32x4 a, f32x4 b) { v4u w; w.x = pk2(a[0], a[1]); w.y = pk2(a[2], a[3]); w.z = pk2(b[0], b[1]); w.w = pk2(b[2], b[3]); return w; }
; __device__ __forceinline__ float ssq8(const f32x4& a, const f32x4& b) { return ((a[0] * a[0] + a[1] * a[1]) + (a[2] * a[2] + a[3] * a[3])) + ((b[0] * b[0] + b[1] * b[1]) + (b[2] * b[2] + b[3] * b[3])); }
; __device__ __forceinline__ float shfl_xor_f(float v, int o) {
;     int l; asm volatile("v_mbcnt_lo_u32_b32 %0, -1, 0\n\tv_mbcnt_hi_u32_b32 %0, -1, %0" : "=v"(l));
;     return __builtin_bit_cast(float, __builtin_amdgcn_ds_bpermute((l ^ o) << 2, __builtin_bit_cast(int, v)));
; }
; __device__ __forceinline__ float wave_sum(float v) {
; #pragma unroll
;     for (int o = 1; o < 64; o <<= 1) v += shfl_xor_f(v, o);
;     return v;
; template <int XF32> __device__ __forceinline__ void norm_mod_phase(const void* x, const float* modl, int ch_shift, int ch_scale, bf16* H, int gw, int NGW, int lane) {
;     ...
;         for (int rr = 0; rr < 8; ++rr) {
;             const unsigned char* xr = (const unsigned char*)x + (size_t)(r0 + rr) * rowb; f32x4 v[4][2]; float s = 0.f;
; #pragma unroll
;             for (int j = 0; j < 4; ++j) ld_row8<XF32>(xr, lane, j, v[j][0], v[j][1]);
; #pragma unroll
;             for (int j = 0; j < 4; ++j) s += ssq8(v[j][0], v[j][1]);
;             const float rstd = 1.f / sqrtf(wave_sum(s) * (1.f / DM) + EPS);
;             v4u* o = (v4u*)(H + (size_t)(r0 + rr) * DM);
; #pragma unroll
;             for (int j = 0; j < 4; ++j) o[lane + 64 * j] = pk8(v[j][0] * rstd * sc[j][0] + sh[j][0], v[j][1] * rstd * sc[j][1] + sh[j][1]);
;         }
	v_mov_b32_e32 v80, v105
	v_mov_b32_e32 v76, v104
	v_pk_mul_f32 v[78:79], v[98:99], v[80:81] op_sel_hi:[0,1]
	v_mov_b32_e32 v80, v108
	v_mov_b32_e32 v81, v82
	v_mov_b32_e32 v82, v109
	v_pk_mul_f32 v[76:77], v[98:99], v[76:77] op_sel_hi:[0,1]
	v_pk_mul_f32 v[80:81], v[98:99], v[80:81] op_sel_hi:[0,1]
	v_pk_mul_f32 v[82:83], v[98:99], v[82:83] op_sel_hi:[0,1]
	v_pk_fma_f32 v[78:79], v[56:57], v[78:79], v[14:15]
	v_pk_fma_f32 v[76:77], v[58:59], v[76:77], v[12:13]
	v_pk_fma_f32 v[82:83], v[52:53], v[82:83], v[10:11]
	v_pk_fma_f32 v[80:81], v[54:55], v[80:81], v[8:9]
	v_cvt_pk_bf16_f32 v76, v76, v77
	v_cvt_pk_bf16_f32 v77, v78, v79
	v_cvt_pk_bf16_f32 v78, v80, v81
	v_cvt_pk_bf16_f32 v79, v82, v83
	global_store_dwordx4 v[96:97], v[76:79], off offset:1024
	v_pk_mul_f32 v[80:81], v[98:99], v[114:115] op_sel_hi:[0,1]
	v_pk_mul_f32 v[82:83], v[98:99], v[86:87] op_sel_hi:[0,1]
	v_pk_mul_f32 v[76:77], v[98:99], v[112:113] op_sel_hi:[0,1]
	v_pk_mul_f32 v[78:79], v[98:99], v[84:85] op_sel_hi:[0,1]
	v_pk_fma_f32 v[78:79], v[64:65], v[78:79], v[22:23]
	v_pk_fma_f32 v[76:77], v[66:67], v[76:77], v[20:21]
	v_pk_fma_f32 v[82:83], v[60:61], v[82:83], v[18:19]
	v_pk_fma_f32 v[80:81], v[62:63], v[80:81], v[16:17]
	v_cvt_pk_bf16_f32 v76, v76, v77
	v_cvt_pk_bf16_f32 v77, v78, v79
	v_cvt_pk_bf16_f32 v78, v80, v81
	v_cvt_pk_bf16_f32 v79, v82, v83
	global_store_dwordx4 v[96:97], v[76:79], off offset:2048
	v_pk_mul_f32 v[80:81], v[94:95], v[98:99] op_sel_hi:[1,0]
	v_pk_mul_f32 v[82:83], v[90:91], v[98:99] op_sel_hi:[1,0]
	v_pk_mul_f32 v[76:77], v[92:93], v[98:99] op_sel_hi:[1,0]
	v_pk_mul_f32 v[78:79], v[88:89], v[98:99] op_sel_hi:[1,0]
	v_pk_fma_f32 v[76:77], v[74:75], v[76:77], v[28:29]
	v_pk_fma_f32 v[78:79], v[72:73], v[78:79], v[30:31]
	v_pk_fma_f32 v[82:83], v[68:69], v[82:83], v[26:27]
	v_pk_fma_f32 v[80:81], v[70:71], v[80:81], v[24:25]
	v_cvt_pk_bf16_f32 v76, v76, v77
	v_cvt_pk_bf16_f32 v77, v78, v79
	v_cvt_pk_bf16_f32 v78, v80, v81
	v_cvt_pk_bf16_f32 v79, v82, v83
	global_store_dwordx4 v[96:97], v[76:79], off offset:3072
	s_waitcnt vmcnt(11)
	v_lshlrev_b32_e32 v97, 16, v179
	v_lshlrev_b32_e32 v96, 16, v178
	v_and_b32_e32 v77, 0xffff0000, v179
	v_and_b32_e32 v76, 0xffff0000, v178
	v_lshlrev_b32_e32 v101, 16, v181
	v_lshlrev_b32_e32 v100, 16, v180
	v_and_b32_e32 v79, 0xffff0000, v181
	v_and_b32_e32 v78, 0xffff0000, v180
	v_pk_mul_f32 v[98:99], v[76:77], v[76:77]
	v_pk_mul_f32 v[102:103], v[78:79], v[78:79]
	s_waitcnt vmcnt(8)
	v_lshlrev_b32_e32 v92, 16, v190
	v_and_b32_e32 v93, 0xffff0000, v190
	v_pk_fma_f32 v[98:99], v[96:97], v[96:97], v[98:99]
	v_pk_fma_f32 v[102:103], v[100:101], v[100:101], v[102:103]
	v_lshlrev_b32_e32 v105, 16, v183
	v_lshlrev_b32_e32 v104, 16, v182
	v_and_b32_e32 v81, 0xffff0000, v183
	v_and_b32_e32 v80, 0xffff0000, v182
	v_lshlrev_b32_e32 v109, 16, v185
	v_lshlrev_b32_e32 v108, 16, v184
	v_and_b32_e32 v83, 0xffff0000, v185
	v_and_b32_e32 v82, 0xffff0000, v184
	v_pk_mul_f32 v[106:107], v[80:81], v[80:81]
	v_pk_mul_f32 v[110:111], v[82:83], v[82:83]
	v_mul_f32_e32 v116, v92, v92
	v_mul_f32_e32 v117, v93, v93
	v_pk_add_f32 v[98:99], v[98:99], v[98:99] op_sel:[0,1] op_sel_hi:[1,0]
	v_pk_add_f32 v[102:103], v[102:103], v[102:103] op_sel:[0,1] op_sel_hi:[1,0]
	v_lshlrev_b32_e32 v88, 16, v191
	v_and_b32_e32 v89, 0xffff0000, v191
	v_pk_fma_f32 v[106:107], v[104:105], v[104:105], v[106:107]
	v_pk_fma_f32 v[110:111], v[108:109], v[108:109], v[110:111]
	v_mov_b32_e32 v99, v116
	v_mov_b32_e32 v103, v117
	v_mul_f32_e32 v118, v88, v88
	v_mul_f32_e32 v119, v89, v89
	v_pk_add_f32 v[98:99], v[98:99], v[102:103]
	v_pk_add_f32 v[102:103], v[106:107], v[106:107] op_sel:[0,1] op_sel_hi:[1,0]
	v_pk_add_f32 v[106:107], v[110:111], v[110:111] op_sel:[0,1] op_sel_hi:[1,0]
	v_mov_b32_e32 v103, v118
	v_mov_b32_e32 v107, v119
	v_lshlrev_b32_e32 v112, 16, v186
	v_and_b32_e32 v113, 0xffff0000, v186
	v_lshlrev_b32_e32 v84, 16, v187
	v_and_b32_e32 v85, 0xffff0000, v187
	v_pk_add_f32 v[102:103], v[102:103], v[106:107]
	v_lshlrev_b32_e32 v94, 16, v192
	v_and_b32_e32 v95, 0xffff0000, v192
	v_pk_add_f32 v[98:99], v[98:99], v[102:103]
	v_mul_f32_e32 v102, v113, v113
	v_mul_f32_e32 v106, v85, v85
	v_mul_f32_e32 v120, v94, v94
	v_mul_f32_e32 v121, v95, v95
	v_pk_fma_f32 v[102:103], v[112:113], v[112:113], v[102:103] op_sel_hi:[1,1,0]
	v_pk_fma_f32 v[106:107], v[84:85], v[84:85], v[106:107] op_sel_hi:[1,1,0]
	v_lshlrev_b32_e32 v114, 16, v188
	v_and_b32_e32 v115, 0xffff0000, v188
	v_lshlrev_b32_e32 v86, 16, v189
	v_and_b32_e32 v87, 0xffff0000, v189
	v_mov_b32_e32 v103, v120
	v_mov_b32_e32 v107, v121
	v_lshlrev_b32_e32 v90, 16, v193
	v_and_b32_e32 v91, 0xffff0000, v193
	s_add_i32 s100, s4, -1
	s_ashr_i32 s101, s100, 31
	s_lshl_b64 s[100:101], s[100:101], 12
	v_lshl_add_u64 v[210:211], v[32:33], 0, s[100:101]
	s_nop 0
	global_load_dwordx4 v[178:181], v[210:211], off
	global_load_dwordx4 v[182:185], v[210:211], off offset:1024
	global_load_dwordx4 v[186:189], v[210:211], off offset:2048
	global_load_dwordx4 v[190:193], v[210:211], off offset:3072
	v_pk_add_f32 v[102:103], v[102:103], v[106:107]
	v_mul_f32_e32 v106, v115, v115
	v_mul_f32_e32 v110, v87, v87
	v_mul_f32_e32 v122, v90, v90
	v_mul_f32_e32 v123, v91, v91
	v_pk_fma_f32 v[106:107], v[114:115], v[114:115], v[106:107] op_sel_hi:[1,1,0]
	v_pk_fma_f32 v[110:111], v[86:87], v[86:87], v[110:111] op_sel_hi:[1,1,0]
	v_mov_b32_e32 v107, v122
	v_mov_b32_e32 v111, v123
	v_pk_add_f32 v[106:107], v[106:107], v[110:111]
	s_nop 0
	v_pk_add_f32 v[102:103], v[102:103], v[106:107]
	s_nop 0
	v_pk_add_f32 v[98:99], v[98:99], v[102:103]
	s_nop 0
	v_add_f32_e32 v98, v98, v99
	s_nop 1
	v_add_f32_dpp v98, v98, v98 quad_perm:[1,0,3,2] row_mask:0xf bank_mask:0xf
; __device__ __forceinline__ v4u pk8(f32x4 a, f32x4 b) { v4u w; w.x = pk2(a[0], a[1]); w.y = pk2(a[2], a[3]); w.z = pk2(b[0], b[1]); w.w = pk2(b[2], b[3]); return w; }
; __device__ __forceinline__ float ssq8(const f32x4& a, const f32x4& b) { return ((a[0] * a[0] + a[1] * a[1]) + (a[2] * a[2] + a[3] * a[3])) + ((b[0] * b[0] + b[1] * b[1]) + (b[2] * b[2] + b[3] * b[3])); }
; __device__ __forceinline__ float shfl_xor_f(float v, int o) {
;     int l; asm volatile("v_mbcnt_lo_u32_b32 %0, -1, 0\n\tv_mbcnt_hi_u32_b32 %0, -1, %0" : "=v"(l));
;     return __builtin_bit_cast(float, __builtin_amdgcn_ds_bpermute((l ^ o) << 2, __builtin_bit_cast(int, v)));
; }
; __device__ __forceinline__ float wave_sum(float v) {
; #pragma unroll
;     for (int o = 1; o < 64; o <<= 1) v += shfl_xor_f(v, o);
;     return v;
; template <int XF32> __device__ __forceinline__ void norm_mod_phase(const void* x, const float* modl, int ch_shift, int ch_scale, bf16* H, int gw, int NGW, int lane) {
;     ...
;         for (int rr = 0; rr < 8; ++rr) {
;             const unsigned char* xr = (const unsigned char*)x + (size_t)(r0 + rr) * rowb; f32x4 v[4][2]; float s = 0.f;
; #pragma unroll
;             for (int j = 0; j < 4; ++j) ld_row8<XF32>(xr, lane, j, v[j][0], v[j][1]);
; #pragma unroll
;             for (int j = 0; j < 4; ++j) s += ssq8(v[j][0], v[j][1]);
;             const float rstd = 1.f / sqrtf(wave_sum(s) * (1.f / DM) + EPS);
;             v4u* o = (v4u*)(H + (size_t)(r0 + rr) * DM);
; #pragma unroll
;             for (int j = 0; j < 4; ++j) o[lane + 64 * j] = pk8(v[j][0] * rstd * sc[j][0] + sh[j][0], v[j][1] * rstd * sc[j][1] + sh[j][1]);
;         }
	s_nop 1
	v_add_f32_dpp v98, v98, v98 quad_perm:[2,3,0,1] row_mask:0xf bank_mask:0xf
	s_nop 1
	v_add_f32_dpp v98, v98, v98 row_half_mirror row_mask:0xf bank_mask:0xf
	s_nop 1
	v_add_f32_dpp v98, v98, v98 row_mirror row_mask:0xf bank_mask:0xf
	v_mov_b32_e32 v99, v98
	s_nop 1
	v_permlane16_swap_b32_e32 v99, v98
	s_nop 1
	v_add_f32_e32 v98, v98, v99
	v_mov_b32_e32 v99, v98
	s_nop 1
	v_permlane32_swap_b32_e32 v99, v98
	s_nop 1
	v_add_f32_e32 v98, v98, v99
	v_fmamk_f32 v98, v98, 0x3a000000, v224
	v_cmp_gt_f32_e32 vcc, s41, v98
	v_mul_f32_e32 v99, 0x4f800000, v98
	s_nop 0
	v_cndmask_b32_e32 v98, v98, v99, vcc
	v_sqrt_f32_e32 v99, v98
	s_nop 0
	v_add_u32_e32 v102, -1, v99
	v_fma_f32 v103, -v102, v99, v98
	v_cmp_ge_f32_e64 s[0:1], 0, v103
	v_add_u32_e32 v103, 1, v99
	s_nop 0
	v_cndmask_b32_e64 v102, v99, v102, s[0:1]
	v_fma_f32 v99, -v103, v99, v98
	v_cmp_lt_f32_e64 s[0:1], 0, v99
	s_nop 1
	v_cndmask_b32_e64 v99, v102, v103, s[0:1]
	v_mul_f32_e32 v102, 0x37800000, v99
	v_cndmask_b32_e32 v99, v99, v102, vcc
	v_cmp_class_f32_e32 vcc, v98, v225
	s_nop 1
	v_cndmask_b32_e32 v98, v99, v98, vcc
	v_div_scale_f32 v99, s[0:1], v98, v98, 1.0
	v_rcp_f32_e32 v102, v99
	s_add_i32 s0, s4, -2
	s_ashr_i32 s1, s0, 31
	v_fma_f32 v103, -v99, v102, 1.0
	v_fmac_f32_e32 v102, v103, v102
	v_div_scale_f32 v103, vcc, 1.0, v98, 1.0
	v_mul_f32_e32 v106, v103, v102
	v_fma_f32 v107, -v99, v106, v103
	v_fmac_f32_e32 v106, v107, v102
	v_fma_f32 v99, -v99, v106, v103
	v_div_fmas_f32 v99, v99, v102, v106
	v_div_fixup_f32 v98, v99, v98, 1.0
	v_mov_b32_e32 v102, v96
	v_mov_b32_e32 v103, v76
	v_mov_b32_e32 v76, v97
	v_pk_mul_f32 v[102:103], v[98:99], v[102:103] op_sel_hi:[0,1]
	v_pk_mul_f32 v[76:77], v[98:99], v[76:77] op_sel_hi:[0,1]
	v_pk_fma_f32 v[96:97], v[48:49], v[76:77], v[6:7]
	v_pk_fma_f32 v[76:77], v[50:51], v[102:103], v[4:5]
	v_mov_b32_e32 v102, v100
	v_mov_b32_e32 v103, v78
	v_mov_b32_e32 v78, v101
	v_pk_mul_f32 v[102:103], v[98:99], v[102:103] op_sel_hi:[0,1]
	v_pk_mul_f32 v[78:79], v[98:99], v[78:79] op_sel_hi:[0,1]
	v_pk_fma_f32 v[100:101], v[44:45], v[78:79], v[2:3]
	v_pk_fma_f32 v[78:79], v[46:47], v[102:103], v[0:1]
	v_cvt_pk_bf16_f32 v76, v76, v77
	v_cvt_pk_bf16_f32 v77, v96, v97
	v_cvt_pk_bf16_f32 v78, v78, v79
	v_cvt_pk_bf16_f32 v79, v100, v101
	v_lshl_add_u64 v[96:97], v[34:35], 0, s[60:61]
	global_store_dwordx4 v[96:97], v[76:79], off
	s_lshl_b64 s[60:61], s[0:1], 12
	s_nop 0
	v_mov_b32_e32 v77, v80
	v_mov_b32_e32 v80, v105
	v_mov_b32_e32 v76, v104
	v_pk_mul_f32 v[78:79], v[98:99], v[80:81] op_sel_hi:[0,1]
	v_mov_b32_e32 v80, v108
	v_mov_b32_e32 v81, v82
	v_mov_b32_e32 v82, v109
	v_pk_mul_f32 v[76:77], v[98:99], v[76:77] op_sel_hi:[0,1]
	v_pk_mul_f32 v[80:81], v[98:99], v[80:81] op_sel_hi:[0,1]
	v_pk_mul_f32 v[82:83], v[98:99], v[82:83] op_sel_hi:[0,1]
	v_pk_fma_f32 v[78:79], v[56:57], v[78:79], v[14:15]
	v_pk_fma_f32 v[76:77], v[58:59], v[76:77], v[12:13]
	v_pk_fma_f32 v[82:83], v[52:53], v[82:83], v[10:11]
	v_pk_fma_f32 v[80:81], v[54:55], v[80:81], v[8:9]
	v_cvt_pk_bf16_f32 v76, v76, v77
	v_cvt_pk_bf16_f32 v77, v78, v79
	v_cvt_pk_bf16_f32 v78, v80, v81
	v_cvt_pk_bf16_f32 v79, v82, v83
	global_store_dwordx4 v[96:97], v[76:79], off offset:1024
	v_pk_mul_f32 v[80:81], v[98:99], v[114:115] op_sel_hi:[0,1]
	v_pk_mul_f32 v[82:83], v[98:99], v[86:87] op_sel_hi:[0,1]
	v_pk_mul_f32 v[76:77], v[98:99], v[112:113] op_sel_hi:[0,1]
	v_pk_mul_f32 v[78:79], v[98:99], v[84:85] op_sel_hi:[0,1]
	v_pk_fma_f32 v[78:79], v[64:65], v[78:79], v[22:23]
	v_pk_fma_f32 v[76:77], v[66:67], v[76:77], v[20:21]
	v_pk_fma_f32 v[82:83], v[60:61], v[82:83], v[18:19]
	v_pk_fma_f32 v[80:81], v[62:63], v[80:81], v[16:17]
	v_cvt_pk_bf16_f32 v76, v76, v77
	v_cvt_pk_bf16_f32 v77, v78, v79
	v_cvt_pk_bf16_f32 v78, v80, v81
	v_cvt_pk_bf16_f32 v79, v82, v83
	global_store_dwordx4 v[96:97], v[76:79], off offset:2048
	v_pk_mul_f32 v[80:81], v[94:95], v[98:99] op_sel_hi:[1,0]
	v_pk_mul_f32 v[82:83], v[90:91], v[98:99] op_sel_hi:[1,0]
	v_pk_mul_f32 v[76:77], v[92:93], v[98:99] op_sel_hi:[1,0]
	v_pk_mul_f32 v[78:79], v[88:89], v[98:99] op_sel_hi:[1,0]
	v_pk_fma_f32 v[76:77], v[74:75], v[76:77], v[28:29]
	v_pk_fma_f32 v[78:79], v[72:73], v[78:79], v[30:31]
	v_pk_fma_f32 v[82:83], v[68:69], v[82:83], v[26:27]
	v_pk_fma_f32 v[80:81], v[70:71], v[80:81], v[24:25]
	v_cvt_pk_bf16_f32 v76, v76, v77
	v_cvt_pk_bf16_f32 v77, v78, v79
	v_cvt_pk_bf16_f32 v78, v80, v81
	v_cvt_pk_bf16_f32 v79, v82, v83
	global_store_dwordx4 v[96:97], v[76:79], off offset:3072
	s_waitcnt vmcnt(11)
	v_lshlrev_b32_e32 v97, 16, v195
	v_lshlrev_b32_e32 v96, 16, v194
	v_and_b32_e32 v77, 0xffff0000, v195
	v_and_b32_e32 v76, 0xffff0000, v194
	v_lshlrev_b32_e32 v101, 16, v197
	v_lshlrev_b32_e32 v100, 16, v196
	v_and_b32_e32 v79, 0xffff0000, v197
	v_and_b32_e32 v78, 0xffff0000, v196
	v_pk_mul_f32 v[98:99], v[76:77], v[76:77]
	v_pk_mul_f32 v[102:103], v[78:79], v[78:79]
	s_waitcnt vmcnt(8)
; __device__ __forceinline__ v4u pk8(f32x4 a, f32x4 b) { v4u w; w.x = pk2(a[0], a[1]); w.y = pk2(a[2], a[3]); w.z = pk2(b[0], b[1]); w.w = pk2(b[2], b[3]); return w; }
; __device__ __forceinline__ float ssq8(const f32x4& a, const f32x4& b) { return ((a[0] * a[0] + a[1] * a[1]) + (a[2] * a[2] + a[3] * a[3])) + ((b[0] * b[0] + b[1] * b[1]) + (b[2] * b[2] + b[3] * b[3])); }
; __device__ __forceinline__ float shfl_xor_f(float v, int o) {
;     int l; asm volatile("v_mbcnt_lo_u32_b32 %0, -1, 0\n\tv_mbcnt_hi_u32_b32 %0, -1, %0" : "=v"(l));
;     return __builtin_bit_cast(float, __builtin_amdgcn_ds_bpermute((l ^ o) << 2, __builtin_bit_cast(int, v)));
; }
; __device__ __forceinline__ float wave_sum(float v) {
; #pragma unroll
;     for (int o = 1; o < 64; o <<= 1) v += shfl_xor_f(v, o);
;     return v;
; template <int XF32> __device__ __forceinline__ void norm_mod_phase(const void* x, const float* modl, int ch_shift, int ch_scale, bf16* H, int gw, int NGW, int lane) {
;     ...
;         for (int rr = 0; rr < 8; ++rr) {
;             const unsigned char* xr = (const unsigned char*)x + (size_t)(r0 + rr) * rowb; f32x4 v[4][2]; float s = 0.f;
; #pragma unroll
;             for (int j = 0; j < 4; ++j) ld_row8<XF32>(xr, lane, j, v[j][0], v[j][1]);
; #pragma unroll
;             for (int j = 0; j < 4; ++j) s += ssq8(v[j][0], v[j][1]);
;             const float rstd = 1.f / sqrtf(wave_sum(s) * (1.f / DM) + EPS);
;             v4u* o = (v4u*)(H + (size_t)(r0 + rr) * DM);
; #pragma unroll
;             for (int j = 0; j < 4; ++j) o[lane + 64 * j] = pk8(v[j][0] * rstd * sc[j][0] + sh[j][0], v[j][1] * rstd * sc[j][1] + sh[j][1]);
;         }
	v_lshlrev_b32_e32 v92, 16, v206
	v_and_b32_e32 v93, 0xffff0000, v206
	v_pk_fma_f32 v[98:99], v[96:97], v[96:97], v[98:99]
	v_pk_fma_f32 v[102:103], v[100:101], v[100:101], v[102:103]
	v_lshlrev_b32_e32 v105, 16, v199
	v_lshlrev_b32_e32 v104, 16, v198
	v_and_b32_e32 v81, 0xffff0000, v199
	v_and_b32_e32 v80, 0xffff0000, v198
	v_lshlrev_b32_e32 v109, 16, v201
	v_lshlrev_b32_e32 v108, 16, v200
	v_and_b32_e32 v83, 0xffff0000, v201
	v_and_b32_e32 v82, 0xffff0000, v200
	v_pk_mul_f32 v[106:107], v[80:81], v[80:81]
	v_pk_mul_f32 v[110:111], v[82:83], v[82:83]
	v_mul_f32_e32 v116, v92, v92
	v_mul_f32_e32 v117, v93, v93
	v_pk_add_f32 v[98:99], v[98:99], v[98:99] op_sel:[0,1] op_sel_hi:[1,0]
	v_pk_add_f32 v[102:103], v[102:103], v[102:103] op_sel:[0,1] op_sel_hi:[1,0]
	v_lshlrev_b32_e32 v88, 16, v207
	v_and_b32_e32 v89, 0xffff0000, v207
	v_pk_fma_f32 v[106:107], v[104:105], v[104:105], v[106:107]
	v_pk_fma_f32 v[110:111], v[108:109], v[108:109], v[110:111]
	v_mov_b32_e32 v99, v116
	v_mov_b32_e32 v103, v117
	v_mul_f32_e32 v118, v88, v88
	v_mul_f32_e32 v119, v89, v89
	v_pk_add_f32 v[98:99], v[98:99], v[102:103]
	v_pk_add_f32 v[102:103], v[106:107], v[106:107] op_sel:[0,1] op_sel_hi:[1,0]
	v_pk_add_f32 v[106:107], v[110:111], v[110:111] op_sel:[0,1] op_sel_hi:[1,0]
	v_mov_b32_e32 v103, v118
	v_mov_b32_e32 v107, v119
	v_lshlrev_b32_e32 v112, 16, v202
	v_and_b32_e32 v113, 0xffff0000, v202
	v_lshlrev_b32_e32 v84, 16, v203
	v_and_b32_e32 v85, 0xffff0000, v203
	v_pk_add_f32 v[102:103], v[102:103], v[106:107]
	v_lshlrev_b32_e32 v94, 16, v208
	v_and_b32_e32 v95, 0xffff0000, v208
	v_pk_add_f32 v[98:99], v[98:99], v[102:103]
	v_mul_f32_e32 v102, v113, v113
	v_mul_f32_e32 v106, v85, v85
	v_mul_f32_e32 v120, v94, v94
	v_mul_f32_e32 v121, v95, v95
	v_pk_fma_f32 v[102:103], v[112:113], v[112:113], v[102:103] op_sel_hi:[1,1,0]
	v_pk_fma_f32 v[106:107], v[84:85], v[84:85], v[106:107] op_sel_hi:[1,1,0]
	v_lshlrev_b32_e32 v114, 16, v204
	v_and_b32_e32 v115, 0xffff0000, v204
	v_lshlrev_b32_e32 v86, 16, v205
	v_and_b32_e32 v87, 0xffff0000, v205
	v_mov_b32_e32 v103, v120
	v_mov_b32_e32 v107, v121
	v_lshlrev_b32_e32 v90, 16, v209
	v_and_b32_e32 v91, 0xffff0000, v209
	s_add_i32 s100, s4, 0
	s_ashr_i32 s101, s100, 31
	s_lshl_b64 s[100:101], s[100:101], 12
	v_lshl_add_u64 v[210:211], v[32:33], 0, s[100:101]
	s_nop 0
	global_load_dwordx4 v[194:197], v[210:211], off
	global_load_dwordx4 v[198:201], v[210:211], off offset:1024
	global_load_dwordx4 v[202:205], v[210:211], off offset:2048
	global_load_dwordx4 v[206:209], v[210:211], off offset:3072
	v_pk_add_f32 v[102:103], v[102:103], v[106:107]
	v_mul_f32_e32 v106, v115, v115
	v_mul_f32_e32 v110, v87, v87
	v_mul_f32_e32 v122, v90, v90
	v_mul_f32_e32 v123, v91, v91
	v_pk_fma_f32 v[106:107], v[114:115], v[114:115], v[106:107] op_sel_hi:[1,1,0]
	v_pk_fma_f32 v[110:111], v[86:87], v[86:87], v[110:111] op_sel_hi:[1,1,0]
	v_mov_b32_e32 v107, v122
	v_mov_b32_e32 v111, v123
	v_pk_add_f32 v[106:107], v[106:107], v[110:111]
	s_nop 0
	v_pk_add_f32 v[102:103], v[102:103], v[106:107]
	s_nop 0
	v_pk_add_f32 v[98:99], v[98:99], v[102:103]
	s_nop 0
	v_add_f32_e32 v98, v98, v99
	s_nop 1
	v_add_f32_dpp v98, v98, v98 quad_perm:[1,0,3,2] row_mask:0xf bank_mask:0xf
	s_nop 1
	v_add_f32_dpp v98, v98, v98 quad_perm:[2,3,0,1] row_mask:0xf bank_mask:0xf
	s_nop 1
	v_add_f32_dpp v98, v98, v98 row_half_mirror row_mask:0xf bank_mask:0xf
	s_nop 1
	v_add_f32_dpp v98, v98, v98 row_mirror row_mask:0xf bank_mask:0xf
	v_mov_b32_e32 v99, v98
	s_nop 1
	v_permlane16_swap_b32_e32 v99, v98
	s_nop 1
	v_add_f32_e32 v98, v98, v99
	v_mov_b32_e32 v99, v98
	s_nop 1
	v_permlane32_swap_b32_e32 v99, v98
	s_nop 1
	v_add_f32_e32 v98, v98, v99
	v_fmamk_f32 v98, v98, 0x3a000000, v224
	v_cmp_gt_f32_e32 vcc, s41, v98
	v_mul_f32_e32 v99, 0x4f800000, v98
	s_nop 0
	v_cndmask_b32_e32 v98, v98, v99, vcc
	v_sqrt_f32_e32 v99, v98
	s_nop 0
	v_add_u32_e32 v102, -1, v99
	v_fma_f32 v103, -v102, v99, v98
	v_cmp_ge_f32_e64 s[0:1], 0, v103
	v_add_u32_e32 v103, 1, v99
	s_nop 0
	v_cndmask_b32_e64 v102, v99, v102, s[0:1]
	v_fma_f32 v99, -v103, v99, v98
	v_cmp_lt_f32_e64 s[0:1], 0, v99
	s_nop 1
	v_cndmask_b32_e64 v99, v102, v103, s[0:1]
	v_mul_f32_e32 v102, 0x37800000, v99
	v_cndmask_b32_e32 v99, v99, v102, vcc
	v_cmp_class_f32_e32 vcc, v98, v225
	s_nop 1
	v_cndmask_b32_e32 v98, v99, v98, vcc
	v_div_scale_f32 v99, s[0:1], v98, v98, 1.0
	v_rcp_f32_e32 v102, v99
	s_add_i32 s0, s4, -1
	s_ashr_i32 s1, s0, 31
	v_fma_f32 v103, -v99, v102, 1.0
	v_fmac_f32_e32 v102, v103, v102
	v_div_scale_f32 v103, vcc, 1.0, v98, 1.0
	v_mul_f32_e32 v106, v103, v102
	v_fma_f32 v107, -v99, v106, v103
	v_fmac_f32_e32 v106, v107, v102
	v_fma_f32 v99, -v99, v106, v103
	v_div_fmas_f32 v99, v99, v102, v106
	v_div_fixup_f32 v98, v99, v98, 1.0
	v_mov_b32_e32 v102, v96
	v_mov_b32_e32 v103, v76
	v_mov_b32_e32 v76, v97
	v_pk_mul_f32 v[102:103], v[98:99], v[102:103] op_sel_hi:[0,1]
	v_pk_mul_f32 v[76:77], v[98:99], v[76:77] op_sel_hi:[0,1]
	v_pk_fma_f32 v[96:97], v[48:49], v[76:77], v[6:7]
	v_pk_fma_f32 v[76:77], v[50:51], v[102:103], v[4:5]
	v_mov_b32_e32 v102, v100
	v_mov_b32_e32 v103, v78
	v_mov_b32_e32 v78, v101
	v_pk_mul_f32 v[102:103], v[98:99], v[102:103] op_sel_hi:[0,1]
	v_pk_mul_f32 v[78:79], v[98:99], v[78:79] op_sel_hi:[0,1]
	v_pk_fma_f32 v[100:101], v[44:45], v[78:79], v[2:3]
	v_pk_fma_f32 v[78:79], v[46:47], v[102:103], v[0:1]
	v_cvt_pk_bf16_f32 v76, v76, v77
	v_cvt_pk_bf16_f32 v77, v96, v97
	v_cvt_pk_bf16_f32 v78, v78, v79
	v_cvt_pk_bf16_f32 v79, v100, v101
	v_lshl_add_u64 v[96:97], v[34:35], 0, s[60:61]
	global_store_dwordx4 v[96:97], v[76:79], off
	s_lshl_b64 s[60:61], s[0:1], 12
	s_nop 0
	v_mov_b32_e32 v77, v80
; __device__ __forceinline__ v4u pk8(f32x4 a, f32x4 b) { v4u w; w.x = pk2(a[0], a[1]); w.y = pk2(a[2], a[3]); w.z = pk2(b[0], b[1]); w.w = pk2(b[2], b[3]); return w; }
; __device__ __forceinline__ float ssq8(const f32x4& a, const f32x4& b) { return ((a[0] * a[0] + a[1] * a[1]) + (a[2] * a[2] + a[3] * a[3])) + ((b[0] * b[0] + b[1] * b[1]) + (b[2] * b[2] + b[3] * b[3])); }
; __device__ __forceinline__ float shfl_xor_f(float v, int o) {
;     int l; asm volatile("v_mbcnt_lo_u32_b32 %0, -1, 0\n\tv_mbcnt_hi_u32_b32 %0, -1, %0" : "=v"(l));
;     return __builtin_bit_cast(float, __builtin_amdgcn_ds_bpermute((l ^ o) << 2, __builtin_bit_cast(int, v)));
; }
; __device__ __forceinline__ float wave_sum(float v) {
; #pragma unroll
;     for (int o = 1; o < 64; o <<= 1) v += shfl_xor_f(v, o);
;     return v;
; template <int XF32> __device__ __forceinline__ void norm_mod_phase(const void* x, const float* modl, int ch_shift, int ch_scale, bf16* H, int gw, int NGW, int lane) {
;     ...
;         for (int rr = 0; rr < 8; ++rr) {
;             const unsigned char* xr = (const unsigned char*)x + (size_t)(r0 + rr) * rowb; f32x4 v[4][2]; float s = 0.f;
; #pragma unroll
;             for (int j = 0; j < 4; ++j) ld_row8<XF32>(xr, lane, j, v[j][0], v[j][1]);
; #pragma unroll
;             for (int j = 0; j < 4; ++j) s += ssq8(v[j][0], v[j][1]);
;             const float rstd = 1.f / sqrtf(wave_sum(s) * (1.f / DM) + EPS);
;             v4u* o = (v4u*)(H + (size_t)(r0 + rr) * DM);
; #pragma unroll
;             for (int j = 0; j < 4; ++j) o[lane + 64 * j] = pk8(v[j][0] * rstd * sc[j][0] + sh[j][0], v[j][1] * rstd * sc[j][1] + sh[j][1]);
;         }
	v_mov_b32_e32 v80, v105
	v_mov_b32_e32 v76, v104
	v_pk_mul_f32 v[78:79], v[98:99], v[80:81] op_sel_hi:[0,1]
	v_mov_b32_e32 v80, v108
	v_mov_b32_e32 v81, v82
	v_mov_b32_e32 v82, v109
	v_pk_mul_f32 v[76:77], v[98:99], v[76:77] op_sel_hi:[0,1]
	v_pk_mul_f32 v[80:81], v[98:99], v[80:81] op_sel_hi:[0,1]
	v_pk_mul_f32 v[82:83], v[98:99], v[82:83] op_sel_hi:[0,1]
	v_pk_fma_f32 v[78:79], v[56:57], v[78:79], v[14:15]
	v_pk_fma_f32 v[76:77], v[58:59], v[76:77], v[12:13]
	v_pk_fma_f32 v[82:83], v[52:53], v[82:83], v[10:11]
	v_pk_fma_f32 v[80:81], v[54:55], v[80:81], v[8:9]
	v_cvt_pk_bf16_f32 v76, v76, v77
	v_cvt_pk_bf16_f32 v77, v78, v79
	v_cvt_pk_bf16_f32 v78, v80, v81
	v_cvt_pk_bf16_f32 v79, v82, v83
	global_store_dwordx4 v[96:97], v[76:79], off offset:1024
	v_pk_mul_f32 v[80:81], v[98:99], v[114:115] op_sel_hi:[0,1]
	v_pk_mul_f32 v[82:83], v[98:99], v[86:87] op_sel_hi:[0,1]
	v_pk_mul_f32 v[76:77], v[98:99], v[112:113] op_sel_hi:[0,1]
	v_pk_mul_f32 v[78:79], v[98:99], v[84:85] op_sel_hi:[0,1]
	v_pk_fma_f32 v[78:79], v[64:65], v[78:79], v[22:23]
	v_pk_fma_f32 v[76:77], v[66:67], v[76:77], v[20:21]
	v_pk_fma_f32 v[82:83], v[60:61], v[82:83], v[18:19]
	v_pk_fma_f32 v[80:81], v[62:63], v[80:81], v[16:17]
	v_cvt_pk_bf16_f32 v76, v76, v77
	v_cvt_pk_bf16_f32 v77, v78, v79
	v_cvt_pk_bf16_f32 v78, v80, v81
	v_cvt_pk_bf16_f32 v79, v82, v83
	global_store_dwordx4 v[96:97], v[76:79], off offset:2048
	v_pk_mul_f32 v[80:81], v[94:95], v[98:99] op_sel_hi:[1,0]
	v_pk_mul_f32 v[82:83], v[90:91], v[98:99] op_sel_hi:[1,0]
	v_pk_mul_f32 v[76:77], v[92:93], v[98:99] op_sel_hi:[1,0]
	v_pk_mul_f32 v[78:79], v[88:89], v[98:99] op_sel_hi:[1,0]
	v_pk_fma_f32 v[76:77], v[74:75], v[76:77], v[28:29]
	v_pk_fma_f32 v[78:79], v[72:73], v[78:79], v[30:31]
	v_pk_fma_f32 v[82:83], v[68:69], v[82:83], v[26:27]
	v_pk_fma_f32 v[80:81], v[70:71], v[80:81], v[24:25]
	v_cvt_pk_bf16_f32 v76, v76, v77
	v_cvt_pk_bf16_f32 v77, v78, v79
	v_cvt_pk_bf16_f32 v78, v80, v81
	v_cvt_pk_bf16_f32 v79, v82, v83
	global_store_dwordx4 v[96:97], v[76:79], off offset:3072
	s_waitcnt vmcnt(11)
	v_lshlrev_b32_e32 v97, 16, v179
	v_lshlrev_b32_e32 v96, 16, v178
	v_and_b32_e32 v77, 0xffff0000, v179
	v_and_b32_e32 v76, 0xffff0000, v178
	v_lshlrev_b32_e32 v101, 16, v181
	v_lshlrev_b32_e32 v100, 16, v180
	v_and_b32_e32 v79, 0xffff0000, v181
	v_and_b32_e32 v78, 0xffff0000, v180
	v_pk_mul_f32 v[98:99], v[76:77], v[76:77]
	v_pk_mul_f32 v[102:103], v[78:79], v[78:79]
	s_waitcnt vmcnt(8)
	v_lshlrev_b32_e32 v92, 16, v190
	v_and_b32_e32 v93, 0xffff0000, v190
	v_pk_fma_f32 v[98:99], v[96:97], v[96:97], v[98:99]
	v_pk_fma_f32 v[102:103], v[100:101], v[100:101], v[102:103]
	v_lshlrev_b32_e32 v105, 16, v183
	v_lshlrev_b32_e32 v104, 16, v182
	v_and_b32_e32 v81, 0xffff0000, v183
	v_and_b32_e32 v80, 0xffff0000, v182
	v_lshlrev_b32_e32 v109, 16, v185
	v_lshlrev_b32_e32 v108, 16, v184
	v_and_b32_e32 v83, 0xffff0000, v185
	v_and_b32_e32 v82, 0xffff0000, v184
	v_pk_mul_f32 v[106:107], v[80:81], v[80:81]
	v_pk_mul_f32 v[110:111], v[82:83], v[82:83]
	v_mul_f32_e32 v116, v92, v92
	v_mul_f32_e32 v117, v93, v93
	v_pk_add_f32 v[98:99], v[98:99], v[98:99] op_sel:[0,1] op_sel_hi:[1,0]
	v_pk_add_f32 v[102:103], v[102:103], v[102:103] op_sel:[0,1] op_sel_hi:[1,0]
	v_lshlrev_b32_e32 v88, 16, v191
	v_and_b32_e32 v89, 0xffff0000, v191
	v_pk_fma_f32 v[106:107], v[104:105], v[104:105], v[106:107]
	v_pk_fma_f32 v[110:111], v[108:109], v[108:109], v[110:111]
	v_mov_b32_e32 v99, v116
	v_mov_b32_e32 v103, v117
	v_mul_f32_e32 v118, v88, v88
	v_mul_f32_e32 v119, v89, v89
	v_pk_add_f32 v[98:99], v[98:99], v[102:103]
	v_pk_add_f32 v[102:103], v[106:107], v[106:107] op_sel:[0,1] op_sel_hi:[1,0]
	v_pk_add_f32 v[106:107], v[110:111], v[110:111] op_sel:[0,1] op_sel_hi:[1,0]
	v_mov_b32_e32 v103, v118
	v_mov_b32_e32 v107, v119
	v_lshlrev_b32_e32 v112, 16, v186
	v_and_b32_e32 v113, 0xffff0000, v186
	v_lshlrev_b32_e32 v84, 16, v187
	v_and_b32_e32 v85, 0xffff0000, v187
	v_pk_add_f32 v[102:103], v[102:103], v[106:107]
	v_lshlrev_b32_e32 v94, 16, v192
	v_and_b32_e32 v95, 0xffff0000, v192
	v_pk_add_f32 v[98:99], v[98:99], v[102:103]
	v_mul_f32_e32 v102, v113, v113
	v_mul_f32_e32 v106, v85, v85
	v_mul_f32_e32 v120, v94, v94
	v_mul_f32_e32 v121, v95, v95
	v_pk_fma_f32 v[102:103], v[112:113], v[112:113], v[102:103] op_sel_hi:[1,1,0]
	v_pk_fma_f32 v[106:107], v[84:85], v[84:85], v[106:107] op_sel_hi:[1,1,0]
	v_lshlrev_b32_e32 v114, 16, v188
	v_and_b32_e32 v115, 0xffff0000, v188
	v_lshlrev_b32_e32 v86, 16, v189
	v_and_b32_e32 v87, 0xffff0000, v189
	v_mov_b32_e32 v103, v120
	v_mov_b32_e32 v107, v121
	v_lshlrev_b32_e32 v90, 16, v193
	v_and_b32_e32 v91, 0xffff0000, v193
	v_pk_add_f32 v[102:103], v[102:103], v[106:107]
	v_mul_f32_e32 v106, v115, v115
	v_mul_f32_e32 v110, v87, v87
	v_mul_f32_e32 v122, v90, v90
	v_mul_f32_e32 v123, v91, v91
	v_pk_fma_f32 v[106:107], v[114:115], v[114:115], v[106:107] op_sel_hi:[1,1,0]
	v_pk_fma_f32 v[110:111], v[86:87], v[86:87], v[110:111] op_sel_hi:[1,1,0]
	v_mov_b32_e32 v107, v122
	v_mov_b32_e32 v111, v123
	v_pk_add_f32 v[106:107], v[106:107], v[110:111]
	s_nop 0
	v_pk_add_f32 v[102:103], v[102:103], v[106:107]
	s_nop 0
	v_pk_add_f32 v[98:99], v[98:99], v[102:103]
	s_nop 0
	v_add_f32_e32 v98, v98, v99
	s_nop 1
	v_add_f32_dpp v98, v98, v98 quad_perm:[1,0,3,2] row_mask:0xf bank_mask:0xf
	s_nop 1
	v_add_f32_dpp v98, v98, v98 quad_perm:[2,3,0,1] row_mask:0xf bank_mask:0xf
	s_nop 1
	v_add_f32_dpp v98, v98, v98 row_half_mirror row_mask:0xf bank_mask:0xf
	s_nop 1
	v_add_f32_dpp v98, v98, v98 row_mirror row_mask:0xf bank_mask:0xf
	v_mov_b32_e32 v99, v98
	s_nop 1
	v_permlane16_swap_b32_e32 v99, v98
	s_nop 1
	v_add_f32_e32 v98, v98, v99
; __device__ __forceinline__ v4u pk8(f32x4 a, f32x4 b) { v4u w; w.x = pk2(a[0], a[1]); w.y = pk2(a[2], a[3]); w.z = pk2(b[0], b[1]); w.w = pk2(b[2], b[3]); return w; }
; __device__ __forceinline__ float ssq8(const f32x4& a, const f32x4& b) { return ((a[0] * a[0] + a[1] * a[1]) + (a[2] * a[2] + a[3] * a[3])) + ((b[0] * b[0] + b[1] * b[1]) + (b[2] * b[2] + b[3] * b[3])); }
; __device__ __forceinline__ float shfl_xor_f(float v, int o) {
;     int l; asm volatile("v_mbcnt_lo_u32_b32 %0, -1, 0\n\tv_mbcnt_hi_u32_b32 %0, -1, %0" : "=v"(l));
;     return __builtin_bit_cast(float, __builtin_amdgcn_ds_bpermute((l ^ o) << 2, __builtin_bit_cast(int, v)));
; }
; __device__ __forceinline__ float wave_sum(float v) {
; #pragma unroll
;     for (int o = 1; o < 64; o <<= 1) v += shfl_xor_f(v, o);
;     return v;
; template <int XF32> __device__ __forceinline__ void norm_mod_phase(const void* x, const float* modl, int ch_shift, int ch_scale, bf16* H, int gw, int NGW, int lane) {
;     ...
;         for (int rr = 0; rr < 8; ++rr) {
;             const unsigned char* xr = (const unsigned char*)x + (size_t)(r0 + rr) * rowb; f32x4 v[4][2]; float s = 0.f;
; #pragma unroll
;             for (int j = 0; j < 4; ++j) ld_row8<XF32>(xr, lane, j, v[j][0], v[j][1]);
; #pragma unroll
;             for (int j = 0; j < 4; ++j) s += ssq8(v[j][0], v[j][1]);
;             const float rstd = 1.f / sqrtf(wave_sum(s) * (1.f / DM) + EPS);
;             v4u* o = (v4u*)(H + (size_t)(r0 + rr) * DM);
; #pragma unroll
;             for (int j = 0; j < 4; ++j) o[lane + 64 * j] = pk8(v[j][0] * rstd * sc[j][0] + sh[j][0], v[j][1] * rstd * sc[j][1] + sh[j][1]);
;         }
	v_mov_b32_e32 v99, v98
	s_nop 1
	v_permlane32_swap_b32_e32 v99, v98
	s_nop 1
	v_add_f32_e32 v98, v98, v99
	v_fmamk_f32 v98, v98, 0x3a000000, v224
	v_cmp_gt_f32_e32 vcc, s41, v98
	v_mul_f32_e32 v99, 0x4f800000, v98
	s_nop 0
	v_cndmask_b32_e32 v98, v98, v99, vcc
	v_sqrt_f32_e32 v99, v98
	s_nop 0
	v_add_u32_e32 v102, -1, v99
	v_fma_f32 v103, -v102, v99, v98
	v_cmp_ge_f32_e64 s[0:1], 0, v103
	v_add_u32_e32 v103, 1, v99
	s_nop 0
	v_cndmask_b32_e64 v102, v99, v102, s[0:1]
	v_fma_f32 v99, -v103, v99, v98
	v_cmp_lt_f32_e64 s[0:1], 0, v99
	s_nop 1
	v_cndmask_b32_e64 v99, v102, v103, s[0:1]
	v_mul_f32_e32 v102, 0x37800000, v99
	v_cndmask_b32_e32 v99, v99, v102, vcc
	v_cmp_class_f32_e32 vcc, v98, v225
	s_nop 1
	v_cndmask_b32_e32 v98, v99, v98, vcc
	v_div_scale_f32 v99, s[0:1], v98, v98, 1.0
	v_rcp_f32_e32 v102, v99
	s_nop 0
	v_fma_f32 v103, -v99, v102, 1.0
	v_fmac_f32_e32 v102, v103, v102
	v_div_scale_f32 v103, vcc, 1.0, v98, 1.0
	v_mul_f32_e32 v106, v103, v102
	v_fma_f32 v107, -v99, v106, v103
	v_fmac_f32_e32 v106, v107, v102
	v_fma_f32 v99, -v99, v106, v103
	v_div_fmas_f32 v99, v99, v102, v106
	v_div_fixup_f32 v98, v99, v98, 1.0
	v_mov_b32_e32 v102, v96
	v_mov_b32_e32 v103, v76
	v_mov_b32_e32 v76, v97
	v_pk_mul_f32 v[102:103], v[98:99], v[102:103] op_sel_hi:[0,1]
	v_pk_mul_f32 v[76:77], v[98:99], v[76:77] op_sel_hi:[0,1]
	v_pk_fma_f32 v[96:97], v[48:49], v[76:77], v[6:7]
	v_pk_fma_f32 v[76:77], v[50:51], v[102:103], v[4:5]
	v_mov_b32_e32 v102, v100
	v_mov_b32_e32 v103, v78
	v_mov_b32_e32 v78, v101
	v_pk_mul_f32 v[102:103], v[98:99], v[102:103] op_sel_hi:[0,1]
	v_pk_mul_f32 v[78:79], v[98:99], v[78:79] op_sel_hi:[0,1]
	v_pk_fma_f32 v[100:101], v[44:45], v[78:79], v[2:3]
	v_pk_fma_f32 v[78:79], v[46:47], v[102:103], v[0:1]
	v_cvt_pk_bf16_f32 v76, v76, v77
	v_cvt_pk_bf16_f32 v77, v96, v97
	v_cvt_pk_bf16_f32 v78, v78, v79
	v_cvt_pk_bf16_f32 v79, v100, v101
	v_lshl_add_u64 v[96:97], v[34:35], 0, s[60:61]
	global_store_dwordx4 v[96:97], v[76:79], off
	s_lshl_b64 s[60:61], s[4:5], 12
	s_add_i32 s4, s4, s10
	v_mov_b32_e32 v77, v80
	v_mov_b32_e32 v80, v105
	v_mov_b32_e32 v76, v104
	v_pk_mul_f32 v[78:79], v[98:99], v[80:81] op_sel_hi:[0,1]
	v_mov_b32_e32 v80, v108
	v_mov_b32_e32 v81, v82
	v_mov_b32_e32 v82, v109
	v_pk_mul_f32 v[76:77], v[98:99], v[76:77] op_sel_hi:[0,1]
	v_pk_mul_f32 v[80:81], v[98:99], v[80:81] op_sel_hi:[0,1]
	v_pk_mul_f32 v[82:83], v[98:99], v[82:83] op_sel_hi:[0,1]
	v_pk_fma_f32 v[78:79], v[56:57], v[78:79], v[14:15]
	v_pk_fma_f32 v[76:77], v[58:59], v[76:77], v[12:13]
	v_pk_fma_f32 v[82:83], v[52:53], v[82:83], v[10:11]
	v_pk_fma_f32 v[80:81], v[54:55], v[80:81], v[8:9]
	v_cvt_pk_bf16_f32 v76, v76, v77
	v_cvt_pk_bf16_f32 v77, v78, v79
	v_cvt_pk_bf16_f32 v78, v80, v81
	v_cvt_pk_bf16_f32 v79, v82, v83
	global_store_dwordx4 v[96:97], v[76:79], off offset:1024
	v_pk_mul_f32 v[80:81], v[98:99], v[114:115] op_sel_hi:[0,1]
	v_pk_mul_f32 v[82:83], v[98:99], v[86:87] op_sel_hi:[0,1]
	v_pk_mul_f32 v[76:77], v[98:99], v[112:113] op_sel_hi:[0,1]
	v_pk_mul_f32 v[78:79], v[98:99], v[84:85] op_sel_hi:[0,1]
	v_pk_fma_f32 v[78:79], v[64:65], v[78:79], v[22:23]
	v_pk_fma_f32 v[76:77], v[66:67], v[76:77], v[20:21]
	v_pk_fma_f32 v[82:83], v[60:61], v[82:83], v[18:19]
	v_pk_fma_f32 v[80:81], v[62:63], v[80:81], v[16:17]
	v_cvt_pk_bf16_f32 v76, v76, v77
	v_cvt_pk_bf16_f32 v77, v78, v79
	v_cvt_pk_bf16_f32 v78, v80, v81
	v_cvt_pk_bf16_f32 v79, v82, v83
	global_store_dwordx4 v[96:97], v[76:79], off offset:2048
	v_pk_mul_f32 v[80:81], v[94:95], v[98:99] op_sel_hi:[1,0]
	v_pk_mul_f32 v[82:83], v[90:91], v[98:99] op_sel_hi:[1,0]
	v_pk_mul_f32 v[76:77], v[92:93], v[98:99] op_sel_hi:[1,0]
	v_pk_mul_f32 v[78:79], v[88:89], v[98:99] op_sel_hi:[1,0]
	v_pk_fma_f32 v[76:77], v[74:75], v[76:77], v[28:29]
	v_pk_fma_f32 v[78:79], v[72:73], v[78:79], v[30:31]
	v_pk_fma_f32 v[82:83], v[68:69], v[82:83], v[26:27]
	v_pk_fma_f32 v[80:81], v[70:71], v[80:81], v[24:25]
	v_cvt_pk_bf16_f32 v76, v76, v77
	v_cvt_pk_bf16_f32 v77, v78, v79
	v_cvt_pk_bf16_f32 v78, v80, v81
	v_cvt_pk_bf16_f32 v79, v82, v83
	global_store_dwordx4 v[96:97], v[76:79], off offset:3072
	s_cmpk_lt_i32 s56, 0x800
	s_waitcnt vmcnt(7)
	v_lshlrev_b32_e32 v97, 16, v195
	v_lshlrev_b32_e32 v96, 16, v194
	v_and_b32_e32 v77, 0xffff0000, v195
	v_and_b32_e32 v76, 0xffff0000, v194
	v_lshlrev_b32_e32 v101, 16, v197
	v_lshlrev_b32_e32 v100, 16, v196
	v_and_b32_e32 v79, 0xffff0000, v197
	v_and_b32_e32 v78, 0xffff0000, v196
	v_pk_mul_f32 v[98:99], v[76:77], v[76:77]
	v_pk_mul_f32 v[102:103], v[78:79], v[78:79]
	s_waitcnt vmcnt(4)
; __device__ __forceinline__ v4u pk8(f32x4 a, f32x4 b) { v4u w; w.x = pk2(a[0], a[1]); w.y = pk2(a[2], a[3]); w.z = pk2(b[0], b[1]); w.w = pk2(b[2], b[3]); return w; }
; __device__ __forceinline__ float ssq8(const f32x4& a, const f32x4& b) { return ((a[0] * a[0] + a[1] * a[1]) + (a[2] * a[2] + a[3] * a[3])) + ((b[0] * b[0] + b[1] * b[1]) + (b[2] * b[2] + b[3] * b[3])); }
; __device__ __forceinline__ float shfl_xor_f(float v, int o) {
;     int l; asm volatile("v_mbcnt_lo_u32_b32 %0, -1, 0\n\tv_mbcnt_hi_u32_b32 %0, -1, %0" : "=v"(l));
;     return __builtin_bit_cast(float, __builtin_amdgcn_ds_bpermute((l ^ o) << 2, __builtin_bit_cast(int, v)));
; }
; __device__ __forceinline__ float wave_sum(float v) {
; #pragma unroll
;     for (int o = 1; o < 64; o <<= 1) v += shfl_xor_f(v, o);
;     return v;
; template <int XF32> __device__ __forceinline__ void norm_mod_phase(const void* x, const float* modl, int ch_shift, int ch_scale, bf16* H, int gw, int NGW, int lane) {
;     ...
;         for (int rr = 0; rr < 8; ++rr) {
;             const unsigned char* xr = (const unsigned char*)x + (size_t)(r0 + rr) * rowb; f32x4 v[4][2]; float s = 0.f;
; #pragma unroll
;             for (int j = 0; j < 4; ++j) ld_row8<XF32>(xr, lane, j, v[j][0], v[j][1]);
; #pragma unroll
;             for (int j = 0; j < 4; ++j) s += ssq8(v[j][0], v[j][1]);
;             const float rstd = 1.f / sqrtf(wave_sum(s) * (1.f / DM) + EPS);
;             v4u* o = (v4u*)(H + (size_t)(r0 + rr) * DM);
; #pragma unroll
;             for (int j = 0; j < 4; ++j) o[lane + 64 * j] = pk8(v[j][0] * rstd * sc[j][0] + sh[j][0], v[j][1] * rstd * sc[j][1] + sh[j][1]);
;         }
	v_lshlrev_b32_e32 v92, 16, v206
	v_and_b32_e32 v93, 0xffff0000, v206
	v_pk_fma_f32 v[98:99], v[96:97], v[96:97], v[98:99]
	v_pk_fma_f32 v[102:103], v[100:101], v[100:101], v[102:103]
	v_lshlrev_b32_e32 v105, 16, v199
	v_lshlrev_b32_e32 v104, 16, v198
	v_and_b32_e32 v81, 0xffff0000, v199
	v_and_b32_e32 v80, 0xffff0000, v198
	v_lshlrev_b32_e32 v109, 16, v201
	v_lshlrev_b32_e32 v108, 16, v200
	v_and_b32_e32 v83, 0xffff0000, v201
	v_and_b32_e32 v82, 0xffff0000, v200
	v_pk_mul_f32 v[106:107], v[80:81], v[80:81]
	v_pk_mul_f32 v[110:111], v[82:83], v[82:83]
	v_mul_f32_e32 v116, v92, v92
	v_mul_f32_e32 v117, v93, v93
	v_pk_add_f32 v[98:99], v[98:99], v[98:99] op_sel:[0,1] op_sel_hi:[1,0]
	v_pk_add_f32 v[102:103], v[102:103], v[102:103] op_sel:[0,1] op_sel_hi:[1,0]
	v_lshlrev_b32_e32 v88, 16, v207
	v_and_b32_e32 v89, 0xffff0000, v207
	v_pk_fma_f32 v[106:107], v[104:105], v[104:105], v[106:107]
	v_pk_fma_f32 v[110:111], v[108:109], v[108:109], v[110:111]
	v_mov_b32_e32 v99, v116
	v_mov_b32_e32 v103, v117
	v_mul_f32_e32 v118, v88, v88
	v_mul_f32_e32 v119, v89, v89
	v_pk_add_f32 v[98:99], v[98:99], v[102:103]
	v_pk_add_f32 v[102:103], v[106:107], v[106:107] op_sel:[0,1] op_sel_hi:[1,0]
	v_pk_add_f32 v[106:107], v[110:111], v[110:111] op_sel:[0,1] op_sel_hi:[1,0]
	v_mov_b32_e32 v103, v118
	v_mov_b32_e32 v107, v119
	v_lshlrev_b32_e32 v112, 16, v202
	v_and_b32_e32 v113, 0xffff0000, v202
	v_lshlrev_b32_e32 v84, 16, v203
	v_and_b32_e32 v85, 0xffff0000, v203
	v_pk_add_f32 v[102:103], v[102:103], v[106:107]
	v_lshlrev_b32_e32 v94, 16, v208
	v_and_b32_e32 v95, 0xffff0000, v208
	v_pk_add_f32 v[98:99], v[98:99], v[102:103]
	v_mul_f32_e32 v102, v113, v113
	v_mul_f32_e32 v106, v85, v85
	v_mul_f32_e32 v120, v94, v94
	v_mul_f32_e32 v121, v95, v95
	v_pk_fma_f32 v[102:103], v[112:113], v[112:113], v[102:103] op_sel_hi:[1,1,0]
	v_pk_fma_f32 v[106:107], v[84:85], v[84:85], v[106:107] op_sel_hi:[1,1,0]
	v_lshlrev_b32_e32 v114, 16, v204
	v_and_b32_e32 v115, 0xffff0000, v204
	v_lshlrev_b32_e32 v86, 16, v205
	v_and_b32_e32 v87, 0xffff0000, v205
	v_mov_b32_e32 v103, v120
	v_mov_b32_e32 v107, v121
	v_lshlrev_b32_e32 v90, 16, v209
	v_and_b32_e32 v91, 0xffff0000, v209
	v_pk_add_f32 v[102:103], v[102:103], v[106:107]
	v_mul_f32_e32 v106, v115, v115
	v_mul_f32_e32 v110, v87, v87
	v_mul_f32_e32 v122, v90, v90
	v_mul_f32_e32 v123, v91, v91
	v_pk_fma_f32 v[106:107], v[114:115], v[114:115], v[106:107] op_sel_hi:[1,1,0]
	v_pk_fma_f32 v[110:111], v[86:87], v[86:87], v[110:111] op_sel_hi:[1,1,0]
	v_mov_b32_e32 v107, v122
	v_mov_b32_e32 v111, v123
	v_pk_add_f32 v[106:107], v[106:107], v[110:111]
	s_nop 0
	v_pk_add_f32 v[102:103], v[102:103], v[106:107]
	s_nop 0
	v_pk_add_f32 v[98:99], v[98:99], v[102:103]
	s_nop 0
	v_add_f32_e32 v98, v98, v99
	s_nop 1
	v_add_f32_dpp v98, v98, v98 quad_perm:[1,0,3,2] row_mask:0xf bank_mask:0xf
	s_nop 1
	v_add_f32_dpp v98, v98, v98 quad_perm:[2,3,0,1] row_mask:0xf bank_mask:0xf
	s_nop 1
	v_add_f32_dpp v98, v98, v98 row_half_mirror row_mask:0xf bank_mask:0xf
	s_nop 1
	v_add_f32_dpp v98, v98, v98 row_mirror row_mask:0xf bank_mask:0xf
	v_mov_b32_e32 v99, v98
	s_nop 1
	v_permlane16_swap_b32_e32 v99, v98
	s_nop 1
	v_add_f32_e32 v98, v98, v99
	v_mov_b32_e32 v99, v98
	s_nop 1
	v_permlane32_swap_b32_e32 v99, v98
	s_nop 1
	v_add_f32_e32 v98, v98, v99
	v_fmamk_f32 v98, v98, 0x3a000000, v224
	v_cmp_gt_f32_e32 vcc, s41, v98
	v_mul_f32_e32 v99, 0x4f800000, v98
	s_nop 0
	v_cndmask_b32_e32 v98, v98, v99, vcc
	v_sqrt_f32_e32 v99, v98
	s_nop 0
	v_add_u32_e32 v102, -1, v99
	v_fma_f32 v103, -v102, v99, v98
; __device__ __forceinline__ v4u pk8(f32x4 a, f32x4 b) { v4u w; w.x = pk2(a[0], a[1]); w.y = pk2(a[2], a[3]); w.z = pk2(b[0], b[1]); w.w = pk2(b[2], b[3]); return w; }
; template <int XF32> __device__ __forceinline__ void norm_mod_phase(const void* x, const float* modl, int ch_shift, int ch_scale, bf16* H, int gw, int NGW, int lane) {
;     ...
;             const float rstd = 1.f / sqrtf(wave_sum(s) * (1.f / DM) + EPS);
;             v4u* o = (v4u*)(H + (size_t)(r0 + rr) * DM);
; #pragma unroll
;             for (int j = 0; j < 4; ++j) o[lane + 64 * j] = pk8(v[j][0] * rstd * sc[j][0] + sh[j][0], v[j][1] * rstd * sc[j][1] + sh[j][1]);
;         }
	v_cmp_ge_f32_e64 s[0:1], 0, v103
	v_add_u32_e32 v103, 1, v99
	s_nop 0
	v_cndmask_b32_e64 v102, v99, v102, s[0:1]
	v_fma_f32 v99, -v103, v99, v98
	v_cmp_lt_f32_e64 s[0:1], 0, v99
	s_nop 1
	v_cndmask_b32_e64 v99, v102, v103, s[0:1]
	v_mul_f32_e32 v102, 0x37800000, v99
	v_cndmask_b32_e32 v99, v99, v102, vcc
	v_cmp_class_f32_e32 vcc, v98, v225
	s_nop 1
	v_cndmask_b32_e32 v98, v99, v98, vcc
	v_div_scale_f32 v99, s[0:1], v98, v98, 1.0
	v_rcp_f32_e32 v102, v99
	s_nop 0
	v_fma_f32 v103, -v99, v102, 1.0
	v_fmac_f32_e32 v102, v103, v102
	v_div_scale_f32 v103, vcc, 1.0, v98, 1.0
	v_mul_f32_e32 v106, v103, v102
	v_fma_f32 v107, -v99, v106, v103
	v_fmac_f32_e32 v106, v107, v102
	v_fma_f32 v99, -v99, v106, v103
	v_div_fmas_f32 v99, v99, v102, v106
	v_div_fixup_f32 v98, v99, v98, 1.0
	v_mov_b32_e32 v103, v76
	v_mov_b32_e32 v76, v97
	v_mov_b32_e32 v102, v96
	v_pk_mul_f32 v[76:77], v[98:99], v[76:77] op_sel_hi:[0,1]
	v_pk_mul_f32 v[102:103], v[98:99], v[102:103] op_sel_hi:[0,1]
	v_pk_fma_f32 v[6:7], v[48:49], v[76:77], v[6:7]
	v_mov_b32_e32 v48, v100
	v_mov_b32_e32 v49, v78
	v_mov_b32_e32 v78, v101
	v_pk_fma_f32 v[4:5], v[50:51], v[102:103], v[4:5]
	v_pk_mul_f32 v[48:49], v[98:99], v[48:49] op_sel_hi:[0,1]
	v_pk_mul_f32 v[50:51], v[98:99], v[78:79] op_sel_hi:[0,1]
	v_pk_fma_f32 v[44:45], v[44:45], v[50:51], v[2:3]
	v_pk_fma_f32 v[2:3], v[46:47], v[48:49], v[0:1]
	v_cvt_pk_bf16_f32 v0, v4, v5
	v_cvt_pk_bf16_f32 v1, v6, v7
	v_cvt_pk_bf16_f32 v2, v2, v3
	v_cvt_pk_bf16_f32 v3, v44, v45
	v_lshl_add_u64 v[4:5], v[34:35], 0, s[60:61]
	global_store_dwordx4 v[4:5], v[0:3], off
	v_mov_b32_e32 v6, v108
	v_mov_b32_e32 v7, v82
	v_mov_b32_e32 v0, v104
	v_mov_b32_e32 v1, v80
	v_pk_mul_f32 v[0:1], v[98:99], v[0:1] op_sel_hi:[0,1]
	v_mov_b32_e32 v80, v105
	v_mov_b32_e32 v82, v109
	v_pk_mul_f32 v[2:3], v[98:99], v[80:81] op_sel_hi:[0,1]
	v_pk_fma_f32 v[0:1], v[58:59], v[0:1], v[12:13]
	v_pk_mul_f32 v[6:7], v[98:99], v[6:7] op_sel_hi:[0,1]
	v_pk_mul_f32 v[12:13], v[98:99], v[82:83] op_sel_hi:[0,1]
	v_pk_fma_f32 v[2:3], v[56:57], v[2:3], v[14:15]
	v_pk_fma_f32 v[10:11], v[52:53], v[12:13], v[10:11]
	v_pk_fma_f32 v[6:7], v[54:55], v[6:7], v[8:9]
	v_cvt_pk_bf16_f32 v0, v0, v1
	v_cvt_pk_bf16_f32 v1, v2, v3
	v_cvt_pk_bf16_f32 v2, v6, v7
	v_cvt_pk_bf16_f32 v3, v10, v11
	global_store_dwordx4 v[4:5], v[0:3], off offset:1024
	v_pk_mul_f32 v[6:7], v[98:99], v[114:115] op_sel_hi:[0,1]
	v_pk_mul_f32 v[8:9], v[98:99], v[86:87] op_sel_hi:[0,1]
	v_pk_mul_f32 v[0:1], v[98:99], v[112:113] op_sel_hi:[0,1]
	v_pk_mul_f32 v[2:3], v[98:99], v[84:85] op_sel_hi:[0,1]
	v_pk_fma_f32 v[2:3], v[64:65], v[2:3], v[22:23]
	v_pk_fma_f32 v[0:1], v[66:67], v[0:1], v[20:21]
	v_pk_fma_f32 v[8:9], v[60:61], v[8:9], v[18:19]
	v_pk_fma_f32 v[6:7], v[62:63], v[6:7], v[16:17]
	v_cvt_pk_bf16_f32 v0, v0, v1
	v_cvt_pk_bf16_f32 v1, v2, v3
	v_cvt_pk_bf16_f32 v2, v6, v7
	v_cvt_pk_bf16_f32 v3, v8, v9
	global_store_dwordx4 v[4:5], v[0:3], off offset:2048
	v_pk_mul_f32 v[6:7], v[94:95], v[98:99] op_sel_hi:[1,0]
	v_pk_mul_f32 v[8:9], v[90:91], v[98:99] op_sel_hi:[1,0]
	v_pk_mul_f32 v[0:1], v[92:93], v[98:99] op_sel_hi:[1,0]
	v_pk_mul_f32 v[2:3], v[88:89], v[98:99] op_sel_hi:[1,0]
	v_pk_fma_f32 v[0:1], v[74:75], v[0:1], v[28:29]
	v_pk_fma_f32 v[2:3], v[72:73], v[2:3], v[30:31]
	v_pk_fma_f32 v[8:9], v[68:69], v[8:9], v[26:27]
	v_pk_fma_f32 v[6:7], v[70:71], v[6:7], v[24:25]
	v_cvt_pk_bf16_f32 v0, v0, v1
	v_cvt_pk_bf16_f32 v1, v2, v3
	v_cvt_pk_bf16_f32 v2, v6, v7
	v_cvt_pk_bf16_f32 v3, v8, v9
	global_store_dwordx4 v[4:5], v[0:3], off offset:3072
	s_cbranch_scc1 .LBB0_919

; __device__ __forceinline__ float ssq8(const f32x4& a, const f32x4& b) { return ((a[0] * a[0] + a[1] * a[1]) + (a[2] * a[2] + a[3] * a[3])) + ((b[0] * b[0] + b[1] * b[1]) + (b[2] * b[2] + b[3] * b[3])); }
; __device__ __forceinline__ void final_norm_phase(const bf16* x, const float* gain, float* out, int gw, int NGW, int lane) {
;     ...
;     for (int row = gw; row < M; row += NGW) {
;         const bf16* xr = x + (size_t)row * DM; f32x4 v[4][2]; float s = 0.f;
; #pragma unroll
;         for (int j = 0; j < 4; ++j) ld_row8<0>(xr, lane, j, v[j][0], v[j][1]);
; #pragma unroll
;         for (int j = 0; j < 4; ++j) s += ssq8(v[j][0], v[j][1]);
.LBB0_1127:
	global_load_dwordx4 v[44:47], v[54:55], off offset:3072
	global_load_dwordx4 v[40:43], v[54:55], off
	global_load_dwordx4 v[36:39], v[54:55], off offset:1024
	global_load_dwordx4 v[32:35], v[54:55], off offset:2048
	v_mbcnt_lo_u32_b32 v60, -1, 0
	v_mbcnt_hi_u32_b32 v60, -1, v60
	v_mbcnt_lo_u32_b32 v61, -1, 0
	v_mbcnt_hi_u32_b32 v61, -1, v61
	v_mbcnt_lo_u32_b32 v62, -1, 0
	v_mbcnt_hi_u32_b32 v62, -1, v62
	v_mbcnt_lo_u32_b32 v63, -1, 0
	v_mbcnt_hi_u32_b32 v63, -1, v63
	v_mbcnt_lo_u32_b32 v64, -1, 0
	v_mbcnt_hi_u32_b32 v64, -1, v64
	v_mbcnt_lo_u32_b32 v65, -1, 0
	v_mbcnt_hi_u32_b32 v65, -1, v65
	s_nop 0
	v_lshlrev_b32_e32 v60, 2, v60
	v_lshlrev_b32_e32 v64, 2, v64
	v_lshlrev_b32_e32 v65, 2, v65
	v_xor_b32_e32 v104, 64, v64
	v_xor_b32_e32 v105, 0x80, v65
	v_lshlrev_b32_e32 v61, 2, v61
	v_lshlrev_b32_e32 v62, 2, v62
	v_lshlrev_b32_e32 v63, 2, v63
	v_xor_b32_e32 v89, 4, v60
	v_xor_b32_e32 v91, 8, v61
	v_xor_b32_e32 v93, 16, v62
	v_xor_b32_e32 v95, 32, v63
	s_add_i32 s16, s16, s10
	v_lshl_add_u64 v[56:57], s[4:5], 0, v[48:49]
	v_lshl_add_u64 v[76:77], s[4:5], 0, v[50:51]
	v_lshl_add_u64 v[78:79], s[4:5], 0, v[52:53]
	s_add_u32 s4, s4, s6
	s_addc_u32 s5, s5, s7
	v_lshl_add_u64 v[54:55], v[54:55], 0, s[2:3]
	s_cmpk_lt_i32 s16, 0x4000
	s_waitcnt vmcnt(3)
	v_lshlrev_b32_e32 v60, 16, v44
	s_waitcnt vmcnt(2)
	v_lshlrev_b32_e32 v65, 16, v41
	v_lshlrev_b32_e32 v64, 16, v40
	v_and_b32_e32 v41, 0xffff0000, v41
	v_and_b32_e32 v40, 0xffff0000, v40
	v_lshlrev_b32_e32 v67, 16, v43
	v_lshlrev_b32_e32 v66, 16, v42
	v_and_b32_e32 v43, 0xffff0000, v43
	v_and_b32_e32 v42, 0xffff0000, v42
	s_waitcnt vmcnt(1)
	v_lshlrev_b32_e32 v69, 16, v37
	v_lshlrev_b32_e32 v68, 16, v36
	v_and_b32_e32 v37, 0xffff0000, v37
	v_and_b32_e32 v36, 0xffff0000, v36
	v_lshlrev_b32_e32 v71, 16, v39
	v_lshlrev_b32_e32 v70, 16, v38
	v_and_b32_e32 v39, 0xffff0000, v39
	v_and_b32_e32 v38, 0xffff0000, v38
	s_waitcnt vmcnt(0)
; __device__ __forceinline__ float ssq8(const f32x4& a, const f32x4& b) { return ((a[0] * a[0] + a[1] * a[1]) + (a[2] * a[2] + a[3] * a[3])) + ((b[0] * b[0] + b[1] * b[1]) + (b[2] * b[2] + b[3] * b[3])); }
; __device__ __forceinline__ float shfl_xor_f(float v, int o) {
;     int l; asm volatile("v_mbcnt_lo_u32_b32 %0, -1, 0\n\tv_mbcnt_hi_u32_b32 %0, -1, %0" : "=v"(l));
;     return __builtin_bit_cast(float, __builtin_amdgcn_ds_bpermute((l ^ o) << 2, __builtin_bit_cast(int, v)));
; }
; __device__ __forceinline__ float wave_sum(float v) {
; #pragma unroll
;     for (int o = 1; o < 64; o <<= 1) v += shfl_xor_f(v, o);
;     return v;
; __device__ __forceinline__ void final_norm_phase(const bf16* x, const float* gain, float* out, int gw, int NGW, int lane) {
;     ...
;     for (int row = gw; row < M; row += NGW) {
;         const bf16* xr = x + (size_t)row * DM; f32x4 v[4][2]; float s = 0.f;
; #pragma unroll
;         for (int j = 0; j < 4; ++j) ld_row8<0>(xr, lane, j, v[j][0], v[j][1]);
; #pragma unroll
;         for (int j = 0; j < 4; ++j) s += ssq8(v[j][0], v[j][1]);
;         const float rstd = 1.f / sqrtf(wave_sum(s) * (1.f / DM) + EPS);
;         f32x4* o = (f32x4*)(out + (size_t)row * DM);
; #pragma unroll
;         for (int j = 0; j < 4; ++j) { o[2 * (lane + 64 * j)] = v[j][0] * rstd * gv[j][0]; o[2 * (lane + 64 * j) + 1] = v[j][1] * rstd * gv[j][1]; }
;     }
	v_lshlrev_b32_e32 v72, 16, v32
	v_and_b32_e32 v73, 0xffff0000, v32
	v_lshlrev_b32_e32 v32, 16, v33
	v_and_b32_e32 v33, 0xffff0000, v33
	v_lshlrev_b32_e32 v74, 16, v34
	v_and_b32_e32 v75, 0xffff0000, v34
	v_lshlrev_b32_e32 v34, 16, v35
	v_and_b32_e32 v35, 0xffff0000, v35
	v_pk_mul_f32 v[80:81], v[40:41], v[40:41]
	v_pk_mul_f32 v[82:83], v[42:43], v[42:43]
	v_pk_mul_f32 v[84:85], v[36:37], v[36:37]
	v_pk_mul_f32 v[86:87], v[38:39], v[38:39]
	v_and_b32_e32 v61, 0xffff0000, v44
	v_lshlrev_b32_e32 v44, 16, v45
	v_and_b32_e32 v45, 0xffff0000, v45
	v_lshlrev_b32_e32 v62, 16, v46
	v_and_b32_e32 v63, 0xffff0000, v46
	v_lshlrev_b32_e32 v46, 16, v47
	v_and_b32_e32 v47, 0xffff0000, v47
	v_mul_f32_e32 v88, v73, v73
	v_mul_f32_e32 v90, v33, v33
	v_mul_f32_e32 v92, v75, v75
	v_mul_f32_e32 v94, v35, v35
	v_mov_b32_e32 v96, v64
	v_mov_b32_e32 v97, v40
	v_mov_b32_e32 v40, v65
	v_mov_b32_e32 v98, v66
	v_mov_b32_e32 v99, v42
	v_mov_b32_e32 v42, v67
	v_mov_b32_e32 v100, v68
	v_mov_b32_e32 v101, v36
	v_mov_b32_e32 v36, v69
	v_mov_b32_e32 v102, v70
	v_mov_b32_e32 v103, v38
	v_mov_b32_e32 v38, v71
	v_pk_fma_f32 v[64:65], v[64:65], v[64:65], v[80:81]
	v_pk_fma_f32 v[66:67], v[66:67], v[66:67], v[82:83]
	v_pk_fma_f32 v[68:69], v[68:69], v[68:69], v[84:85]
	v_pk_fma_f32 v[70:71], v[70:71], v[70:71], v[86:87]
	v_mul_f32_e32 v106, v60, v60
	v_mul_f32_e32 v107, v61, v61
	v_mul_f32_e32 v108, v44, v44
	v_mul_f32_e32 v109, v45, v45
	v_mul_f32_e32 v110, v62, v62
	v_mul_f32_e32 v111, v63, v63
	v_mul_f32_e32 v112, v46, v46
	v_mul_f32_e32 v113, v47, v47
	v_pk_fma_f32 v[80:81], v[72:73], v[72:73], v[88:89] op_sel_hi:[1,1,0]
	v_pk_fma_f32 v[82:83], v[32:33], v[32:33], v[90:91] op_sel_hi:[1,1,0]
	v_pk_fma_f32 v[84:85], v[74:75], v[74:75], v[92:93] op_sel_hi:[1,1,0]
	v_pk_fma_f32 v[86:87], v[34:35], v[34:35], v[94:95] op_sel_hi:[1,1,0]
	v_pk_add_f32 v[64:65], v[64:65], v[64:65] op_sel:[0,1] op_sel_hi:[1,0]
	v_pk_add_f32 v[66:67], v[66:67], v[66:67] op_sel:[0,1] op_sel_hi:[1,0]
	v_pk_add_f32 v[68:69], v[68:69], v[68:69] op_sel:[0,1] op_sel_hi:[1,0]
	v_pk_add_f32 v[70:71], v[70:71], v[70:71] op_sel:[0,1] op_sel_hi:[1,0]
	v_mov_b32_e32 v81, v110
	v_mov_b32_e32 v83, v111
	v_mov_b32_e32 v85, v112
	v_mov_b32_e32 v87, v113
	v_mov_b32_e32 v65, v106
	v_mov_b32_e32 v67, v107
	v_mov_b32_e32 v69, v108
	v_mov_b32_e32 v71, v109
	v_pk_add_f32 v[80:81], v[80:81], v[82:83]
	v_pk_add_f32 v[82:83], v[84:85], v[86:87]
	v_pk_add_f32 v[64:65], v[64:65], v[66:67]
	v_pk_add_f32 v[66:67], v[68:69], v[70:71]
	v_pk_add_f32 v[68:69], v[80:81], v[82:83]
	v_pk_add_f32 v[64:65], v[64:65], v[66:67]
	s_nop 0
	v_pk_add_f32 v[64:65], v[64:65], v[68:69]
	s_nop 0
	v_add_f32_e32 v64, v64, v65
	s_nop 1
	v_add_f32_dpp v64, v64, v64 quad_perm:[1,0,3,2] row_mask:0xf bank_mask:0xf
	s_nop 1
	v_add_f32_dpp v64, v64, v64 quad_perm:[2,3,0,1] row_mask:0xf bank_mask:0xf
	s_nop 1
	v_add_f32_dpp v64, v64, v64 row_half_mirror row_mask:0xf bank_mask:0xf
	s_nop 1
	v_add_f32_dpp v64, v64, v64 row_mirror row_mask:0xf bank_mask:0xf
	v_mov_b32_e32 v65, v64
	s_nop 1
	v_permlane16_swap_b32_e32 v65, v64
	s_nop 1
	v_add_f32_e32 v64, v64, v65
	v_mov_b32_e32 v65, v64
	s_nop 1
	v_permlane32_swap_b32_e32 v65, v64
	s_nop 1
	v_add_f32_e32 v64, v64, v65
	v_fmamk_f32 v64, v64, 0x3a000000, v58
	v_mul_f32_e32 v65, 0x4f800000, v64
	v_cmp_gt_f32_e32 vcc, s8, v64
	s_nop 1
	v_cndmask_b32_e32 v64, v64, v65, vcc
	v_sqrt_f32_e32 v65, v64
	s_nop 0
	v_add_u32_e32 v66, -1, v65
	v_add_u32_e32 v67, 1, v65
	v_fma_f32 v68, -v66, v65, v64
	v_fma_f32 v69, -v67, v65, v64
	v_cmp_ge_f32_e64 s[0:1], 0, v68
	s_nop 1
	v_cndmask_b32_e64 v65, v65, v66, s[0:1]
	v_cmp_lt_f32_e64 s[0:1], 0, v69
	s_nop 1
	v_cndmask_b32_e64 v65, v65, v67, s[0:1]
	v_mul_f32_e32 v66, 0x37800000, v65
	v_cndmask_b32_e32 v65, v65, v66, vcc
	v_cmp_class_f32_e32 vcc, v64, v59
	s_nop 1
	v_cndmask_b32_e32 v64, v65, v64, vcc
	v_div_scale_f32 v65, s[0:1], v64, v64, 1.0
	v_rcp_f32_e32 v67, v65
	v_div_scale_f32 v66, vcc, 1.0, v64, 1.0
	v_fma_f32 v68, -v65, v67, 1.0
	v_fmac_f32_e32 v67, v68, v67
	v_mul_f32_e32 v68, v66, v67
	v_fma_f32 v69, -v65, v68, v66
	v_fmac_f32_e32 v68, v69, v67
	v_fma_f32 v65, -v65, v68, v66
	v_div_fmas_f32 v65, v65, v67, v68
	v_div_fixup_f32 v64, v65, v64, 1.0
	v_pk_mul_f32 v[66:67], v[64:65], v[96:97] op_sel_hi:[0,1]
	v_pk_mul_f32 v[40:41], v[64:65], v[40:41] op_sel_hi:[0,1]
	v_pk_mul_f32 v[68:69], v[64:65], v[98:99] op_sel_hi:[0,1]
	v_pk_mul_f32 v[42:43], v[64:65], v[42:43] op_sel_hi:[0,1]
	v_pk_mul_f32 v[70:71], v[64:65], v[100:101] op_sel_hi:[0,1]
	v_pk_mul_f32 v[80:81], v[64:65], v[36:37] op_sel_hi:[0,1]
	v_pk_mul_f32 v[82:83], v[64:65], v[102:103] op_sel_hi:[0,1]
	v_pk_mul_f32 v[84:85], v[64:65], v[38:39] op_sel_hi:[0,1]
	v_pk_mul_f32 v[72:73], v[64:65], v[72:73] op_sel_hi:[0,1]
	v_pk_mul_f32 v[86:87], v[64:65], v[32:33] op_sel_hi:[0,1]
	v_pk_mul_f32 v[74:75], v[64:65], v[74:75] op_sel_hi:[0,1]
	v_pk_mul_f32 v[88:89], v[64:65], v[34:35] op_sel_hi:[0,1]
	v_pk_mul_f32 v[90:91], v[60:61], v[64:65] op_sel_hi:[1,0]
	v_pk_mul_f32 v[92:93], v[44:45], v[64:65] op_sel_hi:[1,0]
	v_pk_mul_f32 v[94:95], v[62:63], v[64:65] op_sel_hi:[1,0]
	v_pk_mul_f32 v[96:97], v[46:47], v[64:65] op_sel_hi:[1,0]
	v_pk_mul_f32 v[34:35], v[6:7], v[40:41]
	v_pk_mul_f32 v[32:33], v[4:5], v[66:67]
	v_pk_mul_f32 v[38:39], v[2:3], v[42:43]
	v_pk_mul_f32 v[36:37], v[0:1], v[68:69]
	v_pk_mul_f32 v[42:43], v[14:15], v[80:81]
	v_pk_mul_f32 v[40:41], v[12:13], v[70:71]
	v_pk_mul_f32 v[46:47], v[10:11], v[84:85]
	v_pk_mul_f32 v[44:45], v[8:9], v[82:83]
	v_pk_mul_f32 v[62:63], v[22:23], v[86:87]
	v_pk_mul_f32 v[60:61], v[20:21], v[72:73]
	v_pk_mul_f32 v[66:67], v[18:19], v[88:89]
	v_pk_mul_f32 v[64:65], v[16:17], v[74:75]
	v_pk_mul_f32 v[70:71], v[30:31], v[92:93]
	v_pk_mul_f32 v[68:69], v[28:29], v[90:91]
	v_pk_mul_f32 v[74:75], v[26:27], v[96:97]
	v_pk_mul_f32 v[72:73], v[24:25], v[94:95]
	global_store_dwordx4 v[56:57], v[32:35], off
	global_store_dwordx4 v[56:57], v[36:39], off offset:16
	global_store_dwordx4 v[56:57], v[40:43], off offset:2048
	global_store_dwordx4 v[56:57], v[44:47], off offset:2064
	global_store_dwordx4 v[76:77], v[60:63], off
	global_store_dwordx4 v[76:77], v[64:67], off offset:16
	global_store_dwordx4 v[78:79], v[68:71], off
	global_store_dwordx4 v[78:79], v[72:75], off offset:16
	s_cbranch_scc1 .LBB0_1127
